# nt (streaming) cache policy on epilogue stores that are not re-read soon: SwiGLU ACT (G1/G6), merge-gate u8 (G3b), LU + layer-1 weight-conversion stores in the GA phase; on top of v54
# speedup vs baseline: 1.0013x; 1.0002x over previous
; __device__ __forceinline__ void row_rstd(const unsigned long long* ssq, int row0, float (&rs)[2][4]) {
;     unsigned long long q[2][4];
; #pragma unroll
;     for (int ai = 0; ai < 2; ++ai)
; #pragma unroll
;         for (int m = 0; m < 4; ++m) q[ai][m] = ssq[row0 + ai * HALF + m * 16];
;     asm volatile("" : "+v"(q[0][0]), "+v"(q[0][1]), "+v"(q[0][2]), "+v"(q[0][3]), "+v"(q[1][0]), "+v"(q[1][1]), "+v"(q[1][2]), "+v"(q[1][3]));
; #pragma unroll
;     for (int ai = 0; ai < 2; ++ai)
; #pragma unroll
;         for (int m = 0; m < 4; ++m) {
;             const float qf = __builtin_fmaf((float)(unsigned)(q[ai][m] >> 32), 4294967296.0f, (float)(unsigned)q[ai][m]);
;     template <int QVV> __device__ __forceinline__ void run(f32x4 (&acc)[2][2][4][2], const Unit& u, int wr, int wc, int fr, int fq) const {
;         constexpr int nai = (QVV == 2) ? 1 : 2; const int r0 = u.pm * BM + (QVV == 2 ? (u.seg - 1) * HALF : 0);
;         char* tb = (char*)(O + (size_t)r0 * DFF + u.pn * HALF);
;         const int v = u.pm < 4 ? 4 : ((u.pm - 4) >> 5);
;         const char* swb = (const char*)(sw + (size_t)v * SWLD + u.pn * BM);
;         unsigned lo = (unsigned)((wr * 64 + fr) * DFF + wc * 32 + 8 * fq) * 2u;
;         unsigned co = (unsigned)(wc * 32 + 8 * fq) * 4u;
;         asm volatile("" : "+v"(lo), "+v"(co));
;         float rs[2][4]; row_rstd(ssq, r0 + wr * 64 + fr, rs);
;         f32x4 sg[2], su[2], sgn[2];
; #pragma unroll
;         for (int n = 0; n < 2; ++n) { sg[n] = *(const f32x4*)(swb + co + n * 16); su[n] = *(const f32x4*)(swb + co + HALF * 4 + n * 16); sgn[n] = sg[n] * (-LOG2E); }
; #pragma unroll
;         for (int ai = 0; ai < 2; ++ai)
; #pragma unroll
;             for (int m = 0; m < 4; ++m) { if (ai >= nai) continue;
;                 const float r = rs[ai][m], rn = r * (-LOG2E);
;                 f32x4 o[2];
; #pragma unroll
;                 for (int n = 0; n < 2; ++n) {
;                     const f32x4 gt = acc[ai][0][m][n] * r + sg[n], up = acc[ai][1][m][n] * r + su[n], ex = acc[ai][0][m][n] * rn + sgn[n];
;                     f32x4 den, rc;
; #pragma unroll
;                     for (int i = 0; i < 4; ++i) den[i] = __builtin_amdgcn_exp2f(ex[i]);
;                     den = den + 1.0f;
; #pragma unroll
;                     for (int i = 0; i < 4; ++i) rc[i] = __builtin_amdgcn_rcpf(den[i]);
;                     o[n] = (gt * up) * rc; }
.LBB0_228:
	s_lshl_b32 s30, s49, 8
	v_add_u32_e32 v82, s30, v169
	v_ashrrev_i32_e32 v83, 31, v82
	v_mov_b32_e32 v166, v170
	v_mov_b32_e32 v98, v171
	v_lshl_add_u64 v[82:83], v[82:83], 3, s[34:35]
	global_load_dwordx2 v[150:151], v[82:83], off
	global_load_dwordx2 v[152:153], v[82:83], off offset:128
	global_load_dwordx2 v[154:155], v[82:83], off offset:256
	global_load_dwordx2 v[156:157], v[82:83], off offset:384
	global_load_dwordx2 v[178:179], v[82:83], off offset:1024
	global_load_dwordx2 v[180:181], v[82:83], off offset:1152
	global_load_dwordx2 v[182:183], v[82:83], off offset:1280
	global_load_dwordx2 v[184:185], v[82:83], off offset:1408
	s_mul_i32 s31, s49, 0x2b0000
	s_mul_hi_i32 s30, s30, 0x2b00
	s_add_u32 s49, s5, s31
	s_addc_u32 s50, s7, s30
	s_lshl_b32 s30, s48, 7
	s_ashr_i32 s31, s30, 31
	s_lshl_b64 s[30:31], s[30:31], 1
	s_add_u32 s30, s49, s30
	s_addc_u32 s31, s50, s31
	s_lshl_b64 s[42:43], s[42:43], 2
	s_add_u32 s49, s2, s42
	s_addc_u32 s50, s3, s43
	s_lshl_b32 s42, s48, 8
	s_ashr_i32 s43, s42, 31
	s_lshl_b64 s[42:43], s[42:43], 2
	s_add_u32 s42, s49, s42
	s_addc_u32 s43, s50, s43
	s_flbit_i32_b32 s48, 0
	s_min_u32 s48, s48, 32
	s_sub_i32 s49, 32, s48
	v_mov_b32_e32 v167, v175
	v_lshl_add_u64 v[146:147], s[30:31], 0, v[166:167]
	s_waitcnt vmcnt(0)
	global_load_dwordx4 v[86:89], v98, s[42:43] offset:16
	global_load_dwordx4 v[102:105], v98, s[42:43]
	global_load_dwordx4 v[82:85], v98, s[42:43] offset:528
	s_nop 0
	global_load_dwordx4 v[98:101], v98, s[42:43] offset:512
	v_mov_b32_e32 v174, v151
	v_cvt_f32_u32_e32 v148, v150
	v_lshlrev_b64 v[150:151], s48, v[174:175]
	v_mov_b32_e32 v174, v153
	v_cvt_f32_u32_e32 v158, v152
	v_min_u32_e32 v150, 1, v150
	v_lshlrev_b64 v[152:153], s48, v[174:175]
	v_mov_b32_e32 v174, v155
	v_or_b32_e32 v155, v151, v150
	v_min_u32_e32 v152, 1, v152
	v_lshlrev_b64 v[150:151], s48, v[174:175]
	v_mov_b32_e32 v174, v157
	v_cvt_f32_u32_e32 v155, v155
	v_or_b32_e32 v157, v153, v152
	v_min_u32_e32 v150, 1, v150
	v_lshlrev_b64 v[152:153], s48, v[174:175]
	v_mov_b32_e32 v174, v179
	v_cvt_f32_u32_e32 v157, v157
	v_or_b32_e32 v162, v151, v150
	v_min_u32_e32 v152, 1, v152
	v_lshlrev_b64 v[150:151], s48, v[174:175]
	v_mov_b32_e32 v174, v181
	v_cvt_f32_u32_e32 v162, v162
	v_or_b32_e32 v164, v153, v152
	v_min_u32_e32 v150, 1, v150
	v_lshlrev_b64 v[152:153], s48, v[174:175]
	v_mov_b32_e32 v174, v183
	v_cvt_f32_u32_e32 v154, v154
	v_cvt_f32_u32_e32 v164, v164
	v_or_b32_e32 v168, v151, v150
	v_lshlrev_b64 v[150:151], s48, v[174:175]
	v_cvt_f32_u32_e32 v156, v156
	v_min_u32_e32 v152, 1, v152
	v_mov_b32_e32 v174, v185
	v_ldexp_f32 v155, v155, s49
	v_cvt_f32_u32_e32 v168, v168
	v_min_u32_e32 v150, 1, v150
	v_cvt_f32_u32_e32 v160, v178
	v_or_b32_e32 v178, v153, v152
	v_lshlrev_b64 v[152:153], s48, v[174:175]
	v_fmac_f32_e32 v148, 0x4f800000, v155
	v_ldexp_f32 v155, v157, s49
	v_or_b32_e32 v150, v151, v150
	v_cvt_f32_u32_e32 v157, v178
	v_min_u32_e32 v151, 1, v152
	v_fmamk_f32 v148, v148, 0x30000000, v231
	v_fmac_f32_e32 v158, 0x4f800000, v155
	v_ldexp_f32 v152, v162, s49
	v_cvt_f32_u32_e32 v150, v150
	v_cvt_f32_u32_e32 v167, v180
	v_cvt_f32_u32_e32 v177, v182
	v_or_b32_e32 v151, v153, v151
	v_rsq_f32_e32 v174, v148
	v_fmamk_f32 v148, v158, 0x30000000, v231
	v_fmac_f32_e32 v154, 0x4f800000, v152
	v_ldexp_f32 v152, v164, s49
	v_cvt_f32_u32_e32 v151, v151
	v_rsq_f32_e32 v178, v148
	v_fmamk_f32 v148, v154, 0x30000000, v231
	v_fmac_f32_e32 v156, 0x4f800000, v152
	v_ldexp_f32 v152, v168, s49
	v_cvt_f32_u32_e32 v188, v184
	v_rsq_f32_e32 v168, v148
	v_fmamk_f32 v148, v156, 0x30000000, v231
	v_fmac_f32_e32 v160, 0x4f800000, v152
	v_ldexp_f32 v152, v157, s49
	v_rsq_f32_e32 v164, v148
	v_fmamk_f32 v148, v160, 0x30000000, v231
	v_ldexp_f32 v150, v150, s49
	v_fmac_f32_e32 v167, 0x4f800000, v152
	v_rsq_f32_e32 v162, v148
	v_fmac_f32_e32 v177, 0x4f800000, v150
	v_mul_f32_e32 v148, 0xbfb8aa3b, v174
	s_mov_b32 s42, 0xbfb8aa3b
	v_fmamk_f32 v152, v167, 0x30000000, v231
	v_ldexp_f32 v150, v151, s49
	v_fmamk_f32 v151, v177, 0x30000000, v231
	v_pk_mul_f32 v[182:183], v[142:143], v[148:149] op_sel_hi:[1,0]
	s_waitcnt vmcnt(2)
	v_pk_mul_f32 v[156:157], v[102:103], s[42:43] op_sel_hi:[1,0]
	v_rsq_f32_e32 v160, v152
	v_fmac_f32_e32 v188, 0x4f800000, v150
	v_pk_mul_f32 v[180:181], v[144:145], v[148:149] op_sel_hi:[1,0]
	v_pk_mul_f32 v[184:185], v[136:137], v[148:149] op_sel_hi:[1,0]
	v_pk_mul_f32 v[186:187], v[134:135], v[148:149] op_sel_hi:[1,0]
	v_rsq_f32_e32 v158, v151
	v_pk_mul_f32 v[154:155], v[104:105], s[42:43] op_sel_hi:[1,0]
	v_pk_mul_f32 v[150:151], v[88:89], s[42:43] op_sel_hi:[1,0]
	v_pk_mul_f32 v[152:153], v[86:87], s[42:43] op_sel_hi:[1,0]
	v_pk_fma_f32 v[144:145], v[144:145], v[174:175], v[104:105] op_sel_hi:[1,0,1]
	v_pk_fma_f32 v[142:143], v[142:143], v[174:175], v[102:103] op_sel_hi:[1,0,1]
	s_waitcnt vmcnt(0)
;     template <int QVV> __device__ __forceinline__ void run(f32x4 (&acc)[2][2][4][2], const Unit& u, int wr, int wc, int fr, int fq) const {
;     ...
; #pragma unroll
;         for (int ai = 0; ai < 2; ++ai)
; #pragma unroll
;             for (int m = 0; m < 4; ++m) { if (ai >= nai) continue;
;                 const float r = rs[ai][m], rn = r * (-LOG2E);
;                 f32x4 o[2];
; #pragma unroll
;                 for (int n = 0; n < 2; ++n) {
;                     const f32x4 gt = acc[ai][0][m][n] * r + sg[n], up = acc[ai][1][m][n] * r + su[n], ex = acc[ai][0][m][n] * rn + sgn[n];
;                     f32x4 den, rc;
; #pragma unroll
;                     for (int i = 0; i < 4; ++i) den[i] = __builtin_amdgcn_exp2f(ex[i]);
;                     den = den + 1.0f;
; #pragma unroll
;                     for (int i = 0; i < 4; ++i) rc[i] = __builtin_amdgcn_rcpf(den[i]);
;                     o[n] = (gt * up) * rc; }
;                 u32x4 w; w.x = pk2(o[0][0], o[0][1]); w.y = pk2(o[0][2], o[0][3]); w.z = pk2(o[1][0], o[1][1]); w.w = pk2(o[1][2], o[1][3]);
;                 *(u32x4*)(tb + lo + (unsigned)(ai * HALF + m * 16) * (DFF * 2)) = w; }
	v_pk_fma_f32 v[140:141], v[140:141], v[174:175], v[100:101] op_sel_hi:[1,0,1]
	v_pk_fma_f32 v[138:139], v[138:139], v[174:175], v[98:99] op_sel_hi:[1,0,1]
	v_pk_fma_f32 v[136:137], v[136:137], v[174:175], v[88:89] op_sel_hi:[1,0,1]
	v_pk_fma_f32 v[134:135], v[134:135], v[174:175], v[86:87] op_sel_hi:[1,0,1]
	v_pk_fma_f32 v[132:133], v[132:133], v[174:175], v[84:85] op_sel_hi:[1,0,1]
	v_pk_fma_f32 v[130:131], v[130:131], v[174:175], v[82:83] op_sel_hi:[1,0,1]
	v_add_f32_e32 v167, v156, v182
	v_add_f32_e32 v174, v157, v183
	v_add_f32_e32 v177, v154, v180
	v_add_f32_e32 v179, v155, v181
	v_pk_mul_f32 v[138:139], v[142:143], v[138:139]
	v_pk_mul_f32 v[140:141], v[144:145], v[140:141]
	v_add_f32_e32 v142, v152, v186
	v_add_f32_e32 v143, v153, v187
	v_add_f32_e32 v144, v150, v184
	v_add_f32_e32 v145, v151, v185
	v_pk_mul_f32 v[130:131], v[134:135], v[130:131]
	v_exp_f32_e32 v134, v167
	v_exp_f32_e32 v135, v174
	v_pk_mul_f32 v[132:133], v[136:137], v[132:133]
	v_exp_f32_e32 v136, v177
	v_exp_f32_e32 v137, v179
	v_exp_f32_e32 v142, v142
	v_exp_f32_e32 v144, v144
	v_exp_f32_e32 v145, v145
	v_exp_f32_e32 v143, v143
	v_pk_add_f32 v[134:135], v[134:135], 1.0 op_sel_hi:[1,0]
	v_pk_add_f32 v[136:137], v[136:137], 1.0 op_sel_hi:[1,0]
	v_pk_add_f32 v[144:145], v[144:145], 1.0 op_sel_hi:[1,0]
	v_pk_add_f32 v[142:143], v[142:143], 1.0 op_sel_hi:[1,0]
	v_rcp_f32_e32 v134, v134
	v_rcp_f32_e32 v135, v135
	v_rcp_f32_e32 v136, v136
	v_rcp_f32_e32 v137, v137
	v_rcp_f32_e32 v142, v142
	v_rcp_f32_e32 v144, v144
	v_rcp_f32_e32 v145, v145
	v_rcp_f32_e32 v143, v143
	v_pk_mul_f32 v[134:135], v[138:139], v[134:135]
	v_pk_mul_f32 v[136:137], v[140:141], v[136:137]
	v_pk_mul_f32 v[138:139], v[132:133], v[144:145]
	v_pk_mul_f32 v[132:133], v[130:131], v[142:143]
	v_cvt_pk_bf16_f32 v130, v134, v135
	v_mul_f32_e32 v134, 0xbfb8aa3b, v178
	v_cvt_pk_bf16_f32 v131, v136, v137
	v_pk_mul_f32 v[136:137], v[128:129], v[134:135] op_sel_hi:[1,0]
	v_pk_mul_f32 v[140:141], v[126:127], v[134:135] op_sel_hi:[1,0]
	v_add_f32_e32 v135, v154, v136
	v_exp_f32_e32 v136, v135
	v_add_f32_e32 v135, v155, v137
	v_pk_fma_f32 v[128:129], v[128:129], v[178:179], v[104:105] op_sel_hi:[1,0,1]
	v_pk_fma_f32 v[126:127], v[126:127], v[178:179], v[102:103] op_sel_hi:[1,0,1]
	v_pk_fma_f32 v[124:125], v[124:125], v[178:179], v[100:101] op_sel_hi:[1,0,1]
	v_pk_fma_f32 v[122:123], v[122:123], v[178:179], v[98:99] op_sel_hi:[1,0,1]
	v_pk_mul_f32 v[124:125], v[128:129], v[124:125]
	v_pk_mul_f32 v[122:123], v[126:127], v[122:123]
	v_pk_mul_f32 v[126:127], v[120:121], v[134:135] op_sel_hi:[1,0]
	v_pk_mul_f32 v[128:129], v[118:119], v[134:135] op_sel_hi:[1,0]
	v_cvt_pk_bf16_f32 v132, v132, v133
	v_add_f32_e32 v133, v156, v140
	v_add_f32_e32 v128, v152, v128
	v_add_f32_e32 v129, v153, v129
	v_add_f32_e32 v126, v150, v126
	v_add_f32_e32 v127, v151, v127
	v_exp_f32_e32 v140, v133
	v_add_f32_e32 v133, v157, v141
	v_exp_f32_e32 v128, v128
	v_exp_f32_e32 v126, v126
	v_exp_f32_e32 v127, v127
	v_exp_f32_e32 v129, v129
	v_exp_f32_e32 v141, v133
	v_cvt_pk_bf16_f32 v133, v138, v139
	v_pk_add_f32 v[126:127], v[126:127], 1.0 op_sel_hi:[1,0]
	v_pk_add_f32 v[128:129], v[128:129], 1.0 op_sel_hi:[1,0]
	global_store_dwordx4 v166, v[130:133], s[30:31] nt
	v_rcp_f32_e32 v128, v128
	v_rcp_f32_e32 v129, v129
	v_pk_add_f32 v[132:133], v[140:141], 1.0 op_sel_hi:[1,0]
	v_rcp_f32_e32 v126, v126
	v_rcp_f32_e32 v127, v127
	v_rcp_f32_e32 v132, v132
	v_rcp_f32_e32 v133, v133
	v_pk_fma_f32 v[120:121], v[120:121], v[178:179], v[88:89] op_sel_hi:[1,0,1]
	v_pk_fma_f32 v[118:119], v[118:119], v[178:179], v[86:87] op_sel_hi:[1,0,1]
	v_pk_fma_f32 v[116:117], v[116:117], v[178:179], v[84:85] op_sel_hi:[1,0,1]
	v_pk_fma_f32 v[114:115], v[114:115], v[178:179], v[82:83] op_sel_hi:[1,0,1]
	v_pk_mul_f32 v[116:117], v[120:121], v[116:117]
	v_pk_mul_f32 v[114:115], v[118:119], v[114:115]
	v_pk_mul_f32 v[118:119], v[116:117], v[126:127]
	v_pk_mul_f32 v[116:117], v[114:115], v[128:129]
	v_pk_mul_f32 v[122:123], v[122:123], v[132:133]
	v_cvt_pk_bf16_f32 v116, v116, v117
	v_cvt_pk_bf16_f32 v117, v118, v119
	v_mul_f32_e32 v118, 0xbfb8aa3b, v168
	v_exp_f32_e32 v137, v135
	v_cvt_pk_bf16_f32 v114, v122, v123
	v_pk_mul_f32 v[122:123], v[110:111], v[118:119] op_sel_hi:[1,0]
	v_pk_mul_f32 v[120:121], v[112:113], v[118:119] op_sel_hi:[1,0]
	v_add_f32_e32 v119, v156, v122
	v_exp_f32_e32 v122, v119
	v_add_f32_e32 v119, v157, v123
	v_exp_f32_e32 v123, v119
	v_add_f32_e32 v119, v154, v120
	v_pk_add_f32 v[130:131], v[136:137], 1.0 op_sel_hi:[1,0]
	v_exp_f32_e32 v120, v119
	v_add_f32_e32 v119, v155, v121
	v_pk_fma_f32 v[112:113], v[112:113], v[168:169], v[104:105] op_sel_hi:[1,0,1]
	v_pk_fma_f32 v[110:111], v[110:111], v[168:169], v[102:103] op_sel_hi:[1,0,1]
	v_pk_fma_f32 v[108:109], v[108:109], v[168:169], v[100:101] op_sel_hi:[1,0,1]
	v_pk_fma_f32 v[106:107], v[106:107], v[168:169], v[98:99] op_sel_hi:[1,0,1]
	v_rcp_f32_e32 v130, v130
	v_rcp_f32_e32 v131, v131
	v_pk_mul_f32 v[106:107], v[110:111], v[106:107]
	v_pk_mul_f32 v[108:109], v[112:113], v[108:109]
	v_pk_mul_f32 v[110:111], v[96:97], v[118:119] op_sel_hi:[1,0]
	v_pk_mul_f32 v[112:113], v[94:95], v[118:119] op_sel_hi:[1,0]
	v_add_f32_e32 v110, v150, v110
	v_add_f32_e32 v112, v152, v112
	v_add_f32_e32 v113, v153, v113
	v_add_f32_e32 v111, v151, v111
	v_exp_f32_e32 v112, v112
	v_exp_f32_e32 v110, v110
	v_exp_f32_e32 v111, v111
	v_exp_f32_e32 v113, v113
	v_pk_mul_f32 v[124:125], v[124:125], v[130:131]
	s_mov_b32 s30, 0x2b000
	v_cvt_pk_bf16_f32 v115, v124, v125
	v_add_co_u32_e32 v124, vcc, s30, v146
	v_pk_add_f32 v[110:111], v[110:111], 1.0 op_sel_hi:[1,0]
	s_nop 0
	v_addc_co_u32_e32 v125, vcc, 0, v147, vcc
;     template <int QVV> __device__ __forceinline__ void run(f32x4 (&acc)[2][2][4][2], const Unit& u, int wr, int wc, int fr, int fq) const {
;     ...
; #pragma unroll
;         for (int ai = 0; ai < 2; ++ai)
; #pragma unroll
;             for (int m = 0; m < 4; ++m) { if (ai >= nai) continue;
;                 const float r = rs[ai][m], rn = r * (-LOG2E);
;                 f32x4 o[2];
; #pragma unroll
;                 for (int n = 0; n < 2; ++n) {
;                     const f32x4 gt = acc[ai][0][m][n] * r + sg[n], up = acc[ai][1][m][n] * r + su[n], ex = acc[ai][0][m][n] * rn + sgn[n];
;                     f32x4 den, rc;
; #pragma unroll
;                     for (int i = 0; i < 4; ++i) den[i] = __builtin_amdgcn_exp2f(ex[i]);
;                     den = den + 1.0f;
; #pragma unroll
;                     for (int i = 0; i < 4; ++i) rc[i] = __builtin_amdgcn_rcpf(den[i]);
;                     o[n] = (gt * up) * rc; }
;                 u32x4 w; w.x = pk2(o[0][0], o[0][1]); w.y = pk2(o[0][2], o[0][3]); w.z = pk2(o[1][0], o[1][1]); w.w = pk2(o[1][2], o[1][3]);
;                 *(u32x4*)(tb + lo + (unsigned)(ai * HALF + m * 16) * (DFF * 2)) = w; }
	v_pk_add_f32 v[112:113], v[112:113], 1.0 op_sel_hi:[1,0]
	global_store_dwordx4 v[124:125], v[114:117], off nt
	v_rcp_f32_e32 v112, v112
	v_rcp_f32_e32 v113, v113
	v_pk_add_f32 v[116:117], v[122:123], 1.0 op_sel_hi:[1,0]
	v_rcp_f32_e32 v110, v110
	v_rcp_f32_e32 v111, v111
	v_rcp_f32_e32 v116, v116
	v_rcp_f32_e32 v117, v117
	v_pk_fma_f32 v[96:97], v[96:97], v[168:169], v[88:89] op_sel_hi:[1,0,1]
	v_pk_fma_f32 v[94:95], v[94:95], v[168:169], v[86:87] op_sel_hi:[1,0,1]
	v_pk_fma_f32 v[92:93], v[92:93], v[168:169], v[84:85] op_sel_hi:[1,0,1]
	v_pk_fma_f32 v[90:91], v[90:91], v[168:169], v[82:83] op_sel_hi:[1,0,1]
	v_pk_mul_f32 v[92:93], v[96:97], v[92:93]
	v_pk_mul_f32 v[90:91], v[94:95], v[90:91]
	v_pk_mul_f32 v[94:95], v[92:93], v[110:111]
	v_pk_mul_f32 v[92:93], v[90:91], v[112:113]
	v_pk_mul_f32 v[106:107], v[106:107], v[116:117]
	v_cvt_pk_bf16_f32 v92, v92, v93
	v_cvt_pk_bf16_f32 v93, v94, v95
	v_mul_f32_e32 v94, 0xbfb8aa3b, v164
	v_exp_f32_e32 v121, v119
	v_cvt_pk_bf16_f32 v90, v106, v107
	v_pk_mul_f32 v[106:107], v[78:79], v[94:95] op_sel_hi:[1,0]
	v_pk_mul_f32 v[96:97], v[80:81], v[94:95] op_sel_hi:[1,0]
	v_add_f32_e32 v95, v156, v106
	v_exp_f32_e32 v106, v95
	v_add_f32_e32 v95, v157, v107
	v_exp_f32_e32 v107, v95
	v_add_f32_e32 v95, v154, v96
	v_pk_add_f32 v[114:115], v[120:121], 1.0 op_sel_hi:[1,0]
	v_exp_f32_e32 v96, v95
	v_add_f32_e32 v95, v155, v97
	v_pk_fma_f32 v[80:81], v[80:81], v[164:165], v[104:105] op_sel_hi:[1,0,1]
	v_pk_fma_f32 v[78:79], v[78:79], v[164:165], v[102:103] op_sel_hi:[1,0,1]
	v_pk_fma_f32 v[76:77], v[76:77], v[164:165], v[100:101] op_sel_hi:[1,0,1]
	v_pk_fma_f32 v[74:75], v[74:75], v[164:165], v[98:99] op_sel_hi:[1,0,1]
	v_rcp_f32_e32 v114, v114
	v_rcp_f32_e32 v115, v115
	v_pk_mul_f32 v[74:75], v[78:79], v[74:75]
	v_pk_mul_f32 v[76:77], v[80:81], v[76:77]
	v_pk_mul_f32 v[78:79], v[72:73], v[94:95] op_sel_hi:[1,0]
	v_pk_mul_f32 v[80:81], v[70:71], v[94:95] op_sel_hi:[1,0]
	v_add_f32_e32 v78, v150, v78
	v_add_f32_e32 v80, v152, v80
	v_add_f32_e32 v81, v153, v81
	v_add_f32_e32 v79, v151, v79
	v_exp_f32_e32 v80, v80
	v_exp_f32_e32 v78, v78
	v_exp_f32_e32 v79, v79
	v_exp_f32_e32 v81, v81
	v_pk_mul_f32 v[108:109], v[108:109], v[114:115]
	s_mov_b32 s30, 0x56000
	v_cvt_pk_bf16_f32 v91, v108, v109
	v_add_co_u32_e32 v108, vcc, s30, v146
	v_pk_add_f32 v[78:79], v[78:79], 1.0 op_sel_hi:[1,0]
	s_nop 0
	v_addc_co_u32_e32 v109, vcc, 0, v147, vcc
	v_pk_add_f32 v[80:81], v[80:81], 1.0 op_sel_hi:[1,0]
	global_store_dwordx4 v[108:109], v[90:93], off nt
	v_rcp_f32_e32 v80, v80
	v_rcp_f32_e32 v81, v81
	v_pk_add_f32 v[92:93], v[106:107], 1.0 op_sel_hi:[1,0]
	v_rcp_f32_e32 v78, v78
	v_rcp_f32_e32 v79, v79
	v_rcp_f32_e32 v92, v92
	v_rcp_f32_e32 v93, v93
	v_pk_fma_f32 v[72:73], v[72:73], v[164:165], v[88:89] op_sel_hi:[1,0,1]
	v_pk_fma_f32 v[70:71], v[70:71], v[164:165], v[86:87] op_sel_hi:[1,0,1]
	v_pk_fma_f32 v[68:69], v[68:69], v[164:165], v[84:85] op_sel_hi:[1,0,1]
	v_pk_fma_f32 v[66:67], v[66:67], v[164:165], v[82:83] op_sel_hi:[1,0,1]
	v_pk_mul_f32 v[68:69], v[72:73], v[68:69]
	v_pk_mul_f32 v[66:67], v[70:71], v[66:67]
	v_pk_mul_f32 v[70:71], v[68:69], v[78:79]
	v_pk_mul_f32 v[68:69], v[66:67], v[80:81]
	v_pk_mul_f32 v[74:75], v[74:75], v[92:93]
	v_cvt_pk_bf16_f32 v68, v68, v69
	v_cvt_pk_bf16_f32 v69, v70, v71
	v_mul_f32_e32 v70, 0xbfb8aa3b, v162
	v_exp_f32_e32 v97, v95
	v_cvt_pk_bf16_f32 v66, v74, v75
	v_pk_mul_f32 v[74:75], v[62:63], v[70:71] op_sel_hi:[1,0]
	v_pk_mul_f32 v[72:73], v[64:65], v[70:71] op_sel_hi:[1,0]
	v_add_f32_e32 v71, v156, v74
	v_exp_f32_e32 v74, v71
	v_add_f32_e32 v71, v157, v75
	v_exp_f32_e32 v75, v71
	v_add_f32_e32 v71, v154, v72
	v_pk_add_f32 v[90:91], v[96:97], 1.0 op_sel_hi:[1,0]
	v_exp_f32_e32 v72, v71
	v_add_f32_e32 v71, v155, v73
	v_pk_fma_f32 v[64:65], v[64:65], v[162:163], v[104:105] op_sel_hi:[1,0,1]
	v_pk_fma_f32 v[62:63], v[62:63], v[162:163], v[102:103] op_sel_hi:[1,0,1]
	v_pk_fma_f32 v[60:61], v[60:61], v[162:163], v[100:101] op_sel_hi:[1,0,1]
	v_pk_fma_f32 v[58:59], v[58:59], v[162:163], v[98:99] op_sel_hi:[1,0,1]
	v_rcp_f32_e32 v90, v90
	v_rcp_f32_e32 v91, v91
	v_pk_mul_f32 v[58:59], v[62:63], v[58:59]
	v_pk_mul_f32 v[60:61], v[64:65], v[60:61]
	v_pk_mul_f32 v[62:63], v[56:57], v[70:71] op_sel_hi:[1,0]
	v_pk_mul_f32 v[64:65], v[54:55], v[70:71] op_sel_hi:[1,0]
	v_add_f32_e32 v62, v150, v62
	v_add_f32_e32 v64, v152, v64
	v_add_f32_e32 v65, v153, v65
	v_add_f32_e32 v63, v151, v63
	v_exp_f32_e32 v64, v64
	v_exp_f32_e32 v62, v62
	v_exp_f32_e32 v63, v63
	v_exp_f32_e32 v65, v65
	v_pk_mul_f32 v[76:77], v[76:77], v[90:91]
	s_mov_b32 s30, 0x81000
	v_cvt_pk_bf16_f32 v67, v76, v77
	v_add_co_u32_e32 v76, vcc, s30, v146
	v_pk_add_f32 v[62:63], v[62:63], 1.0 op_sel_hi:[1,0]
	s_nop 0
	v_addc_co_u32_e32 v77, vcc, 0, v147, vcc
	v_pk_add_f32 v[64:65], v[64:65], 1.0 op_sel_hi:[1,0]
	global_store_dwordx4 v[76:77], v[66:69], off nt
	v_rcp_f32_e32 v64, v64
	v_rcp_f32_e32 v65, v65
	v_pk_add_f32 v[68:69], v[74:75], 1.0 op_sel_hi:[1,0]
	v_rcp_f32_e32 v62, v62
	v_rcp_f32_e32 v63, v63
	v_rcp_f32_e32 v68, v68
	v_rcp_f32_e32 v69, v69
	v_pk_fma_f32 v[56:57], v[56:57], v[162:163], v[88:89] op_sel_hi:[1,0,1]
	v_pk_fma_f32 v[54:55], v[54:55], v[162:163], v[86:87] op_sel_hi:[1,0,1]
	v_pk_fma_f32 v[52:53], v[52:53], v[162:163], v[84:85] op_sel_hi:[1,0,1]
	v_pk_fma_f32 v[50:51], v[50:51], v[162:163], v[82:83] op_sel_hi:[1,0,1]
	v_pk_mul_f32 v[52:53], v[56:57], v[52:53]
	v_pk_mul_f32 v[50:51], v[54:55], v[50:51]
	v_pk_mul_f32 v[54:55], v[52:53], v[62:63]
	v_pk_mul_f32 v[52:53], v[50:51], v[64:65]
	v_pk_mul_f32 v[58:59], v[58:59], v[68:69]
	v_cvt_pk_bf16_f32 v52, v52, v53
	v_cvt_pk_bf16_f32 v53, v54, v55
;     template <int QVV> __device__ __forceinline__ void run(f32x4 (&acc)[2][2][4][2], const Unit& u, int wr, int wc, int fr, int fq) const {
;     ...
; #pragma unroll
;         for (int ai = 0; ai < 2; ++ai)
; #pragma unroll
;             for (int m = 0; m < 4; ++m) { if (ai >= nai) continue;
;                 const float r = rs[ai][m], rn = r * (-LOG2E);
;                 f32x4 o[2];
; #pragma unroll
;                 for (int n = 0; n < 2; ++n) {
;                     const f32x4 gt = acc[ai][0][m][n] * r + sg[n], up = acc[ai][1][m][n] * r + su[n], ex = acc[ai][0][m][n] * rn + sgn[n];
;                     f32x4 den, rc;
; #pragma unroll
;                     for (int i = 0; i < 4; ++i) den[i] = __builtin_amdgcn_exp2f(ex[i]);
;                     den = den + 1.0f;
; #pragma unroll
;                     for (int i = 0; i < 4; ++i) rc[i] = __builtin_amdgcn_rcpf(den[i]);
;                     o[n] = (gt * up) * rc; }
;                 u32x4 w; w.x = pk2(o[0][0], o[0][1]); w.y = pk2(o[0][2], o[0][3]); w.z = pk2(o[1][0], o[1][1]); w.w = pk2(o[1][2], o[1][3]);
;                 *(u32x4*)(tb + lo + (unsigned)(ai * HALF + m * 16) * (DFF * 2)) = w; }
	v_mul_f32_e32 v54, 0xbfb8aa3b, v160
	v_exp_f32_e32 v73, v71
	v_cvt_pk_bf16_f32 v50, v58, v59
	v_pk_mul_f32 v[58:59], v[46:47], v[54:55] op_sel_hi:[1,0]
	v_pk_mul_f32 v[56:57], v[48:49], v[54:55] op_sel_hi:[1,0]
	v_add_f32_e32 v55, v156, v58
	v_exp_f32_e32 v58, v55
	v_add_f32_e32 v55, v157, v59
	v_exp_f32_e32 v59, v55
	v_add_f32_e32 v55, v154, v56
	v_pk_add_f32 v[66:67], v[72:73], 1.0 op_sel_hi:[1,0]
	v_exp_f32_e32 v56, v55
	v_add_f32_e32 v55, v155, v57
	v_pk_fma_f32 v[48:49], v[48:49], v[160:161], v[104:105] op_sel_hi:[1,0,1]
	v_pk_fma_f32 v[46:47], v[46:47], v[160:161], v[102:103] op_sel_hi:[1,0,1]
	v_pk_fma_f32 v[44:45], v[44:45], v[160:161], v[100:101] op_sel_hi:[1,0,1]
	v_pk_fma_f32 v[42:43], v[42:43], v[160:161], v[98:99] op_sel_hi:[1,0,1]
	v_rcp_f32_e32 v66, v66
	v_rcp_f32_e32 v67, v67
	v_pk_mul_f32 v[42:43], v[46:47], v[42:43]
	v_pk_mul_f32 v[44:45], v[48:49], v[44:45]
	v_pk_mul_f32 v[46:47], v[40:41], v[54:55] op_sel_hi:[1,0]
	v_pk_mul_f32 v[48:49], v[38:39], v[54:55] op_sel_hi:[1,0]
	v_add_f32_e32 v46, v150, v46
	v_add_f32_e32 v48, v152, v48
	v_add_f32_e32 v49, v153, v49
	v_add_f32_e32 v47, v151, v47
	v_exp_f32_e32 v48, v48
	v_exp_f32_e32 v46, v46
	v_exp_f32_e32 v47, v47
	v_exp_f32_e32 v49, v49
	v_pk_mul_f32 v[60:61], v[60:61], v[66:67]
	s_mov_b32 s30, 0x158000
	v_cvt_pk_bf16_f32 v51, v60, v61
	v_add_co_u32_e32 v60, vcc, s30, v146
	v_pk_add_f32 v[46:47], v[46:47], 1.0 op_sel_hi:[1,0]
	s_nop 0
	v_addc_co_u32_e32 v61, vcc, 0, v147, vcc
	v_pk_add_f32 v[48:49], v[48:49], 1.0 op_sel_hi:[1,0]
	global_store_dwordx4 v[60:61], v[50:53], off nt
	v_rcp_f32_e32 v48, v48
	v_rcp_f32_e32 v49, v49
	v_pk_add_f32 v[52:53], v[58:59], 1.0 op_sel_hi:[1,0]
	v_rcp_f32_e32 v46, v46
	v_rcp_f32_e32 v47, v47
	v_rcp_f32_e32 v52, v52
	v_rcp_f32_e32 v53, v53
	v_pk_fma_f32 v[40:41], v[40:41], v[160:161], v[88:89] op_sel_hi:[1,0,1]
	v_pk_fma_f32 v[38:39], v[38:39], v[160:161], v[86:87] op_sel_hi:[1,0,1]
	v_pk_fma_f32 v[36:37], v[36:37], v[160:161], v[84:85] op_sel_hi:[1,0,1]
	v_pk_fma_f32 v[34:35], v[34:35], v[160:161], v[82:83] op_sel_hi:[1,0,1]
	v_pk_mul_f32 v[36:37], v[40:41], v[36:37]
	v_pk_mul_f32 v[34:35], v[38:39], v[34:35]
	v_pk_mul_f32 v[38:39], v[36:37], v[46:47]
	v_pk_mul_f32 v[36:37], v[34:35], v[48:49]
	v_pk_mul_f32 v[42:43], v[42:43], v[52:53]
	v_cvt_pk_bf16_f32 v36, v36, v37
	v_cvt_pk_bf16_f32 v37, v38, v39
	v_mul_f32_e32 v38, 0xbfb8aa3b, v158
	v_exp_f32_e32 v57, v55
	v_cvt_pk_bf16_f32 v34, v42, v43
	v_pk_mul_f32 v[42:43], v[30:31], v[38:39] op_sel_hi:[1,0]
	v_pk_mul_f32 v[40:41], v[32:33], v[38:39] op_sel_hi:[1,0]
	v_add_f32_e32 v39, v156, v42
	v_exp_f32_e32 v42, v39
	v_add_f32_e32 v39, v157, v43
	v_exp_f32_e32 v43, v39
	v_add_f32_e32 v39, v154, v40
	v_pk_add_f32 v[50:51], v[56:57], 1.0 op_sel_hi:[1,0]
	v_exp_f32_e32 v40, v39
	v_add_f32_e32 v39, v155, v41
	v_pk_fma_f32 v[32:33], v[32:33], v[158:159], v[104:105] op_sel_hi:[1,0,1]
	v_pk_fma_f32 v[30:31], v[30:31], v[158:159], v[102:103] op_sel_hi:[1,0,1]
	v_pk_fma_f32 v[28:29], v[28:29], v[158:159], v[100:101] op_sel_hi:[1,0,1]
	v_pk_fma_f32 v[26:27], v[26:27], v[158:159], v[98:99] op_sel_hi:[1,0,1]
	v_rcp_f32_e32 v50, v50
	v_rcp_f32_e32 v51, v51
	v_pk_mul_f32 v[26:27], v[30:31], v[26:27]
	v_pk_mul_f32 v[28:29], v[32:33], v[28:29]
	v_pk_mul_f32 v[30:31], v[24:25], v[38:39] op_sel_hi:[1,0]
	v_pk_mul_f32 v[32:33], v[22:23], v[38:39] op_sel_hi:[1,0]
	v_add_f32_e32 v30, v150, v30
	v_add_f32_e32 v32, v152, v32
	v_add_f32_e32 v33, v153, v33
	v_add_f32_e32 v31, v151, v31
	v_exp_f32_e32 v32, v32
	v_exp_f32_e32 v30, v30
	v_exp_f32_e32 v31, v31
	v_exp_f32_e32 v33, v33
	v_pk_mul_f32 v[44:45], v[44:45], v[50:51]
	s_mov_b32 s30, 0x183000
	v_cvt_pk_bf16_f32 v35, v44, v45
	v_add_co_u32_e32 v44, vcc, s30, v146
	v_pk_add_f32 v[30:31], v[30:31], 1.0 op_sel_hi:[1,0]
	s_nop 0
	v_addc_co_u32_e32 v45, vcc, 0, v147, vcc
; #define PG8_BAR __builtin_amdgcn_s_barrier()
;     ...
;         if (!has_next) break;
;         if (!cur.keep) {
; #pragma unroll
;             for (int a = 0; a < 2; ++a)
; #pragma unroll
;                 for (int b = 0; b < 2; ++b)
; #pragma unroll
;                     for (int m = 0; m < 4; ++m)
; #pragma unroll
;                         for (int n = 0; n < 2; ++n) { f32x2 z0, z1; asm("v_mov_b64 %0, 0\n\tv_mov_b64 %1, 0" : "=v"(z0), "=v"(z1));
;                     acc[a][b][m][n] = __builtin_shufflevector(z0, z1, 0, 1, 2, 3); }
;         }
;         cur = nxt; cA = nA; cB = nB; ++ui;
;         if (wr == 1) PG8_BAR;
;     template <int QVV> __device__ __forceinline__ void run(f32x4 (&acc)[2][2][4][2], const Unit& u, int wr, int wc, int fr, int fq) const {
;     ...
; #pragma unroll
;         for (int ai = 0; ai < 2; ++ai)
; #pragma unroll
;             for (int m = 0; m < 4; ++m) { if (ai >= nai) continue;
;                 const float r = rs[ai][m], rn = r * (-LOG2E);
;                 f32x4 o[2];
; #pragma unroll
;                 for (int n = 0; n < 2; ++n) {
;                     const f32x4 gt = acc[ai][0][m][n] * r + sg[n], up = acc[ai][1][m][n] * r + su[n], ex = acc[ai][0][m][n] * rn + sgn[n];
;                     f32x4 den, rc;
; #pragma unroll
;                     for (int i = 0; i < 4; ++i) den[i] = __builtin_amdgcn_exp2f(ex[i]);
;                     den = den + 1.0f;
; #pragma unroll
;                     for (int i = 0; i < 4; ++i) rc[i] = __builtin_amdgcn_rcpf(den[i]);
;                     o[n] = (gt * up) * rc; }
;                 u32x4 w; w.x = pk2(o[0][0], o[0][1]); w.y = pk2(o[0][2], o[0][3]); w.z = pk2(o[1][0], o[1][1]); w.w = pk2(o[1][2], o[1][3]);
;                 *(u32x4*)(tb + lo + (unsigned)(ai * HALF + m * 16) * (DFF * 2)) = w; }
	v_pk_add_f32 v[32:33], v[32:33], 1.0 op_sel_hi:[1,0]
	v_fmamk_f32 v148, v188, 0x30000000, v231
	global_store_dwordx4 v[44:45], v[34:37], off nt
	v_rcp_f32_e32 v32, v32
	v_rcp_f32_e32 v33, v33
	v_pk_add_f32 v[36:37], v[42:43], 1.0 op_sel_hi:[1,0]
	v_rcp_f32_e32 v30, v30
	v_rcp_f32_e32 v31, v31
	v_rsq_f32_e32 v148, v148
	v_rcp_f32_e32 v36, v36
	v_rcp_f32_e32 v37, v37
	v_pk_fma_f32 v[24:25], v[24:25], v[158:159], v[88:89] op_sel_hi:[1,0,1]
	v_pk_fma_f32 v[22:23], v[22:23], v[158:159], v[86:87] op_sel_hi:[1,0,1]
	v_pk_fma_f32 v[20:21], v[20:21], v[158:159], v[84:85] op_sel_hi:[1,0,1]
	v_pk_fma_f32 v[18:19], v[18:19], v[158:159], v[82:83] op_sel_hi:[1,0,1]
	v_pk_mul_f32 v[20:21], v[24:25], v[20:21]
	v_pk_mul_f32 v[18:19], v[22:23], v[18:19]
	v_pk_mul_f32 v[22:23], v[20:21], v[30:31]
	v_pk_mul_f32 v[20:21], v[18:19], v[32:33]
	v_pk_mul_f32 v[26:27], v[26:27], v[36:37]
	v_cvt_pk_bf16_f32 v20, v20, v21
	v_cvt_pk_bf16_f32 v21, v22, v23
	v_mul_f32_e32 v22, 0xbfb8aa3b, v148
	v_cvt_pk_bf16_f32 v18, v26, v27
	v_pk_mul_f32 v[26:27], v[14:15], v[22:23] op_sel_hi:[1,0]
	v_exp_f32_e32 v41, v39
	v_pk_mul_f32 v[24:25], v[16:17], v[22:23] op_sel_hi:[1,0]
	v_add_f32_e32 v23, v156, v26
	v_exp_f32_e32 v26, v23
	v_add_f32_e32 v23, v157, v27
	v_exp_f32_e32 v27, v23
	v_add_f32_e32 v23, v154, v24
	v_exp_f32_e32 v24, v23
	v_add_f32_e32 v23, v155, v25
	v_pk_fma_f32 v[16:17], v[16:17], v[148:149], v[104:105] op_sel_hi:[1,0,1]
	v_pk_fma_f32 v[14:15], v[14:15], v[148:149], v[102:103] op_sel_hi:[1,0,1]
	v_pk_fma_f32 v[12:13], v[12:13], v[148:149], v[100:101] op_sel_hi:[1,0,1]
	v_pk_fma_f32 v[10:11], v[10:11], v[148:149], v[98:99] op_sel_hi:[1,0,1]
	v_pk_add_f32 v[34:35], v[40:41], 1.0 op_sel_hi:[1,0]
	v_pk_mul_f32 v[10:11], v[14:15], v[10:11]
	v_pk_mul_f32 v[12:13], v[16:17], v[12:13]
	v_pk_mul_f32 v[14:15], v[8:9], v[22:23] op_sel_hi:[1,0]
	v_pk_mul_f32 v[16:17], v[6:7], v[22:23] op_sel_hi:[1,0]
	v_rcp_f32_e32 v34, v34
	v_rcp_f32_e32 v35, v35
	v_add_f32_e32 v16, v152, v16
	v_add_f32_e32 v17, v153, v17
	v_add_f32_e32 v14, v150, v14
	v_add_f32_e32 v15, v151, v15
	v_exp_f32_e32 v16, v16
	v_exp_f32_e32 v14, v14
	v_exp_f32_e32 v15, v15
	v_exp_f32_e32 v17, v17
	v_exp_f32_e32 v25, v23
	v_pk_mul_f32 v[28:29], v[28:29], v[34:35]
	s_mov_b32 s30, 0x1ae000
	v_cvt_pk_bf16_f32 v19, v28, v29
	v_add_co_u32_e32 v28, vcc, s30, v146
	v_pk_add_f32 v[14:15], v[14:15], 1.0 op_sel_hi:[1,0]
	v_pk_add_f32 v[16:17], v[16:17], 1.0 op_sel_hi:[1,0]
	v_addc_co_u32_e32 v29, vcc, 0, v147, vcc
	v_rcp_f32_e32 v16, v16
	v_rcp_f32_e32 v17, v17
	v_rcp_f32_e32 v14, v14
	v_rcp_f32_e32 v15, v15
	global_store_dwordx4 v[28:29], v[18:21], off nt
	v_pk_fma_f32 v[8:9], v[8:9], v[148:149], v[88:89] op_sel_hi:[1,0,1]
	v_pk_fma_f32 v[6:7], v[6:7], v[148:149], v[86:87] op_sel_hi:[1,0,1]
	v_pk_add_f32 v[18:19], v[24:25], 1.0 op_sel_hi:[1,0]
	v_pk_add_f32 v[20:21], v[26:27], 1.0 op_sel_hi:[1,0]
	v_rcp_f32_e32 v18, v18
	v_rcp_f32_e32 v20, v20
	v_rcp_f32_e32 v21, v21
	v_rcp_f32_e32 v19, v19
	v_pk_fma_f32 v[4:5], v[4:5], v[148:149], v[84:85] op_sel_hi:[1,0,1]
	v_pk_fma_f32 v[2:3], v[2:3], v[148:149], v[82:83] op_sel_hi:[1,0,1]
	v_pk_mul_f32 v[4:5], v[8:9], v[4:5]
	v_pk_mul_f32 v[2:3], v[6:7], v[2:3]
	v_pk_mul_f32 v[6:7], v[4:5], v[14:15]
	v_pk_mul_f32 v[4:5], v[2:3], v[16:17]
	v_pk_mul_f32 v[12:13], v[12:13], v[18:19]
	v_cvt_pk_bf16_f32 v4, v4, v5
	v_cvt_pk_bf16_f32 v5, v6, v7
	v_add_co_u32_e32 v6, vcc, 0x1d9000, v146
	v_pk_mul_f32 v[10:11], v[10:11], v[20:21]
	s_nop 0
	v_addc_co_u32_e32 v7, vcc, 0, v147, vcc
	v_cvt_pk_bf16_f32 v2, v10, v11
	v_cvt_pk_bf16_f32 v3, v12, v13
	s_andn2_b64 vcc, exec, s[38:39]
	s_mov_b64 s[30:31], -1
	global_store_dwordx4 v[6:7], v[2:5], off nt
	s_cbranch_vccnz .LBB0_215
	s_andn2_b64 vcc, exec, s[44:45]
	v_mov_b64 v[2:3], 0
	v_mov_b64 v[4:5], 0
	s_cbranch_vccnz .LBB0_214
	s_barrier
	s_branch .LBB0_214

; __device__ __forceinline__ void row_rstd(const unsigned long long* ssq, int row0, float (&rs)[2][4]) {
;     unsigned long long q[2][4];
; #pragma unroll
;     for (int ai = 0; ai < 2; ++ai)
; #pragma unroll
;         for (int m = 0; m < 4; ++m) q[ai][m] = ssq[row0 + ai * HALF + m * 16];
;     asm volatile("" : "+v"(q[0][0]), "+v"(q[0][1]), "+v"(q[0][2]), "+v"(q[0][3]), "+v"(q[1][0]), "+v"(q[1][1]), "+v"(q[1][2]), "+v"(q[1][3]));
; #pragma unroll
;     for (int ai = 0; ai < 2; ++ai)
; #pragma unroll
;         for (int m = 0; m < 4; ++m) {
;             const float qf = __builtin_fmaf((float)(unsigned)(q[ai][m] >> 32), 4294967296.0f, (float)(unsigned)q[ai][m]);
;     template <int QVV> __device__ __forceinline__ void run(f32x4 (&acc)[2][2][4][2], const Unit& u, int wr, int wc, int fr, int fq) const {
;         constexpr int nai = (QVV == 2) ? 1 : 2; const int r0 = u.pm * BM + (QVV == 2 ? (u.seg - 1) * HALF : 0);
;         char* tb = (char*)(O + (size_t)r0 * DFF + u.pn * HALF);
;         const int v = u.pm < 4 ? 4 : ((u.pm - 4) >> 5);
;         const char* swb = (const char*)(sw + (size_t)v * SWLD + u.pn * BM);
;         unsigned lo = (unsigned)((wr * 64 + fr) * DFF + wc * 32 + 8 * fq) * 2u;
;         unsigned co = (unsigned)(wc * 32 + 8 * fq) * 4u;
;         asm volatile("" : "+v"(lo), "+v"(co));
;         float rs[2][4]; row_rstd(ssq, r0 + wr * 64 + fr, rs);
;         f32x4 sg[2], su[2], sgn[2];
; #pragma unroll
;         for (int n = 0; n < 2; ++n) { sg[n] = *(const f32x4*)(swb + co + n * 16); su[n] = *(const f32x4*)(swb + co + HALF * 4 + n * 16); sgn[n] = sg[n] * (-LOG2E); }
; #pragma unroll
;         for (int ai = 0; ai < 2; ++ai)
; #pragma unroll
;             for (int m = 0; m < 4; ++m) { if (ai >= nai) continue;
;                 const float r = rs[ai][m], rn = r * (-LOG2E);
;                 f32x4 o[2];
; #pragma unroll
;                 for (int n = 0; n < 2; ++n) {
;                     const f32x4 gt = acc[ai][0][m][n] * r + sg[n], up = acc[ai][1][m][n] * r + su[n], ex = acc[ai][0][m][n] * rn + sgn[n];
;                     f32x4 den, rc;
; #pragma unroll
;                     for (int i = 0; i < 4; ++i) den[i] = __builtin_amdgcn_exp2f(ex[i]);
;                     den = den + 1.0f;
; #pragma unroll
;                     for (int i = 0; i < 4; ++i) rc[i] = __builtin_amdgcn_rcpf(den[i]);
;                     o[n] = (gt * up) * rc; }
.LBB0_245:
	s_movk_i32 s8, 0x1580
	v_mul_lo_u32 v66, v70, s8
	s_lshl_b32 s8, s10, 8
	v_readlane_b32 s10, v253, 9
	v_or3_b32 v66, v66, v71, s19
	s_or_b32 s8, s8, s10
	v_or_b32_e32 v67, s19, v71
	v_lshlrev_b32_e32 v86, 1, v66
	v_add_u32_e32 v66, s8, v70
	v_lshlrev_b32_e32 v82, 2, v67
	v_ashrrev_i32_e32 v67, 31, v66
	v_lshl_add_u64 v[66:67], v[66:67], 3, s[34:35]
	global_load_dwordx2 v[84:85], v[66:67], off
	global_load_dwordx2 v[88:89], v[66:67], off offset:128
	global_load_dwordx2 v[90:91], v[66:67], off offset:256
	global_load_dwordx2 v[92:93], v[66:67], off offset:384
	global_load_dwordx2 v[68:69], v[66:67], off offset:1024
	global_load_dwordx2 v[70:71], v[66:67], off offset:1152
	global_load_dwordx2 v[72:73], v[66:67], off offset:1280
	s_nop 0
	global_load_dwordx2 v[66:67], v[66:67], off offset:1408
	s_mul_hi_i32 s10, s8, 0x2b00
	s_mulk_i32 s8, 0x2b00
	s_add_u32 s5, s5, s8
	s_addc_u32 s7, s7, s10
	s_lshl_b32 s10, s9, 7
	s_ashr_i32 s11, s10, 31
	s_lshl_b64 s[10:11], s[10:11], 1
	s_add_u32 s30, s5, s10
	s_addc_u32 s31, s7, s11
	s_lshl_b64 s[10:11], s[38:39], 2
	s_add_u32 s5, s2, s10
	s_addc_u32 s7, s3, s11
	s_lshl_b32 s2, s9, 8
	s_ashr_i32 s3, s2, 31
	s_lshl_b64 s[2:3], s[2:3], 2
	s_add_u32 s2, s5, s2
	s_addc_u32 s3, s7, s3
	v_mov_b32_e32 v87, v175
	s_waitcnt vmcnt(0)
	global_load_dwordx4 v[78:81], v82, s[2:3]
	global_load_dwordx4 v[70:73], v82, s[2:3] offset:16
	global_load_dwordx4 v[74:77], v82, s[2:3] offset:512
	global_load_dwordx4 v[66:69], v82, s[2:3] offset:528
	s_flbit_i32_b32 s2, 0
	s_min_u32 s2, s2, 32
	v_mov_b32_e32 v174, v89
	v_lshl_add_u64 v[82:83], s[30:31], 0, v[86:87]
	v_cvt_f32_u32_e32 v87, v88
	v_lshlrev_b64 v[88:89], s2, v[174:175]
	v_mov_b32_e32 v174, v91
	v_cvt_f32_u32_e32 v95, v90
	v_cvt_f32_u32_e32 v96, v84
	v_min_u32_e32 v84, 1, v88
	v_lshlrev_b64 v[90:91], s2, v[174:175]
	v_mov_b32_e32 v174, v93
	v_or_b32_e32 v84, v89, v84
	v_min_u32_e32 v90, 1, v90
	v_lshlrev_b64 v[88:89], s2, v[174:175]
	v_mov_b32_e32 v174, v85
	v_cvt_f32_u32_e32 v93, v84
	v_or_b32_e32 v90, v91, v90
	v_min_u32_e32 v88, 1, v88
	v_lshlrev_b64 v[84:85], s2, v[174:175]
	v_cvt_f32_u32_e32 v90, v90
	v_or_b32_e32 v88, v89, v88
	v_min_u32_e32 v84, 1, v84
	v_cvt_f32_u32_e32 v88, v88
	v_or_b32_e32 v84, v85, v84
	s_sub_i32 s3, 32, s2
	v_cvt_f32_u32_e32 v92, v92
	v_cvt_f32_u32_e32 v84, v84
	v_ldexp_f32 v85, v93, s3
	v_fmac_f32_e32 v87, 0x4f800000, v85
	v_ldexp_f32 v85, v90, s3
	v_fmac_f32_e32 v95, 0x4f800000, v85
	v_ldexp_f32 v85, v88, s3
	v_fmac_f32_e32 v92, 0x4f800000, v85
	v_ldexp_f32 v84, v84, s3
	v_fmamk_f32 v87, v87, 0x30000000, v231
	v_fmamk_f32 v85, v92, 0x30000000, v231
	v_fmac_f32_e32 v96, 0x4f800000, v84
	v_rsq_f32_e32 v94, v87
	v_rsq_f32_e32 v84, v85
	v_fmamk_f32 v85, v96, 0x30000000, v231
	v_rsq_f32_e32 v96, v85
	v_mul_f32_e32 v90, 0xbfb8aa3b, v94
	v_pk_mul_f32 v[98:99], v[56:57], v[90:91] op_sel_hi:[1,0]
	v_pk_mul_f32 v[100:101], v[54:55], v[90:91] op_sel_hi:[1,0]
	v_pk_mul_f32 v[102:103], v[40:41], v[90:91] op_sel_hi:[1,0]
	v_pk_mul_f32 v[104:105], v[38:39], v[90:91] op_sel_hi:[1,0]
	v_mul_f32_e32 v90, 0xbfb8aa3b, v96
	s_mov_b32 s2, 0xbfb8aa3b
	v_fmamk_f32 v87, v95, 0x30000000, v231
	v_pk_mul_f32 v[106:107], v[64:65], v[90:91] op_sel_hi:[1,0]
	v_pk_mul_f32 v[108:109], v[62:63], v[90:91] op_sel_hi:[1,0]
	v_pk_mul_f32 v[110:111], v[60:61], v[90:91] op_sel_hi:[1,0]
	v_pk_mul_f32 v[112:113], v[58:59], v[90:91] op_sel_hi:[1,0]
	v_rsq_f32_e32 v88, v87
	s_waitcnt vmcnt(3)
	v_pk_mul_f32 v[114:115], v[80:81], s[2:3] op_sel_hi:[1,0]
	v_pk_mul_f32 v[116:117], v[78:79], s[2:3] op_sel_hi:[1,0]
	s_waitcnt vmcnt(2)
	v_pk_mul_f32 v[90:91], v[72:73], s[2:3] op_sel_hi:[1,0]
	v_pk_mul_f32 v[92:93], v[70:71], s[2:3] op_sel_hi:[1,0]
	v_pk_fma_f32 v[64:65], v[64:65], v[96:97], v[80:81] op_sel_hi:[1,0,1]
	v_pk_fma_f32 v[62:63], v[62:63], v[96:97], v[78:79] op_sel_hi:[1,0,1]
	s_waitcnt vmcnt(1)
	v_pk_fma_f32 v[52:53], v[52:53], v[96:97], v[76:77] op_sel_hi:[1,0,1]
	v_pk_fma_f32 v[50:51], v[50:51], v[96:97], v[74:75] op_sel_hi:[1,0,1]
	v_pk_fma_f32 v[60:61], v[60:61], v[96:97], v[72:73] op_sel_hi:[1,0,1]
	v_pk_fma_f32 v[58:59], v[58:59], v[96:97], v[70:71] op_sel_hi:[1,0,1]
	s_waitcnt vmcnt(0)
	v_pk_fma_f32 v[48:49], v[48:49], v[96:97], v[68:69] op_sel_hi:[1,0,1]
	v_pk_fma_f32 v[46:47], v[46:47], v[96:97], v[66:67] op_sel_hi:[1,0,1]
	v_pk_fma_f32 v[56:57], v[56:57], v[94:95], v[80:81] op_sel_hi:[1,0,1]
	v_pk_fma_f32 v[54:55], v[54:55], v[94:95], v[78:79] op_sel_hi:[1,0,1]
	v_pk_fma_f32 v[44:45], v[44:45], v[94:95], v[76:77] op_sel_hi:[1,0,1]
	v_pk_fma_f32 v[42:43], v[42:43], v[94:95], v[74:75] op_sel_hi:[1,0,1]
	v_add_f32_e32 v85, v116, v108
	v_add_f32_e32 v87, v117, v109
	v_add_f32_e32 v89, v114, v106
	v_add_f32_e32 v95, v115, v107
	v_pk_mul_f32 v[50:51], v[62:63], v[50:51]
	v_pk_mul_f32 v[52:53], v[64:65], v[52:53]
	v_add_f32_e32 v62, v92, v112
	v_add_f32_e32 v63, v93, v113
	v_add_f32_e32 v64, v90, v110
	v_add_f32_e32 v65, v91, v111
	v_pk_mul_f32 v[46:47], v[58:59], v[46:47]
	v_pk_mul_f32 v[48:49], v[60:61], v[48:49]
	v_add_f32_e32 v96, v116, v100
	v_add_f32_e32 v97, v117, v101
	v_add_f32_e32 v98, v114, v98
	v_add_f32_e32 v99, v115, v99
	v_pk_mul_f32 v[42:43], v[54:55], v[42:43]
	v_pk_mul_f32 v[44:45], v[56:57], v[44:45]
	v_exp_f32_e32 v54, v85
	v_exp_f32_e32 v55, v87
	v_exp_f32_e32 v56, v89
	v_exp_f32_e32 v57, v95
	v_exp_f32_e32 v58, v62
	v_exp_f32_e32 v59, v63
	v_exp_f32_e32 v60, v64
	v_exp_f32_e32 v61, v65
	v_exp_f32_e32 v62, v96
	v_exp_f32_e32 v63, v97
	v_exp_f32_e32 v64, v98
	v_exp_f32_e32 v65, v99
	v_pk_add_f32 v[56:57], v[56:57], 1.0 op_sel_hi:[1,0]
	v_pk_add_f32 v[54:55], v[54:55], 1.0 op_sel_hi:[1,0]
	v_pk_add_f32 v[60:61], v[60:61], 1.0 op_sel_hi:[1,0]
; #define PG8_WAIT_V(n) asm volatile("s_waitcnt vmcnt(" #n ")" ::: "memory")
; #define PG8_BAR __builtin_amdgcn_s_barrier()
;     ...
;     PG8_WAIT_V(0);
;     PG8_BAR;
;     template <int QVV> __device__ __forceinline__ void run(f32x4 (&acc)[2][2][4][2], const Unit& u, int wr, int wc, int fr, int fq) const {
;     ...
; #pragma unroll
;         for (int ai = 0; ai < 2; ++ai)
; #pragma unroll
;             for (int m = 0; m < 4; ++m) { if (ai >= nai) continue;
;                 const float r = rs[ai][m], rn = r * (-LOG2E);
;                 f32x4 o[2];
; #pragma unroll
;                 for (int n = 0; n < 2; ++n) {
;                     const f32x4 gt = acc[ai][0][m][n] * r + sg[n], up = acc[ai][1][m][n] * r + su[n], ex = acc[ai][0][m][n] * rn + sgn[n];
;                     f32x4 den, rc;
; #pragma unroll
;                     for (int i = 0; i < 4; ++i) den[i] = __builtin_amdgcn_exp2f(ex[i]);
;                     den = den + 1.0f;
; #pragma unroll
;                     for (int i = 0; i < 4; ++i) rc[i] = __builtin_amdgcn_rcpf(den[i]);
;                     o[n] = (gt * up) * rc; }
;                 u32x4 w; w.x = pk2(o[0][0], o[0][1]); w.y = pk2(o[0][2], o[0][3]); w.z = pk2(o[1][0], o[1][1]); w.w = pk2(o[1][2], o[1][3]);
;                 *(u32x4*)(tb + lo + (unsigned)(ai * HALF + m * 16) * (DFF * 2)) = w; }
	v_pk_add_f32 v[58:59], v[58:59], 1.0 op_sel_hi:[1,0]
	v_pk_add_f32 v[64:65], v[64:65], 1.0 op_sel_hi:[1,0]
	v_pk_add_f32 v[62:63], v[62:63], 1.0 op_sel_hi:[1,0]
	v_rcp_f32_e32 v54, v54
	v_rcp_f32_e32 v55, v55
	v_rcp_f32_e32 v56, v56
	v_rcp_f32_e32 v57, v57
	v_rcp_f32_e32 v58, v58
	v_rcp_f32_e32 v59, v59
	v_rcp_f32_e32 v60, v60
	v_rcp_f32_e32 v61, v61
	v_add_f32_e32 v100, v92, v104
	v_add_f32_e32 v101, v93, v105
	v_add_f32_e32 v102, v90, v102
	v_add_f32_e32 v103, v91, v103
	v_rcp_f32_e32 v62, v62
	v_rcp_f32_e32 v63, v63
	v_rcp_f32_e32 v64, v64
	v_rcp_f32_e32 v65, v65
	v_exp_f32_e32 v96, v100
	v_exp_f32_e32 v97, v101
	v_exp_f32_e32 v98, v102
	v_exp_f32_e32 v99, v103
	v_pk_mul_f32 v[52:53], v[52:53], v[56:57]
	v_pk_mul_f32 v[50:51], v[50:51], v[54:55]
	v_pk_mul_f32 v[48:49], v[48:49], v[60:61]
	v_pk_mul_f32 v[46:47], v[46:47], v[58:59]
	v_pk_mul_f32 v[54:55], v[44:45], v[64:65]
	v_pk_mul_f32 v[56:57], v[42:43], v[62:63]
	v_cvt_pk_bf16_f32 v42, v50, v51
	v_cvt_pk_bf16_f32 v43, v52, v53
	v_cvt_pk_bf16_f32 v44, v46, v47
	v_cvt_pk_bf16_f32 v45, v48, v49
	v_pk_add_f32 v[98:99], v[98:99], 1.0 op_sel_hi:[1,0]
	global_store_dwordx4 v86, v[42:45], s[30:31] nt
	v_pk_fma_f32 v[40:41], v[40:41], v[94:95], v[72:73] op_sel_hi:[1,0,1]
	v_pk_fma_f32 v[38:39], v[38:39], v[94:95], v[70:71] op_sel_hi:[1,0,1]
	v_pk_add_f32 v[42:43], v[96:97], 1.0 op_sel_hi:[1,0]
	v_rcp_f32_e32 v44, v98
	v_rcp_f32_e32 v42, v42
	v_rcp_f32_e32 v43, v43
	v_rcp_f32_e32 v45, v99
	v_pk_fma_f32 v[36:37], v[36:37], v[94:95], v[68:69] op_sel_hi:[1,0,1]
	v_pk_fma_f32 v[34:35], v[34:35], v[94:95], v[66:67] op_sel_hi:[1,0,1]
	v_pk_mul_f32 v[36:37], v[40:41], v[36:37]
	v_pk_mul_f32 v[34:35], v[38:39], v[34:35]
	v_pk_mul_f32 v[38:39], v[36:37], v[44:45]
	v_pk_mul_f32 v[36:37], v[34:35], v[42:43]
	v_pk_fma_f32 v[28:29], v[28:29], v[88:89], v[76:77] op_sel_hi:[1,0,1]
	v_cvt_pk_bf16_f32 v36, v36, v37
	v_cvt_pk_bf16_f32 v37, v38, v39
	v_mul_f32_e32 v38, 0xbfb8aa3b, v88
	v_pk_mul_f32 v[42:43], v[30:31], v[38:39] op_sel_hi:[1,0]
	v_pk_mul_f32 v[40:41], v[32:33], v[38:39] op_sel_hi:[1,0]
	v_add_f32_e32 v39, v116, v42
	v_exp_f32_e32 v42, v39
	v_add_f32_e32 v39, v117, v43
	v_exp_f32_e32 v43, v39
	v_add_f32_e32 v39, v114, v40
	v_exp_f32_e32 v40, v39
	v_add_f32_e32 v39, v115, v41
	v_pk_fma_f32 v[32:33], v[32:33], v[88:89], v[80:81] op_sel_hi:[1,0,1]
	v_pk_fma_f32 v[30:31], v[30:31], v[88:89], v[78:79] op_sel_hi:[1,0,1]
	v_pk_fma_f32 v[26:27], v[26:27], v[88:89], v[74:75] op_sel_hi:[1,0,1]
	v_pk_mul_f32 v[28:29], v[32:33], v[28:29]
	v_pk_mul_f32 v[26:27], v[30:31], v[26:27]
	v_pk_mul_f32 v[30:31], v[24:25], v[38:39] op_sel_hi:[1,0]
	v_pk_mul_f32 v[32:33], v[22:23], v[38:39] op_sel_hi:[1,0]
	v_add_f32_e32 v30, v90, v30
	v_add_f32_e32 v32, v92, v32
	v_add_f32_e32 v33, v93, v33
	v_add_f32_e32 v31, v91, v31
	v_exp_f32_e32 v32, v32
	v_exp_f32_e32 v30, v30
	v_exp_f32_e32 v31, v31
	v_exp_f32_e32 v33, v33
	s_mov_b32 s2, 0x2b000
	v_add_co_u32_e32 v44, vcc, s2, v82
	v_cvt_pk_bf16_f32 v34, v56, v57
	v_cvt_pk_bf16_f32 v35, v54, v55
	v_addc_co_u32_e32 v45, vcc, 0, v83, vcc
	v_pk_add_f32 v[30:31], v[30:31], 1.0 op_sel_hi:[1,0]
	v_pk_add_f32 v[32:33], v[32:33], 1.0 op_sel_hi:[1,0]
	global_store_dwordx4 v[44:45], v[34:37], off nt
	v_rcp_f32_e32 v32, v32
	v_rcp_f32_e32 v33, v33
	v_pk_add_f32 v[36:37], v[42:43], 1.0 op_sel_hi:[1,0]
	v_rcp_f32_e32 v30, v30
	v_rcp_f32_e32 v31, v31
	v_rcp_f32_e32 v36, v36
	v_rcp_f32_e32 v37, v37
	v_pk_fma_f32 v[24:25], v[24:25], v[88:89], v[72:73] op_sel_hi:[1,0,1]
	v_pk_fma_f32 v[22:23], v[22:23], v[88:89], v[70:71] op_sel_hi:[1,0,1]
	v_pk_fma_f32 v[20:21], v[20:21], v[88:89], v[68:69] op_sel_hi:[1,0,1]
	v_pk_fma_f32 v[18:19], v[18:19], v[88:89], v[66:67] op_sel_hi:[1,0,1]
	v_pk_mul_f32 v[20:21], v[24:25], v[20:21]
	v_pk_mul_f32 v[18:19], v[22:23], v[18:19]
	v_pk_mul_f32 v[22:23], v[20:21], v[30:31]
	v_pk_mul_f32 v[20:21], v[18:19], v[32:33]
	v_pk_mul_f32 v[26:27], v[26:27], v[36:37]
	v_cvt_pk_bf16_f32 v20, v20, v21
	v_cvt_pk_bf16_f32 v21, v22, v23
	v_mul_f32_e32 v22, 0xbfb8aa3b, v84
	v_exp_f32_e32 v41, v39
	v_cvt_pk_bf16_f32 v18, v26, v27
	v_pk_mul_f32 v[26:27], v[14:15], v[22:23] op_sel_hi:[1,0]
	v_pk_mul_f32 v[24:25], v[16:17], v[22:23] op_sel_hi:[1,0]
	v_add_f32_e32 v23, v116, v26
	v_exp_f32_e32 v26, v23
	v_add_f32_e32 v23, v117, v27
	v_exp_f32_e32 v27, v23
	v_add_f32_e32 v23, v114, v24
	v_pk_add_f32 v[34:35], v[40:41], 1.0 op_sel_hi:[1,0]
	v_exp_f32_e32 v24, v23
	v_add_f32_e32 v23, v115, v25
	v_pk_fma_f32 v[16:17], v[16:17], v[84:85], v[80:81] op_sel_hi:[1,0,1]
	v_pk_fma_f32 v[14:15], v[14:15], v[84:85], v[78:79] op_sel_hi:[1,0,1]
	v_pk_fma_f32 v[12:13], v[12:13], v[84:85], v[76:77] op_sel_hi:[1,0,1]
	v_pk_fma_f32 v[10:11], v[10:11], v[84:85], v[74:75] op_sel_hi:[1,0,1]
	v_rcp_f32_e32 v34, v34
	v_rcp_f32_e32 v35, v35
	v_pk_mul_f32 v[10:11], v[14:15], v[10:11]
	v_pk_mul_f32 v[12:13], v[16:17], v[12:13]
	v_pk_mul_f32 v[14:15], v[8:9], v[22:23] op_sel_hi:[1,0]
	v_pk_mul_f32 v[16:17], v[6:7], v[22:23] op_sel_hi:[1,0]
	v_add_f32_e32 v14, v90, v14
	v_add_f32_e32 v16, v92, v16
	v_add_f32_e32 v17, v93, v17
	v_add_f32_e32 v15, v91, v15
	v_exp_f32_e32 v16, v16
	v_exp_f32_e32 v14, v14
	v_exp_f32_e32 v15, v15
	v_exp_f32_e32 v17, v17
	v_exp_f32_e32 v25, v23
	v_pk_mul_f32 v[28:29], v[28:29], v[34:35]
	s_mov_b32 s2, 0x56000
	v_cvt_pk_bf16_f32 v19, v28, v29
	v_add_co_u32_e32 v28, vcc, s2, v82
	v_pk_add_f32 v[14:15], v[14:15], 1.0 op_sel_hi:[1,0]
	s_nop 0
	v_addc_co_u32_e32 v29, vcc, 0, v83, vcc
	v_pk_add_f32 v[16:17], v[16:17], 1.0 op_sel_hi:[1,0]
	global_store_dwordx4 v[28:29], v[18:21], off nt
	v_rcp_f32_e32 v16, v16
	v_rcp_f32_e32 v17, v17
	v_pk_add_f32 v[18:19], v[24:25], 1.0 op_sel_hi:[1,0]
	v_pk_add_f32 v[20:21], v[26:27], 1.0 op_sel_hi:[1,0]
	v_rcp_f32_e32 v14, v14
	v_rcp_f32_e32 v15, v15
	v_rcp_f32_e32 v20, v20
	v_rcp_f32_e32 v21, v21
	v_rcp_f32_e32 v18, v18
	v_rcp_f32_e32 v19, v19
	v_pk_fma_f32 v[8:9], v[8:9], v[84:85], v[72:73] op_sel_hi:[1,0,1]
	v_pk_fma_f32 v[6:7], v[6:7], v[84:85], v[70:71] op_sel_hi:[1,0,1]
	v_pk_fma_f32 v[4:5], v[4:5], v[84:85], v[68:69] op_sel_hi:[1,0,1]
	v_pk_fma_f32 v[2:3], v[2:3], v[84:85], v[66:67] op_sel_hi:[1,0,1]
	v_pk_mul_f32 v[4:5], v[8:9], v[4:5]
	v_pk_mul_f32 v[2:3], v[6:7], v[2:3]
	v_pk_mul_f32 v[6:7], v[4:5], v[14:15]
	v_pk_mul_f32 v[4:5], v[2:3], v[16:17]
	v_pk_mul_f32 v[12:13], v[12:13], v[18:19]
	v_pk_mul_f32 v[10:11], v[10:11], v[20:21]
	v_cvt_pk_bf16_f32 v4, v4, v5
	v_cvt_pk_bf16_f32 v5, v6, v7
	v_add_co_u32_e32 v6, vcc, 0x81000, v82
	v_cvt_pk_bf16_f32 v2, v10, v11
	v_cvt_pk_bf16_f32 v3, v12, v13
	v_addc_co_u32_e32 v7, vcc, 0, v83, vcc
	global_store_dwordx4 v[6:7], v[2:5], off nt
	s_waitcnt vmcnt(0)
	s_barrier

; #define LAS __attribute__((address_space(3)))
; #define GAS __attribute__((address_space(1)))
; #define LDS_WAIT() asm volatile("s_waitcnt lgkmcnt(0)" ::: "memory")
; __device__ __forceinline__ void transpose_item(const float* W, int K, int N, bf16_t* WT, int k0, int n0, int drow0, LAS float* scr, int lane) {
;     f32x4 v[8];
; #pragma unroll
;     for (int j = 0; j < 8; ++j) v[j] = *(const f32x4*)(W + (size_t)(k0 + (lane >> 3) + 8 * j) * N + n0 + 4 * (lane & 7));
; #pragma unroll
;     for (int j = 0; j < 8; ++j) { LAS float* d = scr + ((lane >> 3) + 8 * j) * 33 + 4 * (lane & 7); d[0] = v[j].x; d[1] = v[j].y; d[2] = v[j].z; d[3] = v[j].w; }
;     LDS_WAIT(); asm volatile("" ::: "memory");
;     const int c = lane & 7;
; #pragma unroll
;     for (int j = 0; j < 4; ++j) { const int n = (lane >> 3) + 8 * j; const LAS float* s = scr + (8 * c) * 33 + n;
;         u32x4 o; o.x = pk2(s[0 * 33], s[1 * 33]); o.y = pk2(s[2 * 33], s[3 * 33]); o.z = pk2(s[4 * 33], s[5 * 33]); o.w = pk2(s[6 * 33], s[7 * 33]);
;         *(GAS u32x4*)(WT + (size_t)(drow0 + n) * K + k0 + 8 * c) = o; }
;     LDS_WAIT(); asm volatile("" ::: "memory");
; }
; __device__ __forceinline__ void transpose_matrix(const float* W, int K, int N, bf16_t* WT, int rowmode, LAS float* scr, int gw, int ngw, int lane) {
;     const int nblk = N / 32, nitems = (K / 64) * nblk;
;     for (int it = gw; it < nitems; it += ngw) {
;         const int kb = it / nblk, nb = it - kb * nblk, n0 = 32 * nb;
;         int drow0 = n0;
;         if (rowmode == 1) { const int up = n0 >= DFF, j0 = up ? n0 - DFF : n0; drow0 = 256 * (j0 >> 7) + 128 * up + (j0 & 127); }
;         if (rowmode == 2 && n0 >= 5120 && n0 < 6400) {
;             const int tb = 5120 + (((n0 - 5120) >> 8) << 8), hh = ((n0 - tb) >> 7) & 1, d0 = (n0 - tb) & 127; drow0 = tb + ((d0 & 32) ? 128 : 0) + hh * 64 + ((d0 >> 6) << 5); }
;         if (rowmode == 2 && n0 >= 3072 && n0 < 5120) { const int wh = n0 >= 4096, j0 = n0 - 3072 - wh * 1024; drow0 = 3072 + 256 * (j0 >> 7) + 128 * wh + (j0 & 127); }
;         transpose_item(W, K, N, WT, 64 * kb, n0, drow0, scr, lane);
.LBB0_747:
	s_mul_hi_i32 s7, s5, 0x2fa0be83
	s_lshr_b32 s8, s7, 31
	s_ashr_i32 s7, s7, 6
	s_add_i32 s9, s7, s8
	s_mul_i32 s8, s9, 0xffffd500
	s_mul_i32 s7, s9, 0xfffffea8
	s_add_i32 s8, s1, s8
	s_add_i32 s7, s5, s7
	s_add_i32 s11, s8, 0xffffea80
	s_cmpk_gt_i32 s7, 0xab
	s_cselect_b32 s7, s11, s8
	s_cselect_b32 s11, 0x80, 0
	s_lshl_b32 s30, s9, 6
	s_ashr_i32 s9, s8, 31
	v_or_b32_e32 v44, s30, v30
	v_lshl_add_u64 v[2:3], s[8:9], 2, v[26:27]
	v_mad_i64_i32 v[4:5], s[8:9], v44, s27, v[2:3]
	global_load_dwordx4 v[36:39], v[4:5], off
	v_or_b32_e32 v4, 8, v44
	v_mad_i64_i32 v[4:5], s[8:9], v4, s27, v[2:3]
	global_load_dwordx4 v[40:43], v[4:5], off
	v_or_b32_e32 v4, 16, v44
	v_mad_i64_i32 v[4:5], s[8:9], v4, s27, v[2:3]
	global_load_dwordx4 v[22:25], v[4:5], off
	v_or_b32_e32 v4, 24, v44
	v_mad_i64_i32 v[4:5], s[8:9], v4, s27, v[2:3]
	global_load_dwordx4 v[18:21], v[4:5], off
	v_or_b32_e32 v4, 32, v44
	v_mad_i64_i32 v[4:5], s[8:9], v4, s27, v[2:3]
	global_load_dwordx4 v[14:17], v[4:5], off
	v_or_b32_e32 v4, 40, v44
	v_mad_i64_i32 v[4:5], s[8:9], v4, s27, v[2:3]
	global_load_dwordx4 v[10:13], v[4:5], off
	v_or_b32_e32 v4, 48, v44
	v_mad_i64_i32 v[4:5], s[8:9], v4, s27, v[2:3]
	global_load_dwordx4 v[6:9], v[4:5], off
	v_or_b32_e32 v4, 56, v44
	v_mad_i64_i32 v[2:3], s[8:9], v4, s27, v[2:3]
	global_load_dwordx4 v[2:5], v[2:3], off
	s_lshl_b32 s12, s7, 1
	s_and_b32 s7, s7, 0x60
	s_and_b32 s12, s12, 0xffffff00
	s_or_b32 s7, s7, s11
	s_or_b32 s7, s7, s12
	s_ashr_i32 s31, s30, 31
	s_add_i32 s5, s5, s10
	s_add_i32 s1, s1, s2
	s_cmpk_lt_i32 s5, 0x2b00
	s_waitcnt vmcnt(7)
	ds_write2_b32 v35, v36, v37 offset1:1
	ds_write2_b32 v35, v38, v39 offset0:2 offset1:3
	v_add_u32_e32 v36, 0x420, v35
	s_waitcnt vmcnt(6)
	ds_write2_b32 v36, v40, v41 offset1:1
	v_add_u32_e32 v36, 0x428, v35
	ds_write2_b32 v36, v42, v43 offset1:1
	v_add_u32_e32 v36, 0x840, v35
	s_waitcnt vmcnt(5)
	ds_write2_b32 v36, v22, v23 offset1:1
	v_add_u32_e32 v22, 0x848, v35
	ds_write2_b32 v22, v24, v25 offset1:1
	v_add_u32_e32 v22, 0xc60, v35
	s_waitcnt vmcnt(4)
	ds_write2_b32 v22, v18, v19 offset1:1
	v_add_u32_e32 v18, 0xc68, v35
	ds_write2_b32 v18, v20, v21 offset1:1
	v_add_u32_e32 v18, 0x1080, v35
	s_waitcnt vmcnt(3)
	ds_write2_b32 v18, v14, v15 offset1:1
	v_add_u32_e32 v14, 0x1088, v35
	ds_write2_b32 v14, v16, v17 offset1:1
	v_add_u32_e32 v14, 0x14a0, v35
	s_waitcnt vmcnt(2)
	ds_write2_b32 v14, v10, v11 offset1:1
	v_add_u32_e32 v10, 0x14a8, v35
	ds_write2_b32 v10, v12, v13 offset1:1
	v_add_u32_e32 v10, 0x18c0, v35
	s_waitcnt vmcnt(1)
	ds_write2_b32 v10, v6, v7 offset1:1
	v_add_u32_e32 v6, 0x18c8, v35
	ds_write2_b32 v6, v8, v9 offset1:1
	v_add_u32_e32 v6, 0x1ce0, v35
	s_waitcnt vmcnt(0)
	ds_write2_b32 v6, v2, v3 offset1:1
	v_add_u32_e32 v2, 0x1ce8, v35
	ds_write2_b32 v2, v4, v5 offset1:1
	s_waitcnt lgkmcnt(0)
	ds_read2_b32 v[8:9], v34 offset0:33 offset1:41
	ds_read2_b32 v[10:11], v34 offset1:8
	ds_read2_b32 v[12:13], v34 offset0:66 offset1:74
	ds_read2_b32 v[14:15], v34 offset0:99 offset1:107
	ds_read2_b32 v[16:17], v34 offset0:132 offset1:140
	ds_read2_b32 v[18:19], v34 offset0:165 offset1:173
	ds_read2_b32 v[20:21], v34 offset0:198 offset1:206
	ds_read2_b32 v[22:23], v34 offset0:231 offset1:239
	v_or_b32_e32 v24, s7, v30
	v_ashrrev_i32_e32 v25, 31, v24
	v_lshl_add_u64 v[6:7], s[30:31], 1, v[28:29]
	v_lshlrev_b64 v[24:25], 12, v[24:25]
	s_waitcnt lgkmcnt(6)
	v_cvt_pk_bf16_f32 v2, v10, v8
	s_waitcnt lgkmcnt(4)
	v_cvt_pk_bf16_f32 v3, v12, v14
	s_waitcnt lgkmcnt(2)
	v_cvt_pk_bf16_f32 v4, v16, v18
	s_waitcnt lgkmcnt(0)
	v_cvt_pk_bf16_f32 v5, v20, v22
	v_lshl_add_u64 v[24:25], v[6:7], 0, v[24:25]
	v_or_b32_e32 v8, s7, v31
	global_store_dwordx4 v[24:25], v[2:5], off nt
	v_or_b32_e32 v24, s7, v32
	v_ashrrev_i32_e32 v25, 31, v24
	v_cvt_pk_bf16_f32 v2, v11, v9
	v_ashrrev_i32_e32 v9, 31, v8
	v_lshlrev_b64 v[8:9], 12, v[8:9]
	v_cvt_pk_bf16_f32 v3, v13, v15
	v_cvt_pk_bf16_f32 v4, v17, v19
	v_cvt_pk_bf16_f32 v5, v21, v23
	v_lshl_add_u64 v[8:9], v[6:7], 0, v[8:9]
	global_store_dwordx4 v[8:9], v[2:5], off nt
	ds_read2_b32 v[8:9], v34 offset0:49 offset1:57
	ds_read2_b32 v[10:11], v34 offset0:16 offset1:24
	ds_read2_b32 v[12:13], v34 offset0:82 offset1:90
	ds_read2_b32 v[14:15], v34 offset0:115 offset1:123
	ds_read2_b32 v[16:17], v34 offset0:148 offset1:156
	ds_read2_b32 v[18:19], v34 offset0:181 offset1:189
	ds_read2_b32 v[20:21], v34 offset0:214 offset1:222
	ds_read2_b32 v[22:23], v34 offset0:247 offset1:255
	v_lshlrev_b64 v[24:25], 12, v[24:25]
	s_waitcnt lgkmcnt(6)
	v_cvt_pk_bf16_f32 v2, v10, v8
	s_waitcnt lgkmcnt(4)
	v_cvt_pk_bf16_f32 v3, v12, v14
	s_waitcnt lgkmcnt(2)
	v_cvt_pk_bf16_f32 v4, v16, v18
	s_waitcnt lgkmcnt(0)
	v_cvt_pk_bf16_f32 v5, v20, v22
	v_lshl_add_u64 v[24:25], v[6:7], 0, v[24:25]
	v_or_b32_e32 v8, s7, v33
	global_store_dwordx4 v[24:25], v[2:5], off nt
	s_nop 1
	v_cvt_pk_bf16_f32 v2, v11, v9
	v_ashrrev_i32_e32 v9, 31, v8
	v_lshlrev_b64 v[8:9], 12, v[8:9]
	v_cvt_pk_bf16_f32 v3, v13, v15
	v_cvt_pk_bf16_f32 v4, v17, v19
	v_cvt_pk_bf16_f32 v5, v21, v23
	v_lshl_add_u64 v[6:7], v[6:7], 0, v[8:9]
	global_store_dwordx4 v[6:7], v[2:5], off nt
	s_waitcnt lgkmcnt(0)
	s_cbranch_scc1 .LBB0_747

; #define LAS __attribute__((address_space(3)))
; #define GAS __attribute__((address_space(1)))
; #define LDS_WAIT() asm volatile("s_waitcnt lgkmcnt(0)" ::: "memory")
; __device__ __forceinline__ void transpose_item(const float* W, int K, int N, bf16_t* WT, int k0, int n0, int drow0, LAS float* scr, int lane) {
;     f32x4 v[8];
; #pragma unroll
;     for (int j = 0; j < 8; ++j) v[j] = *(const f32x4*)(W + (size_t)(k0 + (lane >> 3) + 8 * j) * N + n0 + 4 * (lane & 7));
; #pragma unroll
;     for (int j = 0; j < 8; ++j) { LAS float* d = scr + ((lane >> 3) + 8 * j) * 33 + 4 * (lane & 7); d[0] = v[j].x; d[1] = v[j].y; d[2] = v[j].z; d[3] = v[j].w; }
;     LDS_WAIT(); asm volatile("" ::: "memory");
;     const int c = lane & 7;
; #pragma unroll
;     for (int j = 0; j < 4; ++j) { const int n = (lane >> 3) + 8 * j; const LAS float* s = scr + (8 * c) * 33 + n;
;         u32x4 o; o.x = pk2(s[0 * 33], s[1 * 33]); o.y = pk2(s[2 * 33], s[3 * 33]); o.z = pk2(s[4 * 33], s[5 * 33]); o.w = pk2(s[6 * 33], s[7 * 33]);
;         *(GAS u32x4*)(WT + (size_t)(drow0 + n) * K + k0 + 8 * c) = o; }
;     LDS_WAIT(); asm volatile("" ::: "memory");
; }
; __device__ __forceinline__ void transpose_matrix(const float* W, int K, int N, bf16_t* WT, int rowmode, LAS float* scr, int gw, int ngw, int lane) {
;     const int nblk = N / 32, nitems = (K / 64) * nblk;
;     for (int it = gw; it < nitems; it += ngw) {
;         const int kb = it / nblk, nb = it - kb * nblk, n0 = 32 * nb;
;         int drow0 = n0;
;         if (rowmode == 1) { const int up = n0 >= DFF, j0 = up ? n0 - DFF : n0; drow0 = 256 * (j0 >> 7) + 128 * up + (j0 & 127); }
;         if (rowmode == 2 && n0 >= 5120 && n0 < 6400) {
;             const int tb = 5120 + (((n0 - 5120) >> 8) << 8), hh = ((n0 - tb) >> 7) & 1, d0 = (n0 - tb) & 127; drow0 = tb + ((d0 & 32) ? 128 : 0) + hh * 64 + ((d0 >> 6) << 5); }
;         if (rowmode == 2 && n0 >= 3072 && n0 < 5120) { const int wh = n0 >= 4096, j0 = n0 - 3072 - wh * 1024; drow0 = 3072 + 256 * (j0 >> 7) + 128 * wh + (j0 & 127); }
;         transpose_item(W, K, N, WT, 64 * kb, n0, drow0, scr, lane);
.LBB0_750:
	s_ashr_i32 s7, s5, 31
	s_lshr_b32 s7, s7, 26
	s_add_i32 s7, s5, s7
	s_lshl_b32 s8, s7, 5
	s_and_b32 s8, s8, 0xfffff800
	s_and_b32 s42, s7, 0xffffffc0
	s_sub_i32 s30, s1, s8
	v_or_b32_e32 v40, s42, v24
	s_ashr_i32 s31, s30, 31
	v_ashrrev_i32_e32 v41, 31, v40
	v_or_b32_e32 v6, 8, v40
	v_lshl_add_u64 v[22:23], s[30:31], 2, v[18:19]
	v_lshlrev_b64 v[2:3], 13, v[40:41]
	v_ashrrev_i32_e32 v7, 31, v6
	v_lshl_add_u64 v[2:3], v[22:23], 0, v[2:3]
	v_lshlrev_b64 v[6:7], 13, v[6:7]
	v_or_b32_e32 v10, 16, v40
	global_load_dwordx4 v[2:5], v[2:3], off
	v_lshl_add_u64 v[6:7], v[22:23], 0, v[6:7]
	v_ashrrev_i32_e32 v11, 31, v10
	global_load_dwordx4 v[6:9], v[6:7], off
	v_lshlrev_b64 v[10:11], 13, v[10:11]
	v_or_b32_e32 v14, 24, v40
	v_lshl_add_u64 v[10:11], v[22:23], 0, v[10:11]
	v_ashrrev_i32_e32 v15, 31, v14
	global_load_dwordx4 v[10:13], v[10:11], off
	v_lshlrev_b64 v[14:15], 13, v[14:15]
	v_or_b32_e32 v28, 32, v40
	v_lshl_add_u64 v[14:15], v[22:23], 0, v[14:15]
	v_ashrrev_i32_e32 v29, 31, v28
	global_load_dwordx4 v[14:17], v[14:15], off
	v_lshlrev_b64 v[28:29], 13, v[28:29]
	v_or_b32_e32 v32, 40, v40
	v_lshl_add_u64 v[28:29], v[22:23], 0, v[28:29]
	v_ashrrev_i32_e32 v33, 31, v32
	global_load_dwordx4 v[28:31], v[28:29], off
	v_lshlrev_b64 v[32:33], 13, v[32:33]
	v_or_b32_e32 v36, 48, v40
	v_lshl_add_u64 v[32:33], v[22:23], 0, v[32:33]
	v_ashrrev_i32_e32 v37, 31, v36
	global_load_dwordx4 v[32:35], v[32:33], off
	v_lshlrev_b64 v[36:37], 13, v[36:37]
	v_or_b32_e32 v40, 56, v40
	v_lshl_add_u64 v[36:37], v[22:23], 0, v[36:37]
	v_ashrrev_i32_e32 v41, 31, v40
	global_load_dwordx4 v[36:39], v[36:37], off
	v_lshlrev_b64 v[40:41], 13, v[40:41]
	v_lshl_add_u64 v[22:23], v[22:23], 0, v[40:41]
	global_load_dwordx4 v[40:43], v[22:23], off
	s_ashr_i32 s43, s42, 31
	v_add_u32_e32 v27, s30, v24
	s_add_i32 s5, s5, s10
	s_add_i32 s1, s1, s2
	s_cmpk_lt_i32 s5, 0x1580
	s_waitcnt vmcnt(7)
	ds_write2_b32 v26, v2, v3 offset1:1
	ds_write2_b32 v26, v4, v5 offset0:2 offset1:3
	v_add_u32_e32 v2, 0x420, v26
	s_waitcnt vmcnt(6)
	ds_write2_b32 v2, v6, v7 offset1:1
	v_add_u32_e32 v2, 0x428, v26
	ds_write2_b32 v2, v8, v9 offset1:1
	v_add_u32_e32 v2, 0x840, v26
	v_lshl_add_u64 v[6:7], s[42:43], 1, v[20:21]
	s_waitcnt vmcnt(5)
	ds_write2_b32 v2, v10, v11 offset1:1
	v_add_u32_e32 v2, 0x848, v26
	ds_write2_b32 v2, v12, v13 offset1:1
	v_add_u32_e32 v2, 0xc60, v26
	s_waitcnt vmcnt(4)
	ds_write2_b32 v2, v14, v15 offset1:1
	v_add_u32_e32 v2, 0xc68, v26
	ds_write2_b32 v2, v16, v17 offset1:1
	v_add_u32_e32 v2, 0x1080, v26
	s_waitcnt vmcnt(3)
	ds_write2_b32 v2, v28, v29 offset1:1
	v_add_u32_e32 v2, 0x1088, v26
	ds_write2_b32 v2, v30, v31 offset1:1
	v_add_u32_e32 v2, 0x14a0, v26
	s_waitcnt vmcnt(2)
	ds_write2_b32 v2, v32, v33 offset1:1
	v_add_u32_e32 v2, 0x14a8, v26
	ds_write2_b32 v2, v34, v35 offset1:1
	v_add_u32_e32 v2, 0x18c0, v26
	v_mad_i64_i32 v[32:33], s[8:9], v27, s57, v[6:7]
	s_waitcnt vmcnt(1)
	ds_write2_b32 v2, v36, v37 offset1:1
	v_add_u32_e32 v2, 0x18c8, v26
	ds_write2_b32 v2, v38, v39 offset1:1
	v_add_u32_e32 v2, 0x1ce0, v26
	s_waitcnt vmcnt(0)
	ds_write2_b32 v2, v40, v41 offset1:1
	v_add_u32_e32 v2, 0x1ce8, v26
	ds_write2_b32 v2, v42, v43 offset1:1
	s_waitcnt lgkmcnt(0)
	ds_read2_b32 v[8:9], v25 offset0:33 offset1:41
	ds_read2_b32 v[10:11], v25 offset1:8
	ds_read2_b32 v[12:13], v25 offset0:66 offset1:74
	ds_read2_b32 v[14:15], v25 offset0:99 offset1:107
	ds_read2_b32 v[16:17], v25 offset0:132 offset1:140
	ds_read2_b32 v[22:23], v25 offset0:165 offset1:173
	ds_read2_b32 v[28:29], v25 offset0:198 offset1:206
	ds_read2_b32 v[30:31], v25 offset0:231 offset1:239
	s_waitcnt lgkmcnt(6)
	v_cvt_pk_bf16_f32 v2, v10, v8
	s_waitcnt lgkmcnt(4)
	v_cvt_pk_bf16_f32 v3, v12, v14
	s_waitcnt lgkmcnt(2)
	v_cvt_pk_bf16_f32 v4, v16, v22
	s_waitcnt lgkmcnt(0)
	v_cvt_pk_bf16_f32 v5, v28, v30
	v_add_u32_e32 v8, 8, v27
	global_store_dwordx4 v[32:33], v[2:5], off nt
	s_nop 1
	v_cvt_pk_bf16_f32 v2, v11, v9
	v_cvt_pk_bf16_f32 v3, v13, v15
	v_cvt_pk_bf16_f32 v4, v17, v23
	v_cvt_pk_bf16_f32 v5, v29, v31
	v_mad_i64_i32 v[8:9], s[8:9], v8, s57, v[6:7]
	global_store_dwordx4 v[8:9], v[2:5], off nt
	ds_read2_b32 v[8:9], v25 offset0:49 offset1:57
	ds_read2_b32 v[10:11], v25 offset0:16 offset1:24
	ds_read2_b32 v[12:13], v25 offset0:82 offset1:90
	ds_read2_b32 v[14:15], v25 offset0:115 offset1:123
	ds_read2_b32 v[16:17], v25 offset0:148 offset1:156
	ds_read2_b32 v[22:23], v25 offset0:181 offset1:189
	ds_read2_b32 v[28:29], v25 offset0:214 offset1:222
	ds_read2_b32 v[30:31], v25 offset0:247 offset1:255
	s_waitcnt lgkmcnt(6)
	v_cvt_pk_bf16_f32 v2, v10, v8
	v_add_u32_e32 v8, 16, v27
	s_waitcnt lgkmcnt(4)
	v_cvt_pk_bf16_f32 v3, v12, v14
	s_waitcnt lgkmcnt(2)
	v_cvt_pk_bf16_f32 v4, v16, v22
	s_waitcnt lgkmcnt(0)
	v_cvt_pk_bf16_f32 v5, v28, v30
	v_mad_i64_i32 v[32:33], s[8:9], v8, s57, v[6:7]
	v_add_u32_e32 v8, 24, v27
	global_store_dwordx4 v[32:33], v[2:5], off nt
	v_mad_i64_i32 v[6:7], s[8:9], v8, s57, v[6:7]
	s_nop 0
	v_cvt_pk_bf16_f32 v2, v11, v9
	v_cvt_pk_bf16_f32 v3, v13, v15
	v_cvt_pk_bf16_f32 v4, v17, v23
	v_cvt_pk_bf16_f32 v5, v29, v31
	global_store_dwordx4 v[6:7], v[2:5], off nt
	s_waitcnt lgkmcnt(0)
	s_cbranch_scc1 .LBB0_750

; #define LAS __attribute__((address_space(3)))
; #define GAS __attribute__((address_space(1)))
; #define LDS_WAIT() asm volatile("s_waitcnt lgkmcnt(0)" ::: "memory")
; __device__ __forceinline__ void transpose_item(const float* W, int K, int N, bf16_t* WT, int k0, int n0, int drow0, LAS float* scr, int lane) {
;     f32x4 v[8];
; #pragma unroll
;     for (int j = 0; j < 8; ++j) v[j] = *(const f32x4*)(W + (size_t)(k0 + (lane >> 3) + 8 * j) * N + n0 + 4 * (lane & 7));
; #pragma unroll
;     for (int j = 0; j < 8; ++j) { LAS float* d = scr + ((lane >> 3) + 8 * j) * 33 + 4 * (lane & 7); d[0] = v[j].x; d[1] = v[j].y; d[2] = v[j].z; d[3] = v[j].w; }
;     LDS_WAIT(); asm volatile("" ::: "memory");
;     const int c = lane & 7;
; #pragma unroll
;     for (int j = 0; j < 4; ++j) { const int n = (lane >> 3) + 8 * j; const LAS float* s = scr + (8 * c) * 33 + n;
;         u32x4 o; o.x = pk2(s[0 * 33], s[1 * 33]); o.y = pk2(s[2 * 33], s[3 * 33]); o.z = pk2(s[4 * 33], s[5 * 33]); o.w = pk2(s[6 * 33], s[7 * 33]);
;         *(GAS u32x4*)(WT + (size_t)(drow0 + n) * K + k0 + 8 * c) = o; }
;     LDS_WAIT(); asm volatile("" ::: "memory");
; }
; __device__ __forceinline__ void transpose_matrix(const float* W, int K, int N, bf16_t* WT, int rowmode, LAS float* scr, int gw, int ngw, int lane) {
;     const int nblk = N / 32, nitems = (K / 64) * nblk;
;     for (int it = gw; it < nitems; it += ngw) {
;         const int kb = it / nblk, nb = it - kb * nblk, n0 = 32 * nb;
;         int drow0 = n0;
;         if (rowmode == 1) { const int up = n0 >= DFF, j0 = up ? n0 - DFF : n0; drow0 = 256 * (j0 >> 7) + 128 * up + (j0 & 127); }
;         if (rowmode == 2 && n0 >= 5120 && n0 < 6400) {
;             const int tb = 5120 + (((n0 - 5120) >> 8) << 8), hh = ((n0 - tb) >> 7) & 1, d0 = (n0 - tb) & 127; drow0 = tb + ((d0 & 32) ? 128 : 0) + hh * 64 + ((d0 >> 6) << 5); }
;         if (rowmode == 2 && n0 >= 3072 && n0 < 5120) { const int wh = n0 >= 4096, j0 = n0 - 3072 - wh * 1024; drow0 = 3072 + 256 * (j0 >> 7) + 128 * wh + (j0 & 127); }
;         transpose_item(W, K, N, WT, 64 * kb, n0, drow0, scr, lane);
.LBB0_755:
	s_lshl_b32 s30, s12, 6
	v_or_b32_e32 v13, s30, v36
	s_ashr_i32 s43, s42, 31
	v_lshl_add_u64 v[8:9], s[42:43], 2, v[4:5]
	v_or_b32_e32 v18, 8, v13
	v_mad_i64_i32 v[14:15], s[12:13], v13, s16, v[8:9]
	v_mad_i64_i32 v[18:19], s[12:13], v18, s16, v[8:9]
	global_load_dwordx4 v[14:17], v[14:15], off
	v_or_b32_e32 v22, 16, v13
	global_load_dwordx4 v[18:21], v[18:19], off
	v_mad_i64_i32 v[22:23], s[12:13], v22, s16, v[8:9]
	global_load_dwordx4 v[22:25], v[22:23], off
	s_waitcnt vmcnt(4)
	v_or_b32_e32 v26, 24, v13
	v_mad_i64_i32 v[26:27], s[12:13], v26, s16, v[8:9]
	global_load_dwordx4 v[26:29], v[26:27], off
	v_or_b32_e32 v30, 32, v13
	v_mad_i64_i32 v[30:31], s[12:13], v30, s16, v[8:9]
	global_load_dwordx4 v[30:33], v[30:31], off
	v_or_b32_e32 v34, 40, v13
	v_mad_i64_i32 v[34:35], s[12:13], v34, s16, v[8:9]
	global_load_dwordx4 v[44:47], v[34:35], off
	v_or_b32_e32 v34, 48, v13
	v_mad_i64_i32 v[34:35], s[12:13], v34, s16, v[8:9]
	global_load_dwordx4 v[48:51], v[34:35], off
	v_or_b32_e32 v13, 56, v13
	v_mad_i64_i32 v[8:9], s[12:13], v13, s16, v[8:9]
	global_load_dwordx4 v[52:55], v[8:9], off
	v_add_u32_e32 v8, 0x420, v12
	v_add_u32_e32 v34, s11, v36
	s_ashr_i32 s31, s30, 31
	v_ashrrev_i32_e32 v35, 31, v34
	v_lshlrev_b64 v[34:35], 12, v[34:35]
	s_add_i32 s9, s9, s10
	s_add_i32 s5, s5, s7
	s_add_i32 s8, s8, s2
	s_cmpk_lt_i32 s9, 0x3200
	s_waitcnt vmcnt(7)
	ds_write2_b32 v12, v14, v15 offset1:1
	ds_write2_b32 v12, v16, v17 offset0:2 offset1:3
	s_waitcnt vmcnt(6)
	ds_write2_b32 v8, v18, v19 offset1:1
	v_add_u32_e32 v8, 0x428, v12
	ds_write2_b32 v8, v20, v21 offset1:1
	v_add_u32_e32 v8, 0x840, v12
	s_waitcnt vmcnt(5)
	ds_write2_b32 v8, v22, v23 offset1:1
	v_add_u32_e32 v8, 0x848, v12
	ds_write2_b32 v8, v24, v25 offset1:1
	v_add_u32_e32 v8, 0xc60, v12
	s_waitcnt vmcnt(4)
	ds_write2_b32 v8, v26, v27 offset1:1
	v_add_u32_e32 v8, 0xc68, v12
	ds_write2_b32 v8, v28, v29 offset1:1
	v_add_u32_e32 v8, 0x1080, v12
	s_waitcnt vmcnt(3)
	ds_write2_b32 v8, v30, v31 offset1:1
	v_add_u32_e32 v8, 0x1088, v12
	ds_write2_b32 v8, v32, v33 offset1:1
	v_add_u32_e32 v8, 0x14a0, v12
	s_waitcnt vmcnt(2)
	ds_write2_b32 v8, v44, v45 offset1:1
	v_add_u32_e32 v8, 0x14a8, v12
	ds_write2_b32 v8, v46, v47 offset1:1
	v_add_u32_e32 v8, 0x18c0, v12
	s_waitcnt vmcnt(1)
	ds_write2_b32 v8, v48, v49 offset1:1
	v_add_u32_e32 v8, 0x18c8, v12
	ds_write2_b32 v8, v50, v51 offset1:1
	v_add_u32_e32 v8, 0x1ce0, v12
	s_waitcnt vmcnt(0)
	ds_write2_b32 v8, v52, v53 offset1:1
	v_add_u32_e32 v8, 0x1ce8, v12
	ds_write2_b32 v8, v54, v55 offset1:1
	s_waitcnt lgkmcnt(0)
	ds_read2_b32 v[18:19], v11 offset0:33 offset1:41
	ds_read2_b32 v[20:21], v11 offset1:8
	ds_read2_b32 v[22:23], v11 offset0:66 offset1:74
	ds_read2_b32 v[24:25], v11 offset0:99 offset1:107
	ds_read2_b32 v[26:27], v11 offset0:132 offset1:140
	ds_read2_b32 v[28:29], v11 offset0:165 offset1:173
	ds_read2_b32 v[30:31], v11 offset0:198 offset1:206
	ds_read2_b32 v[32:33], v11 offset0:231 offset1:239
	v_lshl_add_u64 v[8:9], s[30:31], 1, v[6:7]
	s_waitcnt lgkmcnt(6)
	v_cvt_pk_bf16_f32 v14, v20, v18
	s_waitcnt lgkmcnt(4)
	v_cvt_pk_bf16_f32 v15, v22, v24
	s_waitcnt lgkmcnt(2)
	v_cvt_pk_bf16_f32 v16, v26, v28
	s_waitcnt lgkmcnt(0)
	v_cvt_pk_bf16_f32 v17, v30, v32
	v_lshl_add_u64 v[34:35], v[8:9], 0, v[34:35]
	v_add_u32_e32 v18, s11, v38
	global_store_dwordx4 v[34:35], v[14:17], off nt
	v_add_u32_e32 v34, s11, v40
	v_ashrrev_i32_e32 v35, 31, v34
	v_cvt_pk_bf16_f32 v14, v21, v19
	v_ashrrev_i32_e32 v19, 31, v18
	v_lshlrev_b64 v[18:19], 12, v[18:19]
	v_cvt_pk_bf16_f32 v15, v23, v25
	v_cvt_pk_bf16_f32 v16, v27, v29
	v_cvt_pk_bf16_f32 v17, v31, v33
	v_lshl_add_u64 v[18:19], v[8:9], 0, v[18:19]
	global_store_dwordx4 v[18:19], v[14:17], off nt
	ds_read2_b32 v[18:19], v11 offset0:49 offset1:57
	ds_read2_b32 v[20:21], v11 offset0:16 offset1:24
	ds_read2_b32 v[22:23], v11 offset0:82 offset1:90
	ds_read2_b32 v[24:25], v11 offset0:115 offset1:123
	ds_read2_b32 v[26:27], v11 offset0:148 offset1:156
	ds_read2_b32 v[28:29], v11 offset0:181 offset1:189
	ds_read2_b32 v[30:31], v11 offset0:214 offset1:222
	ds_read2_b32 v[32:33], v11 offset0:247 offset1:255
	v_lshlrev_b64 v[34:35], 12, v[34:35]
	s_waitcnt lgkmcnt(6)
	v_cvt_pk_bf16_f32 v14, v20, v18
	s_waitcnt lgkmcnt(4)
	v_cvt_pk_bf16_f32 v15, v22, v24
	s_waitcnt lgkmcnt(2)
	v_cvt_pk_bf16_f32 v16, v26, v28
	s_waitcnt lgkmcnt(0)
	v_cvt_pk_bf16_f32 v17, v30, v32
	v_lshl_add_u64 v[34:35], v[8:9], 0, v[34:35]
	v_add_u32_e32 v18, s11, v42
	global_store_dwordx4 v[34:35], v[14:17], off nt
	s_nop 1
	v_cvt_pk_bf16_f32 v14, v21, v19
	v_ashrrev_i32_e32 v19, 31, v18
	v_lshlrev_b64 v[18:19], 12, v[18:19]
	v_cvt_pk_bf16_f32 v15, v23, v25
	v_cvt_pk_bf16_f32 v16, v27, v29
	v_cvt_pk_bf16_f32 v17, v31, v33
	v_lshl_add_u64 v[8:9], v[8:9], 0, v[18:19]
	global_store_dwordx4 v[8:9], v[14:17], off nt
	s_waitcnt lgkmcnt(0)
	s_cbranch_scc0 .LBB0_758

; #define LAS __attribute__((address_space(3)))
; #define GAS __attribute__((address_space(1)))
; __device__ __forceinline__ void transpose_item(const float* W, int K, int N, bf16_t* WT, int k0, int n0, int drow0, LAS float* scr, int lane) {
;     f32x4 v[8];
; #pragma unroll
;     for (int j = 0; j < 8; ++j) v[j] = *(const f32x4*)(W + (size_t)(k0 + (lane >> 3) + 8 * j) * N + n0 + 4 * (lane & 7));
; #pragma unroll
;     for (int j = 0; j < 8; ++j) { LAS float* d = scr + ((lane >> 3) + 8 * j) * 33 + 4 * (lane & 7); d[0] = v[j].x; d[1] = v[j].y; d[2] = v[j].z; d[3] = v[j].w; }
;     LDS_WAIT(); asm volatile("" ::: "memory");
;     const int c = lane & 7;
; #pragma unroll
;     for (int j = 0; j < 4; ++j) { const int n = (lane >> 3) + 8 * j; const LAS float* s = scr + (8 * c) * 33 + n;
;         u32x4 o; o.x = pk2(s[0 * 33], s[1 * 33]); o.y = pk2(s[2 * 33], s[3 * 33]); o.z = pk2(s[4 * 33], s[5 * 33]); o.w = pk2(s[6 * 33], s[7 * 33]);
;         *(GAS u32x4*)(WT + (size_t)(drow0 + n) * K + k0 + 8 * c) = o; }
;     LDS_WAIT(); asm volatile("" ::: "memory");
; }
; __device__ __forceinline__ void transpose_matrix(const float* W, int K, int N, bf16_t* WT, int rowmode, LAS float* scr, int gw, int ngw, int lane) {
;     const int nblk = N / 32, nitems = (K / 64) * nblk;
;     for (int it = gw; it < nitems; it += ngw) {
;         const int kb = it / nblk, nb = it - kb * nblk, n0 = 32 * nb;
;         int drow0 = n0;
;         if (rowmode == 1) { const int up = n0 >= DFF, j0 = up ? n0 - DFF : n0; drow0 = 256 * (j0 >> 7) + 128 * up + (j0 & 127); }
;         if (rowmode == 2 && n0 >= 5120 && n0 < 6400) {
;             const int tb = 5120 + (((n0 - 5120) >> 8) << 8), hh = ((n0 - tb) >> 7) & 1, d0 = (n0 - tb) & 127; drow0 = tb + ((d0 & 32) ? 128 : 0) + hh * 64 + ((d0 >> 6) << 5); }
;         if (rowmode == 2 && n0 >= 3072 && n0 < 5120) { const int wh = n0 >= 4096, j0 = n0 - 3072 - wh * 1024; drow0 = 3072 + 256 * (j0 >> 7) + 128 * wh + (j0 & 127); }
;         transpose_item(W, K, N, WT, 64 * kb, n0, drow0, scr, lane);
; __device__ __forceinline__ void convert_weights(const Args& a, int layer, LAS unsigned char* lds, int gw, int ngw, int wave, int lane) {
;     ...
;     for (int i = 0; i < 3; ++i)
;         transpose_matrix(a.w_branch + ((size_t)layer * 3 + i) * 1024 * DM, 1024, DM, (bf16_t*)(wb + W_BR) + (size_t)i * DM * 1024, 0, scr, gw, ngw, lane);
.LBB0_763:
	s_ashr_i32 s7, s5, 31
	s_lshr_b32 s7, s7, 26
	s_add_i32 s7, s5, s7
	s_lshl_b32 s8, s7, 5
	s_and_b32 s8, s8, 0xfffff800
	s_and_b32 s44, s7, 0xffffffc0
	s_sub_i32 s42, s3, s8
	v_or_b32_e32 v54, s44, v36
	s_ashr_i32 s43, s42, 31
	v_ashrrev_i32_e32 v55, 31, v54
	v_or_b32_e32 v6, 8, v54
	v_lshl_add_u64 v[20:21], s[42:43], 2, v[16:17]
	v_lshlrev_b64 v[2:3], 13, v[54:55]
	v_ashrrev_i32_e32 v7, 31, v6
	v_or_b32_e32 v10, 16, v54
	v_lshl_add_u64 v[2:3], v[20:21], 0, v[2:3]
	v_lshlrev_b64 v[6:7], 13, v[6:7]
	v_ashrrev_i32_e32 v11, 31, v10
	v_or_b32_e32 v22, 24, v54
	global_load_dwordx4 v[2:5], v[2:3], off
	v_lshl_add_u64 v[6:7], v[20:21], 0, v[6:7]
	v_lshlrev_b64 v[10:11], 13, v[10:11]
	v_ashrrev_i32_e32 v23, 31, v22
	s_waitcnt vmcnt(2)
	v_or_b32_e32 v26, 32, v54
	global_load_dwordx4 v[6:9], v[6:7], off
	v_lshl_add_u64 v[10:11], v[20:21], 0, v[10:11]
	v_lshlrev_b64 v[22:23], 13, v[22:23]
	v_ashrrev_i32_e32 v27, 31, v26
	global_load_dwordx4 v[10:13], v[10:11], off
	v_lshl_add_u64 v[22:23], v[20:21], 0, v[22:23]
	v_lshlrev_b64 v[26:27], 13, v[26:27]
	v_or_b32_e32 v32, 40, v54
	global_load_dwordx4 v[22:25], v[22:23], off
	v_lshl_add_u64 v[26:27], v[20:21], 0, v[26:27]
	v_ashrrev_i32_e32 v33, 31, v32
	global_load_dwordx4 v[26:29], v[26:27], off
	v_lshlrev_b64 v[32:33], 13, v[32:33]
	v_or_b32_e32 v50, 48, v54
	v_lshl_add_u64 v[32:33], v[20:21], 0, v[32:33]
	v_ashrrev_i32_e32 v51, 31, v50
	global_load_dwordx4 v[32:35], v[32:33], off
	v_lshlrev_b64 v[50:51], 13, v[50:51]
	v_or_b32_e32 v54, 56, v54
	v_lshl_add_u64 v[50:51], v[20:21], 0, v[50:51]
	v_ashrrev_i32_e32 v55, 31, v54
	global_load_dwordx4 v[50:53], v[50:51], off
	v_lshlrev_b64 v[54:55], 13, v[54:55]
	v_lshl_add_u64 v[20:21], v[20:21], 0, v[54:55]
	global_load_dwordx4 v[54:57], v[20:21], off
	v_add_u32_e32 v20, v44, v37
	s_ashr_i32 s45, s44, 31
	s_add_i32 s5, s5, s10
	s_add_i32 s3, s3, s2
	s_cmpk_lt_i32 s5, 0x400
	s_waitcnt vmcnt(7)
	ds_write2_b32 v20, v2, v3 offset1:1
	ds_write2_b32 v20, v4, v5 offset0:2 offset1:3
	v_add_u32_e32 v2, v44, v39
	s_waitcnt vmcnt(6)
	ds_write2_b32 v2, v6, v7 offset1:1
	ds_write2_b32 v2, v8, v9 offset0:2 offset1:3
	v_add_u32_e32 v2, v44, v41
	s_waitcnt vmcnt(5)
	ds_write2_b32 v2, v10, v11 offset1:1
	ds_write2_b32 v2, v12, v13 offset0:2 offset1:3
	v_add_u32_e32 v2, v44, v43
	s_waitcnt vmcnt(4)
	ds_write2_b32 v2, v22, v23 offset1:1
	ds_write2_b32 v2, v24, v25 offset0:2 offset1:3
	v_add_u32_e32 v2, 0x1080, v20
	v_lshl_add_u64 v[6:7], s[44:45], 1, v[18:19]
	s_waitcnt vmcnt(3)
	ds_write2_b32 v2, v26, v27 offset1:1
	v_add_u32_e32 v2, 0x1088, v20
	ds_write2_b32 v2, v28, v29 offset1:1
	v_add_u32_e32 v2, 0x14a0, v20
	s_waitcnt vmcnt(2)
	ds_write2_b32 v2, v32, v33 offset1:1
	v_add_u32_e32 v2, 0x14a8, v20
	ds_write2_b32 v2, v34, v35 offset1:1
	v_add_u32_e32 v2, 0x18c0, v20
	s_waitcnt vmcnt(1)
	ds_write2_b32 v2, v50, v51 offset1:1
	v_add_u32_e32 v2, 0x18c8, v20
	ds_write2_b32 v2, v52, v53 offset1:1
	v_add_u32_e32 v2, 0x1ce0, v20
	s_waitcnt vmcnt(0)
	ds_write2_b32 v2, v54, v55 offset1:1
	v_add_u32_e32 v2, 0x1ce8, v20
	ds_write2_b32 v2, v56, v57 offset1:1
	s_waitcnt lgkmcnt(0)
	ds_read2_b32 v[2:3], v45 offset1:33
	ds_read2_b32 v[4:5], v45 offset0:66 offset1:99
	ds_read2_b32 v[8:9], v45 offset0:198 offset1:231
	s_waitcnt lgkmcnt(2)
	v_cvt_pk_bf16_f32 v2, v2, v3
	s_waitcnt lgkmcnt(1)
	v_cvt_pk_bf16_f32 v3, v4, v5
	ds_read2_b32 v[4:5], v45 offset0:132 offset1:165
	s_waitcnt lgkmcnt(0)
	v_cvt_pk_bf16_f32 v4, v4, v5
	v_cvt_pk_bf16_f32 v5, v8, v9
	v_add_u32_e32 v8, s42, v36
	v_ashrrev_i32_e32 v9, 31, v8
	v_lshlrev_b64 v[8:9], 11, v[8:9]
	v_lshl_add_u64 v[8:9], v[6:7], 0, v[8:9]
	global_store_dwordx4 v[8:9], v[2:5], off nt
	ds_read2_b32 v[2:3], v46 offset1:33
	ds_read2_b32 v[4:5], v46 offset0:66 offset1:99
	ds_read2_b32 v[8:9], v46 offset0:198 offset1:231
	s_waitcnt lgkmcnt(2)
	v_cvt_pk_bf16_f32 v2, v2, v3
	s_waitcnt lgkmcnt(1)
	v_cvt_pk_bf16_f32 v3, v4, v5
	ds_read2_b32 v[4:5], v46 offset0:132 offset1:165
	s_waitcnt lgkmcnt(0)
	v_cvt_pk_bf16_f32 v4, v4, v5
	v_cvt_pk_bf16_f32 v5, v8, v9
	v_add_u32_e32 v8, s42, v38
	v_ashrrev_i32_e32 v9, 31, v8
	v_lshlrev_b64 v[8:9], 11, v[8:9]
	v_lshl_add_u64 v[8:9], v[6:7], 0, v[8:9]
	global_store_dwordx4 v[8:9], v[2:5], off nt
	ds_read2_b32 v[2:3], v47 offset1:33
	ds_read2_b32 v[4:5], v47 offset0:66 offset1:99
	ds_read2_b32 v[8:9], v47 offset0:198 offset1:231
	s_waitcnt lgkmcnt(2)
	v_cvt_pk_bf16_f32 v2, v2, v3
	s_waitcnt lgkmcnt(1)
	v_cvt_pk_bf16_f32 v3, v4, v5
	ds_read2_b32 v[4:5], v47 offset0:132 offset1:165
	s_waitcnt lgkmcnt(0)
	v_cvt_pk_bf16_f32 v4, v4, v5
	v_cvt_pk_bf16_f32 v5, v8, v9
	v_add_u32_e32 v8, s42, v40
	v_ashrrev_i32_e32 v9, 31, v8
	v_lshlrev_b64 v[8:9], 11, v[8:9]
	v_lshl_add_u64 v[8:9], v[6:7], 0, v[8:9]
	global_store_dwordx4 v[8:9], v[2:5], off nt
	ds_read2_b32 v[2:3], v48 offset1:33
	ds_read2_b32 v[4:5], v48 offset0:66 offset1:99
	ds_read2_b32 v[8:9], v48 offset0:198 offset1:231
	s_waitcnt lgkmcnt(2)
	v_cvt_pk_bf16_f32 v2, v2, v3
	s_waitcnt lgkmcnt(1)
	v_cvt_pk_bf16_f32 v3, v4, v5
	ds_read2_b32 v[4:5], v48 offset0:132 offset1:165
	s_waitcnt lgkmcnt(0)
	v_cvt_pk_bf16_f32 v4, v4, v5
	v_cvt_pk_bf16_f32 v5, v8, v9
	v_add_u32_e32 v8, s42, v42
	v_ashrrev_i32_e32 v9, 31, v8
	v_lshlrev_b64 v[8:9], 11, v[8:9]
	v_lshl_add_u64 v[6:7], v[6:7], 0, v[8:9]
	global_store_dwordx4 v[6:7], v[2:5], off nt
	s_waitcnt lgkmcnt(0)
	s_cbranch_scc1 .LBB0_763
	s_branch .LBB0_760

; #define LAS __attribute__((address_space(3)))
; #define GAS __attribute__((address_space(1)))
; #define LDS_WAIT() asm volatile("s_waitcnt lgkmcnt(0)" ::: "memory")
; __device__ __forceinline__ void transpose_item(const float* W, int K, int N, bf16_t* WT, int k0, int n0, int drow0, LAS float* scr, int lane) {
;     f32x4 v[8];
; #pragma unroll
;     for (int j = 0; j < 8; ++j) v[j] = *(const f32x4*)(W + (size_t)(k0 + (lane >> 3) + 8 * j) * N + n0 + 4 * (lane & 7));
; #pragma unroll
;     for (int j = 0; j < 8; ++j) { LAS float* d = scr + ((lane >> 3) + 8 * j) * 33 + 4 * (lane & 7); d[0] = v[j].x; d[1] = v[j].y; d[2] = v[j].z; d[3] = v[j].w; }
;     LDS_WAIT(); asm volatile("" ::: "memory");
;     const int c = lane & 7;
; #pragma unroll
;     for (int j = 0; j < 4; ++j) { const int n = (lane >> 3) + 8 * j; const LAS float* s = scr + (8 * c) * 33 + n;
;         u32x4 o; o.x = pk2(s[0 * 33], s[1 * 33]); o.y = pk2(s[2 * 33], s[3 * 33]); o.z = pk2(s[4 * 33], s[5 * 33]); o.w = pk2(s[6 * 33], s[7 * 33]);
;         *(GAS u32x4*)(WT + (size_t)(drow0 + n) * K + k0 + 8 * c) = o; }
;     LDS_WAIT(); asm volatile("" ::: "memory");
; }
; __device__ __forceinline__ void transpose_matrix(const float* W, int K, int N, bf16_t* WT, int rowmode, LAS float* scr, int gw, int ngw, int lane) {
;     const int nblk = N / 32, nitems = (K / 64) * nblk;
;     for (int it = gw; it < nitems; it += ngw) {
;         const int kb = it / nblk, nb = it - kb * nblk, n0 = 32 * nb;
;         int drow0 = n0;
;         if (rowmode == 1) { const int up = n0 >= DFF, j0 = up ? n0 - DFF : n0; drow0 = 256 * (j0 >> 7) + 128 * up + (j0 & 127); }
;         if (rowmode == 2 && n0 >= 5120 && n0 < 6400) {
;             const int tb = 5120 + (((n0 - 5120) >> 8) << 8), hh = ((n0 - tb) >> 7) & 1, d0 = (n0 - tb) & 127; drow0 = tb + ((d0 & 32) ? 128 : 0) + hh * 64 + ((d0 >> 6) << 5); }
;         if (rowmode == 2 && n0 >= 3072 && n0 < 5120) { const int wh = n0 >= 4096, j0 = n0 - 3072 - wh * 1024; drow0 = 3072 + 256 * (j0 >> 7) + 128 * wh + (j0 & 127); }
;         transpose_item(W, K, N, WT, 64 * kb, n0, drow0, scr, lane);
.LBB0_766:
	s_ashr_i32 s7, s5, 31
	s_lshr_b32 s7, s7, 26
	s_add_i32 s7, s5, s7
	s_lshl_b32 s8, s7, 5
	s_and_b32 s8, s8, 0xfffff800
	s_and_b32 s42, s7, 0xffffffc0
	s_sub_i32 s30, s3, s8
	s_waitcnt vmcnt(1)
	v_or_b32_e32 v28, s42, v36
	s_ashr_i32 s31, s30, 31
	v_ashrrev_i32_e32 v29, 31, v28
	v_or_b32_e32 v6, 8, v28
	v_lshl_add_u64 v[18:19], s[30:31], 2, v[14:15]
	v_lshlrev_b64 v[2:3], 13, v[28:29]
	v_ashrrev_i32_e32 v7, 31, v6
	v_or_b32_e32 v10, 16, v28
	v_lshl_add_u64 v[2:3], v[18:19], 0, v[2:3]
	v_lshlrev_b64 v[6:7], 13, v[6:7]
	v_ashrrev_i32_e32 v11, 31, v10
	v_or_b32_e32 v20, 24, v28
	global_load_dwordx4 v[2:5], v[2:3], off
	v_lshl_add_u64 v[6:7], v[18:19], 0, v[6:7]
	v_lshlrev_b64 v[10:11], 13, v[10:11]
	v_ashrrev_i32_e32 v21, 31, v20
	v_or_b32_e32 v24, 32, v28
	global_load_dwordx4 v[6:9], v[6:7], off
	v_lshl_add_u64 v[10:11], v[18:19], 0, v[10:11]
	v_lshlrev_b64 v[20:21], 13, v[20:21]
	v_ashrrev_i32_e32 v25, 31, v24
	global_load_dwordx4 v[10:13], v[10:11], off
	v_lshl_add_u64 v[20:21], v[18:19], 0, v[20:21]
	v_lshlrev_b64 v[24:25], 13, v[24:25]
	v_or_b32_e32 v32, 40, v28
	global_load_dwordx4 v[20:23], v[20:21], off
	v_lshl_add_u64 v[24:25], v[18:19], 0, v[24:25]
	v_ashrrev_i32_e32 v33, 31, v32
	global_load_dwordx4 v[24:27], v[24:25], off
	v_lshlrev_b64 v[32:33], 13, v[32:33]
	v_or_b32_e32 v50, 48, v28
	v_lshl_add_u64 v[32:33], v[18:19], 0, v[32:33]
	v_ashrrev_i32_e32 v51, 31, v50
	global_load_dwordx4 v[32:35], v[32:33], off
	v_lshlrev_b64 v[50:51], 13, v[50:51]
	v_or_b32_e32 v28, 56, v28
	v_lshl_add_u64 v[50:51], v[18:19], 0, v[50:51]
	v_ashrrev_i32_e32 v29, 31, v28
	global_load_dwordx4 v[50:53], v[50:51], off
	v_lshlrev_b64 v[28:29], 13, v[28:29]
	v_lshl_add_u64 v[18:19], v[18:19], 0, v[28:29]
	global_load_dwordx4 v[54:57], v[18:19], off
	v_add_u32_e32 v18, v44, v37
	s_ashr_i32 s43, s42, 31
	s_add_i32 s5, s5, s10
	s_add_i32 s3, s3, s2
	s_cmpk_lt_i32 s5, 0x800
	s_waitcnt vmcnt(7)
	ds_write2_b32 v18, v2, v3 offset1:1
	ds_write2_b32 v18, v4, v5 offset0:2 offset1:3
	v_add_u32_e32 v2, v44, v39
	s_waitcnt vmcnt(6)
	ds_write2_b32 v2, v6, v7 offset1:1
	ds_write2_b32 v2, v8, v9 offset0:2 offset1:3
	v_add_u32_e32 v2, v44, v41
	s_waitcnt vmcnt(5)
	ds_write2_b32 v2, v10, v11 offset1:1
	ds_write2_b32 v2, v12, v13 offset0:2 offset1:3
	v_add_u32_e32 v2, v44, v43
	s_waitcnt vmcnt(4)
	ds_write2_b32 v2, v20, v21 offset1:1
	ds_write2_b32 v2, v22, v23 offset0:2 offset1:3
	v_add_u32_e32 v2, 0x1080, v18
	v_lshl_add_u64 v[6:7], s[42:43], 1, v[16:17]
	s_waitcnt vmcnt(3)
	ds_write2_b32 v2, v24, v25 offset1:1
	v_add_u32_e32 v2, 0x1088, v18
	ds_write2_b32 v2, v26, v27 offset1:1
	v_add_u32_e32 v2, 0x14a0, v18
	s_waitcnt vmcnt(2)
	ds_write2_b32 v2, v32, v33 offset1:1
	v_add_u32_e32 v2, 0x14a8, v18
	ds_write2_b32 v2, v34, v35 offset1:1
	v_add_u32_e32 v2, 0x18c0, v18
	s_waitcnt vmcnt(1)
	ds_write2_b32 v2, v50, v51 offset1:1
	v_add_u32_e32 v2, 0x18c8, v18
	ds_write2_b32 v2, v52, v53 offset1:1
	v_add_u32_e32 v2, 0x1ce0, v18
	s_waitcnt vmcnt(0)
	ds_write2_b32 v2, v54, v55 offset1:1
	v_add_u32_e32 v2, 0x1ce8, v18
	ds_write2_b32 v2, v56, v57 offset1:1
	s_waitcnt lgkmcnt(0)
	ds_read2_b32 v[2:3], v45 offset1:33
	ds_read2_b32 v[4:5], v45 offset0:66 offset1:99
	ds_read2_b32 v[8:9], v45 offset0:198 offset1:231
	s_waitcnt lgkmcnt(2)
	v_cvt_pk_bf16_f32 v2, v2, v3
	s_waitcnt lgkmcnt(1)
	v_cvt_pk_bf16_f32 v3, v4, v5
	ds_read2_b32 v[4:5], v45 offset0:132 offset1:165
	s_waitcnt lgkmcnt(0)
	v_cvt_pk_bf16_f32 v4, v4, v5
	v_cvt_pk_bf16_f32 v5, v8, v9
	v_add_u32_e32 v8, s30, v36
	v_ashrrev_i32_e32 v9, 31, v8
	v_lshlrev_b64 v[8:9], 12, v[8:9]
	v_lshl_add_u64 v[8:9], v[6:7], 0, v[8:9]
	global_store_dwordx4 v[8:9], v[2:5], off nt
	ds_read2_b32 v[2:3], v46 offset1:33
	ds_read2_b32 v[4:5], v46 offset0:66 offset1:99
	ds_read2_b32 v[8:9], v46 offset0:198 offset1:231
	s_waitcnt lgkmcnt(2)
	v_cvt_pk_bf16_f32 v2, v2, v3
	s_waitcnt lgkmcnt(1)
	v_cvt_pk_bf16_f32 v3, v4, v5
	ds_read2_b32 v[4:5], v46 offset0:132 offset1:165
	s_waitcnt lgkmcnt(0)
	v_cvt_pk_bf16_f32 v4, v4, v5
	v_cvt_pk_bf16_f32 v5, v8, v9
	v_add_u32_e32 v8, s30, v38
	v_ashrrev_i32_e32 v9, 31, v8
	v_lshlrev_b64 v[8:9], 12, v[8:9]
	v_lshl_add_u64 v[8:9], v[6:7], 0, v[8:9]
	global_store_dwordx4 v[8:9], v[2:5], off nt
	ds_read2_b32 v[2:3], v47 offset1:33
	ds_read2_b32 v[4:5], v47 offset0:66 offset1:99
	ds_read2_b32 v[8:9], v47 offset0:198 offset1:231
	s_waitcnt lgkmcnt(2)
	v_cvt_pk_bf16_f32 v2, v2, v3
	s_waitcnt lgkmcnt(1)
	v_cvt_pk_bf16_f32 v3, v4, v5
	ds_read2_b32 v[4:5], v47 offset0:132 offset1:165
	s_waitcnt lgkmcnt(0)
	v_cvt_pk_bf16_f32 v4, v4, v5
	v_cvt_pk_bf16_f32 v5, v8, v9
	v_add_u32_e32 v8, s30, v40
	v_ashrrev_i32_e32 v9, 31, v8
	v_lshlrev_b64 v[8:9], 12, v[8:9]
	v_lshl_add_u64 v[8:9], v[6:7], 0, v[8:9]
	global_store_dwordx4 v[8:9], v[2:5], off nt
	ds_read2_b32 v[2:3], v48 offset1:33
	ds_read2_b32 v[4:5], v48 offset0:66 offset1:99
	ds_read2_b32 v[8:9], v48 offset0:198 offset1:231
	s_waitcnt lgkmcnt(2)
	v_cvt_pk_bf16_f32 v2, v2, v3
	s_waitcnt lgkmcnt(1)
	v_cvt_pk_bf16_f32 v3, v4, v5
	ds_read2_b32 v[4:5], v48 offset0:132 offset1:165
	s_waitcnt lgkmcnt(0)
	v_cvt_pk_bf16_f32 v4, v4, v5
	v_cvt_pk_bf16_f32 v5, v8, v9
	v_add_u32_e32 v8, s30, v42
	v_ashrrev_i32_e32 v9, 31, v8
	v_lshlrev_b64 v[8:9], 12, v[8:9]
	v_lshl_add_u64 v[6:7], v[6:7], 0, v[8:9]
	global_store_dwordx4 v[6:7], v[2:5], off nt
	s_waitcnt lgkmcnt(0)
	s_cbranch_scc1 .LBB0_766

; #define LAS __attribute__((address_space(3)))
; #define GAS __attribute__((address_space(1)))
; #define LDS_WAIT() asm volatile("s_waitcnt lgkmcnt(0)" ::: "memory")
; __device__ __forceinline__ void transpose_item(const float* W, int K, int N, bf16_t* WT, int k0, int n0, int drow0, LAS float* scr, int lane) {
;     f32x4 v[8];
; #pragma unroll
;     for (int j = 0; j < 8; ++j) v[j] = *(const f32x4*)(W + (size_t)(k0 + (lane >> 3) + 8 * j) * N + n0 + 4 * (lane & 7));
; #pragma unroll
;     for (int j = 0; j < 8; ++j) { LAS float* d = scr + ((lane >> 3) + 8 * j) * 33 + 4 * (lane & 7); d[0] = v[j].x; d[1] = v[j].y; d[2] = v[j].z; d[3] = v[j].w; }
;     LDS_WAIT(); asm volatile("" ::: "memory");
;     const int c = lane & 7;
; #pragma unroll
;     for (int j = 0; j < 4; ++j) { const int n = (lane >> 3) + 8 * j; const LAS float* s = scr + (8 * c) * 33 + n;
;         u32x4 o; o.x = pk2(s[0 * 33], s[1 * 33]); o.y = pk2(s[2 * 33], s[3 * 33]); o.z = pk2(s[4 * 33], s[5 * 33]); o.w = pk2(s[6 * 33], s[7 * 33]);
;         *(GAS u32x4*)(WT + (size_t)(drow0 + n) * K + k0 + 8 * c) = o; }
;     LDS_WAIT(); asm volatile("" ::: "memory");
; }
; __device__ __forceinline__ void transpose_matrix(const float* W, int K, int N, bf16_t* WT, int rowmode, LAS float* scr, int gw, int ngw, int lane) {
;     const int nblk = N / 32, nitems = (K / 64) * nblk;
;     for (int it = gw; it < nitems; it += ngw) {
;         const int kb = it / nblk, nb = it - kb * nblk, n0 = 32 * nb;
;         int drow0 = n0;
;         if (rowmode == 1) { const int up = n0 >= DFF, j0 = up ? n0 - DFF : n0; drow0 = 256 * (j0 >> 7) + 128 * up + (j0 & 127); }
;         if (rowmode == 2 && n0 >= 5120 && n0 < 6400) {
;             const int tb = 5120 + (((n0 - 5120) >> 8) << 8), hh = ((n0 - tb) >> 7) & 1, d0 = (n0 - tb) & 127; drow0 = tb + ((d0 & 32) ? 128 : 0) + hh * 64 + ((d0 >> 6) << 5); }
;         if (rowmode == 2 && n0 >= 3072 && n0 < 5120) { const int wh = n0 >= 4096, j0 = n0 - 3072 - wh * 1024; drow0 = 3072 + 256 * (j0 >> 7) + 128 * wh + (j0 & 127); }
;         transpose_item(W, K, N, WT, 64 * kb, n0, drow0, scr, lane);
.LBB0_769:
	s_mul_hi_i32 s7, s5, 0x2fa0be83
	s_lshr_b32 s8, s7, 31
	s_ashr_i32 s7, s7, 6
	s_add_i32 s9, s7, s8
	s_mul_i32 s8, s9, 0xffffd500
	s_mul_i32 s7, s9, 0xfffffea8
	s_add_i32 s8, s3, s8
	s_add_i32 s7, s5, s7
	s_add_i32 s11, s8, 0xffffea80
	s_cmpk_gt_i32 s7, 0xab
	s_cselect_b32 s7, s11, s8
	s_cselect_b32 s11, 0x80, 0
	s_lshl_b32 s30, s9, 6
	s_ashr_i32 s9, s8, 31
	v_or_b32_e32 v49, s30, v36
	v_lshl_add_u64 v[2:3], s[8:9], 2, v[32:33]
	v_mad_i64_i32 v[4:5], s[8:9], v49, s27, v[2:3]
	global_load_dwordx4 v[50:53], v[4:5], off
	v_or_b32_e32 v4, 8, v49
	v_mad_i64_i32 v[4:5], s[8:9], v4, s27, v[2:3]
	global_load_dwordx4 v[26:29], v[4:5], off
	v_or_b32_e32 v4, 16, v49
	v_mad_i64_i32 v[4:5], s[8:9], v4, s27, v[2:3]
	global_load_dwordx4 v[22:25], v[4:5], off
	v_or_b32_e32 v4, 24, v49
	v_mad_i64_i32 v[4:5], s[8:9], v4, s27, v[2:3]
	global_load_dwordx4 v[18:21], v[4:5], off
	v_or_b32_e32 v4, 32, v49
	v_mad_i64_i32 v[4:5], s[8:9], v4, s27, v[2:3]
	global_load_dwordx4 v[14:17], v[4:5], off
	v_or_b32_e32 v4, 40, v49
	v_mad_i64_i32 v[4:5], s[8:9], v4, s27, v[2:3]
	global_load_dwordx4 v[10:13], v[4:5], off
	v_or_b32_e32 v4, 48, v49
	v_mad_i64_i32 v[4:5], s[8:9], v4, s27, v[2:3]
	global_load_dwordx4 v[6:9], v[4:5], off
	v_or_b32_e32 v4, 56, v49
	v_mad_i64_i32 v[2:3], s[8:9], v4, s27, v[2:3]
	global_load_dwordx4 v[2:5], v[2:3], off
	v_add_u32_e32 v49, v44, v37
	s_lshl_b32 s12, s7, 1
	s_and_b32 s7, s7, 0x60
	s_and_b32 s12, s12, 0xffffff00
	s_or_b32 s7, s7, s11
	s_or_b32 s7, s7, s12
	s_ashr_i32 s31, s30, 31
	s_add_i32 s5, s5, s10
	s_add_i32 s3, s3, s2
	s_cmpk_lt_i32 s5, 0x2b00
	s_waitcnt vmcnt(7)
	ds_write2_b32 v49, v50, v51 offset1:1
	ds_write2_b32 v49, v52, v53 offset0:2 offset1:3
	v_add_u32_e32 v50, v44, v39
	s_waitcnt vmcnt(6)
	ds_write2_b32 v50, v26, v27 offset1:1
	ds_write2_b32 v50, v28, v29 offset0:2 offset1:3
	v_add_u32_e32 v26, v44, v41
	s_waitcnt vmcnt(5)
	ds_write2_b32 v26, v22, v23 offset1:1
	ds_write2_b32 v26, v24, v25 offset0:2 offset1:3
	v_add_u32_e32 v22, v44, v43
	s_waitcnt vmcnt(4)
	ds_write2_b32 v22, v18, v19 offset1:1
	ds_write2_b32 v22, v20, v21 offset0:2 offset1:3
	v_add_u32_e32 v18, 0x1080, v49
	s_waitcnt vmcnt(3)
	ds_write2_b32 v18, v14, v15 offset1:1
	v_add_u32_e32 v14, 0x1088, v49
	ds_write2_b32 v14, v16, v17 offset1:1
	v_add_u32_e32 v14, 0x14a0, v49
	s_waitcnt vmcnt(2)
	ds_write2_b32 v14, v10, v11 offset1:1
	v_add_u32_e32 v10, 0x14a8, v49
	ds_write2_b32 v10, v12, v13 offset1:1
	v_add_u32_e32 v10, 0x18c0, v49
	s_waitcnt vmcnt(1)
	ds_write2_b32 v10, v6, v7 offset1:1
	v_add_u32_e32 v6, 0x18c8, v49
	ds_write2_b32 v6, v8, v9 offset1:1
	v_add_u32_e32 v6, 0x1ce0, v49
	s_waitcnt vmcnt(0)
	ds_write2_b32 v6, v2, v3 offset1:1
	v_add_u32_e32 v2, 0x1ce8, v49
	ds_write2_b32 v2, v4, v5 offset1:1
	s_waitcnt lgkmcnt(0)
	ds_read2_b32 v[2:3], v45 offset1:33
	ds_read2_b32 v[4:5], v45 offset0:66 offset1:99
	ds_read2_b32 v[8:9], v45 offset0:198 offset1:231
	v_lshl_add_u64 v[6:7], s[30:31], 1, v[34:35]
	s_waitcnt lgkmcnt(2)
	v_cvt_pk_bf16_f32 v2, v2, v3
	s_waitcnt lgkmcnt(1)
	v_cvt_pk_bf16_f32 v3, v4, v5
	ds_read2_b32 v[4:5], v45 offset0:132 offset1:165
	s_waitcnt lgkmcnt(0)
	v_cvt_pk_bf16_f32 v4, v4, v5
	v_cvt_pk_bf16_f32 v5, v8, v9
	v_or_b32_e32 v8, s7, v36
	v_ashrrev_i32_e32 v9, 31, v8
	v_lshlrev_b64 v[8:9], 12, v[8:9]
	v_lshl_add_u64 v[8:9], v[6:7], 0, v[8:9]
	global_store_dwordx4 v[8:9], v[2:5], off nt
	ds_read2_b32 v[2:3], v46 offset1:33
	ds_read2_b32 v[4:5], v46 offset0:66 offset1:99
	ds_read2_b32 v[8:9], v46 offset0:198 offset1:231
	s_waitcnt lgkmcnt(2)
	v_cvt_pk_bf16_f32 v2, v2, v3
	s_waitcnt lgkmcnt(1)
	v_cvt_pk_bf16_f32 v3, v4, v5
	ds_read2_b32 v[4:5], v46 offset0:132 offset1:165
	s_waitcnt lgkmcnt(0)
	v_cvt_pk_bf16_f32 v4, v4, v5
	v_cvt_pk_bf16_f32 v5, v8, v9
	v_or_b32_e32 v8, s7, v38
	v_ashrrev_i32_e32 v9, 31, v8
	v_lshlrev_b64 v[8:9], 12, v[8:9]
	v_lshl_add_u64 v[8:9], v[6:7], 0, v[8:9]
	global_store_dwordx4 v[8:9], v[2:5], off nt
	ds_read2_b32 v[2:3], v47 offset1:33
	ds_read2_b32 v[4:5], v47 offset0:66 offset1:99
	ds_read2_b32 v[8:9], v47 offset0:198 offset1:231
	s_waitcnt lgkmcnt(2)
	v_cvt_pk_bf16_f32 v2, v2, v3
	s_waitcnt lgkmcnt(1)
	v_cvt_pk_bf16_f32 v3, v4, v5
	ds_read2_b32 v[4:5], v47 offset0:132 offset1:165
	s_waitcnt lgkmcnt(0)
	v_cvt_pk_bf16_f32 v4, v4, v5
	v_cvt_pk_bf16_f32 v5, v8, v9
	v_or_b32_e32 v8, s7, v40
	v_ashrrev_i32_e32 v9, 31, v8
	v_lshlrev_b64 v[8:9], 12, v[8:9]
	v_lshl_add_u64 v[8:9], v[6:7], 0, v[8:9]
	global_store_dwordx4 v[8:9], v[2:5], off nt
	ds_read2_b32 v[2:3], v48 offset1:33
	ds_read2_b32 v[4:5], v48 offset0:66 offset1:99
	ds_read2_b32 v[8:9], v48 offset0:198 offset1:231
	s_waitcnt lgkmcnt(2)
	v_cvt_pk_bf16_f32 v2, v2, v3
	s_waitcnt lgkmcnt(1)
	v_cvt_pk_bf16_f32 v3, v4, v5
	ds_read2_b32 v[4:5], v48 offset0:132 offset1:165
	s_waitcnt lgkmcnt(0)
	v_cvt_pk_bf16_f32 v4, v4, v5
	v_cvt_pk_bf16_f32 v5, v8, v9
	v_or_b32_e32 v8, s7, v42
	v_ashrrev_i32_e32 v9, 31, v8
	v_lshlrev_b64 v[8:9], 12, v[8:9]
	v_lshl_add_u64 v[6:7], v[6:7], 0, v[8:9]
	global_store_dwordx4 v[6:7], v[2:5], off nt
	s_waitcnt lgkmcnt(0)
	s_cbranch_scc1 .LBB0_769
	v_readlane_b32 s11, v254, 50

; #define LAS __attribute__((address_space(3)))
; #define GAS __attribute__((address_space(1)))
; #define LDS_WAIT() asm volatile("s_waitcnt lgkmcnt(0)" ::: "memory")
; __device__ __forceinline__ void transpose_item(const float* W, int K, int N, bf16_t* WT, int k0, int n0, int drow0, LAS float* scr, int lane) {
;     f32x4 v[8];
; #pragma unroll
;     for (int j = 0; j < 8; ++j) v[j] = *(const f32x4*)(W + (size_t)(k0 + (lane >> 3) + 8 * j) * N + n0 + 4 * (lane & 7));
; #pragma unroll
;     for (int j = 0; j < 8; ++j) { LAS float* d = scr + ((lane >> 3) + 8 * j) * 33 + 4 * (lane & 7); d[0] = v[j].x; d[1] = v[j].y; d[2] = v[j].z; d[3] = v[j].w; }
;     LDS_WAIT(); asm volatile("" ::: "memory");
;     const int c = lane & 7;
; #pragma unroll
;     for (int j = 0; j < 4; ++j) { const int n = (lane >> 3) + 8 * j; const LAS float* s = scr + (8 * c) * 33 + n;
;         u32x4 o; o.x = pk2(s[0 * 33], s[1 * 33]); o.y = pk2(s[2 * 33], s[3 * 33]); o.z = pk2(s[4 * 33], s[5 * 33]); o.w = pk2(s[6 * 33], s[7 * 33]);
;         *(GAS u32x4*)(WT + (size_t)(drow0 + n) * K + k0 + 8 * c) = o; }
;     LDS_WAIT(); asm volatile("" ::: "memory");
; }
; __device__ __forceinline__ void transpose_matrix(const float* W, int K, int N, bf16_t* WT, int rowmode, LAS float* scr, int gw, int ngw, int lane) {
;     const int nblk = N / 32, nitems = (K / 64) * nblk;
;     for (int it = gw; it < nitems; it += ngw) {
;         const int kb = it / nblk, nb = it - kb * nblk, n0 = 32 * nb;
;         int drow0 = n0;
;         if (rowmode == 1) { const int up = n0 >= DFF, j0 = up ? n0 - DFF : n0; drow0 = 256 * (j0 >> 7) + 128 * up + (j0 & 127); }
;         if (rowmode == 2 && n0 >= 5120 && n0 < 6400) {
;             const int tb = 5120 + (((n0 - 5120) >> 8) << 8), hh = ((n0 - tb) >> 7) & 1, d0 = (n0 - tb) & 127; drow0 = tb + ((d0 & 32) ? 128 : 0) + hh * 64 + ((d0 >> 6) << 5); }
;         if (rowmode == 2 && n0 >= 3072 && n0 < 5120) { const int wh = n0 >= 4096, j0 = n0 - 3072 - wh * 1024; drow0 = 3072 + 256 * (j0 >> 7) + 128 * wh + (j0 & 127); }
;         transpose_item(W, K, N, WT, 64 * kb, n0, drow0, scr, lane);
.LBB0_773:
	s_ashr_i32 s5, s3, 31
	s_lshr_b32 s5, s5, 26
	s_add_i32 s5, s3, s5
	s_lshl_b32 s7, s5, 5
	s_and_b32 s7, s7, 0xfffff800
	s_and_b32 s38, s5, 0xffffffc0
	s_sub_i32 s30, s1, s7
	v_or_b32_e32 v50, s38, v36
	s_ashr_i32 s31, s30, 31
	v_ashrrev_i32_e32 v51, 31, v50
	v_or_b32_e32 v6, 8, v50
	v_lshl_add_u64 v[18:19], s[30:31], 2, v[14:15]
	v_lshlrev_b64 v[2:3], 13, v[50:51]
	v_ashrrev_i32_e32 v7, 31, v6
	v_or_b32_e32 v10, 16, v50
	v_lshl_add_u64 v[2:3], v[18:19], 0, v[2:3]
	v_lshlrev_b64 v[6:7], 13, v[6:7]
	v_ashrrev_i32_e32 v11, 31, v10
	v_or_b32_e32 v20, 24, v50
	global_load_dwordx4 v[2:5], v[2:3], off
	v_lshl_add_u64 v[6:7], v[18:19], 0, v[6:7]
	v_lshlrev_b64 v[10:11], 13, v[10:11]
	v_ashrrev_i32_e32 v21, 31, v20
	v_or_b32_e32 v24, 32, v50
	global_load_dwordx4 v[6:9], v[6:7], off
	v_lshl_add_u64 v[10:11], v[18:19], 0, v[10:11]
	v_lshlrev_b64 v[20:21], 13, v[20:21]
	v_ashrrev_i32_e32 v25, 31, v24
	global_load_dwordx4 v[10:13], v[10:11], off
	v_lshl_add_u64 v[20:21], v[18:19], 0, v[20:21]
	v_lshlrev_b64 v[24:25], 13, v[24:25]
	s_waitcnt vmcnt(4)
	v_or_b32_e32 v28, 40, v50
	global_load_dwordx4 v[20:23], v[20:21], off
	v_lshl_add_u64 v[24:25], v[18:19], 0, v[24:25]
	v_ashrrev_i32_e32 v29, 31, v28
	global_load_dwordx4 v[24:27], v[24:25], off
	v_lshlrev_b64 v[28:29], 13, v[28:29]
	v_or_b32_e32 v32, 48, v50
	v_lshl_add_u64 v[28:29], v[18:19], 0, v[28:29]
	v_ashrrev_i32_e32 v33, 31, v32
	global_load_dwordx4 v[28:31], v[28:29], off
	v_lshlrev_b64 v[32:33], 13, v[32:33]
	v_or_b32_e32 v50, 56, v50
	v_lshl_add_u64 v[32:33], v[18:19], 0, v[32:33]
	v_ashrrev_i32_e32 v51, 31, v50
	global_load_dwordx4 v[32:35], v[32:33], off
	v_lshlrev_b64 v[50:51], 13, v[50:51]
	v_lshl_add_u64 v[18:19], v[18:19], 0, v[50:51]
	global_load_dwordx4 v[50:53], v[18:19], off
	v_add_u32_e32 v18, v44, v37
	s_ashr_i32 s39, s38, 31
	s_add_i32 s3, s3, s10
	s_add_i32 s1, s1, s2
	s_cmpk_lt_i32 s3, 0x1580
	s_waitcnt vmcnt(7)
	ds_write2_b32 v18, v2, v3 offset1:1
	ds_write2_b32 v18, v4, v5 offset0:2 offset1:3
	v_add_u32_e32 v2, v44, v39
	s_waitcnt vmcnt(6)
	ds_write2_b32 v2, v6, v7 offset1:1
	ds_write2_b32 v2, v8, v9 offset0:2 offset1:3
	v_add_u32_e32 v2, v44, v41
	s_waitcnt vmcnt(5)
	ds_write2_b32 v2, v10, v11 offset1:1
	ds_write2_b32 v2, v12, v13 offset0:2 offset1:3
	v_add_u32_e32 v2, v44, v43
	s_waitcnt vmcnt(4)
	ds_write2_b32 v2, v20, v21 offset1:1
	ds_write2_b32 v2, v22, v23 offset0:2 offset1:3
	v_add_u32_e32 v2, 0x1080, v18
	v_lshl_add_u64 v[6:7], s[38:39], 1, v[16:17]
	s_waitcnt vmcnt(3)
	ds_write2_b32 v2, v24, v25 offset1:1
	v_add_u32_e32 v2, 0x1088, v18
	ds_write2_b32 v2, v26, v27 offset1:1
	v_add_u32_e32 v2, 0x14a0, v18
	s_waitcnt vmcnt(2)
	ds_write2_b32 v2, v28, v29 offset1:1
	v_add_u32_e32 v2, 0x14a8, v18
	ds_write2_b32 v2, v30, v31 offset1:1
	v_add_u32_e32 v2, 0x18c0, v18
	s_waitcnt vmcnt(1)
	ds_write2_b32 v2, v32, v33 offset1:1
	v_add_u32_e32 v2, 0x18c8, v18
	ds_write2_b32 v2, v34, v35 offset1:1
	v_add_u32_e32 v2, 0x1ce0, v18
	s_waitcnt vmcnt(0)
	ds_write2_b32 v2, v50, v51 offset1:1
	v_add_u32_e32 v2, 0x1ce8, v18
	ds_write2_b32 v2, v52, v53 offset1:1
	s_waitcnt lgkmcnt(0)
	ds_read2_b32 v[2:3], v45 offset1:33
	ds_read2_b32 v[4:5], v45 offset0:66 offset1:99
	ds_read2_b32 v[8:9], v45 offset0:198 offset1:231
	s_waitcnt lgkmcnt(2)
	v_cvt_pk_bf16_f32 v2, v2, v3
	s_waitcnt lgkmcnt(1)
	v_cvt_pk_bf16_f32 v3, v4, v5
	ds_read2_b32 v[4:5], v45 offset0:132 offset1:165
	s_waitcnt lgkmcnt(0)
	v_cvt_pk_bf16_f32 v4, v4, v5
	v_cvt_pk_bf16_f32 v5, v8, v9
	v_add_u32_e32 v8, s30, v36
	v_mad_i64_i32 v[8:9], s[8:9], v8, s57, v[6:7]
	global_store_dwordx4 v[8:9], v[2:5], off nt
	ds_read2_b32 v[2:3], v46 offset1:33
	ds_read2_b32 v[4:5], v46 offset0:66 offset1:99
	ds_read2_b32 v[8:9], v46 offset0:198 offset1:231
	s_waitcnt lgkmcnt(2)
	v_cvt_pk_bf16_f32 v2, v2, v3
	s_waitcnt lgkmcnt(1)
	v_cvt_pk_bf16_f32 v3, v4, v5
	ds_read2_b32 v[4:5], v46 offset0:132 offset1:165
	s_waitcnt lgkmcnt(0)
	v_cvt_pk_bf16_f32 v4, v4, v5
	v_cvt_pk_bf16_f32 v5, v8, v9
	v_add_u32_e32 v8, s30, v38
	v_mad_i64_i32 v[8:9], s[8:9], v8, s57, v[6:7]
	global_store_dwordx4 v[8:9], v[2:5], off nt
	ds_read2_b32 v[2:3], v47 offset1:33
	ds_read2_b32 v[4:5], v47 offset0:66 offset1:99
	ds_read2_b32 v[8:9], v47 offset0:198 offset1:231
	s_waitcnt lgkmcnt(2)
	v_cvt_pk_bf16_f32 v2, v2, v3
	s_waitcnt lgkmcnt(1)
	v_cvt_pk_bf16_f32 v3, v4, v5
	ds_read2_b32 v[4:5], v47 offset0:132 offset1:165
	s_waitcnt lgkmcnt(0)
	v_cvt_pk_bf16_f32 v4, v4, v5
	v_cvt_pk_bf16_f32 v5, v8, v9
	v_add_u32_e32 v8, s30, v40
	v_mad_i64_i32 v[8:9], s[8:9], v8, s57, v[6:7]
	global_store_dwordx4 v[8:9], v[2:5], off nt
	ds_read2_b32 v[2:3], v48 offset1:33
	ds_read2_b32 v[4:5], v48 offset0:66 offset1:99
	ds_read2_b32 v[8:9], v48 offset0:198 offset1:231
	s_waitcnt lgkmcnt(2)
	v_cvt_pk_bf16_f32 v2, v2, v3
	s_waitcnt lgkmcnt(1)
	v_cvt_pk_bf16_f32 v3, v4, v5
	ds_read2_b32 v[4:5], v48 offset0:132 offset1:165
	s_waitcnt lgkmcnt(0)
	v_cvt_pk_bf16_f32 v4, v4, v5
	v_cvt_pk_bf16_f32 v5, v8, v9
	v_add_u32_e32 v8, s30, v42
	v_mad_i64_i32 v[6:7], s[8:9], v8, s57, v[6:7]
	global_store_dwordx4 v[6:7], v[2:5], off nt
	s_waitcnt lgkmcnt(0)
	s_cbranch_scc1 .LBB0_773

;     __host__ __device__ bool tile(int i, int& pm, int& pn) const { return tile(i, pm, pn, nwg); }
; __device__ __forceinline__ void convert_weights(const Args& a, int layer, LAS unsigned char* lds, int gw, int ngw, int wave, int lane) {
;     ...
;     for (int it = gw * 64 + lane; it < 4096 * 16; it += ngw * 64) {
;         const int row = it >> 4, din0 = (it & 15) * 8;
;         const int tile = row >> 8, gate = (row >> 7) & 1, e = row & 127, d = tile >> 3, q = tile & 7;
;         const float* src = (gate ? a.lru_w_x : a.lru_w_a) + ((((size_t)layer * 2 + d) * 8 + q) * 128 + din0) * 128 + e;
;         u32x4 o; o.x = pk2(src[0 * 128], src[1 * 128]); o.y = pk2(src[2 * 128], src[3 * 128]); o.z = pk2(src[4 * 128], src[5 * 128]); o.w = pk2(src[6 * 128], src[7 * 128]);
;         *(u32x4*)(wg + (size_t)row * 128 + din0) = o;
;     }
.LBB0_776:
	v_and_b32_e32 v5, 0x800, v2
	v_cmp_eq_u32_e32 vcc, 0, v5
	v_mov_b32_e32 v5, s17
	v_mov_b32_e32 v6, s13
	v_ashrrev_i32_e32 v4, 15, v2
	v_cndmask_b32_e32 v7, v5, v6, vcc
	v_mov_b32_e32 v5, s16
	v_mov_b32_e32 v6, s12
	v_cndmask_b32_e32 v6, v5, v6, vcc
	v_ashrrev_i32_e32 v5, 31, v4
	v_lshlrev_b64 v[4:5], 19, v[4:5]
	v_lshlrev_b32_e32 v9, 4, v2
	v_ashrrev_i32_e32 v8, 4, v2
	v_and_b32_e32 v12, 0x78, v3
	v_and_or_b32 v4, v9, s28, v4
	v_lshl_add_u64 v[4:5], v[6:7], 0, v[4:5]
	v_lshlrev_b32_e32 v174, 9, v12
	v_lshlrev_b32_e32 v6, 2, v8
	v_lshl_add_u64 v[4:5], v[4:5], 0, v[174:175]
	v_and_b32_e32 v174, 0x1fc, v6
	v_lshl_add_u64 v[4:5], v[4:5], 0, v[174:175]
	v_lshl_add_u64 v[10:11], v[4:5], 0, s[8:9]
	v_add_co_u32_e32 v4, vcc, s56, v4
	v_add_u32_e32 v2, s1, v2
	s_nop 0
	v_addc_co_u32_e32 v5, vcc, 0, v5, vcc
	global_load_dword v4, v[4:5], off
	s_nop 0
	global_load_dword v5, v[10:11], off offset:512
	v_lshlrev_b32_e32 v174, 1, v12
	v_cmp_lt_i32_e32 vcc, s26, v2
	v_add_u32_e32 v3, s2, v3
	s_or_b64 s[40:41], vcc, s[40:41]
	s_waitcnt vmcnt(0)
	v_cvt_pk_bf16_f32 v4, v4, v5
	global_load_dword v5, v[10:11], off offset:1024
	global_load_dword v6, v[10:11], off offset:1536
	s_waitcnt vmcnt(0)
	v_cvt_pk_bf16_f32 v5, v5, v6
	global_load_dword v6, v[10:11], off offset:2048
	global_load_dword v7, v[10:11], off offset:2560
	s_waitcnt vmcnt(0)
	v_cvt_pk_bf16_f32 v6, v6, v7
	global_load_dword v7, v[10:11], off offset:3072
	global_load_dword v9, v[10:11], off offset:3584
	s_waitcnt vmcnt(0)
	v_cvt_pk_bf16_f32 v7, v7, v9
	v_ashrrev_i32_e32 v9, 31, v8
	v_lshlrev_b64 v[8:9], 8, v[8:9]
	v_lshl_add_u64 v[8:9], s[38:39], 0, v[8:9]
	v_lshl_add_u64 v[8:9], v[8:9], 0, v[174:175]
	global_store_dwordx4 v[8:9], v[4:7], off nt
	s_andn2_b64 exec, exec, s[40:41]
	s_cbranch_execnz .LBB0_776

;     template <int QVV> __device__ __forceinline__ void run(f32x4 (&acc)[2][2][4][2], const Unit& u, int wr, int wc, int fr, int fq) const {
;         const int d = u.pn >> 3, q = u.pn & 7;
;         const char* xb = (const char*)(XA + (size_t)u.pm * BM * 1024 + q * HALF);
;         char* lb = (char*)(LU + ((size_t)(d * 1024 + q * HALF)) * MT + (size_t)u.pm * BM);
;         unsigned cl = (unsigned)(wc * 32 + fr), tl = (unsigned)(wr * 64 + 4 * fq);
;         asm volatile("" : "+v"(cl), "+v"(tl));
;         const float* bb = ba + d * 1024 + q * HALF; const float* xbb = bx + d * 1024 + q * HALF; const float* cbb = c8 + d * 1024 + q * HALF;
;         unsigned short xw[2][2][4][4];
; #pragma unroll
;         for (int n = 0; n < 2; ++n)
; #pragma unroll
;             for (int ai = 0; ai < 2; ++ai)
; #pragma unroll
;                 for (int m = 0; m < 4; ++m)
; #pragma unroll
;                     for (int i = 0; i < 4; ++i) xw[n][ai][m][i] = *(const unsigned short*)(xb + ((tl + (unsigned)(ai * HALF + m * 16 + i)) * 1024u + cl + 16u * n) * 2u);
.LBB0_791:
	s_ashr_i32 s53, s52, 31
	s_ashr_i32 s96, s88, 3
	s_lshl_b64 s[30:31], s[52:53], 19
	s_add_u32 s30, s76, s30
	s_addc_u32 s31, s12, s31
	s_lshl_b32 s7, s88, 7
	s_and_b32 s7, s7, 0x380
	v_mov_b32_e32 v138, v133
	v_mov_b32_e32 v174, v137
	s_lshl_b32 s46, s7, 1
	s_add_u32 s46, s30, s46
	v_lshlrev_b32_e32 v140, 11, v174
	v_lshlrev_b32_e32 v139, 1, v138
	v_add_u32_e32 v149, 0x8000, v140
	s_addc_u32 s47, s31, 0
	v_add_u32_e32 v150, v149, v139
	global_load_ushort v223, v150, s[46:47]
	v_add_u32_e32 v150, 0x8800, v140
	v_add_u32_e32 v151, v150, v139
	global_load_ushort v222, v151, s[46:47]
	v_add_u32_e32 v151, 0x9000, v140
	v_add_u32_e32 v155, v151, v139
	global_load_ushort v221, v155, s[46:47]
	v_add_u32_e32 v155, 0x9800, v140
	v_add_u32_e32 v156, v155, v139
	global_load_ushort v220, v156, s[46:47]
	v_add_u32_e32 v156, 0x10000, v140
	v_add_u32_e32 v157, v156, v139
	global_load_ushort v219, v157, s[46:47]
	v_add_u32_e32 v157, 0x10800, v140
	v_add_u32_e32 v158, v157, v139
	global_load_ushort v218, v158, s[46:47]
	v_add_u32_e32 v158, 0x11000, v140
	v_add_u32_e32 v159, v158, v139
	global_load_ushort v217, v159, s[46:47]
	v_add_u32_e32 v159, 0x11800, v140
	v_add_u32_e32 v160, v159, v139
	global_load_ushort v216, v160, s[46:47]
	v_add_u32_e32 v160, 0x18000, v140
	v_add_u32_e32 v161, v160, v139
	global_load_ushort v215, v161, s[46:47]
	v_add_u32_e32 v161, 0x18800, v140
	v_add_u32_e32 v162, v161, v139
	global_load_ushort v214, v162, s[46:47]
	v_add_u32_e32 v162, 0x19000, v140
	v_add_u32_e32 v163, v162, v139
	global_load_ushort v212, v163, s[46:47]
	v_add_u32_e32 v163, 0x19800, v140
	v_add_u32_e32 v164, v163, v139
	global_load_ushort v213, v164, s[46:47]
	v_add_u32_e32 v164, 0x40000, v140
	v_add_u32_e32 v165, v164, v139
	global_load_ushort v211, v165, s[46:47]
	v_add_u32_e32 v165, 0x40800, v140
	v_add_u32_e32 v166, v165, v139
	global_load_ushort v210, v166, s[46:47]
	v_add_u32_e32 v166, 0x41000, v140
	v_add_u32_e32 v167, v166, v139
	global_load_ushort v209, v167, s[46:47]
	v_add_u32_e32 v167, 0x41800, v140
	v_add_u32_e32 v168, v167, v139
	v_add_u32_e32 v177, 0x48000, v140
	global_load_ushort v208, v168, s[46:47]
	v_add_u32_e32 v168, v177, v139
	v_add_u32_e32 v180, 0x48800, v140
	global_load_ushort v205, v168, s[46:47]
	v_add_u32_e32 v168, v180, v139
	v_add_u32_e32 v181, 0x49000, v140
	global_load_ushort v204, v168, s[46:47]
	v_add_u32_e32 v168, v181, v139
	v_add_u32_e32 v206, 0x49800, v140
	global_load_ushort v202, v168, s[46:47]
	v_add_u32_e32 v168, v206, v139
	v_add_u32_e32 v207, 0x50000, v140
	global_load_ushort v203, v168, s[46:47]
	v_add_u32_e32 v168, v207, v139
	v_add_u32_e32 v224, 0x50800, v140
	global_load_ushort v201, v168, s[46:47]
	v_add_u32_e32 v168, v224, v139
	v_add_u32_e32 v225, 0x51000, v140
	global_load_ushort v200, v168, s[46:47]
	v_add_u32_e32 v168, v225, v139
	v_add_u32_e32 v226, 0x51800, v140
	v_add_u32_e32 v141, 0x58000, v140
	global_load_ushort v199, v168, s[46:47]
	v_add_u32_e32 v168, v226, v139
	global_load_ushort v198, v168, s[46:47]
	v_add_u32_e32 v168, v141, v139
	v_add_u32_e32 v227, 0x58800, v140
	global_load_ushort v197, v168, s[46:47]
	v_add_u32_e32 v168, v227, v139
	v_add_u32_e32 v228, 0x59000, v140
	v_add_u32_e32 v142, 0x800, v140
	v_add_u32_e32 v147, 0x1000, v140
	v_add_u32_e32 v148, 0x1800, v140
	global_load_ushort v196, v168, s[46:47]
	v_add_u32_e32 v168, v228, v139
	v_add_u32_e32 v229, 0x59800, v140
	v_add_u32_e32 v146, v139, v140
	v_add_u32_e32 v144, v142, v139
	v_add_u32_e32 v143, v147, v139
	v_add_u32_e32 v145, v148, v139
	global_load_ushort v195, v168, s[46:47]
	v_add_u32_e32 v168, v229, v139
	v_add_u32_e32 v139, 32, v139
	v_add_u32_e32 v140, v139, v140
	global_load_ushort v194, v168, s[46:47]
	global_load_ushort v193, v140, s[46:47]
	v_add_u32_e32 v140, v139, v142
	global_load_ushort v192, v140, s[46:47]
	v_add_u32_e32 v140, v139, v147
	global_load_ushort v191, v140, s[46:47]
	v_add_u32_e32 v140, v139, v148
	global_load_ushort v190, v140, s[46:47]
	v_add_u32_e32 v140, v139, v149
	global_load_ushort v189, v140, s[46:47]
	v_add_u32_e32 v140, v139, v150
	global_load_ushort v188, v140, s[46:47]
	v_add_u32_e32 v140, v139, v151
	global_load_ushort v187, v140, s[46:47]
	v_add_u32_e32 v140, v139, v155
	global_load_ushort v186, v140, s[46:47]
	v_add_u32_e32 v140, v139, v156
	global_load_ushort v185, v140, s[46:47]
	v_add_u32_e32 v140, v139, v157
	global_load_ushort v184, v140, s[46:47]
	v_add_u32_e32 v140, v139, v158
	global_load_ushort v183, v140, s[46:47]
	v_add_u32_e32 v140, v139, v159
	global_load_ushort v182, v140, s[46:47]
	v_add_u32_e32 v140, v139, v160
	global_load_ushort v179, v140, s[46:47]
	v_add_u32_e32 v140, v139, v161
	global_load_ushort v178, v140, s[46:47]
	v_add_u32_e32 v140, v139, v162
	global_load_ushort v173, v140, s[46:47]
	v_add_u32_e32 v140, v139, v163
	global_load_ushort v172, v140, s[46:47]
	v_add_u32_e32 v140, v139, v164
	global_load_ushort v170, v140, s[46:47]
	v_add_u32_e32 v140, v139, v165
	s_lshl_b32 s50, s96, 10
	global_load_ushort v169, v140, s[46:47]
	v_add_u32_e32 v140, v139, v166
	s_ashr_i32 s51, s50, 31
	global_load_ushort v168, v140, s[46:47]
	v_add_u32_e32 v140, v139, v167
	s_or_b32 s49, s50, s7
	s_lshl_b64 s[30:31], s[52:53], 10
	s_lshl_b64 s[74:75], s[50:51], 2
	global_load_ushort v167, v140, s[46:47]
	v_add_u32_e32 v140, v139, v177
	s_add_u32 s72, s26, s74
	global_load_ushort v166, v140, s[46:47]
	v_add_u32_e32 v140, v139, v180
	s_addc_u32 s73, s27, s75
	global_load_ushort v165, v140, s[46:47]
	v_add_u32_e32 v140, v139, v181
	s_add_u32 s50, s80, s74
	global_load_ushort v164, v140, s[46:47]
;     template <int QVV> __device__ __forceinline__ void run(f32x4 (&acc)[2][2][4][2], const Unit& u, int wr, int wc, int fr, int fq) const {
;     ...
;                     for (int i = 0; i < 4; ++i) xw[n][ai][m][i] = *(const unsigned short*)(xb + ((tl + (unsigned)(ai * HALF + m * 16 + i)) * 1024u + cl + 16u * n) * 2u);
;         const int lane_hi = fq;
; #pragma unroll
;         for (int n = 0; n < 2; ++n) {
;             const unsigned ch = cl + 16u * n;
;             const float bavn = bb[ch] * (-LOG2E), bxvn = xbb[ch] * (-LOG2E), c8l = cbb[ch] * LOG2E;
; #pragma unroll
;             for (int ai = 0; ai < 2; ++ai) {
;                 float Pm[4], Hm[4];
; #pragma unroll
;                 for (int m = 0; m < 4; ++m) {
;                     unsigned w[4]; float av[4], uv[4];
; #pragma unroll
;                     for (int i = 0; i < 4; ++i) {
;                         const float er = 1.0f + __builtin_amdgcn_exp2f(__builtin_fmaf(acc[ai][0][m][n][i], -LOG2E, bavn)), ei = 1.0f + __builtin_amdgcn_exp2f(__builtin_fmaf(acc[ai][1][m][n][i], -LOG2E, bxvn));
;                         const float rr = __builtin_amdgcn_rcpf(er * ei), rgt = rr * ei, igt = rr * er;
;                         const float l2 = c8l * rgt;
;                         const float a1 = __builtin_amdgcn_exp2f(__uint_as_float(pk2(l2, 0.f) << 16));
;                         const float mult = __builtin_amdgcn_sqrtf(fmaxf(__builtin_fmaf(-a1, a1, 1.0f), 0.0f));
;                         w[i] = pk2(l2, mult * igt * __uint_as_float((unsigned)xw[n][ai][m][i] << 16));
;                         av[i] = a1; uv[i] = __uint_as_float(w[i] & 0xffff0000u);
;                     }
;                     *(u32x4*)(lb + ((size_t)ch * MT + tl + (unsigned)(ai * HALF + m * 16)) * 4u) = (u32x4){w[0], w[1], w[2], w[3]};
;                     float P = 1.f, H = 0.f;
;                     if (d == 0) {
; #pragma unroll
;                         for (int i = 0; i < 4; ++i) { H = av[i] * H + uv[i]; P *= av[i]; }
	v_add_u32_e32 v140, v139, v206
	s_addc_u32 s51, s11, s75
	global_load_ushort v163, v140, s[46:47]
	v_add_u32_e32 v140, v139, v207
	s_add_u32 s53, s28, s74
	global_load_ushort v162, v140, s[46:47]
	v_add_u32_e32 v140, v139, v224
	s_mul_hi_i32 s48, s49, 0x21000
	s_mul_i32 s49, s49, 0x21000
	s_addc_u32 s89, s29, s75
	global_load_ushort v161, v140, s[46:47]
	v_add_u32_e32 v140, v139, v225
	v_readlane_b32 s74, v254, 47
	global_load_ushort v160, v140, s[46:47]
	v_add_u32_e32 v140, v139, v226
	s_add_u32 s49, s74, s49
	global_load_ushort v159, v140, s[46:47]
	v_add_u32_e32 v140, v139, v141
	s_addc_u32 s48, s23, s48
	global_load_ushort v158, v140, s[46:47]
	v_add_u32_e32 v140, v139, v227
	s_add_u32 s86, s49, s30
	global_load_ushort v157, v140, s[46:47]
	v_add_u32_e32 v140, v139, v228
	v_add_u32_e32 v139, v139, v229
	s_addc_u32 s87, s48, s31
	s_lshl_b32 s30, s7, 2
	global_load_ushort v156, v140, s[46:47]
	global_load_ushort v155, v139, s[46:47]
	s_add_u32 s72, s72, s30
	v_mov_b32_e32 v139, v175
	s_addc_u32 s73, s73, 0
	v_lshlrev_b64 v[140:141], 2, v[138:139]
	v_lshl_add_u64 v[148:149], s[72:73], 0, v[140:141]
	global_load_dword v142, v[148:149], off
	s_add_u32 s74, s50, s30
	s_addc_u32 s75, s51, 0
	v_lshl_add_u64 v[148:149], s[74:75], 0, v[140:141]
	s_add_u32 s90, s53, s30
	s_addc_u32 s91, s89, 0
	v_lshl_add_u64 v[140:141], s[90:91], 0, v[140:141]
	s_cmp_gt_u32 s88, 7
	s_cselect_b64 s[50:51], -1, 0
	s_cmp_lt_u32 s88, 8
	s_mov_b32 s48, 0x8400
	s_cselect_b64 s[30:31], -1, 0
	s_and_b64 vcc, exec, s[30:31]
	s_waitcnt vmcnt(0)
	v_mul_f32_e32 v206, 0xbfb8aa3b, v142
	global_load_dword v142, v[148:149], off
	v_fmamk_f32 v126, v126, 0xbfb8aa3b, v206
	v_exp_f32_e32 v148, v126
	s_waitcnt vmcnt(0)
	v_mul_f32_e32 v207, 0xbfb8aa3b, v142
	v_fmamk_f32 v122, v122, 0xbfb8aa3b, v207
	v_exp_f32_e32 v149, v122
	v_fmamk_f32 v123, v123, 0xbfb8aa3b, v207
	v_exp_f32_e32 v123, v123
	global_load_dword v142, v[140:141], off
	v_pk_add_f32 v[148:149], v[148:149], 1.0 op_sel_hi:[1,0]
	s_nop 0
	v_mul_f32_e32 v122, v148, v149
	v_rcp_f32_e32 v122, v122
	s_nop 0
	v_mul_f32_e32 v147, v149, v122
	v_mul_f32_e32 v148, v148, v122
	global_load_ushort v122, v146, s[46:47]
	s_waitcnt vmcnt(0)
	v_lshlrev_b32_e32 v146, 16, v122
	v_fmamk_f32 v122, v127, 0xbfb8aa3b, v206
	v_exp_f32_e32 v122, v122
	s_nop 0
	v_pk_add_f32 v[122:123], v[122:123], 1.0 op_sel_hi:[1,0]
	s_nop 0
	v_mul_f32_e32 v126, v122, v123
	v_rcp_f32_e32 v126, v126
	s_nop 0
	v_mul_f32_e32 v150, v122, v126
	global_load_ushort v122, v144, s[46:47]
	v_mul_f32_e32 v149, v123, v126
	v_fmamk_f32 v123, v124, 0xbfb8aa3b, v207
	v_exp_f32_e32 v123, v123
	s_waitcnt vmcnt(0)
	v_lshlrev_b32_e32 v151, 16, v122
	v_fmamk_f32 v122, v128, 0xbfb8aa3b, v206
	v_exp_f32_e32 v122, v122
	s_nop 0
	v_pk_add_f32 v[122:123], v[122:123], 1.0 op_sel_hi:[1,0]
	s_nop 0
	v_mul_f32_e32 v124, v122, v123
	v_rcp_f32_e32 v124, v124
	s_nop 0
	v_mul_f32_e32 v180, v123, v124
	v_mul_f32_e32 v124, v122, v124
	global_load_ushort v122, v143, s[46:47]
	v_fmamk_f32 v123, v125, 0xbfb8aa3b, v207
	v_exp_f32_e32 v123, v123
	v_mad_u64_u32 v[140:141], s[48:49], v138, s48, v[174:175]
	s_waitcnt vmcnt(0)
	v_lshlrev_b32_e32 v181, 16, v122
	v_fmamk_f32 v122, v129, 0xbfb8aa3b, v206
	v_exp_f32_e32 v122, v122
	s_nop 0
	v_pk_add_f32 v[128:129], v[122:123], 1.0 op_sel_hi:[1,0]
	s_nop 0
	v_mul_f32_e32 v122, v128, v129
	v_rcp_f32_e32 v177, v122
	v_mov_b32_e32 v143, v129
	v_pk_mul_f32 v[126:127], v[142:143], v[176:177]
	s_nop 0
	v_mul_f32_e32 v122, v126, v147
	v_cvt_pk_bf16_f32 v123, v122, 0
	v_lshlrev_b32_e32 v123, 16, v123
	v_exp_f32_e32 v142, v123
	s_nop 0
	v_fma_f32 v123, -v142, v142, 1.0
	v_max_f32_e32 v123, 0, v123
	v_sqrt_f32_e32 v123, v123
	s_nop 0
	v_mul_f32_e32 v123, v148, v123
	v_mul_f32_e32 v123, v123, v146
	v_cvt_pk_bf16_f32 v122, v122, v123
	v_mul_f32_e32 v123, v126, v149
	v_cvt_pk_bf16_f32 v125, v123, 0
	v_lshlrev_b32_e32 v125, 16, v125
	v_exp_f32_e32 v143, v125
	v_and_b32_e32 v144, 0xffff0000, v122
	v_fma_f32 v125, -v143, v143, 1.0
	v_max_f32_e32 v125, 0, v125
	v_sqrt_f32_e32 v125, v125
	s_nop 0
	v_mul_f32_e32 v125, v150, v125
	v_mul_f32_e32 v125, v125, v151
	v_cvt_pk_bf16_f32 v123, v123, v125
	v_mul_f32_e32 v125, v126, v180
	v_cvt_pk_bf16_f32 v129, v125, 0
	v_lshlrev_b32_e32 v129, 16, v129
	v_exp_f32_e32 v149, v129
	v_and_b32_e32 v146, 0xffff0000, v123
	v_fma_f32 v129, -v149, v149, 1.0
	v_max_f32_e32 v129, 0, v129
	v_sqrt_f32_e32 v129, v129
	s_nop 0
	v_mul_f32_e32 v124, v124, v129
	v_mul_f32_e32 v124, v124, v181
	v_cvt_pk_bf16_f32 v124, v125, v124
	v_mul_f32_e32 v125, v128, v177
	v_pk_mul_f32 v[128:129], v[126:127], v[126:127] op_sel:[0,1] op_sel_hi:[1,0]
	v_and_b32_e32 v224, 0xffff0000, v124
	v_cvt_pk_bf16_f32 v127, v128, 0
	v_lshlrev_b32_e32 v127, 16, v127
	v_exp_f32_e32 v148, v127
	s_nop 0
	v_fma_f32 v127, -v148, v148, 1.0
	v_max_f32_e32 v127, 0, v127
	v_sqrt_f32_e32 v127, v127
	s_nop 0
	v_mul_f32_e32 v125, v125, v127
	global_load_ushort v127, v145, s[46:47]
	s_mov_b64 s[46:47], -1
	s_waitcnt vmcnt(0)
	v_lshlrev_b32_e32 v127, 16, v127
	v_mul_f32_e32 v125, v125, v127
	v_cvt_pk_bf16_f32 v125, v128, v125
	v_and_b32_e32 v150, 0xffff0000, v125
	v_lshl_add_u64 v[128:129], v[140:141], 2, s[86:87]
	global_store_dwordx4 v[128:129], v[122:125], off nt
	s_cbranch_vccz .LBB0_793
	s_nop 0
	v_fma_f32 v122, 0, v142, v144
	v_fma_f32 v122, v143, v122, v146
	v_mul_f32_e32 v123, v142, v143
	v_fma_f32 v122, v149, v122, v224
	v_pk_mul_f32 v[140:141], v[148:149], v[122:123]
	v_mov_b32_e32 v151, v148
	v_pk_fma_f32 v[124:125], v[148:149], v[122:123], v[150:151]
	v_pk_mul_f32 v[122:123], v[140:141], v[150:151]
	s_mov_b64 s[46:47], 0

;     template <int QVV> __device__ __forceinline__ void run(f32x4 (&acc)[2][2][4][2], const Unit& u, int wr, int wc, int fr, int fq) const {
;     ...
;                     for (int i = 0; i < 4; ++i) {
;                         const float er = 1.0f + __builtin_amdgcn_exp2f(__builtin_fmaf(acc[ai][0][m][n][i], -LOG2E, bavn)), ei = 1.0f + __builtin_amdgcn_exp2f(__builtin_fmaf(acc[ai][1][m][n][i], -LOG2E, bxvn));
;                         const float rr = __builtin_amdgcn_rcpf(er * ei), rgt = rr * ei, igt = rr * er;
;                         const float l2 = c8l * rgt;
;                         const float a1 = __builtin_amdgcn_exp2f(__uint_as_float(pk2(l2, 0.f) << 16));
;                         const float mult = __builtin_amdgcn_sqrtf(fmaxf(__builtin_fmaf(-a1, a1, 1.0f), 0.0f));
;                         w[i] = pk2(l2, mult * igt * __uint_as_float((unsigned)xw[n][ai][m][i] << 16));
;                         av[i] = a1; uv[i] = __uint_as_float(w[i] & 0xffff0000u);
;                     }
;                     *(u32x4*)(lb + ((size_t)ch * MT + tl + (unsigned)(ai * HALF + m * 16)) * 4u) = (u32x4){w[0], w[1], w[2], w[3]};
;                     float P = 1.f, H = 0.f;
;                     if (d == 0) {
; #pragma unroll
;                         for (int i = 0; i < 4; ++i) { H = av[i] * H + uv[i]; P *= av[i]; }
;                     } else {
; #pragma unroll
;                         for (int i = 3; i >= 0; --i) { H = av[i] * H + uv[i]; P *= av[i]; }
;                     }
; #pragma unroll
;                     for (int sft = 16; sft < 64; sft <<= 1) {
;                         const float Pq = __shfl_xor(P, sft), Hq = __shfl_xor(H, sft);
;                         const bool lowhalf = ((lane_hi * 16) & sft) == 0;
;                         const bool mine_first = (d == 0) ? lowhalf : !lowhalf;
;                         const float Px = mine_first ? P : Pq, Hx = mine_first ? H : Hq, Py = mine_first ? Pq : P, Hy = mine_first ? Hq : H;
;                         P = Px * Py; H = Py * Hx + Hy;
.LBB0_795:
	s_nop 0
	v_xor_b32_e32 v122, 16, v230
	v_cmp_lt_i32_e32 vcc, v122, v232
	s_xor_b64 s[46:47], s[40:41], s[50:51]
	v_fmamk_f32 v118, v118, 0xbfb8aa3b, v206
	v_cndmask_b32_e32 v122, v230, v122, vcc
	v_lshlrev_b32_e32 v127, 2, v122
	ds_bpermute_b32 v122, v127, v124
	ds_bpermute_b32 v140, v127, v123
	v_fmamk_f32 v114, v114, 0xbfb8aa3b, v207
	v_fmamk_f32 v119, v119, 0xbfb8aa3b, v206
	v_fmamk_f32 v115, v115, 0xbfb8aa3b, v207
	s_waitcnt lgkmcnt(1)
	v_cndmask_b32_e64 v125, v122, v124, s[46:47]
	s_waitcnt lgkmcnt(0)
	v_cndmask_b32_e64 v141, v123, v140, s[46:47]
	v_cndmask_b32_e64 v147, v124, v122, s[46:47]
	v_fmac_f32_e32 v147, v141, v125
	v_exp_f32_e32 v124, v118
	v_exp_f32_e32 v125, v114
	v_xor_b32_e32 v122, 32, v230
	v_cmp_lt_i32_e32 vcc, v122, v232
	v_exp_f32_e32 v141, v115
	v_pk_add_f32 v[124:125], v[124:125], 1.0 op_sel_hi:[1,0]
	v_cndmask_b32_e32 v114, v230, v122, vcc
	v_lshlrev_b32_e32 v146, 2, v114
	v_mul_f32_e32 v114, v124, v125
	v_rcp_f32_e32 v144, v114
	v_mul_f32_e32 v114, v123, v140
	v_exp_f32_e32 v140, v119
	v_fmamk_f32 v120, v120, 0xbfb8aa3b, v206
	v_mul_f32_e32 v122, v125, v144
	v_mul_f32_e32 v125, v126, v122
	v_cvt_pk_bf16_f32 v122, v125, 0
	v_lshlrev_b32_e32 v122, 16, v122
	v_exp_f32_e32 v122, v122
	v_pk_add_f32 v[142:143], v[140:141], 1.0 op_sel_hi:[1,0]
	v_mul_f32_e32 v123, v124, v144
	v_mul_f32_e32 v119, v142, v143
	v_fma_f32 v115, -v122, v122, 1.0
	v_max_f32_e32 v115, 0, v115
	v_sqrt_f32_e32 v115, v115
	v_rcp_f32_e32 v119, v119
	v_fmamk_f32 v116, v116, 0xbfb8aa3b, v207
	v_lshlrev_b32_e32 v124, 16, v223
	v_mul_f32_e32 v115, v123, v115
	v_mul_f32_e32 v123, v143, v119
	v_mul_f32_e32 v141, v126, v123
	v_cvt_pk_bf16_f32 v123, v141, 0
	v_lshlrev_b32_e32 v123, 16, v123
	v_exp_f32_e32 v123, v123
	v_exp_f32_e32 v144, v120
	v_exp_f32_e32 v145, v116
	v_mul_f32_e32 v115, v115, v124
	v_cvt_pk_bf16_f32 v140, v125, v115
	v_fma_f32 v115, -v123, v123, 1.0
	v_max_f32_e32 v115, 0, v115
	v_sqrt_f32_e32 v115, v115
	v_mul_f32_e32 v116, v142, v119
	v_pk_add_f32 v[142:143], v[144:145], 1.0 op_sel_hi:[1,0]
	v_fmamk_f32 v120, v121, 0xbfb8aa3b, v206
	v_mul_f32_e32 v119, v142, v143
	v_rcp_f32_e32 v119, v119
	v_mul_f32_e32 v115, v116, v115
	v_lshlrev_b32_e32 v116, 16, v222
	v_mul_f32_e32 v115, v115, v116
	v_fmamk_f32 v117, v117, 0xbfb8aa3b, v207
	v_cvt_pk_bf16_f32 v141, v141, v115
	v_mul_f32_e32 v115, v143, v119
	v_mul_f32_e32 v119, v142, v119
	v_exp_f32_e32 v142, v120
	v_exp_f32_e32 v143, v117
	v_mul_f32_e32 v115, v126, v115
	v_cvt_pk_bf16_f32 v117, v115, 0
	v_lshlrev_b32_e32 v117, 16, v117
	v_exp_f32_e32 v121, v117
	v_pk_add_f32 v[144:145], v[142:143], 1.0 op_sel_hi:[1,0]
	ds_bpermute_b32 v148, v146, v147
	v_mul_f32_e32 v117, v144, v145
	v_rcp_f32_e32 v117, v117
	v_fma_f32 v120, -v121, v121, 1.0
	v_max_f32_e32 v120, 0, v120
	v_sqrt_f32_e32 v125, v120
	v_mul_f32_e32 v120, v145, v117
	v_mul_f32_e32 v143, v126, v120
	v_cvt_pk_bf16_f32 v120, v143, 0
	v_lshlrev_b32_e32 v120, 16, v120
	v_exp_f32_e32 v120, v120
	v_mul_f32_e32 v119, v119, v125
	v_lshlrev_b32_e32 v125, 16, v221
	v_mul_f32_e32 v119, v119, v125
	v_fma_f32 v125, -v120, v120, 1.0
	v_max_f32_e32 v125, 0, v125
	v_sqrt_f32_e32 v125, v125
	ds_bpermute_b32 v118, v146, v114
	v_mul_f32_e32 v117, v144, v117
	v_cvt_pk_bf16_f32 v142, v115, v119
	v_mul_f32_e32 v117, v117, v125
	v_lshlrev_b32_e32 v119, 16, v220
	v_mul_f32_e32 v117, v117, v119
	v_cvt_pk_bf16_f32 v143, v143, v117
	v_cndmask_b32_e64 v117, 0, 1, s[30:31]
	v_and_b32_e32 v124, 0xffff0000, v140
	v_and_b32_e32 v116, 0xffff0000, v141
	v_and_b32_e32 v115, 0xffff0000, v142
	v_and_b32_e32 v144, 0xffff0000, v143
	v_cmp_ne_u32_e64 s[48:49], 1, v117
	s_andn2_b64 vcc, exec, s[30:31]
	s_mov_b64 s[30:31], -1
	global_store_dwordx4 v[128:129], v[140:143], off offset:64 nt
	s_cbranch_vccnz .LBB0_797
	v_fma_f32 v117, 0, v122, v124
	v_fma_f32 v117, v123, v117, v116
	v_mul_f32_e32 v141, v122, v123
	v_fma_f32 v140, v121, v117, v115
	v_pk_mul_f32 v[142:143], v[120:121], v[140:141]
	v_mov_b32_e32 v145, v120
	v_pk_fma_f32 v[140:141], v[120:121], v[140:141], v[144:145]
	v_pk_mul_f32 v[142:143], v[142:143], v[144:145]
	s_mov_b64 s[30:31], 0

;     template <int QVV> __device__ __forceinline__ void run(f32x4 (&acc)[2][2][4][2], const Unit& u, int wr, int wc, int fr, int fq) const {
;     ...
;                     for (int i = 0; i < 4; ++i) {
;                         const float er = 1.0f + __builtin_amdgcn_exp2f(__builtin_fmaf(acc[ai][0][m][n][i], -LOG2E, bavn)), ei = 1.0f + __builtin_amdgcn_exp2f(__builtin_fmaf(acc[ai][1][m][n][i], -LOG2E, bxvn));
;                         const float rr = __builtin_amdgcn_rcpf(er * ei), rgt = rr * ei, igt = rr * er;
;                         const float l2 = c8l * rgt;
;                         const float a1 = __builtin_amdgcn_exp2f(__uint_as_float(pk2(l2, 0.f) << 16));
;                         const float mult = __builtin_amdgcn_sqrtf(fmaxf(__builtin_fmaf(-a1, a1, 1.0f), 0.0f));
;                         w[i] = pk2(l2, mult * igt * __uint_as_float((unsigned)xw[n][ai][m][i] << 16));
;                         av[i] = a1; uv[i] = __uint_as_float(w[i] & 0xffff0000u);
;                     }
;                     *(u32x4*)(lb + ((size_t)ch * MT + tl + (unsigned)(ai * HALF + m * 16)) * 4u) = (u32x4){w[0], w[1], w[2], w[3]};
;                     float P = 1.f, H = 0.f;
;                     if (d == 0) {
; #pragma unroll
;                         for (int i = 0; i < 4; ++i) { H = av[i] * H + uv[i]; P *= av[i]; }
;                     } else {
; #pragma unroll
;                         for (int i = 3; i >= 0; --i) { H = av[i] * H + uv[i]; P *= av[i]; }
;                     }
; #pragma unroll
;                     for (int sft = 16; sft < 64; sft <<= 1) {
;                         const float Pq = __shfl_xor(P, sft), Hq = __shfl_xor(H, sft);
;                         const bool lowhalf = ((lane_hi * 16) & sft) == 0;
;                         const bool mine_first = (d == 0) ? lowhalf : !lowhalf;
;                         const float Px = mine_first ? P : Pq, Hx = mine_first ? H : Hq, Py = mine_first ? Pq : P, Hy = mine_first ? Hq : H;
;                         P = Px * Py; H = Py * Hx + Hy;
.LBB0_799:
	v_fmamk_f32 v110, v110, 0xbfb8aa3b, v206
	v_fmamk_f32 v106, v106, 0xbfb8aa3b, v207
	ds_bpermute_b32 v115, v127, v140
	ds_bpermute_b32 v120, v127, v143
	v_exp_f32_e32 v116, v110
	v_exp_f32_e32 v117, v106
	v_fmamk_f32 v107, v107, 0xbfb8aa3b, v207
	s_waitcnt lgkmcnt(1)
	v_cndmask_b32_e64 v110, v115, v140, s[46:47]
	s_waitcnt lgkmcnt(0)
	v_cndmask_b32_e64 v106, v143, v120, s[46:47]
	v_pk_add_f32 v[116:117], v[116:117], 1.0 op_sel_hi:[1,0]
	v_cndmask_b32_e64 v119, v140, v115, s[46:47]
	v_mul_f32_e32 v115, v143, v120
	v_mul_f32_e32 v120, v116, v117
	v_rcp_f32_e32 v122, v120
	v_fmac_f32_e32 v119, v106, v110
	v_fmamk_f32 v110, v111, 0xbfb8aa3b, v206
	v_exp_f32_e32 v110, v110
	v_mul_f32_e32 v106, v117, v122
	v_mul_f32_e32 v117, v126, v106
	v_cvt_pk_bf16_f32 v106, v117, 0
	v_lshlrev_b32_e32 v106, 16, v106
	v_exp_f32_e32 v106, v106
	v_exp_f32_e32 v111, v107
	v_fmamk_f32 v112, v112, 0xbfb8aa3b, v206
	v_fmamk_f32 v108, v108, 0xbfb8aa3b, v207
	v_fma_f32 v107, -v106, v106, 1.0
	v_pk_add_f32 v[120:121], v[110:111], 1.0 op_sel_hi:[1,0]
	v_max_f32_e32 v107, 0, v107
	v_mul_f32_e32 v110, v120, v121
	v_sqrt_f32_e32 v107, v107
	v_rcp_f32_e32 v111, v110
	v_mul_f32_e32 v110, v116, v122
	v_lshlrev_b32_e32 v116, 16, v219
	v_mul_f32_e32 v110, v110, v107
	v_mul_f32_e32 v107, v121, v111
	v_mul_f32_e32 v121, v126, v107
	v_cvt_pk_bf16_f32 v107, v121, 0
	v_lshlrev_b32_e32 v107, 16, v107
	v_exp_f32_e32 v107, v107
	v_mul_f32_e32 v110, v110, v116
	v_cvt_pk_bf16_f32 v140, v117, v110
	v_exp_f32_e32 v117, v108
	v_fma_f32 v116, -v107, v107, 1.0
	v_max_f32_e32 v116, 0, v116
	v_sqrt_f32_e32 v122, v116
	v_exp_f32_e32 v116, v112
	v_mul_f32_e32 v108, v120, v111
	v_lshlrev_b32_e32 v111, 16, v218
	v_mul_f32_e32 v108, v108, v122
	v_pk_add_f32 v[116:117], v[116:117], 1.0 op_sel_hi:[1,0]
	v_mul_f32_e32 v108, v108, v111
	v_mul_f32_e32 v112, v116, v117
	v_rcp_f32_e32 v112, v112
	v_fmamk_f32 v109, v109, 0xbfb8aa3b, v207
	v_cvt_pk_bf16_f32 v141, v121, v108
	ds_bpermute_b32 v124, v146, v115
	v_mul_f32_e32 v111, v117, v112
	v_mul_f32_e32 v120, v116, v112
	v_fmamk_f32 v112, v113, 0xbfb8aa3b, v206
	v_exp_f32_e32 v116, v112
	v_exp_f32_e32 v117, v109
	v_mul_f32_e32 v111, v126, v111
	v_cvt_pk_bf16_f32 v109, v111, 0
	v_lshlrev_b32_e32 v109, 16, v109
	v_exp_f32_e32 v113, v109
	v_pk_add_f32 v[116:117], v[116:117], 1.0 op_sel_hi:[1,0]
	ds_bpermute_b32 v125, v146, v119
	v_mul_f32_e32 v109, v116, v117
	v_rcp_f32_e32 v109, v109
	v_fma_f32 v112, -v113, v113, 1.0
	v_max_f32_e32 v112, 0, v112
	v_sqrt_f32_e32 v121, v112
	v_mul_f32_e32 v112, v117, v109
	v_mul_f32_e32 v117, v126, v112
	v_cvt_pk_bf16_f32 v112, v117, 0
	v_lshlrev_b32_e32 v112, 16, v112
	v_exp_f32_e32 v112, v112
	v_mul_f32_e32 v120, v120, v121
	v_lshlrev_b32_e32 v121, 16, v217
	v_mul_f32_e32 v120, v120, v121
	v_fma_f32 v121, -v112, v112, 1.0
	v_max_f32_e32 v121, 0, v121
	v_sqrt_f32_e32 v121, v121
	v_mul_f32_e32 v109, v116, v109
	v_lshlrev_b32_e32 v116, 16, v216
	v_cvt_pk_bf16_f32 v142, v111, v120
	v_mul_f32_e32 v109, v109, v121
	v_mul_f32_e32 v109, v109, v116
	v_cvt_pk_bf16_f32 v143, v117, v109
	v_and_b32_e32 v110, 0xffff0000, v140
	v_and_b32_e32 v108, 0xffff0000, v141
	v_and_b32_e32 v111, 0xffff0000, v142
	v_and_b32_e32 v122, 0xffff0000, v143
	s_and_b64 vcc, exec, s[48:49]
	s_mov_b64 s[30:31], -1
	global_store_dwordx4 v[128:129], v[140:143], off offset:128 nt
	s_cbranch_vccnz .LBB0_801
	v_fma_f32 v109, 0, v106, v110
	v_fma_f32 v109, v107, v109, v108
	v_mul_f32_e32 v117, v106, v107
	v_fma_f32 v116, v113, v109, v111
	v_pk_mul_f32 v[120:121], v[112:113], v[116:117]
	v_mov_b32_e32 v123, v112
	v_pk_fma_f32 v[116:117], v[112:113], v[116:117], v[122:123]
	v_pk_mul_f32 v[120:121], v[120:121], v[122:123]
	s_mov_b64 s[30:31], 0

;     template <int QVV> __device__ __forceinline__ void run(f32x4 (&acc)[2][2][4][2], const Unit& u, int wr, int wc, int fr, int fq) const {
;     ...
;                     for (int i = 0; i < 4; ++i) {
;                         const float er = 1.0f + __builtin_amdgcn_exp2f(__builtin_fmaf(acc[ai][0][m][n][i], -LOG2E, bavn)), ei = 1.0f + __builtin_amdgcn_exp2f(__builtin_fmaf(acc[ai][1][m][n][i], -LOG2E, bxvn));
;                         const float rr = __builtin_amdgcn_rcpf(er * ei), rgt = rr * ei, igt = rr * er;
;                         const float l2 = c8l * rgt;
;                         const float a1 = __builtin_amdgcn_exp2f(__uint_as_float(pk2(l2, 0.f) << 16));
;                         const float mult = __builtin_amdgcn_sqrtf(fmaxf(__builtin_fmaf(-a1, a1, 1.0f), 0.0f));
;                         w[i] = pk2(l2, mult * igt * __uint_as_float((unsigned)xw[n][ai][m][i] << 16));
;                         av[i] = a1; uv[i] = __uint_as_float(w[i] & 0xffff0000u);
;                     }
;                     *(u32x4*)(lb + ((size_t)ch * MT + tl + (unsigned)(ai * HALF + m * 16)) * 4u) = (u32x4){w[0], w[1], w[2], w[3]};
;                     float P = 1.f, H = 0.f;
;                     if (d == 0) {
; #pragma unroll
;                         for (int i = 0; i < 4; ++i) { H = av[i] * H + uv[i]; P *= av[i]; }
;                     } else {
; #pragma unroll
;                         for (int i = 3; i >= 0; --i) { H = av[i] * H + uv[i]; P *= av[i]; }
;                     }
; #pragma unroll
;                     for (int sft = 16; sft < 64; sft <<= 1) {
;                         const float Pq = __shfl_xor(P, sft), Hq = __shfl_xor(H, sft);
;                         const bool lowhalf = ((lane_hi * 16) & sft) == 0;
;                         const bool mine_first = (d == 0) ? lowhalf : !lowhalf;
;                         const float Px = mine_first ? P : Pq, Hx = mine_first ? H : Hq, Py = mine_first ? Pq : P, Hy = mine_first ? Hq : H;
;                         P = Px * Py; H = Py * Hx + Hy;
.LBB0_803:
	v_fmamk_f32 v102, v102, 0xbfb8aa3b, v206
	v_fmamk_f32 v98, v98, 0xbfb8aa3b, v207
	ds_bpermute_b32 v108, v127, v116
	v_exp_f32_e32 v106, v102
	v_exp_f32_e32 v107, v98
	ds_bpermute_b32 v109, v127, v121
	v_fmamk_f32 v99, v99, 0xbfb8aa3b, v207
	s_waitcnt lgkmcnt(1)
	v_cndmask_b32_e64 v102, v108, v116, s[46:47]
	v_pk_add_f32 v[106:107], v[106:107], 1.0 op_sel_hi:[1,0]
	v_cndmask_b32_e64 v113, v116, v108, s[46:47]
	v_mul_f32_e32 v108, v106, v107
	v_rcp_f32_e32 v108, v108
	s_waitcnt lgkmcnt(0)
	v_cndmask_b32_e64 v98, v121, v109, s[46:47]
	v_fmac_f32_e32 v113, v98, v102
	v_fmamk_f32 v102, v103, 0xbfb8aa3b, v206
	v_mul_f32_e32 v98, v107, v108
	v_mul_f32_e32 v107, v126, v98
	v_cvt_pk_bf16_f32 v98, v107, 0
	v_lshlrev_b32_e32 v98, 16, v98
	v_exp_f32_e32 v98, v98
	v_exp_f32_e32 v102, v102
	v_exp_f32_e32 v103, v99
	v_mul_f32_e32 v112, v121, v109
	v_fma_f32 v99, -v98, v98, 1.0
	v_max_f32_e32 v99, 0, v99
	v_pk_add_f32 v[110:111], v[102:103], 1.0 op_sel_hi:[1,0]
	v_sqrt_f32_e32 v99, v99
	v_mul_f32_e32 v102, v110, v111
	v_rcp_f32_e32 v103, v102
	v_mul_f32_e32 v102, v106, v108
	v_mul_f32_e32 v102, v102, v99
	v_lshlrev_b32_e32 v106, 16, v215
	v_mul_f32_e32 v99, v111, v103
	v_mul_f32_e32 v109, v126, v99
	v_cvt_pk_bf16_f32 v99, v109, 0
	v_lshlrev_b32_e32 v99, 16, v99
	v_exp_f32_e32 v99, v99
	v_mul_f32_e32 v102, v102, v106
	v_fmamk_f32 v104, v104, 0xbfb8aa3b, v206
	v_fmamk_f32 v100, v100, 0xbfb8aa3b, v207
	v_fma_f32 v106, -v99, v99, 1.0
	v_max_f32_e32 v106, 0, v106
	v_cvt_pk_bf16_f32 v108, v107, v102
	v_sqrt_f32_e32 v111, v106
	v_exp_f32_e32 v106, v104
	v_exp_f32_e32 v107, v100
	v_mul_f32_e32 v100, v110, v103
	v_mul_f32_e32 v100, v100, v111
	v_lshlrev_b32_e32 v103, 16, v214
	v_pk_add_f32 v[106:107], v[106:107], 1.0 op_sel_hi:[1,0]
	v_mul_f32_e32 v100, v100, v103
	v_mul_f32_e32 v104, v106, v107
	v_rcp_f32_e32 v104, v104
	v_fmamk_f32 v101, v101, 0xbfb8aa3b, v207
	ds_bpermute_b32 v116, v146, v112
	ds_bpermute_b32 v117, v146, v113
	v_mul_f32_e32 v103, v107, v104
	v_mul_f32_e32 v110, v106, v104
	v_fmamk_f32 v104, v105, 0xbfb8aa3b, v206
	v_exp_f32_e32 v106, v104
	v_exp_f32_e32 v107, v101
	v_mul_f32_e32 v103, v126, v103
	v_cvt_pk_bf16_f32 v101, v103, 0
	v_lshlrev_b32_e32 v101, 16, v101
	v_exp_f32_e32 v105, v101
	v_pk_add_f32 v[106:107], v[106:107], 1.0 op_sel_hi:[1,0]
	v_cvt_pk_bf16_f32 v109, v109, v100
	v_mul_f32_e32 v101, v106, v107
	v_rcp_f32_e32 v101, v101
	v_fma_f32 v104, -v105, v105, 1.0
	v_max_f32_e32 v104, 0, v104
	v_sqrt_f32_e32 v111, v104
	v_mul_f32_e32 v104, v107, v101
	v_mul_f32_e32 v107, v126, v104
	v_cvt_pk_bf16_f32 v104, v107, 0
	v_lshlrev_b32_e32 v104, 16, v104
	v_exp_f32_e32 v104, v104
	v_mul_f32_e32 v110, v110, v111
	v_lshlrev_b32_e32 v111, 16, v212
	v_mul_f32_e32 v110, v110, v111
	v_fma_f32 v111, -v104, v104, 1.0
	v_max_f32_e32 v111, 0, v111
	v_sqrt_f32_e32 v111, v111
	v_mul_f32_e32 v101, v106, v101
	v_lshlrev_b32_e32 v106, 16, v213
	v_cvt_pk_bf16_f32 v110, v103, v110
	v_mul_f32_e32 v101, v101, v111
	v_mul_f32_e32 v101, v101, v106
	v_cvt_pk_bf16_f32 v111, v107, v101
	v_and_b32_e32 v102, 0xffff0000, v108
	v_and_b32_e32 v100, 0xffff0000, v109
	v_and_b32_e32 v103, 0xffff0000, v110
	v_and_b32_e32 v106, 0xffff0000, v111
	s_and_b64 vcc, exec, s[48:49]
	s_mov_b64 s[30:31], -1
	global_store_dwordx4 v[128:129], v[108:111], off offset:192 nt
	s_cbranch_vccnz .LBB0_805
	v_fma_f32 v101, 0, v98, v102
	v_fma_f32 v101, v99, v101, v100
	v_mul_f32_e32 v109, v98, v99
	v_fma_f32 v108, v105, v101, v103
	v_pk_mul_f32 v[120:121], v[104:105], v[108:109]
	v_mov_b32_e32 v107, v104
	v_pk_fma_f32 v[110:111], v[104:105], v[108:109], v[106:107]
	v_pk_mul_f32 v[108:109], v[120:121], v[106:107]
	s_mov_b64 s[30:31], 0

;     template <int QVV> __device__ __forceinline__ void run(f32x4 (&acc)[2][2][4][2], const Unit& u, int wr, int wc, int fr, int fq) const {
;     ...
;                 for (int m = 0; m < 4; ++m) {
;                     unsigned w[4]; float av[4], uv[4];
; #pragma unroll
;                     for (int i = 0; i < 4; ++i) {
;                         const float er = 1.0f + __builtin_amdgcn_exp2f(__builtin_fmaf(acc[ai][0][m][n][i], -LOG2E, bavn)), ei = 1.0f + __builtin_amdgcn_exp2f(__builtin_fmaf(acc[ai][1][m][n][i], -LOG2E, bxvn));
;                         const float rr = __builtin_amdgcn_rcpf(er * ei), rgt = rr * ei, igt = rr * er;
;                         const float l2 = c8l * rgt;
;                         const float a1 = __builtin_amdgcn_exp2f(__uint_as_float(pk2(l2, 0.f) << 16));
;                         const float mult = __builtin_amdgcn_sqrtf(fmaxf(__builtin_fmaf(-a1, a1, 1.0f), 0.0f));
;                         w[i] = pk2(l2, mult * igt * __uint_as_float((unsigned)xw[n][ai][m][i] << 16));
;                         av[i] = a1; uv[i] = __uint_as_float(w[i] & 0xffff0000u);
;                     }
;                     *(u32x4*)(lb + ((size_t)ch * MT + tl + (unsigned)(ai * HALF + m * 16)) * 4u) = (u32x4){w[0], w[1], w[2], w[3]};
;                     float P = 1.f, H = 0.f;
;                     if (d == 0) {
; #pragma unroll
;                         for (int i = 0; i < 4; ++i) { H = av[i] * H + uv[i]; P *= av[i]; }
.LBB0_813:
	s_or_b64 exec, exec, s[52:53]
	v_fmamk_f32 v94, v94, 0xbfb8aa3b, v206
	v_fmamk_f32 v90, v90, 0xbfb8aa3b, v207
	v_exp_f32_e32 v98, v94
	v_exp_f32_e32 v99, v90
	v_fmamk_f32 v90, v95, 0xbfb8aa3b, v206
	v_fmamk_f32 v91, v91, 0xbfb8aa3b, v207
	v_fmamk_f32 v96, v96, 0xbfb8aa3b, v206
	v_pk_add_f32 v[94:95], v[98:99], 1.0 op_sel_hi:[1,0]
	v_exp_f32_e32 v99, v91
	v_mul_f32_e32 v98, v94, v95
	v_rcp_f32_e32 v102, v98
	v_exp_f32_e32 v98, v90
	v_fmamk_f32 v92, v92, 0xbfb8aa3b, v207
	v_exp_f32_e32 v103, v92
	v_mul_f32_e32 v90, v95, v102
	v_mul_f32_e32 v95, v126, v90
	v_cvt_pk_bf16_f32 v90, v95, 0
	v_lshlrev_b32_e32 v90, 16, v90
	v_exp_f32_e32 v90, v90
	v_pk_add_f32 v[100:101], v[98:99], 1.0 op_sel_hi:[1,0]
	v_mul_f32_e32 v94, v94, v102
	v_mul_f32_e32 v91, v100, v101
	v_rcp_f32_e32 v99, v91
	v_fma_f32 v91, -v90, v90, 1.0
	v_max_f32_e32 v91, 0, v91
	v_sqrt_f32_e32 v91, v91
	v_mul_f32_e32 v101, v101, v99
	v_mul_f32_e32 v104, v126, v101
	v_lshlrev_b32_e32 v98, 16, v211
	v_mul_f32_e32 v94, v94, v91
	v_cvt_pk_bf16_f32 v91, v104, 0
	v_lshlrev_b32_e32 v91, 16, v91
	v_exp_f32_e32 v91, v91
	v_exp_f32_e32 v102, v96
	v_mul_f32_e32 v94, v94, v98
	v_cvt_pk_bf16_f32 v98, v95, v94
	v_fma_f32 v95, -v91, v91, 1.0
	v_max_f32_e32 v95, 0, v95
	v_sqrt_f32_e32 v95, v95
	v_mul_f32_e32 v92, v100, v99
	v_pk_add_f32 v[100:101], v[102:103], 1.0 op_sel_hi:[1,0]
	v_fmamk_f32 v93, v93, 0xbfb8aa3b, v207
	v_mul_f32_e32 v96, v100, v101
	v_rcp_f32_e32 v96, v96
	v_mul_f32_e32 v92, v92, v95
	v_lshlrev_b32_e32 v95, 16, v210
	v_mul_f32_e32 v92, v92, v95
	v_cvt_pk_bf16_f32 v99, v104, v92
	v_mul_f32_e32 v95, v101, v96
	v_mul_f32_e32 v104, v100, v96
	v_fmamk_f32 v96, v97, 0xbfb8aa3b, v206
	v_exp_f32_e32 v100, v96
	v_exp_f32_e32 v101, v93
	v_mul_f32_e32 v95, v126, v95
	v_cvt_pk_bf16_f32 v93, v95, 0
	v_lshlrev_b32_e32 v93, 16, v93
	v_exp_f32_e32 v97, v93
	v_pk_add_f32 v[102:103], v[100:101], 1.0 op_sel_hi:[1,0]
	v_and_b32_e32 v94, 0xffff0000, v98
	v_mul_f32_e32 v93, v102, v103
	v_rcp_f32_e32 v93, v93
	v_fma_f32 v96, -v97, v97, 1.0
	v_max_f32_e32 v96, 0, v96
	v_sqrt_f32_e32 v100, v96
	v_mul_f32_e32 v96, v103, v93
	v_mul_f32_e32 v101, v126, v96
	v_cvt_pk_bf16_f32 v96, v101, 0
	v_lshlrev_b32_e32 v96, 16, v96
	v_exp_f32_e32 v96, v96
	v_mul_f32_e32 v100, v104, v100
	v_lshlrev_b32_e32 v103, 16, v209
	v_mul_f32_e32 v100, v100, v103
	v_fma_f32 v103, -v96, v96, 1.0
	v_max_f32_e32 v103, 0, v103
	v_sqrt_f32_e32 v103, v103
	v_mul_f32_e32 v93, v102, v93
	v_lshlrev_b32_e32 v102, 16, v208
	v_cvt_pk_bf16_f32 v100, v95, v100
	v_mul_f32_e32 v93, v93, v103
	v_mul_f32_e32 v93, v93, v102
	v_cvt_pk_bf16_f32 v101, v101, v93
	v_and_b32_e32 v92, 0xffff0000, v99
	v_and_b32_e32 v95, 0xffff0000, v100
	v_and_b32_e32 v102, 0xffff0000, v101
	s_and_b64 vcc, exec, s[48:49]
	s_mov_b64 s[52:53], -1
	global_store_dwordx4 v[128:129], v[98:101], off offset:512 nt
	s_cbranch_vccnz .LBB0_815
	v_fma_f32 v93, 0, v90, v94
	v_fma_f32 v93, v91, v93, v92
	v_mul_f32_e32 v99, v90, v91
	v_fma_f32 v98, v97, v93, v95
	v_pk_mul_f32 v[104:105], v[96:97], v[98:99]
	v_mov_b32_e32 v103, v96
	v_pk_fma_f32 v[100:101], v[96:97], v[98:99], v[102:103]
	v_pk_mul_f32 v[98:99], v[104:105], v[102:103]
	s_mov_b64 s[52:53], 0

;     template <int QVV> __device__ __forceinline__ void run(f32x4 (&acc)[2][2][4][2], const Unit& u, int wr, int wc, int fr, int fq) const {
;     ...
;                     for (int i = 0; i < 4; ++i) {
;                         const float er = 1.0f + __builtin_amdgcn_exp2f(__builtin_fmaf(acc[ai][0][m][n][i], -LOG2E, bavn)), ei = 1.0f + __builtin_amdgcn_exp2f(__builtin_fmaf(acc[ai][1][m][n][i], -LOG2E, bxvn));
;                         const float rr = __builtin_amdgcn_rcpf(er * ei), rgt = rr * ei, igt = rr * er;
;                         const float l2 = c8l * rgt;
;                         const float a1 = __builtin_amdgcn_exp2f(__uint_as_float(pk2(l2, 0.f) << 16));
;                         const float mult = __builtin_amdgcn_sqrtf(fmaxf(__builtin_fmaf(-a1, a1, 1.0f), 0.0f));
;                         w[i] = pk2(l2, mult * igt * __uint_as_float((unsigned)xw[n][ai][m][i] << 16));
;                         av[i] = a1; uv[i] = __uint_as_float(w[i] & 0xffff0000u);
;                     }
;                     *(u32x4*)(lb + ((size_t)ch * MT + tl + (unsigned)(ai * HALF + m * 16)) * 4u) = (u32x4){w[0], w[1], w[2], w[3]};
;                     float P = 1.f, H = 0.f;
;                     if (d == 0) {
; #pragma unroll
;                         for (int i = 0; i < 4; ++i) { H = av[i] * H + uv[i]; P *= av[i]; }
;                     } else {
; #pragma unroll
;                         for (int i = 3; i >= 0; --i) { H = av[i] * H + uv[i]; P *= av[i]; }
;                     }
; #pragma unroll
;                     for (int sft = 16; sft < 64; sft <<= 1) {
;                         const float Pq = __shfl_xor(P, sft), Hq = __shfl_xor(H, sft);
;                         const bool lowhalf = ((lane_hi * 16) & sft) == 0;
;                         const bool mine_first = (d == 0) ? lowhalf : !lowhalf;
;                         const float Px = mine_first ? P : Pq, Hx = mine_first ? H : Hq, Py = mine_first ? Pq : P, Hy = mine_first ? Hq : H;
;                         P = Px * Py; H = Py * Hx + Hy;
.LBB0_817:
	ds_bpermute_b32 v92, v127, v100
	ds_bpermute_b32 v94, v127, v99
	v_fmamk_f32 v86, v86, 0xbfb8aa3b, v206
	v_fmamk_f32 v82, v82, 0xbfb8aa3b, v207
	v_exp_f32_e32 v90, v86
	v_exp_f32_e32 v91, v82
	s_waitcnt lgkmcnt(1)
	v_cndmask_b32_e64 v86, v92, v100, s[46:47]
	s_waitcnt lgkmcnt(0)
	v_cndmask_b32_e64 v82, v99, v94, s[46:47]
	v_cndmask_b32_e64 v100, v100, v92, s[46:47]
	v_pk_add_f32 v[92:93], v[90:91], 1.0 op_sel_hi:[1,0]
	v_fmac_f32_e32 v100, v82, v86
	v_mul_f32_e32 v82, v92, v93
	v_rcp_f32_e32 v91, v82
	v_fmamk_f32 v87, v87, 0xbfb8aa3b, v206
	v_fmamk_f32 v83, v83, 0xbfb8aa3b, v207
	v_mul_f32_e32 v82, v99, v94
	v_mul_f32_e32 v90, v93, v91
	v_mul_f32_e32 v93, v126, v90
	v_cvt_pk_bf16_f32 v90, v93, 0
	v_lshlrev_b32_e32 v90, 16, v90
	v_exp_f32_e32 v90, v90
	v_exp_f32_e32 v94, v87
	v_exp_f32_e32 v95, v83
	v_mul_f32_e32 v91, v92, v91
	v_fma_f32 v83, -v90, v90, 1.0
	v_max_f32_e32 v83, 0, v83
	v_pk_add_f32 v[96:97], v[94:95], 1.0 op_sel_hi:[1,0]
	v_sqrt_f32_e32 v83, v83
	v_mul_f32_e32 v87, v96, v97
	v_rcp_f32_e32 v87, v87
	v_fmamk_f32 v88, v88, 0xbfb8aa3b, v206
	v_mul_f32_e32 v83, v91, v83
	v_fmamk_f32 v84, v84, 0xbfb8aa3b, v207
	v_mul_f32_e32 v91, v97, v87
	v_mul_f32_e32 v95, v126, v91
	v_cvt_pk_bf16_f32 v91, v95, 0
	v_lshlrev_b32_e32 v91, 16, v91
	v_exp_f32_e32 v91, v91
	v_lshlrev_b32_e32 v92, 16, v205
	v_exp_f32_e32 v98, v88
	v_exp_f32_e32 v99, v84
	v_mul_f32_e32 v83, v83, v92
	v_cvt_pk_bf16_f32 v94, v93, v83
	v_fma_f32 v83, -v91, v91, 1.0
	v_max_f32_e32 v83, 0, v83
	v_sqrt_f32_e32 v83, v83
	v_mul_f32_e32 v84, v96, v87
	v_pk_add_f32 v[96:97], v[98:99], 1.0 op_sel_hi:[1,0]
	v_fmamk_f32 v88, v89, 0xbfb8aa3b, v206
	v_mul_f32_e32 v87, v96, v97
	v_rcp_f32_e32 v87, v87
	v_mul_f32_e32 v83, v84, v83
	v_lshlrev_b32_e32 v84, 16, v204
	v_mul_f32_e32 v83, v83, v84
	v_fmamk_f32 v85, v85, 0xbfb8aa3b, v207
	v_cvt_pk_bf16_f32 v95, v95, v83
	v_mul_f32_e32 v83, v97, v87
	v_mul_f32_e32 v87, v96, v87
	v_exp_f32_e32 v96, v88
	v_exp_f32_e32 v97, v85
	v_mul_f32_e32 v83, v126, v83
	v_cvt_pk_bf16_f32 v85, v83, 0
	v_lshlrev_b32_e32 v85, 16, v85
	v_exp_f32_e32 v89, v85
	v_pk_add_f32 v[98:99], v[96:97], 1.0 op_sel_hi:[1,0]
	ds_bpermute_b32 v101, v146, v100
	v_mul_f32_e32 v85, v98, v99
	v_rcp_f32_e32 v85, v85
	v_fma_f32 v88, -v89, v89, 1.0
	v_max_f32_e32 v88, 0, v88
	v_sqrt_f32_e32 v93, v88
	v_mul_f32_e32 v88, v99, v85
	v_mul_f32_e32 v97, v126, v88
	v_cvt_pk_bf16_f32 v88, v97, 0
	v_lshlrev_b32_e32 v88, 16, v88
	v_exp_f32_e32 v88, v88
	v_mul_f32_e32 v87, v87, v93
	v_lshlrev_b32_e32 v93, 16, v202
	v_mul_f32_e32 v87, v87, v93
	v_fma_f32 v93, -v88, v88, 1.0
	v_max_f32_e32 v93, 0, v93
	v_sqrt_f32_e32 v93, v93
	ds_bpermute_b32 v86, v146, v82
	v_mul_f32_e32 v85, v98, v85
	v_cvt_pk_bf16_f32 v96, v83, v87
	v_mul_f32_e32 v85, v85, v93
	v_lshlrev_b32_e32 v87, 16, v203
	v_mul_f32_e32 v85, v85, v87
	v_cvt_pk_bf16_f32 v97, v97, v85
	v_and_b32_e32 v92, 0xffff0000, v94
	v_and_b32_e32 v84, 0xffff0000, v95
	v_and_b32_e32 v83, 0xffff0000, v96
	v_and_b32_e32 v98, 0xffff0000, v97
	s_and_b64 vcc, exec, s[48:49]
	s_mov_b64 s[52:53], -1
	global_store_dwordx4 v[128:129], v[94:97], off offset:576 nt
	s_cbranch_vccnz .LBB0_819
	v_fma_f32 v85, 0, v90, v92
	v_fma_f32 v85, v91, v85, v84
	v_mul_f32_e32 v95, v90, v91
	v_fma_f32 v94, v89, v85, v83
	v_pk_mul_f32 v[96:97], v[88:89], v[94:95]
	v_mov_b32_e32 v99, v88
	v_pk_fma_f32 v[94:95], v[88:89], v[94:95], v[98:99]
	v_pk_mul_f32 v[96:97], v[96:97], v[98:99]
	s_mov_b64 s[52:53], 0

;     template <int QVV> __device__ __forceinline__ void run(f32x4 (&acc)[2][2][4][2], const Unit& u, int wr, int wc, int fr, int fq) const {
;     ...
;                     for (int i = 0; i < 4; ++i) {
;                         const float er = 1.0f + __builtin_amdgcn_exp2f(__builtin_fmaf(acc[ai][0][m][n][i], -LOG2E, bavn)), ei = 1.0f + __builtin_amdgcn_exp2f(__builtin_fmaf(acc[ai][1][m][n][i], -LOG2E, bxvn));
;                         const float rr = __builtin_amdgcn_rcpf(er * ei), rgt = rr * ei, igt = rr * er;
;                         const float l2 = c8l * rgt;
;                         const float a1 = __builtin_amdgcn_exp2f(__uint_as_float(pk2(l2, 0.f) << 16));
;                         const float mult = __builtin_amdgcn_sqrtf(fmaxf(__builtin_fmaf(-a1, a1, 1.0f), 0.0f));
;                         w[i] = pk2(l2, mult * igt * __uint_as_float((unsigned)xw[n][ai][m][i] << 16));
;                         av[i] = a1; uv[i] = __uint_as_float(w[i] & 0xffff0000u);
;                     }
;                     *(u32x4*)(lb + ((size_t)ch * MT + tl + (unsigned)(ai * HALF + m * 16)) * 4u) = (u32x4){w[0], w[1], w[2], w[3]};
;                     float P = 1.f, H = 0.f;
;                     if (d == 0) {
; #pragma unroll
;                         for (int i = 0; i < 4; ++i) { H = av[i] * H + uv[i]; P *= av[i]; }
;                     } else {
; #pragma unroll
;                         for (int i = 3; i >= 0; --i) { H = av[i] * H + uv[i]; P *= av[i]; }
;                     }
; #pragma unroll
;                     for (int sft = 16; sft < 64; sft <<= 1) {
;                         const float Pq = __shfl_xor(P, sft), Hq = __shfl_xor(H, sft);
;                         const bool lowhalf = ((lane_hi * 16) & sft) == 0;
;                         const bool mine_first = (d == 0) ? lowhalf : !lowhalf;
;                         const float Px = mine_first ? P : Pq, Hx = mine_first ? H : Hq, Py = mine_first ? Pq : P, Hy = mine_first ? Hq : H;
;                         P = Px * Py; H = Py * Hx + Hy;
.LBB0_821:
	v_fmamk_f32 v78, v78, 0xbfb8aa3b, v206
	v_fmamk_f32 v74, v74, 0xbfb8aa3b, v207
	ds_bpermute_b32 v83, v127, v94
	ds_bpermute_b32 v88, v127, v97
	v_exp_f32_e32 v84, v78
	v_exp_f32_e32 v85, v74
	v_fmamk_f32 v75, v75, 0xbfb8aa3b, v207
	s_waitcnt lgkmcnt(1)
	v_cndmask_b32_e64 v78, v83, v94, s[46:47]
	s_waitcnt lgkmcnt(0)
	v_cndmask_b32_e64 v74, v97, v88, s[46:47]
	v_pk_add_f32 v[84:85], v[84:85], 1.0 op_sel_hi:[1,0]
	v_cndmask_b32_e64 v87, v94, v83, s[46:47]
	v_mul_f32_e32 v83, v97, v88
	v_mul_f32_e32 v88, v84, v85
	v_rcp_f32_e32 v90, v88
	v_fmac_f32_e32 v87, v74, v78
	v_fmamk_f32 v78, v79, 0xbfb8aa3b, v206
	v_exp_f32_e32 v78, v78
	v_mul_f32_e32 v74, v85, v90
	v_mul_f32_e32 v85, v126, v74
	v_cvt_pk_bf16_f32 v74, v85, 0
	v_lshlrev_b32_e32 v74, 16, v74
	v_exp_f32_e32 v74, v74
	v_exp_f32_e32 v79, v75
	v_fmamk_f32 v80, v80, 0xbfb8aa3b, v206
	v_fmamk_f32 v76, v76, 0xbfb8aa3b, v207
	v_fma_f32 v75, -v74, v74, 1.0
	v_pk_add_f32 v[88:89], v[78:79], 1.0 op_sel_hi:[1,0]
	v_max_f32_e32 v75, 0, v75
	v_mul_f32_e32 v78, v88, v89
	v_sqrt_f32_e32 v75, v75
	v_rcp_f32_e32 v79, v78
	v_mul_f32_e32 v78, v84, v90
	v_lshlrev_b32_e32 v84, 16, v201
	v_mul_f32_e32 v78, v78, v75
	v_mul_f32_e32 v75, v89, v79
	v_mul_f32_e32 v89, v126, v75
	v_cvt_pk_bf16_f32 v75, v89, 0
	v_lshlrev_b32_e32 v75, 16, v75
	v_exp_f32_e32 v75, v75
	v_mul_f32_e32 v78, v78, v84
	v_cvt_pk_bf16_f32 v94, v85, v78
	v_exp_f32_e32 v85, v76
	v_fma_f32 v84, -v75, v75, 1.0
	v_max_f32_e32 v84, 0, v84
	v_sqrt_f32_e32 v90, v84
	v_exp_f32_e32 v84, v80
	v_mul_f32_e32 v76, v88, v79
	v_lshlrev_b32_e32 v79, 16, v200
	v_mul_f32_e32 v76, v76, v90
	v_pk_add_f32 v[84:85], v[84:85], 1.0 op_sel_hi:[1,0]
	v_mul_f32_e32 v76, v76, v79
	v_mul_f32_e32 v80, v84, v85
	v_rcp_f32_e32 v80, v80
	v_fmamk_f32 v77, v77, 0xbfb8aa3b, v207
	v_cvt_pk_bf16_f32 v95, v89, v76
	ds_bpermute_b32 v92, v146, v83
	v_mul_f32_e32 v79, v85, v80
	v_mul_f32_e32 v88, v84, v80
	v_fmamk_f32 v80, v81, 0xbfb8aa3b, v206
	v_exp_f32_e32 v84, v80
	v_exp_f32_e32 v85, v77
	v_mul_f32_e32 v79, v126, v79
	v_cvt_pk_bf16_f32 v77, v79, 0
	v_lshlrev_b32_e32 v77, 16, v77
	v_exp_f32_e32 v81, v77
	v_pk_add_f32 v[84:85], v[84:85], 1.0 op_sel_hi:[1,0]
	ds_bpermute_b32 v93, v146, v87
	v_mul_f32_e32 v77, v84, v85
	v_rcp_f32_e32 v77, v77
	v_fma_f32 v80, -v81, v81, 1.0
	v_max_f32_e32 v80, 0, v80
	v_sqrt_f32_e32 v89, v80
	v_mul_f32_e32 v80, v85, v77
	v_mul_f32_e32 v85, v126, v80
	v_cvt_pk_bf16_f32 v80, v85, 0
	v_lshlrev_b32_e32 v80, 16, v80
	v_exp_f32_e32 v80, v80
	v_mul_f32_e32 v88, v88, v89
	v_lshlrev_b32_e32 v89, 16, v199
	v_mul_f32_e32 v88, v88, v89
	v_fma_f32 v89, -v80, v80, 1.0
	v_max_f32_e32 v89, 0, v89
	v_sqrt_f32_e32 v89, v89
	v_mul_f32_e32 v77, v84, v77
	v_lshlrev_b32_e32 v84, 16, v198
	v_cvt_pk_bf16_f32 v96, v79, v88
	v_mul_f32_e32 v77, v77, v89
	v_mul_f32_e32 v77, v77, v84
	v_cvt_pk_bf16_f32 v97, v85, v77
	v_and_b32_e32 v78, 0xffff0000, v94
	v_and_b32_e32 v76, 0xffff0000, v95
	v_and_b32_e32 v79, 0xffff0000, v96
	v_and_b32_e32 v90, 0xffff0000, v97
	s_and_b64 vcc, exec, s[48:49]
	s_mov_b64 s[52:53], -1
	global_store_dwordx4 v[128:129], v[94:97], off offset:640 nt
	s_cbranch_vccnz .LBB0_823
	v_fma_f32 v77, 0, v74, v78
	v_fma_f32 v77, v75, v77, v76
	v_mul_f32_e32 v85, v74, v75
	v_fma_f32 v84, v81, v77, v79
	v_pk_mul_f32 v[88:89], v[80:81], v[84:85]
	v_mov_b32_e32 v91, v80
	v_pk_fma_f32 v[84:85], v[80:81], v[84:85], v[90:91]
	v_pk_mul_f32 v[88:89], v[88:89], v[90:91]
	s_mov_b64 s[52:53], 0

;     template <int QVV> __device__ __forceinline__ void run(f32x4 (&acc)[2][2][4][2], const Unit& u, int wr, int wc, int fr, int fq) const {
;     ...
;                     for (int i = 0; i < 4; ++i) {
;                         const float er = 1.0f + __builtin_amdgcn_exp2f(__builtin_fmaf(acc[ai][0][m][n][i], -LOG2E, bavn)), ei = 1.0f + __builtin_amdgcn_exp2f(__builtin_fmaf(acc[ai][1][m][n][i], -LOG2E, bxvn));
;                         const float rr = __builtin_amdgcn_rcpf(er * ei), rgt = rr * ei, igt = rr * er;
;                         const float l2 = c8l * rgt;
;                         const float a1 = __builtin_amdgcn_exp2f(__uint_as_float(pk2(l2, 0.f) << 16));
;                         const float mult = __builtin_amdgcn_sqrtf(fmaxf(__builtin_fmaf(-a1, a1, 1.0f), 0.0f));
;                         w[i] = pk2(l2, mult * igt * __uint_as_float((unsigned)xw[n][ai][m][i] << 16));
;                         av[i] = a1; uv[i] = __uint_as_float(w[i] & 0xffff0000u);
;                     }
;                     *(u32x4*)(lb + ((size_t)ch * MT + tl + (unsigned)(ai * HALF + m * 16)) * 4u) = (u32x4){w[0], w[1], w[2], w[3]};
;                     float P = 1.f, H = 0.f;
;                     if (d == 0) {
; #pragma unroll
;                         for (int i = 0; i < 4; ++i) { H = av[i] * H + uv[i]; P *= av[i]; }
;                     } else {
; #pragma unroll
;                         for (int i = 3; i >= 0; --i) { H = av[i] * H + uv[i]; P *= av[i]; }
;                     }
; #pragma unroll
;                     for (int sft = 16; sft < 64; sft <<= 1) {
;                         const float Pq = __shfl_xor(P, sft), Hq = __shfl_xor(H, sft);
;                         const bool lowhalf = ((lane_hi * 16) & sft) == 0;
;                         const bool mine_first = (d == 0) ? lowhalf : !lowhalf;
;                         const float Px = mine_first ? P : Pq, Hx = mine_first ? H : Hq, Py = mine_first ? Pq : P, Hy = mine_first ? Hq : H;
;                         P = Px * Py; H = Py * Hx + Hy;
.LBB0_825:
	v_fmamk_f32 v70, v70, 0xbfb8aa3b, v206
	v_fmamk_f32 v66, v66, 0xbfb8aa3b, v207
	ds_bpermute_b32 v76, v127, v84
	v_exp_f32_e32 v74, v70
	v_exp_f32_e32 v75, v66
	ds_bpermute_b32 v77, v127, v89
	v_fmamk_f32 v67, v67, 0xbfb8aa3b, v207
	s_waitcnt lgkmcnt(1)
	v_cndmask_b32_e64 v70, v76, v84, s[46:47]
	v_pk_add_f32 v[74:75], v[74:75], 1.0 op_sel_hi:[1,0]
	v_cndmask_b32_e64 v81, v84, v76, s[46:47]
	v_mul_f32_e32 v76, v74, v75
	v_rcp_f32_e32 v78, v76
	s_waitcnt lgkmcnt(0)
	v_cndmask_b32_e64 v66, v89, v77, s[46:47]
	v_fmac_f32_e32 v81, v66, v70
	v_fmamk_f32 v70, v71, 0xbfb8aa3b, v206
	v_mul_f32_e32 v66, v75, v78
	v_mul_f32_e32 v75, v126, v66
	v_cvt_pk_bf16_f32 v66, v75, 0
	v_lshlrev_b32_e32 v66, 16, v66
	v_exp_f32_e32 v66, v66
	v_exp_f32_e32 v70, v70
	v_exp_f32_e32 v71, v67
	v_mul_f32_e32 v80, v89, v77
	v_fma_f32 v67, -v66, v66, 1.0
	v_max_f32_e32 v67, 0, v67
	v_pk_add_f32 v[76:77], v[70:71], 1.0 op_sel_hi:[1,0]
	v_sqrt_f32_e32 v67, v67
	v_mul_f32_e32 v70, v76, v77
	v_rcp_f32_e32 v71, v70
	v_mul_f32_e32 v70, v74, v78
	v_mul_f32_e32 v70, v70, v67
	v_fmamk_f32 v72, v72, 0xbfb8aa3b, v206
	v_mul_f32_e32 v67, v77, v71
	v_mul_f32_e32 v88, v126, v67
	v_cvt_pk_bf16_f32 v67, v88, 0
	v_lshlrev_b32_e32 v67, 16, v67
	v_exp_f32_e32 v67, v67
	v_fmamk_f32 v68, v68, 0xbfb8aa3b, v207
	v_lshlrev_b32_e32 v74, 16, v197
	v_exp_f32_e32 v78, v72
	v_exp_f32_e32 v79, v68
	v_mul_f32_e32 v70, v70, v74
	v_cvt_pk_bf16_f32 v74, v75, v70
	v_fma_f32 v75, -v67, v67, 1.0
	v_max_f32_e32 v75, 0, v75
	v_sqrt_f32_e32 v75, v75
	v_mul_f32_e32 v68, v76, v71
	v_pk_add_f32 v[76:77], v[78:79], 1.0 op_sel_hi:[1,0]
	v_lshlrev_b32_e32 v71, 16, v196
	v_mul_f32_e32 v72, v76, v77
	v_rcp_f32_e32 v72, v72
	v_mul_f32_e32 v68, v68, v75
	v_mul_f32_e32 v68, v68, v71
	v_fmac_f32_e32 v206, 0xbfb8aa3b, v73
	v_fmac_f32_e32 v207, 0xbfb8aa3b, v69
	v_cvt_pk_bf16_f32 v75, v88, v68
	v_mul_f32_e32 v71, v77, v72
	v_mul_f32_e32 v88, v76, v72
	v_exp_f32_e32 v76, v206
	v_exp_f32_e32 v77, v207
	v_mul_f32_e32 v71, v126, v71
	v_cvt_pk_bf16_f32 v69, v71, 0
	v_lshlrev_b32_e32 v69, 16, v69
	v_exp_f32_e32 v73, v69
	v_pk_add_f32 v[78:79], v[76:77], 1.0 op_sel_hi:[1,0]
	ds_bpermute_b32 v84, v146, v80
	v_mul_f32_e32 v69, v78, v79
	v_rcp_f32_e32 v69, v69
	v_fma_f32 v72, -v73, v73, 1.0
	v_max_f32_e32 v72, 0, v72
	v_sqrt_f32_e32 v76, v72
	v_mul_f32_e32 v72, v79, v69
	v_mul_f32_e32 v77, v126, v72
	v_cvt_pk_bf16_f32 v72, v77, 0
	v_lshlrev_b32_e32 v72, 16, v72
	v_exp_f32_e32 v72, v72
	v_mul_f32_e32 v76, v88, v76
	v_lshlrev_b32_e32 v79, 16, v195
	v_mul_f32_e32 v76, v76, v79
	v_fma_f32 v79, -v72, v72, 1.0
	v_max_f32_e32 v79, 0, v79
	v_sqrt_f32_e32 v79, v79
	ds_bpermute_b32 v85, v146, v81
	v_mul_f32_e32 v69, v78, v69
	v_lshlrev_b32_e32 v78, 16, v194
	v_mul_f32_e32 v69, v69, v79
	v_mul_f32_e32 v69, v69, v78
	v_cvt_pk_bf16_f32 v76, v71, v76
	v_cvt_pk_bf16_f32 v77, v77, v69
	v_and_b32_e32 v70, 0xffff0000, v74
	v_and_b32_e32 v68, 0xffff0000, v75
	v_and_b32_e32 v71, 0xffff0000, v76
	v_and_b32_e32 v78, 0xffff0000, v77
	s_and_b64 vcc, exec, s[48:49]
	s_mov_b64 s[52:53], -1
	global_store_dwordx4 v[128:129], v[74:77], off offset:704 nt
	s_cbranch_vccnz .LBB0_827
	v_fma_f32 v69, 0, v66, v70
	v_fma_f32 v69, v67, v69, v68
	v_mul_f32_e32 v75, v66, v67
	v_fma_f32 v74, v73, v69, v71
	v_pk_mul_f32 v[88:89], v[72:73], v[74:75]
	v_mov_b32_e32 v79, v72
	v_pk_fma_f32 v[76:77], v[72:73], v[74:75], v[78:79]
	v_pk_mul_f32 v[74:75], v[88:89], v[78:79]
	s_mov_b64 s[52:53], 0

;     template <int QVV> __device__ __forceinline__ void run(f32x4 (&acc)[2][2][4][2], const Unit& u, int wr, int wc, int fr, int fq) const {
;     ...
;         for (int n = 0; n < 2; ++n) {
;             const unsigned ch = cl + 16u * n;
;             const float bavn = bb[ch] * (-LOG2E), bxvn = xbb[ch] * (-LOG2E), c8l = cbb[ch] * LOG2E;
; #pragma unroll
;             for (int ai = 0; ai < 2; ++ai) {
;                 float Pm[4], Hm[4];
; #pragma unroll
;                 for (int m = 0; m < 4; ++m) {
;                     unsigned w[4]; float av[4], uv[4];
; #pragma unroll
;                     for (int i = 0; i < 4; ++i) {
;                         const float er = 1.0f + __builtin_amdgcn_exp2f(__builtin_fmaf(acc[ai][0][m][n][i], -LOG2E, bavn)), ei = 1.0f + __builtin_amdgcn_exp2f(__builtin_fmaf(acc[ai][1][m][n][i], -LOG2E, bxvn));
;                         const float rr = __builtin_amdgcn_rcpf(er * ei), rgt = rr * ei, igt = rr * er;
;                         const float l2 = c8l * rgt;
;                         const float a1 = __builtin_amdgcn_exp2f(__uint_as_float(pk2(l2, 0.f) << 16));
;                         const float mult = __builtin_amdgcn_sqrtf(fmaxf(__builtin_fmaf(-a1, a1, 1.0f), 0.0f));
;                         w[i] = pk2(l2, mult * igt * __uint_as_float((unsigned)xw[n][ai][m][i] << 16));
;                         av[i] = a1; uv[i] = __uint_as_float(w[i] & 0xffff0000u);
;                     }
;                     *(u32x4*)(lb + ((size_t)ch * MT + tl + (unsigned)(ai * HALF + m * 16)) * 4u) = (u32x4){w[0], w[1], w[2], w[3]};
;                     float P = 1.f, H = 0.f;
;                     if (d == 0) {
; #pragma unroll
;                         for (int i = 0; i < 4; ++i) { H = av[i] * H + uv[i]; P *= av[i]; }
.LBB0_833:
	s_or_b64 exec, exec, s[30:31]
	v_add_u32_e32 v66, 16, v138
	v_mov_b32_e32 v67, v175
	v_lshlrev_b64 v[68:69], 2, v[66:67]
	v_lshl_add_u64 v[70:71], s[72:73], 0, v[68:69]
	global_load_dword v72, v[70:71], off
	v_lshl_add_u64 v[70:71], s[74:75], 0, v[68:69]
	global_load_dword v71, v[70:71], off
	v_lshl_add_u64 v[68:69], s[90:91], 0, v[68:69]
	global_load_dword v70, v[68:69], off
	v_lshlrev_b32_e32 v73, 16, v193
	v_lshlrev_b32_e32 v74, 16, v192
	v_lshlrev_b32_e32 v75, 16, v191
	v_lshlrev_b32_e32 v76, 16, v190
	s_mov_b32 s30, 0x8400
	v_mad_u64_u32 v[68:69], s[30:31], v66, s30, v[174:175]
	s_and_b64 vcc, exec, s[48:49]
	v_lshl_add_u64 v[68:69], v[68:69], 2, s[86:87]
	s_mov_b64 s[30:31], -1
	s_waitcnt vmcnt(2)
	v_mul_f32_e32 v79, 0xbfb8aa3b, v72
	v_fmamk_f32 v62, v62, 0xbfb8aa3b, v79
	s_waitcnt vmcnt(1)
	v_mul_f32_e32 v78, 0xbfb8aa3b, v71
	v_fmamk_f32 v71, v58, 0xbfb8aa3b, v78
	v_fmamk_f32 v63, v63, 0xbfb8aa3b, v79
	v_fmamk_f32 v72, v59, 0xbfb8aa3b, v78
	v_fmamk_f32 v64, v64, 0xbfb8aa3b, v79
	v_fmamk_f32 v77, v60, 0xbfb8aa3b, v78
	v_fmamk_f32 v65, v65, 0xbfb8aa3b, v79
	v_fmamk_f32 v80, v61, 0xbfb8aa3b, v78
	v_exp_f32_e32 v58, v62
	v_exp_f32_e32 v59, v71
	v_exp_f32_e32 v60, v63
	v_exp_f32_e32 v61, v72
	v_exp_f32_e32 v62, v64
	v_exp_f32_e32 v63, v77
	v_exp_f32_e32 v64, v65
	v_exp_f32_e32 v65, v80
	v_pk_add_f32 v[58:59], v[58:59], 1.0 op_sel_hi:[1,0]
	v_pk_add_f32 v[60:61], v[60:61], 1.0 op_sel_hi:[1,0]
	v_pk_add_f32 v[62:63], v[62:63], 1.0 op_sel_hi:[1,0]
	v_pk_add_f32 v[64:65], v[64:65], 1.0 op_sel_hi:[1,0]
	v_mul_f32_e32 v72, v58, v59
	v_mul_f32_e32 v77, v60, v61
	v_mul_f32_e32 v80, v62, v63
	v_mul_f32_e32 v81, v64, v65
	v_mov_b32_e32 v71, v65
	v_rcp_f32_e32 v65, v72
	v_rcp_f32_e32 v72, v77
	v_rcp_f32_e32 v77, v80
	v_rcp_f32_e32 v177, v81
	v_mul_f32_e32 v80, v59, v65
	v_mul_f32_e32 v81, v58, v65
	v_mul_f32_e32 v61, v61, v72
	v_mul_f32_e32 v72, v60, v72
	v_mul_f32_e32 v60, v63, v77
	s_waitcnt vmcnt(0)
	v_pk_mul_f32 v[58:59], v[70:71], v[176:177]
	v_mul_f32_e32 v70, v64, v177
	v_mul_f32_e32 v71, v58, v80
	v_mul_f32_e32 v80, v58, v61
	v_mul_f32_e32 v82, v58, v60
	v_pk_mul_f32 v[64:65], v[58:59], v[58:59] op_sel:[0,1] op_sel_hi:[1,0]
	v_mul_f32_e32 v77, v62, v77
	v_cvt_pk_bf16_f32 v59, v71, 0
	v_cvt_pk_bf16_f32 v60, v80, 0
	v_cvt_pk_bf16_f32 v61, v82, 0
	v_cvt_pk_bf16_f32 v62, v64, 0
	v_lshlrev_b32_e32 v59, 16, v59
	v_lshlrev_b32_e32 v63, 16, v60
	v_lshlrev_b32_e32 v65, 16, v61
	v_lshlrev_b32_e32 v62, 16, v62
	v_exp_f32_e32 v60, v59
	v_exp_f32_e32 v61, v63
	v_exp_f32_e32 v63, v65
	v_exp_f32_e32 v62, v62
	v_fma_f32 v59, -v60, v60, 1.0
	v_fma_f32 v65, -v61, v61, 1.0
	v_fma_f32 v83, -v63, v63, 1.0
	v_fma_f32 v84, -v62, v62, 1.0
	v_max_f32_e32 v59, 0, v59
	v_max_f32_e32 v65, 0, v65
	v_max_f32_e32 v83, 0, v83
	v_max_f32_e32 v84, 0, v84
	v_sqrt_f32_e32 v59, v59
	v_sqrt_f32_e32 v65, v65
	v_sqrt_f32_e32 v83, v83
	v_sqrt_f32_e32 v84, v84
	v_mul_f32_e32 v59, v81, v59
	v_mul_f32_e32 v65, v72, v65
	v_mul_f32_e32 v72, v77, v83
	v_mul_f32_e32 v70, v70, v84
	v_mul_f32_e32 v59, v59, v73
	v_mul_f32_e32 v65, v65, v74
	v_mul_f32_e32 v74, v72, v75
	v_mul_f32_e32 v70, v70, v76
	v_cvt_pk_bf16_f32 v72, v71, v59
	v_cvt_pk_bf16_f32 v73, v80, v65
	v_cvt_pk_bf16_f32 v74, v82, v74
	v_cvt_pk_bf16_f32 v75, v64, v70
	v_and_b32_e32 v64, 0xffff0000, v72
	v_and_b32_e32 v70, 0xffff0000, v73
	v_and_b32_e32 v59, 0xffff0000, v74
	v_and_b32_e32 v76, 0xffff0000, v75
	global_store_dwordx4 v[68:69], v[72:75], off nt
	s_cbranch_vccnz .LBB0_835
	v_fma_f32 v65, 0, v60, v64
	v_fma_f32 v65, v61, v65, v70
	v_mul_f32_e32 v73, v60, v61
	v_fma_f32 v72, v63, v65, v59
	v_pk_mul_f32 v[80:81], v[62:63], v[72:73]
	v_mov_b32_e32 v77, v62
	v_pk_fma_f32 v[74:75], v[62:63], v[72:73], v[76:77]
	v_pk_mul_f32 v[72:73], v[80:81], v[76:77]
	s_mov_b64 s[30:31], 0

;     template <int QVV> __device__ __forceinline__ void run(f32x4 (&acc)[2][2][4][2], const Unit& u, int wr, int wc, int fr, int fq) const {
;     ...
;                     for (int i = 0; i < 4; ++i) {
;                         const float er = 1.0f + __builtin_amdgcn_exp2f(__builtin_fmaf(acc[ai][0][m][n][i], -LOG2E, bavn)), ei = 1.0f + __builtin_amdgcn_exp2f(__builtin_fmaf(acc[ai][1][m][n][i], -LOG2E, bxvn));
;                         const float rr = __builtin_amdgcn_rcpf(er * ei), rgt = rr * ei, igt = rr * er;
;                         const float l2 = c8l * rgt;
;                         const float a1 = __builtin_amdgcn_exp2f(__uint_as_float(pk2(l2, 0.f) << 16));
;                         const float mult = __builtin_amdgcn_sqrtf(fmaxf(__builtin_fmaf(-a1, a1, 1.0f), 0.0f));
;                         w[i] = pk2(l2, mult * igt * __uint_as_float((unsigned)xw[n][ai][m][i] << 16));
;                         av[i] = a1; uv[i] = __uint_as_float(w[i] & 0xffff0000u);
;                     }
;                     *(u32x4*)(lb + ((size_t)ch * MT + tl + (unsigned)(ai * HALF + m * 16)) * 4u) = (u32x4){w[0], w[1], w[2], w[3]};
;                     float P = 1.f, H = 0.f;
;                     if (d == 0) {
; #pragma unroll
;                         for (int i = 0; i < 4; ++i) { H = av[i] * H + uv[i]; P *= av[i]; }
;                     } else {
; #pragma unroll
;                         for (int i = 3; i >= 0; --i) { H = av[i] * H + uv[i]; P *= av[i]; }
;                     }
; #pragma unroll
;                     for (int sft = 16; sft < 64; sft <<= 1) {
;                         const float Pq = __shfl_xor(P, sft), Hq = __shfl_xor(H, sft);
;                         const bool lowhalf = ((lane_hi * 16) & sft) == 0;
;                         const bool mine_first = (d == 0) ? lowhalf : !lowhalf;
;                         const float Px = mine_first ? P : Pq, Hx = mine_first ? H : Hq, Py = mine_first ? Pq : P, Hy = mine_first ? Hq : H;
;                         P = Px * Py; H = Py * Hx + Hy;
.LBB0_837:
	ds_bpermute_b32 v59, v127, v74
	ds_bpermute_b32 v64, v127, v73
	v_fmamk_f32 v54, v54, 0xbfb8aa3b, v79
	v_fmamk_f32 v50, v50, 0xbfb8aa3b, v78
	v_exp_f32_e32 v60, v54
	v_exp_f32_e32 v61, v50
	s_waitcnt lgkmcnt(1)
	v_cndmask_b32_e64 v54, v59, v74, s[46:47]
	s_waitcnt lgkmcnt(0)
	v_cndmask_b32_e64 v50, v73, v64, s[46:47]
	v_cndmask_b32_e64 v59, v74, v59, s[46:47]
	v_pk_add_f32 v[62:63], v[60:61], 1.0 op_sel_hi:[1,0]
	v_fmac_f32_e32 v59, v50, v54
	v_mul_f32_e32 v50, v62, v63
	v_rcp_f32_e32 v61, v50
	v_fmamk_f32 v55, v55, 0xbfb8aa3b, v79
	v_fmamk_f32 v51, v51, 0xbfb8aa3b, v78
	v_mul_f32_e32 v50, v73, v64
	v_mul_f32_e32 v60, v63, v61
	v_mul_f32_e32 v63, v58, v60
	v_cvt_pk_bf16_f32 v60, v63, 0
	v_lshlrev_b32_e32 v60, 16, v60
	v_exp_f32_e32 v60, v60
	v_exp_f32_e32 v64, v55
	v_exp_f32_e32 v65, v51
	v_mul_f32_e32 v61, v62, v61
	v_fma_f32 v51, -v60, v60, 1.0
	v_max_f32_e32 v51, 0, v51
	v_pk_add_f32 v[64:65], v[64:65], 1.0 op_sel_hi:[1,0]
	v_sqrt_f32_e32 v51, v51
	v_mul_f32_e32 v55, v64, v65
	v_rcp_f32_e32 v55, v55
	v_fmamk_f32 v56, v56, 0xbfb8aa3b, v79
	v_mul_f32_e32 v51, v61, v51
	v_fmamk_f32 v52, v52, 0xbfb8aa3b, v78
	v_mul_f32_e32 v61, v65, v55
	v_mul_f32_e32 v72, v58, v61
	v_cvt_pk_bf16_f32 v61, v72, 0
	v_lshlrev_b32_e32 v61, 16, v61
	v_exp_f32_e32 v61, v61
	v_lshlrev_b32_e32 v62, 16, v189
	v_exp_f32_e32 v70, v56
	v_exp_f32_e32 v71, v52
	v_mul_f32_e32 v51, v51, v62
	v_cvt_pk_bf16_f32 v80, v63, v51
	v_fma_f32 v51, -v61, v61, 1.0
	v_max_f32_e32 v51, 0, v51
	v_sqrt_f32_e32 v51, v51
	v_mul_f32_e32 v52, v64, v55
	v_pk_add_f32 v[64:65], v[70:71], 1.0 op_sel_hi:[1,0]
	v_fmamk_f32 v56, v57, 0xbfb8aa3b, v79
	v_mul_f32_e32 v55, v64, v65
	v_rcp_f32_e32 v55, v55
	v_mul_f32_e32 v51, v52, v51
	v_lshlrev_b32_e32 v52, 16, v188
	v_mul_f32_e32 v51, v51, v52
	v_fmamk_f32 v53, v53, 0xbfb8aa3b, v78
	v_cvt_pk_bf16_f32 v81, v72, v51
	v_mul_f32_e32 v51, v65, v55
	v_mul_f32_e32 v55, v64, v55
	v_exp_f32_e32 v64, v56
	v_exp_f32_e32 v65, v53
	v_mul_f32_e32 v51, v58, v51
	v_cvt_pk_bf16_f32 v53, v51, 0
	v_lshlrev_b32_e32 v53, 16, v53
	v_exp_f32_e32 v57, v53
	v_pk_add_f32 v[64:65], v[64:65], 1.0 op_sel_hi:[1,0]
	ds_bpermute_b32 v74, v146, v59
	v_mul_f32_e32 v53, v64, v65
	v_rcp_f32_e32 v53, v53
	v_fma_f32 v56, -v57, v57, 1.0
	v_max_f32_e32 v56, 0, v56
	v_sqrt_f32_e32 v63, v56
	v_mul_f32_e32 v56, v65, v53
	v_mul_f32_e32 v65, v58, v56
	v_cvt_pk_bf16_f32 v56, v65, 0
	v_lshlrev_b32_e32 v56, 16, v56
	v_exp_f32_e32 v56, v56
	v_mul_f32_e32 v55, v55, v63
	v_lshlrev_b32_e32 v63, 16, v187
	v_mul_f32_e32 v55, v55, v63
	v_fma_f32 v63, -v56, v56, 1.0
	v_max_f32_e32 v63, 0, v63
	v_sqrt_f32_e32 v63, v63
	ds_bpermute_b32 v54, v146, v50
	v_mul_f32_e32 v53, v64, v53
	v_cvt_pk_bf16_f32 v82, v51, v55
	v_mul_f32_e32 v53, v53, v63
	v_lshlrev_b32_e32 v55, 16, v186
	v_mul_f32_e32 v53, v53, v55
	v_cvt_pk_bf16_f32 v83, v65, v53
	v_and_b32_e32 v62, 0xffff0000, v80
	v_and_b32_e32 v52, 0xffff0000, v81
	v_and_b32_e32 v51, 0xffff0000, v82
	v_and_b32_e32 v72, 0xffff0000, v83
	s_and_b64 vcc, exec, s[48:49]
	s_mov_b64 s[30:31], -1
	global_store_dwordx4 v[68:69], v[80:83], off offset:64 nt
	s_cbranch_vccnz .LBB0_839
	v_fma_f32 v53, 0, v60, v62
	v_fma_f32 v53, v61, v53, v52
	v_mul_f32_e32 v65, v60, v61
	v_fma_f32 v64, v57, v53, v51
	v_pk_mul_f32 v[70:71], v[56:57], v[64:65]
	v_mov_b32_e32 v73, v56
	v_pk_fma_f32 v[64:65], v[56:57], v[64:65], v[72:73]
	v_pk_mul_f32 v[70:71], v[70:71], v[72:73]
	s_mov_b64 s[30:31], 0

;     template <int QVV> __device__ __forceinline__ void run(f32x4 (&acc)[2][2][4][2], const Unit& u, int wr, int wc, int fr, int fq) const {
;     ...
;                     for (int i = 0; i < 4; ++i) {
;                         const float er = 1.0f + __builtin_amdgcn_exp2f(__builtin_fmaf(acc[ai][0][m][n][i], -LOG2E, bavn)), ei = 1.0f + __builtin_amdgcn_exp2f(__builtin_fmaf(acc[ai][1][m][n][i], -LOG2E, bxvn));
;                         const float rr = __builtin_amdgcn_rcpf(er * ei), rgt = rr * ei, igt = rr * er;
;                         const float l2 = c8l * rgt;
;                         const float a1 = __builtin_amdgcn_exp2f(__uint_as_float(pk2(l2, 0.f) << 16));
;                         const float mult = __builtin_amdgcn_sqrtf(fmaxf(__builtin_fmaf(-a1, a1, 1.0f), 0.0f));
;                         w[i] = pk2(l2, mult * igt * __uint_as_float((unsigned)xw[n][ai][m][i] << 16));
;                         av[i] = a1; uv[i] = __uint_as_float(w[i] & 0xffff0000u);
;                     }
;                     *(u32x4*)(lb + ((size_t)ch * MT + tl + (unsigned)(ai * HALF + m * 16)) * 4u) = (u32x4){w[0], w[1], w[2], w[3]};
;                     float P = 1.f, H = 0.f;
;                     if (d == 0) {
; #pragma unroll
;                         for (int i = 0; i < 4; ++i) { H = av[i] * H + uv[i]; P *= av[i]; }
;                     } else {
; #pragma unroll
;                         for (int i = 3; i >= 0; --i) { H = av[i] * H + uv[i]; P *= av[i]; }
;                     }
; #pragma unroll
;                     for (int sft = 16; sft < 64; sft <<= 1) {
;                         const float Pq = __shfl_xor(P, sft), Hq = __shfl_xor(H, sft);
;                         const bool lowhalf = ((lane_hi * 16) & sft) == 0;
;                         const bool mine_first = (d == 0) ? lowhalf : !lowhalf;
;                         const float Px = mine_first ? P : Pq, Hx = mine_first ? H : Hq, Py = mine_first ? Pq : P, Hy = mine_first ? Hq : H;
;                         P = Px * Py; H = Py * Hx + Hy;
.LBB0_841:
	v_fmamk_f32 v46, v46, 0xbfb8aa3b, v79
	v_fmamk_f32 v42, v42, 0xbfb8aa3b, v78
	ds_bpermute_b32 v51, v127, v64
	ds_bpermute_b32 v56, v127, v71
	v_exp_f32_e32 v52, v46
	v_exp_f32_e32 v53, v42
	v_fmamk_f32 v43, v43, 0xbfb8aa3b, v78
	s_waitcnt lgkmcnt(1)
	v_cndmask_b32_e64 v46, v51, v64, s[46:47]
	s_waitcnt lgkmcnt(0)
	v_cndmask_b32_e64 v42, v71, v56, s[46:47]
	v_pk_add_f32 v[52:53], v[52:53], 1.0 op_sel_hi:[1,0]
	v_cndmask_b32_e64 v55, v64, v51, s[46:47]
	v_mul_f32_e32 v51, v71, v56
	v_mul_f32_e32 v56, v52, v53
	v_rcp_f32_e32 v60, v56
	v_fmac_f32_e32 v55, v42, v46
	v_fmamk_f32 v46, v47, 0xbfb8aa3b, v79
	v_exp_f32_e32 v46, v46
	v_mul_f32_e32 v42, v53, v60
	v_mul_f32_e32 v53, v58, v42
	v_cvt_pk_bf16_f32 v42, v53, 0
	v_lshlrev_b32_e32 v42, 16, v42
	v_exp_f32_e32 v42, v42
	v_exp_f32_e32 v47, v43
	v_fmamk_f32 v48, v48, 0xbfb8aa3b, v79
	v_fmamk_f32 v44, v44, 0xbfb8aa3b, v78
	v_fma_f32 v43, -v42, v42, 1.0
	v_pk_add_f32 v[56:57], v[46:47], 1.0 op_sel_hi:[1,0]
	v_max_f32_e32 v43, 0, v43
	v_mul_f32_e32 v46, v56, v57
	v_sqrt_f32_e32 v43, v43
	v_rcp_f32_e32 v47, v46
	v_mul_f32_e32 v46, v52, v60
	v_lshlrev_b32_e32 v52, 16, v185
	v_mul_f32_e32 v46, v46, v43
	v_mul_f32_e32 v43, v57, v47
	v_mul_f32_e32 v57, v58, v43
	v_cvt_pk_bf16_f32 v43, v57, 0
	v_lshlrev_b32_e32 v43, 16, v43
	v_exp_f32_e32 v43, v43
	v_mul_f32_e32 v46, v46, v52
	v_cvt_pk_bf16_f32 v70, v53, v46
	v_exp_f32_e32 v53, v44
	v_fma_f32 v52, -v43, v43, 1.0
	v_max_f32_e32 v52, 0, v52
	v_sqrt_f32_e32 v60, v52
	v_exp_f32_e32 v52, v48
	v_mul_f32_e32 v44, v56, v47
	v_lshlrev_b32_e32 v47, 16, v184
	v_mul_f32_e32 v44, v44, v60
	v_pk_add_f32 v[52:53], v[52:53], 1.0 op_sel_hi:[1,0]
	v_mul_f32_e32 v44, v44, v47
	v_mul_f32_e32 v48, v52, v53
	v_rcp_f32_e32 v48, v48
	v_fmamk_f32 v45, v45, 0xbfb8aa3b, v78
	v_cvt_pk_bf16_f32 v71, v57, v44
	ds_bpermute_b32 v62, v146, v51
	v_mul_f32_e32 v47, v53, v48
	v_mul_f32_e32 v56, v52, v48
	v_fmamk_f32 v48, v49, 0xbfb8aa3b, v79
	v_exp_f32_e32 v52, v48
	v_exp_f32_e32 v53, v45
	v_mul_f32_e32 v47, v58, v47
	v_cvt_pk_bf16_f32 v45, v47, 0
	v_lshlrev_b32_e32 v45, 16, v45
	v_exp_f32_e32 v49, v45
	v_pk_add_f32 v[52:53], v[52:53], 1.0 op_sel_hi:[1,0]
	ds_bpermute_b32 v63, v146, v55
	v_mul_f32_e32 v45, v52, v53
	v_rcp_f32_e32 v45, v45
	v_fma_f32 v48, -v49, v49, 1.0
	v_max_f32_e32 v48, 0, v48
	v_sqrt_f32_e32 v57, v48
	v_mul_f32_e32 v48, v53, v45
	v_mul_f32_e32 v53, v58, v48
	v_cvt_pk_bf16_f32 v48, v53, 0
	v_lshlrev_b32_e32 v48, 16, v48
	v_exp_f32_e32 v48, v48
	v_mul_f32_e32 v56, v56, v57
	v_lshlrev_b32_e32 v57, 16, v183
	v_mul_f32_e32 v56, v56, v57
	v_fma_f32 v57, -v48, v48, 1.0
	v_max_f32_e32 v57, 0, v57
	v_sqrt_f32_e32 v57, v57
	v_mul_f32_e32 v45, v52, v45
	v_lshlrev_b32_e32 v52, 16, v182
	v_cvt_pk_bf16_f32 v72, v47, v56
	v_mul_f32_e32 v45, v45, v57
	v_mul_f32_e32 v45, v45, v52
	v_cvt_pk_bf16_f32 v73, v53, v45
	v_and_b32_e32 v46, 0xffff0000, v70
	v_and_b32_e32 v44, 0xffff0000, v71
	v_and_b32_e32 v47, 0xffff0000, v72
	v_and_b32_e32 v60, 0xffff0000, v73
	s_and_b64 vcc, exec, s[48:49]
	s_mov_b64 s[30:31], -1
	global_store_dwordx4 v[68:69], v[70:73], off offset:128 nt
	s_cbranch_vccnz .LBB0_843
	v_fma_f32 v45, 0, v42, v46
	v_fma_f32 v45, v43, v45, v44
	v_mul_f32_e32 v53, v42, v43
	v_fma_f32 v52, v49, v45, v47
	v_pk_mul_f32 v[56:57], v[48:49], v[52:53]
	v_mov_b32_e32 v61, v48
	v_pk_fma_f32 v[52:53], v[48:49], v[52:53], v[60:61]
	v_pk_mul_f32 v[56:57], v[56:57], v[60:61]
	s_mov_b64 s[30:31], 0

;     template <int QVV> __device__ __forceinline__ void run(f32x4 (&acc)[2][2][4][2], const Unit& u, int wr, int wc, int fr, int fq) const {
;     ...
;                     for (int i = 0; i < 4; ++i) {
;                         const float er = 1.0f + __builtin_amdgcn_exp2f(__builtin_fmaf(acc[ai][0][m][n][i], -LOG2E, bavn)), ei = 1.0f + __builtin_amdgcn_exp2f(__builtin_fmaf(acc[ai][1][m][n][i], -LOG2E, bxvn));
;                         const float rr = __builtin_amdgcn_rcpf(er * ei), rgt = rr * ei, igt = rr * er;
;                         const float l2 = c8l * rgt;
;                         const float a1 = __builtin_amdgcn_exp2f(__uint_as_float(pk2(l2, 0.f) << 16));
;                         const float mult = __builtin_amdgcn_sqrtf(fmaxf(__builtin_fmaf(-a1, a1, 1.0f), 0.0f));
;                         w[i] = pk2(l2, mult * igt * __uint_as_float((unsigned)xw[n][ai][m][i] << 16));
;                         av[i] = a1; uv[i] = __uint_as_float(w[i] & 0xffff0000u);
;                     }
;                     *(u32x4*)(lb + ((size_t)ch * MT + tl + (unsigned)(ai * HALF + m * 16)) * 4u) = (u32x4){w[0], w[1], w[2], w[3]};
;                     float P = 1.f, H = 0.f;
;                     if (d == 0) {
; #pragma unroll
;                         for (int i = 0; i < 4; ++i) { H = av[i] * H + uv[i]; P *= av[i]; }
;                     } else {
; #pragma unroll
;                         for (int i = 3; i >= 0; --i) { H = av[i] * H + uv[i]; P *= av[i]; }
;                     }
; #pragma unroll
;                     for (int sft = 16; sft < 64; sft <<= 1) {
;                         const float Pq = __shfl_xor(P, sft), Hq = __shfl_xor(H, sft);
;                         const bool lowhalf = ((lane_hi * 16) & sft) == 0;
;                         const bool mine_first = (d == 0) ? lowhalf : !lowhalf;
;                         const float Px = mine_first ? P : Pq, Hx = mine_first ? H : Hq, Py = mine_first ? Pq : P, Hy = mine_first ? Hq : H;
;                         P = Px * Py; H = Py * Hx + Hy;
.LBB0_845:
	v_fmamk_f32 v38, v38, 0xbfb8aa3b, v79
	v_fmamk_f32 v34, v34, 0xbfb8aa3b, v78
	ds_bpermute_b32 v44, v127, v52
	v_exp_f32_e32 v42, v38
	v_exp_f32_e32 v43, v34
	ds_bpermute_b32 v45, v127, v57
	v_fmamk_f32 v35, v35, 0xbfb8aa3b, v78
	s_waitcnt lgkmcnt(1)
	v_cndmask_b32_e64 v38, v44, v52, s[46:47]
	v_pk_add_f32 v[42:43], v[42:43], 1.0 op_sel_hi:[1,0]
	v_cndmask_b32_e64 v49, v52, v44, s[46:47]
	v_mul_f32_e32 v44, v42, v43
	v_rcp_f32_e32 v46, v44
	s_waitcnt lgkmcnt(0)
	v_cndmask_b32_e64 v34, v57, v45, s[46:47]
	v_fmac_f32_e32 v49, v34, v38
	v_fmamk_f32 v38, v39, 0xbfb8aa3b, v79
	v_mul_f32_e32 v34, v43, v46
	v_mul_f32_e32 v43, v58, v34
	v_cvt_pk_bf16_f32 v34, v43, 0
	v_lshlrev_b32_e32 v34, 16, v34
	v_exp_f32_e32 v34, v34
	v_exp_f32_e32 v38, v38
	v_exp_f32_e32 v39, v35
	v_mul_f32_e32 v48, v57, v45
	v_fma_f32 v35, -v34, v34, 1.0
	v_max_f32_e32 v35, 0, v35
	v_pk_add_f32 v[44:45], v[38:39], 1.0 op_sel_hi:[1,0]
	v_sqrt_f32_e32 v35, v35
	v_mul_f32_e32 v38, v44, v45
	v_rcp_f32_e32 v39, v38
	v_mul_f32_e32 v38, v42, v46
	v_mul_f32_e32 v38, v38, v35
	v_fmamk_f32 v40, v40, 0xbfb8aa3b, v79
	v_mul_f32_e32 v35, v45, v39
	v_mul_f32_e32 v56, v58, v35
	v_cvt_pk_bf16_f32 v35, v56, 0
	v_lshlrev_b32_e32 v35, 16, v35
	v_exp_f32_e32 v35, v35
	v_fmamk_f32 v36, v36, 0xbfb8aa3b, v78
	v_lshlrev_b32_e32 v42, 16, v179
	v_exp_f32_e32 v46, v40
	v_exp_f32_e32 v47, v36
	v_mul_f32_e32 v38, v38, v42
	v_cvt_pk_bf16_f32 v42, v43, v38
	v_fma_f32 v43, -v35, v35, 1.0
	v_max_f32_e32 v43, 0, v43
	v_sqrt_f32_e32 v43, v43
	v_mul_f32_e32 v36, v44, v39
	v_pk_add_f32 v[44:45], v[46:47], 1.0 op_sel_hi:[1,0]
	v_lshlrev_b32_e32 v39, 16, v178
	v_mul_f32_e32 v40, v44, v45
	v_rcp_f32_e32 v40, v40
	v_mul_f32_e32 v36, v36, v43
	v_mul_f32_e32 v36, v36, v39
	v_cvt_pk_bf16_f32 v43, v56, v36
	v_mul_f32_e32 v39, v45, v40
	v_mul_f32_e32 v56, v44, v40
	v_fmamk_f32 v40, v41, 0xbfb8aa3b, v79
	v_fmamk_f32 v37, v37, 0xbfb8aa3b, v78
	v_exp_f32_e32 v44, v40
	v_exp_f32_e32 v45, v37
	v_mul_f32_e32 v39, v58, v39
	v_cvt_pk_bf16_f32 v37, v39, 0
	v_lshlrev_b32_e32 v37, 16, v37
	v_exp_f32_e32 v41, v37
	v_pk_add_f32 v[46:47], v[44:45], 1.0 op_sel_hi:[1,0]
	ds_bpermute_b32 v52, v146, v48
	v_mul_f32_e32 v37, v46, v47
	v_rcp_f32_e32 v37, v37
	v_fma_f32 v40, -v41, v41, 1.0
	v_max_f32_e32 v40, 0, v40
	v_sqrt_f32_e32 v44, v40
	v_mul_f32_e32 v40, v47, v37
	v_mul_f32_e32 v45, v58, v40
	v_cvt_pk_bf16_f32 v40, v45, 0
	v_lshlrev_b32_e32 v40, 16, v40
	v_exp_f32_e32 v40, v40
	v_mul_f32_e32 v44, v56, v44
	v_lshlrev_b32_e32 v47, 16, v173
	v_mul_f32_e32 v44, v44, v47
	v_fma_f32 v47, -v40, v40, 1.0
	v_max_f32_e32 v47, 0, v47
	v_sqrt_f32_e32 v47, v47
	ds_bpermute_b32 v53, v146, v49
	v_mul_f32_e32 v37, v46, v37
	v_lshlrev_b32_e32 v46, 16, v172
	v_mul_f32_e32 v37, v37, v47
	v_mul_f32_e32 v37, v37, v46
	v_cvt_pk_bf16_f32 v44, v39, v44
	v_cvt_pk_bf16_f32 v45, v45, v37
	v_and_b32_e32 v38, 0xffff0000, v42
	v_and_b32_e32 v36, 0xffff0000, v43
	v_and_b32_e32 v39, 0xffff0000, v44
	v_and_b32_e32 v46, 0xffff0000, v45
	s_and_b64 vcc, exec, s[48:49]
	s_mov_b64 s[30:31], -1
	global_store_dwordx4 v[68:69], v[42:45], off offset:192 nt
	s_cbranch_vccnz .LBB0_847
	v_fma_f32 v37, 0, v34, v38
	v_fma_f32 v37, v35, v37, v36
	v_mul_f32_e32 v43, v34, v35
	v_fma_f32 v42, v41, v37, v39
	v_pk_mul_f32 v[56:57], v[40:41], v[42:43]
	v_mov_b32_e32 v47, v40
	v_pk_fma_f32 v[44:45], v[40:41], v[42:43], v[46:47]
	v_pk_mul_f32 v[42:43], v[56:57], v[46:47]
	s_mov_b64 s[30:31], 0

;     template <int QVV> __device__ __forceinline__ void run(f32x4 (&acc)[2][2][4][2], const Unit& u, int wr, int wc, int fr, int fq) const {
;     ...
;                 for (int m = 0; m < 4; ++m) {
;                     unsigned w[4]; float av[4], uv[4];
; #pragma unroll
;                     for (int i = 0; i < 4; ++i) {
;                         const float er = 1.0f + __builtin_amdgcn_exp2f(__builtin_fmaf(acc[ai][0][m][n][i], -LOG2E, bavn)), ei = 1.0f + __builtin_amdgcn_exp2f(__builtin_fmaf(acc[ai][1][m][n][i], -LOG2E, bxvn));
;                         const float rr = __builtin_amdgcn_rcpf(er * ei), rgt = rr * ei, igt = rr * er;
;                         const float l2 = c8l * rgt;
;                         const float a1 = __builtin_amdgcn_exp2f(__uint_as_float(pk2(l2, 0.f) << 16));
;                         const float mult = __builtin_amdgcn_sqrtf(fmaxf(__builtin_fmaf(-a1, a1, 1.0f), 0.0f));
;                         w[i] = pk2(l2, mult * igt * __uint_as_float((unsigned)xw[n][ai][m][i] << 16));
;                         av[i] = a1; uv[i] = __uint_as_float(w[i] & 0xffff0000u);
;                     }
;                     *(u32x4*)(lb + ((size_t)ch * MT + tl + (unsigned)(ai * HALF + m * 16)) * 4u) = (u32x4){w[0], w[1], w[2], w[3]};
;                     float P = 1.f, H = 0.f;
;                     if (d == 0) {
; #pragma unroll
;                         for (int i = 0; i < 4; ++i) { H = av[i] * H + uv[i]; P *= av[i]; }
.LBB0_853:
	s_or_b64 exec, exec, s[30:31]
	v_fmamk_f32 v30, v30, 0xbfb8aa3b, v79
	v_fmamk_f32 v26, v26, 0xbfb8aa3b, v78
	v_exp_f32_e32 v34, v30
	v_exp_f32_e32 v35, v26
	v_fmamk_f32 v26, v31, 0xbfb8aa3b, v79
	v_fmamk_f32 v27, v27, 0xbfb8aa3b, v78
	v_fmamk_f32 v32, v32, 0xbfb8aa3b, v79
	v_pk_add_f32 v[30:31], v[34:35], 1.0 op_sel_hi:[1,0]
	v_exp_f32_e32 v35, v27
	v_mul_f32_e32 v34, v30, v31
	v_rcp_f32_e32 v38, v34
	v_exp_f32_e32 v34, v26
	v_fmamk_f32 v28, v28, 0xbfb8aa3b, v78
	v_exp_f32_e32 v39, v28
	v_mul_f32_e32 v26, v31, v38
	v_mul_f32_e32 v31, v58, v26
	v_cvt_pk_bf16_f32 v26, v31, 0
	v_lshlrev_b32_e32 v26, 16, v26
	v_exp_f32_e32 v26, v26
	v_pk_add_f32 v[36:37], v[34:35], 1.0 op_sel_hi:[1,0]
	v_mul_f32_e32 v30, v30, v38
	v_mul_f32_e32 v27, v36, v37
	v_rcp_f32_e32 v35, v27
	v_fma_f32 v27, -v26, v26, 1.0
	v_max_f32_e32 v27, 0, v27
	v_sqrt_f32_e32 v27, v27
	v_mul_f32_e32 v37, v37, v35
	v_mul_f32_e32 v40, v58, v37
	v_lshlrev_b32_e32 v34, 16, v170
	v_mul_f32_e32 v30, v30, v27
	v_cvt_pk_bf16_f32 v27, v40, 0
	v_lshlrev_b32_e32 v27, 16, v27
	v_exp_f32_e32 v27, v27
	v_exp_f32_e32 v38, v32
	v_mul_f32_e32 v30, v30, v34
	v_cvt_pk_bf16_f32 v34, v31, v30
	v_fma_f32 v31, -v27, v27, 1.0
	v_max_f32_e32 v31, 0, v31
	v_sqrt_f32_e32 v31, v31
	v_mul_f32_e32 v28, v36, v35
	v_pk_add_f32 v[36:37], v[38:39], 1.0 op_sel_hi:[1,0]
	v_fmamk_f32 v29, v29, 0xbfb8aa3b, v78
	v_mul_f32_e32 v32, v36, v37
	v_rcp_f32_e32 v32, v32
	v_mul_f32_e32 v28, v28, v31
	v_lshlrev_b32_e32 v31, 16, v169
	v_mul_f32_e32 v28, v28, v31
	v_cvt_pk_bf16_f32 v35, v40, v28
	v_mul_f32_e32 v31, v37, v32
	v_mul_f32_e32 v40, v36, v32
	v_fmamk_f32 v32, v33, 0xbfb8aa3b, v79
	v_exp_f32_e32 v36, v32
	v_exp_f32_e32 v37, v29
	v_mul_f32_e32 v31, v58, v31
	v_cvt_pk_bf16_f32 v29, v31, 0
	v_lshlrev_b32_e32 v29, 16, v29
	v_exp_f32_e32 v33, v29
	v_pk_add_f32 v[38:39], v[36:37], 1.0 op_sel_hi:[1,0]
	v_and_b32_e32 v30, 0xffff0000, v34
	v_mul_f32_e32 v29, v38, v39
	v_rcp_f32_e32 v29, v29
	v_fma_f32 v32, -v33, v33, 1.0
	v_max_f32_e32 v32, 0, v32
	v_sqrt_f32_e32 v36, v32
	v_mul_f32_e32 v32, v39, v29
	v_mul_f32_e32 v37, v58, v32
	v_cvt_pk_bf16_f32 v32, v37, 0
	v_lshlrev_b32_e32 v32, 16, v32
	v_exp_f32_e32 v32, v32
	v_mul_f32_e32 v36, v40, v36
	v_lshlrev_b32_e32 v39, 16, v168
	v_mul_f32_e32 v36, v36, v39
	v_fma_f32 v39, -v32, v32, 1.0
	v_max_f32_e32 v39, 0, v39
	v_sqrt_f32_e32 v39, v39
	v_mul_f32_e32 v29, v38, v29
	v_lshlrev_b32_e32 v38, 16, v167
	v_cvt_pk_bf16_f32 v36, v31, v36
	v_mul_f32_e32 v29, v29, v39
	v_mul_f32_e32 v29, v29, v38
	v_cvt_pk_bf16_f32 v37, v37, v29
	v_and_b32_e32 v28, 0xffff0000, v35
	v_and_b32_e32 v31, 0xffff0000, v36
	v_and_b32_e32 v38, 0xffff0000, v37
	s_and_b64 vcc, exec, s[48:49]
	s_mov_b64 s[30:31], -1
	global_store_dwordx4 v[68:69], v[34:37], off offset:512 nt
	s_cbranch_vccnz .LBB0_855
	v_fma_f32 v29, 0, v26, v30
	v_fma_f32 v29, v27, v29, v28
	v_mul_f32_e32 v35, v26, v27
	v_fma_f32 v34, v33, v29, v31
	v_pk_mul_f32 v[40:41], v[32:33], v[34:35]
	v_mov_b32_e32 v39, v32
	v_pk_fma_f32 v[36:37], v[32:33], v[34:35], v[38:39]
	v_pk_mul_f32 v[34:35], v[40:41], v[38:39]
	s_mov_b64 s[30:31], 0

;     template <int QVV> __device__ __forceinline__ void run(f32x4 (&acc)[2][2][4][2], const Unit& u, int wr, int wc, int fr, int fq) const {
;     ...
;                     for (int i = 0; i < 4; ++i) {
;                         const float er = 1.0f + __builtin_amdgcn_exp2f(__builtin_fmaf(acc[ai][0][m][n][i], -LOG2E, bavn)), ei = 1.0f + __builtin_amdgcn_exp2f(__builtin_fmaf(acc[ai][1][m][n][i], -LOG2E, bxvn));
;                         const float rr = __builtin_amdgcn_rcpf(er * ei), rgt = rr * ei, igt = rr * er;
;                         const float l2 = c8l * rgt;
;                         const float a1 = __builtin_amdgcn_exp2f(__uint_as_float(pk2(l2, 0.f) << 16));
;                         const float mult = __builtin_amdgcn_sqrtf(fmaxf(__builtin_fmaf(-a1, a1, 1.0f), 0.0f));
;                         w[i] = pk2(l2, mult * igt * __uint_as_float((unsigned)xw[n][ai][m][i] << 16));
;                         av[i] = a1; uv[i] = __uint_as_float(w[i] & 0xffff0000u);
;                     }
;                     *(u32x4*)(lb + ((size_t)ch * MT + tl + (unsigned)(ai * HALF + m * 16)) * 4u) = (u32x4){w[0], w[1], w[2], w[3]};
;                     float P = 1.f, H = 0.f;
;                     if (d == 0) {
; #pragma unroll
;                         for (int i = 0; i < 4; ++i) { H = av[i] * H + uv[i]; P *= av[i]; }
;                     } else {
; #pragma unroll
;                         for (int i = 3; i >= 0; --i) { H = av[i] * H + uv[i]; P *= av[i]; }
;                     }
; #pragma unroll
;                     for (int sft = 16; sft < 64; sft <<= 1) {
;                         const float Pq = __shfl_xor(P, sft), Hq = __shfl_xor(H, sft);
;                         const bool lowhalf = ((lane_hi * 16) & sft) == 0;
;                         const bool mine_first = (d == 0) ? lowhalf : !lowhalf;
;                         const float Px = mine_first ? P : Pq, Hx = mine_first ? H : Hq, Py = mine_first ? Pq : P, Hy = mine_first ? Hq : H;
;                         P = Px * Py; H = Py * Hx + Hy;
.LBB0_857:
	ds_bpermute_b32 v28, v127, v36
	ds_bpermute_b32 v30, v127, v35
	v_fmamk_f32 v22, v22, 0xbfb8aa3b, v79
	v_fmamk_f32 v18, v18, 0xbfb8aa3b, v78
	v_exp_f32_e32 v26, v22
	v_exp_f32_e32 v27, v18
	s_waitcnt lgkmcnt(1)
	v_cndmask_b32_e64 v22, v28, v36, s[46:47]
	s_waitcnt lgkmcnt(0)
	v_cndmask_b32_e64 v18, v35, v30, s[46:47]
	v_cndmask_b32_e64 v36, v36, v28, s[46:47]
	v_pk_add_f32 v[28:29], v[26:27], 1.0 op_sel_hi:[1,0]
	v_fmac_f32_e32 v36, v18, v22
	v_mul_f32_e32 v18, v28, v29
	v_rcp_f32_e32 v27, v18
	v_fmamk_f32 v23, v23, 0xbfb8aa3b, v79
	v_fmamk_f32 v19, v19, 0xbfb8aa3b, v78
	v_mul_f32_e32 v18, v35, v30
	v_mul_f32_e32 v26, v29, v27
	v_mul_f32_e32 v29, v58, v26
	v_cvt_pk_bf16_f32 v26, v29, 0
	v_lshlrev_b32_e32 v26, 16, v26
	v_exp_f32_e32 v26, v26
	v_exp_f32_e32 v30, v23
	v_exp_f32_e32 v31, v19
	v_mul_f32_e32 v27, v28, v27
	v_fma_f32 v19, -v26, v26, 1.0
	v_max_f32_e32 v19, 0, v19
	v_pk_add_f32 v[32:33], v[30:31], 1.0 op_sel_hi:[1,0]
	v_sqrt_f32_e32 v19, v19
	v_mul_f32_e32 v23, v32, v33
	v_rcp_f32_e32 v23, v23
	v_fmamk_f32 v24, v24, 0xbfb8aa3b, v79
	v_mul_f32_e32 v19, v27, v19
	v_fmamk_f32 v20, v20, 0xbfb8aa3b, v78
	v_mul_f32_e32 v27, v33, v23
	v_mul_f32_e32 v31, v58, v27
	v_cvt_pk_bf16_f32 v27, v31, 0
	v_lshlrev_b32_e32 v27, 16, v27
	v_exp_f32_e32 v27, v27
	v_lshlrev_b32_e32 v28, 16, v166
	v_exp_f32_e32 v34, v24
	v_exp_f32_e32 v35, v20
	v_mul_f32_e32 v19, v19, v28
	v_cvt_pk_bf16_f32 v30, v29, v19
	v_fma_f32 v19, -v27, v27, 1.0
	v_max_f32_e32 v19, 0, v19
	v_sqrt_f32_e32 v19, v19
	v_mul_f32_e32 v20, v32, v23
	v_pk_add_f32 v[32:33], v[34:35], 1.0 op_sel_hi:[1,0]
	v_fmamk_f32 v24, v25, 0xbfb8aa3b, v79
	v_mul_f32_e32 v23, v32, v33
	v_rcp_f32_e32 v23, v23
	v_mul_f32_e32 v19, v20, v19
	v_lshlrev_b32_e32 v20, 16, v165
	v_mul_f32_e32 v19, v19, v20
	v_fmamk_f32 v21, v21, 0xbfb8aa3b, v78
	v_cvt_pk_bf16_f32 v31, v31, v19
	v_mul_f32_e32 v19, v33, v23
	v_mul_f32_e32 v23, v32, v23
	v_exp_f32_e32 v32, v24
	v_exp_f32_e32 v33, v21
	v_mul_f32_e32 v19, v58, v19
	v_cvt_pk_bf16_f32 v21, v19, 0
	v_lshlrev_b32_e32 v21, 16, v21
	v_exp_f32_e32 v25, v21
	v_pk_add_f32 v[34:35], v[32:33], 1.0 op_sel_hi:[1,0]
	ds_bpermute_b32 v37, v146, v36
	v_mul_f32_e32 v21, v34, v35
	v_rcp_f32_e32 v21, v21
	v_fma_f32 v24, -v25, v25, 1.0
	v_max_f32_e32 v24, 0, v24
	v_sqrt_f32_e32 v29, v24
	v_mul_f32_e32 v24, v35, v21
	v_mul_f32_e32 v33, v58, v24
	v_cvt_pk_bf16_f32 v24, v33, 0
	v_lshlrev_b32_e32 v24, 16, v24
	v_exp_f32_e32 v24, v24
	v_mul_f32_e32 v23, v23, v29
	v_lshlrev_b32_e32 v29, 16, v164
	v_mul_f32_e32 v23, v23, v29
	v_fma_f32 v29, -v24, v24, 1.0
	v_max_f32_e32 v29, 0, v29
	v_sqrt_f32_e32 v29, v29
	ds_bpermute_b32 v22, v146, v18
	v_mul_f32_e32 v21, v34, v21
	v_cvt_pk_bf16_f32 v32, v19, v23
	v_mul_f32_e32 v21, v21, v29
	v_lshlrev_b32_e32 v23, 16, v163
	v_mul_f32_e32 v21, v21, v23
	v_cvt_pk_bf16_f32 v33, v33, v21
	v_and_b32_e32 v28, 0xffff0000, v30
	v_and_b32_e32 v20, 0xffff0000, v31
	v_and_b32_e32 v19, 0xffff0000, v32
	v_and_b32_e32 v34, 0xffff0000, v33
	s_and_b64 vcc, exec, s[48:49]
	s_mov_b64 s[30:31], -1
	global_store_dwordx4 v[68:69], v[30:33], off offset:576 nt
	s_cbranch_vccnz .LBB0_859
	v_fma_f32 v21, 0, v26, v28
	v_fma_f32 v21, v27, v21, v20
	v_mul_f32_e32 v31, v26, v27
	v_fma_f32 v30, v25, v21, v19
	v_pk_mul_f32 v[32:33], v[24:25], v[30:31]
	v_mov_b32_e32 v35, v24
	v_pk_fma_f32 v[30:31], v[24:25], v[30:31], v[34:35]
	v_pk_mul_f32 v[32:33], v[32:33], v[34:35]
	s_mov_b64 s[30:31], 0

;     template <int QVV> __device__ __forceinline__ void run(f32x4 (&acc)[2][2][4][2], const Unit& u, int wr, int wc, int fr, int fq) const {
;     ...
;                     for (int i = 0; i < 4; ++i) {
;                         const float er = 1.0f + __builtin_amdgcn_exp2f(__builtin_fmaf(acc[ai][0][m][n][i], -LOG2E, bavn)), ei = 1.0f + __builtin_amdgcn_exp2f(__builtin_fmaf(acc[ai][1][m][n][i], -LOG2E, bxvn));
;                         const float rr = __builtin_amdgcn_rcpf(er * ei), rgt = rr * ei, igt = rr * er;
;                         const float l2 = c8l * rgt;
;                         const float a1 = __builtin_amdgcn_exp2f(__uint_as_float(pk2(l2, 0.f) << 16));
;                         const float mult = __builtin_amdgcn_sqrtf(fmaxf(__builtin_fmaf(-a1, a1, 1.0f), 0.0f));
;                         w[i] = pk2(l2, mult * igt * __uint_as_float((unsigned)xw[n][ai][m][i] << 16));
;                         av[i] = a1; uv[i] = __uint_as_float(w[i] & 0xffff0000u);
;                     }
;                     *(u32x4*)(lb + ((size_t)ch * MT + tl + (unsigned)(ai * HALF + m * 16)) * 4u) = (u32x4){w[0], w[1], w[2], w[3]};
;                     float P = 1.f, H = 0.f;
;                     if (d == 0) {
; #pragma unroll
;                         for (int i = 0; i < 4; ++i) { H = av[i] * H + uv[i]; P *= av[i]; }
;                     } else {
; #pragma unroll
;                         for (int i = 3; i >= 0; --i) { H = av[i] * H + uv[i]; P *= av[i]; }
;                     }
; #pragma unroll
;                     for (int sft = 16; sft < 64; sft <<= 1) {
;                         const float Pq = __shfl_xor(P, sft), Hq = __shfl_xor(H, sft);
;                         const bool lowhalf = ((lane_hi * 16) & sft) == 0;
;                         const bool mine_first = (d == 0) ? lowhalf : !lowhalf;
;                         const float Px = mine_first ? P : Pq, Hx = mine_first ? H : Hq, Py = mine_first ? Pq : P, Hy = mine_first ? Hq : H;
;                         P = Px * Py; H = Py * Hx + Hy;
.LBB0_861:
	v_fmamk_f32 v14, v14, 0xbfb8aa3b, v79
	v_fmamk_f32 v10, v10, 0xbfb8aa3b, v78
	ds_bpermute_b32 v19, v127, v30
	ds_bpermute_b32 v24, v127, v33
	v_exp_f32_e32 v20, v14
	v_exp_f32_e32 v21, v10
	v_fmamk_f32 v11, v11, 0xbfb8aa3b, v78
	s_waitcnt lgkmcnt(1)
	v_cndmask_b32_e64 v14, v19, v30, s[46:47]
	s_waitcnt lgkmcnt(0)
	v_cndmask_b32_e64 v10, v33, v24, s[46:47]
	v_pk_add_f32 v[20:21], v[20:21], 1.0 op_sel_hi:[1,0]
	v_cndmask_b32_e64 v23, v30, v19, s[46:47]
	v_mul_f32_e32 v19, v33, v24
	v_mul_f32_e32 v24, v20, v21
	v_rcp_f32_e32 v26, v24
	v_fmac_f32_e32 v23, v10, v14
	v_fmamk_f32 v14, v15, 0xbfb8aa3b, v79
	v_exp_f32_e32 v14, v14
	v_mul_f32_e32 v10, v21, v26
	v_mul_f32_e32 v21, v58, v10
	v_cvt_pk_bf16_f32 v10, v21, 0
	v_lshlrev_b32_e32 v10, 16, v10
	v_exp_f32_e32 v10, v10
	v_exp_f32_e32 v15, v11
	v_fmamk_f32 v16, v16, 0xbfb8aa3b, v79
	v_fmamk_f32 v12, v12, 0xbfb8aa3b, v78
	v_fma_f32 v11, -v10, v10, 1.0
	v_pk_add_f32 v[24:25], v[14:15], 1.0 op_sel_hi:[1,0]
	v_max_f32_e32 v11, 0, v11
	v_mul_f32_e32 v14, v24, v25
	v_sqrt_f32_e32 v11, v11
	v_rcp_f32_e32 v15, v14
	v_mul_f32_e32 v14, v20, v26
	v_lshlrev_b32_e32 v20, 16, v162
	v_mul_f32_e32 v14, v14, v11
	v_mul_f32_e32 v11, v25, v15
	v_mul_f32_e32 v25, v58, v11
	v_cvt_pk_bf16_f32 v11, v25, 0
	v_lshlrev_b32_e32 v11, 16, v11
	v_exp_f32_e32 v11, v11
	v_mul_f32_e32 v14, v14, v20
	v_cvt_pk_bf16_f32 v30, v21, v14
	v_exp_f32_e32 v21, v12
	v_fma_f32 v20, -v11, v11, 1.0
	v_max_f32_e32 v20, 0, v20
	v_sqrt_f32_e32 v26, v20
	v_exp_f32_e32 v20, v16
	v_mul_f32_e32 v12, v24, v15
	v_lshlrev_b32_e32 v15, 16, v161
	v_mul_f32_e32 v12, v12, v26
	v_pk_add_f32 v[20:21], v[20:21], 1.0 op_sel_hi:[1,0]
	v_mul_f32_e32 v12, v12, v15
	v_mul_f32_e32 v16, v20, v21
	v_rcp_f32_e32 v16, v16
	v_fmamk_f32 v13, v13, 0xbfb8aa3b, v78
	v_cvt_pk_bf16_f32 v31, v25, v12
	ds_bpermute_b32 v28, v146, v19
	v_mul_f32_e32 v15, v21, v16
	v_mul_f32_e32 v24, v20, v16
	v_fmamk_f32 v16, v17, 0xbfb8aa3b, v79
	v_exp_f32_e32 v20, v16
	v_exp_f32_e32 v21, v13
	v_mul_f32_e32 v15, v58, v15
	v_cvt_pk_bf16_f32 v13, v15, 0
	v_lshlrev_b32_e32 v13, 16, v13
	v_exp_f32_e32 v17, v13
	v_pk_add_f32 v[20:21], v[20:21], 1.0 op_sel_hi:[1,0]
	ds_bpermute_b32 v29, v146, v23
	v_mul_f32_e32 v13, v20, v21
	v_rcp_f32_e32 v13, v13
	v_fma_f32 v16, -v17, v17, 1.0
	v_max_f32_e32 v16, 0, v16
	v_sqrt_f32_e32 v25, v16
	v_mul_f32_e32 v16, v21, v13
	v_mul_f32_e32 v21, v58, v16
	v_cvt_pk_bf16_f32 v16, v21, 0
	v_lshlrev_b32_e32 v16, 16, v16
	v_exp_f32_e32 v16, v16
	v_mul_f32_e32 v24, v24, v25
	v_lshlrev_b32_e32 v25, 16, v160
	v_mul_f32_e32 v24, v24, v25
	v_fma_f32 v25, -v16, v16, 1.0
	v_max_f32_e32 v25, 0, v25
	v_sqrt_f32_e32 v25, v25
	v_mul_f32_e32 v13, v20, v13
	v_lshlrev_b32_e32 v20, 16, v159
	v_cvt_pk_bf16_f32 v32, v15, v24
	v_mul_f32_e32 v13, v13, v25
	v_mul_f32_e32 v13, v13, v20
	v_cvt_pk_bf16_f32 v33, v21, v13
	v_and_b32_e32 v14, 0xffff0000, v30
	v_and_b32_e32 v12, 0xffff0000, v31
	v_and_b32_e32 v15, 0xffff0000, v32
	v_and_b32_e32 v26, 0xffff0000, v33
	s_and_b64 vcc, exec, s[48:49]
	s_mov_b64 s[30:31], -1
	global_store_dwordx4 v[68:69], v[30:33], off offset:640 nt
	s_cbranch_vccnz .LBB0_863
	v_fma_f32 v13, 0, v10, v14
	v_fma_f32 v13, v11, v13, v12
	v_mul_f32_e32 v21, v10, v11
	v_fma_f32 v20, v17, v13, v15
	v_pk_mul_f32 v[24:25], v[16:17], v[20:21]
	v_mov_b32_e32 v27, v16
	v_pk_fma_f32 v[20:21], v[16:17], v[20:21], v[26:27]
	v_pk_mul_f32 v[24:25], v[24:25], v[26:27]
	s_mov_b64 s[30:31], 0

;     template <int QVV> __device__ __forceinline__ void run(f32x4 (&acc)[2][2][4][2], const Unit& u, int wr, int wc, int fr, int fq) const {
;     ...
;                     for (int i = 0; i < 4; ++i) {
;                         const float er = 1.0f + __builtin_amdgcn_exp2f(__builtin_fmaf(acc[ai][0][m][n][i], -LOG2E, bavn)), ei = 1.0f + __builtin_amdgcn_exp2f(__builtin_fmaf(acc[ai][1][m][n][i], -LOG2E, bxvn));
;                         const float rr = __builtin_amdgcn_rcpf(er * ei), rgt = rr * ei, igt = rr * er;
;                         const float l2 = c8l * rgt;
;                         const float a1 = __builtin_amdgcn_exp2f(__uint_as_float(pk2(l2, 0.f) << 16));
;                         const float mult = __builtin_amdgcn_sqrtf(fmaxf(__builtin_fmaf(-a1, a1, 1.0f), 0.0f));
;                         w[i] = pk2(l2, mult * igt * __uint_as_float((unsigned)xw[n][ai][m][i] << 16));
;                         av[i] = a1; uv[i] = __uint_as_float(w[i] & 0xffff0000u);
;                     }
;                     *(u32x4*)(lb + ((size_t)ch * MT + tl + (unsigned)(ai * HALF + m * 16)) * 4u) = (u32x4){w[0], w[1], w[2], w[3]};
;                     float P = 1.f, H = 0.f;
;                     if (d == 0) {
; #pragma unroll
;                         for (int i = 0; i < 4; ++i) { H = av[i] * H + uv[i]; P *= av[i]; }
;                     } else {
; #pragma unroll
;                         for (int i = 3; i >= 0; --i) { H = av[i] * H + uv[i]; P *= av[i]; }
;                     }
; #pragma unroll
;                     for (int sft = 16; sft < 64; sft <<= 1) {
;                         const float Pq = __shfl_xor(P, sft), Hq = __shfl_xor(H, sft);
;                         const bool lowhalf = ((lane_hi * 16) & sft) == 0;
;                         const bool mine_first = (d == 0) ? lowhalf : !lowhalf;
;                         const float Px = mine_first ? P : Pq, Hx = mine_first ? H : Hq, Py = mine_first ? Pq : P, Hy = mine_first ? Hq : H;
;                         P = Px * Py; H = Py * Hx + Hy;
.LBB0_865:
	v_fmamk_f32 v6, v6, 0xbfb8aa3b, v79
	v_fmamk_f32 v2, v2, 0xbfb8aa3b, v78
	ds_bpermute_b32 v12, v127, v20
	v_exp_f32_e32 v10, v6
	v_exp_f32_e32 v11, v2
	ds_bpermute_b32 v13, v127, v25
	v_fmamk_f32 v3, v3, 0xbfb8aa3b, v78
	s_waitcnt lgkmcnt(1)
	v_cndmask_b32_e64 v6, v12, v20, s[46:47]
	v_pk_add_f32 v[10:11], v[10:11], 1.0 op_sel_hi:[1,0]
	v_cndmask_b32_e64 v17, v20, v12, s[46:47]
	v_mul_f32_e32 v12, v10, v11
	v_rcp_f32_e32 v14, v12
	s_waitcnt lgkmcnt(0)
	v_cndmask_b32_e64 v2, v25, v13, s[46:47]
	v_fmac_f32_e32 v17, v2, v6
	v_fmamk_f32 v6, v7, 0xbfb8aa3b, v79
	v_mul_f32_e32 v2, v11, v14
	v_mul_f32_e32 v11, v58, v2
	v_cvt_pk_bf16_f32 v2, v11, 0
	v_lshlrev_b32_e32 v2, 16, v2
	v_exp_f32_e32 v2, v2
	v_exp_f32_e32 v6, v6
	v_exp_f32_e32 v7, v3
	v_mul_f32_e32 v16, v25, v13
	v_fma_f32 v3, -v2, v2, 1.0
	v_max_f32_e32 v3, 0, v3
	v_pk_add_f32 v[12:13], v[6:7], 1.0 op_sel_hi:[1,0]
	v_sqrt_f32_e32 v3, v3
	v_mul_f32_e32 v6, v12, v13
	v_rcp_f32_e32 v7, v6
	v_mul_f32_e32 v6, v10, v14
	v_mul_f32_e32 v6, v6, v3
	v_fmamk_f32 v8, v8, 0xbfb8aa3b, v79
	v_mul_f32_e32 v3, v13, v7
	v_mul_f32_e32 v24, v58, v3
	v_cvt_pk_bf16_f32 v3, v24, 0
	v_lshlrev_b32_e32 v3, 16, v3
	v_exp_f32_e32 v3, v3
	v_fmamk_f32 v4, v4, 0xbfb8aa3b, v78
	v_lshlrev_b32_e32 v10, 16, v158
	v_exp_f32_e32 v14, v8
	v_exp_f32_e32 v15, v4
	v_mul_f32_e32 v6, v6, v10
	v_cvt_pk_bf16_f32 v10, v11, v6
	v_fma_f32 v11, -v3, v3, 1.0
	v_max_f32_e32 v11, 0, v11
	v_sqrt_f32_e32 v11, v11
	v_mul_f32_e32 v4, v12, v7
	v_pk_add_f32 v[12:13], v[14:15], 1.0 op_sel_hi:[1,0]
	v_lshlrev_b32_e32 v7, 16, v157
	v_mul_f32_e32 v8, v12, v13
	v_rcp_f32_e32 v8, v8
	v_mul_f32_e32 v4, v4, v11
	v_mul_f32_e32 v4, v4, v7
	v_fmac_f32_e32 v79, 0xbfb8aa3b, v9
	v_fmac_f32_e32 v78, 0xbfb8aa3b, v5
	v_cvt_pk_bf16_f32 v11, v24, v4
	v_mul_f32_e32 v7, v13, v8
	v_mul_f32_e32 v24, v12, v8
	v_exp_f32_e32 v12, v79
	v_exp_f32_e32 v13, v78
	v_mul_f32_e32 v7, v58, v7
	v_cvt_pk_bf16_f32 v5, v7, 0
	v_lshlrev_b32_e32 v5, 16, v5
	v_exp_f32_e32 v9, v5
	v_pk_add_f32 v[14:15], v[12:13], 1.0 op_sel_hi:[1,0]
	ds_bpermute_b32 v20, v146, v16
	v_mul_f32_e32 v5, v14, v15
	v_rcp_f32_e32 v5, v5
	v_fma_f32 v8, -v9, v9, 1.0
	v_max_f32_e32 v8, 0, v8
	v_sqrt_f32_e32 v12, v8
	v_mul_f32_e32 v8, v15, v5
	v_mul_f32_e32 v13, v58, v8
	v_cvt_pk_bf16_f32 v8, v13, 0
	v_lshlrev_b32_e32 v8, 16, v8
	v_exp_f32_e32 v8, v8
	v_mul_f32_e32 v12, v24, v12
	v_lshlrev_b32_e32 v15, 16, v156
	v_mul_f32_e32 v12, v12, v15
	v_fma_f32 v15, -v8, v8, 1.0
	v_max_f32_e32 v15, 0, v15
	v_sqrt_f32_e32 v15, v15
	ds_bpermute_b32 v21, v146, v17
	v_mul_f32_e32 v5, v14, v5
	v_lshlrev_b32_e32 v14, 16, v155
	v_mul_f32_e32 v5, v5, v15
	v_mul_f32_e32 v5, v5, v14
	v_cvt_pk_bf16_f32 v12, v7, v12
	v_cvt_pk_bf16_f32 v13, v13, v5
	v_and_b32_e32 v6, 0xffff0000, v10
	v_and_b32_e32 v4, 0xffff0000, v11
	v_and_b32_e32 v7, 0xffff0000, v12
	v_and_b32_e32 v14, 0xffff0000, v13
	s_and_b64 vcc, exec, s[48:49]
	s_mov_b64 s[30:31], -1
	global_store_dwordx4 v[68:69], v[10:13], off offset:704 nt
	s_cbranch_vccnz .LBB0_867
	v_fma_f32 v5, 0, v2, v6
	v_fma_f32 v5, v3, v5, v4
	v_mul_f32_e32 v11, v2, v3
	v_fma_f32 v10, v9, v5, v7
	v_pk_mul_f32 v[24:25], v[8:9], v[10:11]
	v_mov_b32_e32 v15, v8
	v_pk_fma_f32 v[12:13], v[8:9], v[10:11], v[14:15]
	v_pk_mul_f32 v[10:11], v[24:25], v[14:15]
	s_mov_b64 s[30:31], 0

; #define LAS __attribute__((address_space(3)))
; #define GAS __attribute__((address_space(1)))
; #define LDS_WAIT() asm volatile("s_waitcnt lgkmcnt(0)" ::: "memory")
; __device__ __forceinline__ void transpose_item(const float* W, int K, int N, bf16_t* WT, int k0, int n0, int drow0, LAS float* scr, int lane) {
;     f32x4 v[8];
; #pragma unroll
;     for (int j = 0; j < 8; ++j) v[j] = *(const f32x4*)(W + (size_t)(k0 + (lane >> 3) + 8 * j) * N + n0 + 4 * (lane & 7));
; #pragma unroll
;     for (int j = 0; j < 8; ++j) { LAS float* d = scr + ((lane >> 3) + 8 * j) * 33 + 4 * (lane & 7); d[0] = v[j].x; d[1] = v[j].y; d[2] = v[j].z; d[3] = v[j].w; }
;     LDS_WAIT(); asm volatile("" ::: "memory");
;     const int c = lane & 7;
; #pragma unroll
;     for (int j = 0; j < 4; ++j) { const int n = (lane >> 3) + 8 * j; const LAS float* s = scr + (8 * c) * 33 + n;
;         u32x4 o; o.x = pk2(s[0 * 33], s[1 * 33]); o.y = pk2(s[2 * 33], s[3 * 33]); o.z = pk2(s[4 * 33], s[5 * 33]); o.w = pk2(s[6 * 33], s[7 * 33]);
;         *(GAS u32x4*)(WT + (size_t)(drow0 + n) * K + k0 + 8 * c) = o; }
;     LDS_WAIT(); asm volatile("" ::: "memory");
; }
; __device__ __forceinline__ void transpose_matrix(const float* W, int K, int N, bf16_t* WT, int rowmode, LAS float* scr, int gw, int ngw, int lane) {
;     const int nblk = N / 32, nitems = (K / 64) * nblk;
;     for (int it = gw; it < nitems; it += ngw) {
;         const int kb = it / nblk, nb = it - kb * nblk, n0 = 32 * nb;
;         int drow0 = n0;
;         if (rowmode == 1) { const int up = n0 >= DFF, j0 = up ? n0 - DFF : n0; drow0 = 256 * (j0 >> 7) + 128 * up + (j0 & 127); }
;         if (rowmode == 2 && n0 >= 5120 && n0 < 6400) {
;             const int tb = 5120 + (((n0 - 5120) >> 8) << 8), hh = ((n0 - tb) >> 7) & 1, d0 = (n0 - tb) & 127; drow0 = tb + ((d0 & 32) ? 128 : 0) + hh * 64 + ((d0 >> 6) << 5); }
;         if (rowmode == 2 && n0 >= 3072 && n0 < 5120) { const int wh = n0 >= 4096, j0 = n0 - 3072 - wh * 1024; drow0 = 3072 + 256 * (j0 >> 7) + 128 * wh + (j0 & 127); }
;         transpose_item(W, K, N, WT, 64 * kb, n0, drow0, scr, lane);
.LBB0_940:
	s_mul_hi_i32 s7, s5, 0x2fa0be83
	s_lshr_b32 s8, s7, 31
	s_ashr_i32 s7, s7, 6
	s_add_i32 s9, s7, s8
	s_mul_i32 s8, s9, 0xffffd500
	s_mul_i32 s7, s9, 0xfffffea8
	s_add_i32 s8, s1, s8
	s_add_i32 s7, s5, s7
	s_add_i32 s11, s8, 0xffffea80
	s_cmpk_gt_i32 s7, 0xab
	s_cselect_b32 s7, s11, s8
	s_cselect_b32 s11, 0x80, 0
	s_lshl_b32 s30, s9, 6
	s_ashr_i32 s9, s8, 31
	v_or_b32_e32 v39, s30, v27
	v_lshl_add_u64 v[2:3], s[8:9], 2, v[28:29]
	v_mad_i64_i32 v[4:5], s[8:9], v39, s27, v[2:3]
	global_load_dwordx4 v[40:43], v[4:5], off
	v_or_b32_e32 v4, 8, v39
	v_mad_i64_i32 v[4:5], s[8:9], v4, s27, v[2:3]
	global_load_dwordx4 v[44:47], v[4:5], off
	v_or_b32_e32 v4, 16, v39
	v_mad_i64_i32 v[4:5], s[8:9], v4, s27, v[2:3]
	global_load_dwordx4 v[22:25], v[4:5], off
	v_or_b32_e32 v4, 24, v39
	v_mad_i64_i32 v[4:5], s[8:9], v4, s27, v[2:3]
	global_load_dwordx4 v[18:21], v[4:5], off
	v_or_b32_e32 v4, 32, v39
	v_mad_i64_i32 v[4:5], s[8:9], v4, s27, v[2:3]
	global_load_dwordx4 v[14:17], v[4:5], off
	v_or_b32_e32 v4, 40, v39
	v_mad_i64_i32 v[4:5], s[8:9], v4, s27, v[2:3]
	global_load_dwordx4 v[10:13], v[4:5], off
	v_or_b32_e32 v4, 48, v39
	v_mad_i64_i32 v[4:5], s[8:9], v4, s27, v[2:3]
	global_load_dwordx4 v[6:9], v[4:5], off
	v_or_b32_e32 v4, 56, v39
	v_mad_i64_i32 v[2:3], s[8:9], v4, s27, v[2:3]
	global_load_dwordx4 v[2:5], v[2:3], off
	v_add_u32_e32 v39, 0x420, v37
	s_lshl_b32 s12, s7, 1
	s_and_b32 s7, s7, 0x60
	s_and_b32 s12, s12, 0xffffff00
	s_or_b32 s7, s7, s11
	s_or_b32 s7, s7, s12
	s_ashr_i32 s31, s30, 31
	s_add_i32 s5, s5, s10
	s_add_i32 s1, s1, s2
	s_cmpk_lt_i32 s5, 0x2b00
	s_waitcnt vmcnt(7)
	ds_write2_b32 v37, v40, v41 offset1:1
	ds_write2_b32 v37, v42, v43 offset0:2 offset1:3
	s_waitcnt vmcnt(6)
	ds_write2_b32 v39, v44, v45 offset1:1
	v_add_u32_e32 v39, 0x428, v37
	ds_write2_b32 v39, v46, v47 offset1:1
	v_add_u32_e32 v39, 0x840, v37
	s_waitcnt vmcnt(5)
	ds_write2_b32 v39, v22, v23 offset1:1
	v_add_u32_e32 v22, 0x848, v37
	ds_write2_b32 v22, v24, v25 offset1:1
	v_add_u32_e32 v22, 0xc60, v37
	s_waitcnt vmcnt(4)
	ds_write2_b32 v22, v18, v19 offset1:1
	v_add_u32_e32 v18, 0xc68, v37
	ds_write2_b32 v18, v20, v21 offset1:1
	v_add_u32_e32 v18, 0x1080, v37
	s_waitcnt vmcnt(3)
	ds_write2_b32 v18, v14, v15 offset1:1
	v_add_u32_e32 v14, 0x1088, v37
	ds_write2_b32 v14, v16, v17 offset1:1
	v_add_u32_e32 v14, 0x14a0, v37
	s_waitcnt vmcnt(2)
	ds_write2_b32 v14, v10, v11 offset1:1
	v_add_u32_e32 v10, 0x14a8, v37
	ds_write2_b32 v10, v12, v13 offset1:1
	v_add_u32_e32 v10, 0x18c0, v37
	s_waitcnt vmcnt(1)
	ds_write2_b32 v10, v6, v7 offset1:1
	v_add_u32_e32 v6, 0x18c8, v37
	ds_write2_b32 v6, v8, v9 offset1:1
	v_add_u32_e32 v6, 0x1ce0, v37
	s_waitcnt vmcnt(0)
	ds_write2_b32 v6, v2, v3 offset1:1
	v_add_u32_e32 v2, 0x1ce8, v37
	ds_write2_b32 v2, v4, v5 offset1:1
	s_waitcnt lgkmcnt(0)
	ds_read2_b32 v[8:9], v36 offset0:33 offset1:41
	ds_read2_b32 v[10:11], v36 offset1:8
	ds_read2_b32 v[12:13], v36 offset0:66 offset1:74
	ds_read2_b32 v[14:15], v36 offset0:99 offset1:107
	ds_read2_b32 v[16:17], v36 offset0:132 offset1:140
	ds_read2_b32 v[18:19], v36 offset0:165 offset1:173
	ds_read2_b32 v[20:21], v36 offset0:198 offset1:206
	ds_read2_b32 v[22:23], v36 offset0:231 offset1:239
	v_or_b32_e32 v24, s7, v27
	v_ashrrev_i32_e32 v25, 31, v24
	v_lshl_add_u64 v[6:7], s[30:31], 1, v[30:31]
	v_lshlrev_b64 v[24:25], 12, v[24:25]
	s_waitcnt lgkmcnt(6)
	v_cvt_pk_bf16_f32 v2, v10, v8
	s_waitcnt lgkmcnt(4)
	v_cvt_pk_bf16_f32 v3, v12, v14
	s_waitcnt lgkmcnt(2)
	v_cvt_pk_bf16_f32 v4, v16, v18
	s_waitcnt lgkmcnt(0)
	v_cvt_pk_bf16_f32 v5, v20, v22
	v_lshl_add_u64 v[24:25], v[6:7], 0, v[24:25]
	v_or_b32_e32 v8, s7, v33
	global_store_dwordx4 v[24:25], v[2:5], off nt
	v_or_b32_e32 v24, s7, v34
	v_ashrrev_i32_e32 v25, 31, v24
	v_cvt_pk_bf16_f32 v2, v11, v9
	v_ashrrev_i32_e32 v9, 31, v8
	v_lshlrev_b64 v[8:9], 12, v[8:9]
	v_cvt_pk_bf16_f32 v3, v13, v15
	v_cvt_pk_bf16_f32 v4, v17, v19
	v_cvt_pk_bf16_f32 v5, v21, v23
	v_lshl_add_u64 v[8:9], v[6:7], 0, v[8:9]
	global_store_dwordx4 v[8:9], v[2:5], off nt
	ds_read2_b32 v[8:9], v36 offset0:49 offset1:57
	ds_read2_b32 v[10:11], v36 offset0:16 offset1:24
	ds_read2_b32 v[12:13], v36 offset0:82 offset1:90
	ds_read2_b32 v[14:15], v36 offset0:115 offset1:123
	ds_read2_b32 v[16:17], v36 offset0:148 offset1:156
	ds_read2_b32 v[18:19], v36 offset0:181 offset1:189
	ds_read2_b32 v[20:21], v36 offset0:214 offset1:222
	ds_read2_b32 v[22:23], v36 offset0:247 offset1:255
	v_lshlrev_b64 v[24:25], 12, v[24:25]
	s_waitcnt lgkmcnt(6)
	v_cvt_pk_bf16_f32 v2, v10, v8
	s_waitcnt lgkmcnt(4)
	v_cvt_pk_bf16_f32 v3, v12, v14
	s_waitcnt lgkmcnt(2)
	v_cvt_pk_bf16_f32 v4, v16, v18
	s_waitcnt lgkmcnt(0)
	v_cvt_pk_bf16_f32 v5, v20, v22
	v_lshl_add_u64 v[24:25], v[6:7], 0, v[24:25]
	v_or_b32_e32 v8, s7, v35
	global_store_dwordx4 v[24:25], v[2:5], off nt
	s_nop 1
	v_cvt_pk_bf16_f32 v2, v11, v9
	v_ashrrev_i32_e32 v9, 31, v8
	v_lshlrev_b64 v[8:9], 12, v[8:9]
	v_cvt_pk_bf16_f32 v3, v13, v15
	v_cvt_pk_bf16_f32 v4, v17, v19
	v_cvt_pk_bf16_f32 v5, v21, v23
	v_lshl_add_u64 v[6:7], v[6:7], 0, v[8:9]
	global_store_dwordx4 v[6:7], v[2:5], off nt
	s_waitcnt lgkmcnt(0)
	s_cbranch_scc1 .LBB0_940

; #define LAS __attribute__((address_space(3)))
; #define GAS __attribute__((address_space(1)))
; #define LDS_WAIT() asm volatile("s_waitcnt lgkmcnt(0)" ::: "memory")
; __device__ __forceinline__ void transpose_item(const float* W, int K, int N, bf16_t* WT, int k0, int n0, int drow0, LAS float* scr, int lane) {
;     f32x4 v[8];
; #pragma unroll
;     for (int j = 0; j < 8; ++j) v[j] = *(const f32x4*)(W + (size_t)(k0 + (lane >> 3) + 8 * j) * N + n0 + 4 * (lane & 7));
; #pragma unroll
;     for (int j = 0; j < 8; ++j) { LAS float* d = scr + ((lane >> 3) + 8 * j) * 33 + 4 * (lane & 7); d[0] = v[j].x; d[1] = v[j].y; d[2] = v[j].z; d[3] = v[j].w; }
;     LDS_WAIT(); asm volatile("" ::: "memory");
;     const int c = lane & 7;
; #pragma unroll
;     for (int j = 0; j < 4; ++j) { const int n = (lane >> 3) + 8 * j; const LAS float* s = scr + (8 * c) * 33 + n;
;         u32x4 o; o.x = pk2(s[0 * 33], s[1 * 33]); o.y = pk2(s[2 * 33], s[3 * 33]); o.z = pk2(s[4 * 33], s[5 * 33]); o.w = pk2(s[6 * 33], s[7 * 33]);
;         *(GAS u32x4*)(WT + (size_t)(drow0 + n) * K + k0 + 8 * c) = o; }
;     LDS_WAIT(); asm volatile("" ::: "memory");
; }
; __device__ __forceinline__ void transpose_matrix(const float* W, int K, int N, bf16_t* WT, int rowmode, LAS float* scr, int gw, int ngw, int lane) {
;     const int nblk = N / 32, nitems = (K / 64) * nblk;
;     for (int it = gw; it < nitems; it += ngw) {
;         const int kb = it / nblk, nb = it - kb * nblk, n0 = 32 * nb;
;         int drow0 = n0;
;         if (rowmode == 1) { const int up = n0 >= DFF, j0 = up ? n0 - DFF : n0; drow0 = 256 * (j0 >> 7) + 128 * up + (j0 & 127); }
;         if (rowmode == 2 && n0 >= 5120 && n0 < 6400) {
;             const int tb = 5120 + (((n0 - 5120) >> 8) << 8), hh = ((n0 - tb) >> 7) & 1, d0 = (n0 - tb) & 127; drow0 = tb + ((d0 & 32) ? 128 : 0) + hh * 64 + ((d0 >> 6) << 5); }
;         if (rowmode == 2 && n0 >= 3072 && n0 < 5120) { const int wh = n0 >= 4096, j0 = n0 - 3072 - wh * 1024; drow0 = 3072 + 256 * (j0 >> 7) + 128 * wh + (j0 & 127); }
;         transpose_item(W, K, N, WT, 64 * kb, n0, drow0, scr, lane);
.LBB0_943:
	s_ashr_i32 s7, s5, 31
	s_lshr_b32 s7, s7, 26
	s_add_i32 s7, s5, s7
	s_lshl_b32 s8, s7, 5
	s_and_b32 s8, s8, 0xfffff800
	s_and_b32 s42, s7, 0xffffffc0
	s_sub_i32 s30, s1, s8
	v_or_b32_e32 v44, s42, v24
	s_ashr_i32 s31, s30, 31
	v_ashrrev_i32_e32 v45, 31, v44
	v_or_b32_e32 v6, 8, v44
	v_lshl_add_u64 v[22:23], s[30:31], 2, v[18:19]
	v_lshlrev_b64 v[2:3], 13, v[44:45]
	v_ashrrev_i32_e32 v7, 31, v6
	v_lshl_add_u64 v[2:3], v[22:23], 0, v[2:3]
	v_lshlrev_b64 v[6:7], 13, v[6:7]
	v_or_b32_e32 v10, 16, v44
	global_load_dwordx4 v[2:5], v[2:3], off
	v_lshl_add_u64 v[6:7], v[22:23], 0, v[6:7]
	v_ashrrev_i32_e32 v11, 31, v10
	global_load_dwordx4 v[6:9], v[6:7], off
	v_lshlrev_b64 v[10:11], 13, v[10:11]
	v_or_b32_e32 v14, 24, v44
	v_lshl_add_u64 v[10:11], v[22:23], 0, v[10:11]
	v_ashrrev_i32_e32 v15, 31, v14
	global_load_dwordx4 v[10:13], v[10:11], off
	v_lshlrev_b64 v[14:15], 13, v[14:15]
	v_or_b32_e32 v28, 32, v44
	v_lshl_add_u64 v[14:15], v[22:23], 0, v[14:15]
	v_ashrrev_i32_e32 v29, 31, v28
	global_load_dwordx4 v[14:17], v[14:15], off
	v_lshlrev_b64 v[28:29], 13, v[28:29]
	v_or_b32_e32 v34, 40, v44
	v_lshl_add_u64 v[28:29], v[22:23], 0, v[28:29]
	v_ashrrev_i32_e32 v35, 31, v34
	global_load_dwordx4 v[28:31], v[28:29], off
	v_lshlrev_b64 v[34:35], 13, v[34:35]
	v_or_b32_e32 v40, 48, v44
	v_lshl_add_u64 v[34:35], v[22:23], 0, v[34:35]
	v_ashrrev_i32_e32 v41, 31, v40
	global_load_dwordx4 v[34:37], v[34:35], off
	v_lshlrev_b64 v[40:41], 13, v[40:41]
	v_or_b32_e32 v44, 56, v44
	v_lshl_add_u64 v[40:41], v[22:23], 0, v[40:41]
	v_ashrrev_i32_e32 v45, 31, v44
	global_load_dwordx4 v[40:43], v[40:41], off
	v_lshlrev_b64 v[44:45], 13, v[44:45]
	v_lshl_add_u64 v[22:23], v[22:23], 0, v[44:45]
	global_load_dwordx4 v[44:47], v[22:23], off
	s_ashr_i32 s43, s42, 31
	v_add_u32_e32 v33, s30, v24
	s_add_i32 s5, s5, s10
	s_add_i32 s1, s1, s2
	s_cmpk_lt_i32 s5, 0x1580
	s_waitcnt vmcnt(7)
	ds_write2_b32 v27, v2, v3 offset1:1
	ds_write2_b32 v27, v4, v5 offset0:2 offset1:3
	v_add_u32_e32 v2, 0x420, v27
	s_waitcnt vmcnt(6)
	ds_write2_b32 v2, v6, v7 offset1:1
	v_add_u32_e32 v2, 0x428, v27
	ds_write2_b32 v2, v8, v9 offset1:1
	v_add_u32_e32 v2, 0x840, v27
	v_lshl_add_u64 v[6:7], s[42:43], 1, v[20:21]
	s_waitcnt vmcnt(5)
	ds_write2_b32 v2, v10, v11 offset1:1
	v_add_u32_e32 v2, 0x848, v27
	ds_write2_b32 v2, v12, v13 offset1:1
	v_add_u32_e32 v2, 0xc60, v27
	s_waitcnt vmcnt(4)
	ds_write2_b32 v2, v14, v15 offset1:1
	v_add_u32_e32 v2, 0xc68, v27
	ds_write2_b32 v2, v16, v17 offset1:1
	v_add_u32_e32 v2, 0x1080, v27
	s_waitcnt vmcnt(3)
	ds_write2_b32 v2, v28, v29 offset1:1
	v_add_u32_e32 v2, 0x1088, v27
	ds_write2_b32 v2, v30, v31 offset1:1
	v_add_u32_e32 v2, 0x14a0, v27
	s_waitcnt vmcnt(2)
	ds_write2_b32 v2, v34, v35 offset1:1
	v_add_u32_e32 v2, 0x14a8, v27
	ds_write2_b32 v2, v36, v37 offset1:1
	v_add_u32_e32 v2, 0x18c0, v27
	v_mad_i64_i32 v[34:35], s[8:9], v33, s57, v[6:7]
	s_waitcnt vmcnt(1)
	ds_write2_b32 v2, v40, v41 offset1:1
	v_add_u32_e32 v2, 0x18c8, v27
	ds_write2_b32 v2, v42, v43 offset1:1
	v_add_u32_e32 v2, 0x1ce0, v27
	s_waitcnt vmcnt(0)
	ds_write2_b32 v2, v44, v45 offset1:1
	v_add_u32_e32 v2, 0x1ce8, v27
	ds_write2_b32 v2, v46, v47 offset1:1
	s_waitcnt lgkmcnt(0)
	ds_read2_b32 v[8:9], v25 offset0:33 offset1:41
	ds_read2_b32 v[10:11], v25 offset1:8
	ds_read2_b32 v[12:13], v25 offset0:66 offset1:74
	ds_read2_b32 v[14:15], v25 offset0:99 offset1:107
	ds_read2_b32 v[16:17], v25 offset0:132 offset1:140
	ds_read2_b32 v[22:23], v25 offset0:165 offset1:173
	ds_read2_b32 v[28:29], v25 offset0:198 offset1:206
	ds_read2_b32 v[30:31], v25 offset0:231 offset1:239
	s_waitcnt lgkmcnt(6)
	v_cvt_pk_bf16_f32 v2, v10, v8
	s_waitcnt lgkmcnt(4)
	v_cvt_pk_bf16_f32 v3, v12, v14
	s_waitcnt lgkmcnt(2)
	v_cvt_pk_bf16_f32 v4, v16, v22
	s_waitcnt lgkmcnt(0)
	v_cvt_pk_bf16_f32 v5, v28, v30
	v_add_u32_e32 v8, 8, v33
	global_store_dwordx4 v[34:35], v[2:5], off nt
	s_nop 1
	v_cvt_pk_bf16_f32 v2, v11, v9
	v_cvt_pk_bf16_f32 v3, v13, v15
	v_cvt_pk_bf16_f32 v4, v17, v23
	v_cvt_pk_bf16_f32 v5, v29, v31
	v_mad_i64_i32 v[8:9], s[8:9], v8, s57, v[6:7]
	global_store_dwordx4 v[8:9], v[2:5], off nt
	ds_read2_b32 v[8:9], v25 offset0:49 offset1:57
	ds_read2_b32 v[10:11], v25 offset0:16 offset1:24
	ds_read2_b32 v[12:13], v25 offset0:82 offset1:90
	ds_read2_b32 v[14:15], v25 offset0:115 offset1:123
	ds_read2_b32 v[16:17], v25 offset0:148 offset1:156
	ds_read2_b32 v[22:23], v25 offset0:181 offset1:189
	ds_read2_b32 v[28:29], v25 offset0:214 offset1:222
	ds_read2_b32 v[30:31], v25 offset0:247 offset1:255
	s_waitcnt lgkmcnt(6)
	v_cvt_pk_bf16_f32 v2, v10, v8
	v_add_u32_e32 v8, 16, v33
	s_waitcnt lgkmcnt(4)
	v_cvt_pk_bf16_f32 v3, v12, v14
	s_waitcnt lgkmcnt(2)
	v_cvt_pk_bf16_f32 v4, v16, v22
	s_waitcnt lgkmcnt(0)
	v_cvt_pk_bf16_f32 v5, v28, v30
	v_mad_i64_i32 v[34:35], s[8:9], v8, s57, v[6:7]
	v_add_u32_e32 v8, 24, v33
	global_store_dwordx4 v[34:35], v[2:5], off nt
	v_mad_i64_i32 v[6:7], s[8:9], v8, s57, v[6:7]
	s_nop 0
	v_cvt_pk_bf16_f32 v2, v11, v9
	v_cvt_pk_bf16_f32 v3, v13, v15
	v_cvt_pk_bf16_f32 v4, v17, v23
	v_cvt_pk_bf16_f32 v5, v29, v31
	global_store_dwordx4 v[6:7], v[2:5], off nt
	s_waitcnt lgkmcnt(0)
	s_cbranch_scc1 .LBB0_943

; #define LAS __attribute__((address_space(3)))
; #define GAS __attribute__((address_space(1)))
; #define LDS_WAIT() asm volatile("s_waitcnt lgkmcnt(0)" ::: "memory")
; __device__ __forceinline__ void transpose_item(const float* W, int K, int N, bf16_t* WT, int k0, int n0, int drow0, LAS float* scr, int lane) {
;     f32x4 v[8];
; #pragma unroll
;     for (int j = 0; j < 8; ++j) v[j] = *(const f32x4*)(W + (size_t)(k0 + (lane >> 3) + 8 * j) * N + n0 + 4 * (lane & 7));
; #pragma unroll
;     for (int j = 0; j < 8; ++j) { LAS float* d = scr + ((lane >> 3) + 8 * j) * 33 + 4 * (lane & 7); d[0] = v[j].x; d[1] = v[j].y; d[2] = v[j].z; d[3] = v[j].w; }
;     LDS_WAIT(); asm volatile("" ::: "memory");
;     const int c = lane & 7;
; #pragma unroll
;     for (int j = 0; j < 4; ++j) { const int n = (lane >> 3) + 8 * j; const LAS float* s = scr + (8 * c) * 33 + n;
;         u32x4 o; o.x = pk2(s[0 * 33], s[1 * 33]); o.y = pk2(s[2 * 33], s[3 * 33]); o.z = pk2(s[4 * 33], s[5 * 33]); o.w = pk2(s[6 * 33], s[7 * 33]);
;         *(GAS u32x4*)(WT + (size_t)(drow0 + n) * K + k0 + 8 * c) = o; }
;     LDS_WAIT(); asm volatile("" ::: "memory");
; }
; __device__ __forceinline__ void transpose_matrix(const float* W, int K, int N, bf16_t* WT, int rowmode, LAS float* scr, int gw, int ngw, int lane) {
;     const int nblk = N / 32, nitems = (K / 64) * nblk;
;     for (int it = gw; it < nitems; it += ngw) {
;         const int kb = it / nblk, nb = it - kb * nblk, n0 = 32 * nb;
;         int drow0 = n0;
;         if (rowmode == 1) { const int up = n0 >= DFF, j0 = up ? n0 - DFF : n0; drow0 = 256 * (j0 >> 7) + 128 * up + (j0 & 127); }
;         if (rowmode == 2 && n0 >= 5120 && n0 < 6400) {
;             const int tb = 5120 + (((n0 - 5120) >> 8) << 8), hh = ((n0 - tb) >> 7) & 1, d0 = (n0 - tb) & 127; drow0 = tb + ((d0 & 32) ? 128 : 0) + hh * 64 + ((d0 >> 6) << 5); }
;         if (rowmode == 2 && n0 >= 3072 && n0 < 5120) { const int wh = n0 >= 4096, j0 = n0 - 3072 - wh * 1024; drow0 = 3072 + 256 * (j0 >> 7) + 128 * wh + (j0 & 127); }
;         transpose_item(W, K, N, WT, 64 * kb, n0, drow0, scr, lane);
.LBB0_948:
	s_lshl_b32 s30, s12, 6
	v_or_b32_e32 v28, s30, v32
	s_ashr_i32 s43, s42, 31
	v_lshl_add_u64 v[8:9], s[42:43], 2, v[4:5]
	v_or_b32_e32 v16, 8, v28
	v_mad_i64_i32 v[12:13], s[12:13], v28, s16, v[8:9]
	v_mad_i64_i32 v[16:17], s[12:13], v16, s16, v[8:9]
	global_load_dwordx4 v[12:15], v[12:13], off
	v_or_b32_e32 v20, 16, v28
	global_load_dwordx4 v[16:19], v[16:17], off
	v_mad_i64_i32 v[20:21], s[12:13], v20, s16, v[8:9]
	global_load_dwordx4 v[20:23], v[20:21], off
	v_or_b32_e32 v24, 24, v28
	v_mad_i64_i32 v[24:25], s[12:13], v24, s16, v[8:9]
	global_load_dwordx4 v[34:37], v[24:25], off
	v_or_b32_e32 v24, 32, v28
	v_mad_i64_i32 v[24:25], s[12:13], v24, s16, v[8:9]
	global_load_dwordx4 v[46:49], v[24:25], off
	v_or_b32_e32 v24, 40, v28
	v_mad_i64_i32 v[24:25], s[12:13], v24, s16, v[8:9]
	global_load_dwordx4 v[50:53], v[24:25], off
	v_or_b32_e32 v24, 48, v28
	v_mad_i64_i32 v[24:25], s[12:13], v24, s16, v[8:9]
	global_load_dwordx4 v[54:57], v[24:25], off
	v_or_b32_e32 v24, 56, v28
	v_mad_i64_i32 v[8:9], s[12:13], v24, s16, v[8:9]
	global_load_dwordx4 v[58:61], v[8:9], off
	v_add_u32_e32 v8, 0x420, v11
	s_ashr_i32 s31, s30, 31
	s_add_i32 s9, s9, s10
	s_add_i32 s5, s5, s7
	s_add_i32 s8, s8, s2
	s_cmpk_lt_i32 s9, 0x3200
	s_waitcnt vmcnt(7)
	ds_write2_b32 v11, v12, v13 offset1:1
	ds_write2_b32 v11, v14, v15 offset0:2 offset1:3
	s_waitcnt vmcnt(6)
	ds_write2_b32 v8, v16, v17 offset1:1
	v_add_u32_e32 v8, 0x428, v11
	ds_write2_b32 v8, v18, v19 offset1:1
	v_add_u32_e32 v8, 0x840, v11
	s_waitcnt vmcnt(5)
	ds_write2_b32 v8, v20, v21 offset1:1
	v_add_u32_e32 v8, 0x848, v11
	ds_write2_b32 v8, v22, v23 offset1:1
	v_add_u32_e32 v8, 0xc60, v11
	s_waitcnt vmcnt(4)
	ds_write2_b32 v8, v34, v35 offset1:1
	v_add_u32_e32 v8, 0xc68, v11
	ds_write2_b32 v8, v36, v37 offset1:1
	v_add_u32_e32 v8, 0x1080, v11
	s_waitcnt vmcnt(3)
	ds_write2_b32 v8, v46, v47 offset1:1
	v_add_u32_e32 v8, 0x1088, v11
	ds_write2_b32 v8, v48, v49 offset1:1
	v_add_u32_e32 v8, 0x14a0, v11
	s_waitcnt vmcnt(2)
	ds_write2_b32 v8, v50, v51 offset1:1
	v_add_u32_e32 v8, 0x14a8, v11
	ds_write2_b32 v8, v52, v53 offset1:1
	v_add_u32_e32 v8, 0x18c0, v11
	s_waitcnt vmcnt(1)
	ds_write2_b32 v8, v54, v55 offset1:1
	v_add_u32_e32 v8, 0x18c8, v11
	ds_write2_b32 v8, v56, v57 offset1:1
	v_add_u32_e32 v8, 0x1ce0, v11
	s_waitcnt vmcnt(0)
	ds_write2_b32 v8, v58, v59 offset1:1
	v_add_u32_e32 v8, 0x1ce8, v11
	ds_write2_b32 v8, v60, v61 offset1:1
	s_waitcnt lgkmcnt(0)
	ds_read2_b32 v[16:17], v10 offset0:33 offset1:41
	ds_read2_b32 v[18:19], v10 offset1:8
	ds_read2_b32 v[20:21], v10 offset0:66 offset1:74
	ds_read2_b32 v[22:23], v10 offset0:99 offset1:107
	ds_read2_b32 v[24:25], v10 offset0:132 offset1:140
	ds_read2_b32 v[28:29], v10 offset0:165 offset1:173
	ds_read2_b32 v[34:35], v10 offset0:198 offset1:206
	ds_read2_b32 v[36:37], v10 offset0:231 offset1:239
	v_add_u32_e32 v46, s11, v32
	v_ashrrev_i32_e32 v47, 31, v46
	v_lshl_add_u64 v[8:9], s[30:31], 1, v[6:7]
	v_lshlrev_b64 v[46:47], 12, v[46:47]
	s_waitcnt lgkmcnt(6)
	v_cvt_pk_bf16_f32 v12, v18, v16
	s_waitcnt lgkmcnt(4)
	v_cvt_pk_bf16_f32 v13, v20, v22
	s_waitcnt lgkmcnt(2)
	v_cvt_pk_bf16_f32 v14, v24, v28
	s_waitcnt lgkmcnt(0)
	v_cvt_pk_bf16_f32 v15, v34, v36
	v_lshl_add_u64 v[46:47], v[8:9], 0, v[46:47]
	v_add_u32_e32 v16, s11, v40
	global_store_dwordx4 v[46:47], v[12:15], off nt
	v_add_u32_e32 v46, s11, v42
	v_ashrrev_i32_e32 v47, 31, v46
	v_cvt_pk_bf16_f32 v12, v19, v17
	v_ashrrev_i32_e32 v17, 31, v16
	v_lshlrev_b64 v[16:17], 12, v[16:17]
	v_cvt_pk_bf16_f32 v13, v21, v23
	v_cvt_pk_bf16_f32 v14, v25, v29
	v_cvt_pk_bf16_f32 v15, v35, v37
	v_lshl_add_u64 v[16:17], v[8:9], 0, v[16:17]
	global_store_dwordx4 v[16:17], v[12:15], off nt
	ds_read2_b32 v[16:17], v10 offset0:49 offset1:57
	ds_read2_b32 v[18:19], v10 offset0:16 offset1:24
	ds_read2_b32 v[20:21], v10 offset0:82 offset1:90
	ds_read2_b32 v[22:23], v10 offset0:115 offset1:123
	ds_read2_b32 v[24:25], v10 offset0:148 offset1:156
	ds_read2_b32 v[28:29], v10 offset0:181 offset1:189
	ds_read2_b32 v[34:35], v10 offset0:214 offset1:222
	ds_read2_b32 v[36:37], v10 offset0:247 offset1:255
	v_lshlrev_b64 v[46:47], 12, v[46:47]
	s_waitcnt lgkmcnt(6)
	v_cvt_pk_bf16_f32 v12, v18, v16
	s_waitcnt lgkmcnt(4)
	v_cvt_pk_bf16_f32 v13, v20, v22
	s_waitcnt lgkmcnt(2)
	v_cvt_pk_bf16_f32 v14, v24, v28
	s_waitcnt lgkmcnt(0)
	v_cvt_pk_bf16_f32 v15, v34, v36
	v_lshl_add_u64 v[46:47], v[8:9], 0, v[46:47]
	v_add_u32_e32 v16, s11, v44
	global_store_dwordx4 v[46:47], v[12:15], off nt
	s_nop 1
	v_cvt_pk_bf16_f32 v12, v19, v17
	v_ashrrev_i32_e32 v17, 31, v16
	v_lshlrev_b64 v[16:17], 12, v[16:17]
	v_cvt_pk_bf16_f32 v13, v21, v23
	v_cvt_pk_bf16_f32 v14, v25, v29
	v_cvt_pk_bf16_f32 v15, v35, v37
	v_lshl_add_u64 v[8:9], v[8:9], 0, v[16:17]
	global_store_dwordx4 v[8:9], v[12:15], off nt
	s_waitcnt lgkmcnt(0)
	s_cbranch_scc0 .LBB0_951

; #define LAS __attribute__((address_space(3)))
; #define GAS __attribute__((address_space(1)))
; #define LDS_WAIT() asm volatile("s_waitcnt lgkmcnt(0)" ::: "memory")
; __device__ __forceinline__ void transpose_item(const float* W, int K, int N, bf16_t* WT, int k0, int n0, int drow0, LAS float* scr, int lane) {
;     f32x4 v[8];
; #pragma unroll
;     for (int j = 0; j < 8; ++j) v[j] = *(const f32x4*)(W + (size_t)(k0 + (lane >> 3) + 8 * j) * N + n0 + 4 * (lane & 7));
; #pragma unroll
;     for (int j = 0; j < 8; ++j) { LAS float* d = scr + ((lane >> 3) + 8 * j) * 33 + 4 * (lane & 7); d[0] = v[j].x; d[1] = v[j].y; d[2] = v[j].z; d[3] = v[j].w; }
;     LDS_WAIT(); asm volatile("" ::: "memory");
;     const int c = lane & 7;
; #pragma unroll
;     for (int j = 0; j < 4; ++j) { const int n = (lane >> 3) + 8 * j; const LAS float* s = scr + (8 * c) * 33 + n;
;         u32x4 o; o.x = pk2(s[0 * 33], s[1 * 33]); o.y = pk2(s[2 * 33], s[3 * 33]); o.z = pk2(s[4 * 33], s[5 * 33]); o.w = pk2(s[6 * 33], s[7 * 33]);
;         *(GAS u32x4*)(WT + (size_t)(drow0 + n) * K + k0 + 8 * c) = o; }
;     LDS_WAIT(); asm volatile("" ::: "memory");
; }
; __device__ __forceinline__ void transpose_matrix(const float* W, int K, int N, bf16_t* WT, int rowmode, LAS float* scr, int gw, int ngw, int lane) {
;     const int nblk = N / 32, nitems = (K / 64) * nblk;
;     for (int it = gw; it < nitems; it += ngw) {
;         const int kb = it / nblk, nb = it - kb * nblk, n0 = 32 * nb;
;         int drow0 = n0;
;         if (rowmode == 1) { const int up = n0 >= DFF, j0 = up ? n0 - DFF : n0; drow0 = 256 * (j0 >> 7) + 128 * up + (j0 & 127); }
;         if (rowmode == 2 && n0 >= 5120 && n0 < 6400) {
;             const int tb = 5120 + (((n0 - 5120) >> 8) << 8), hh = ((n0 - tb) >> 7) & 1, d0 = (n0 - tb) & 127; drow0 = tb + ((d0 & 32) ? 128 : 0) + hh * 64 + ((d0 >> 6) << 5); }
;         if (rowmode == 2 && n0 >= 3072 && n0 < 5120) { const int wh = n0 >= 4096, j0 = n0 - 3072 - wh * 1024; drow0 = 3072 + 256 * (j0 >> 7) + 128 * wh + (j0 & 127); }
;         transpose_item(W, K, N, WT, 64 * kb, n0, drow0, scr, lane);
.LBB0_956:
	s_ashr_i32 s7, s5, 31
	s_lshr_b32 s7, s7, 26
	s_add_i32 s7, s5, s7
	s_lshl_b32 s8, s7, 5
	s_and_b32 s8, s8, 0xfffff800
	s_and_b32 s44, s7, 0xffffffc0
	s_sub_i32 s42, s3, s8
	v_or_b32_e32 v56, s44, v46
	s_ashr_i32 s43, s42, 31
	v_ashrrev_i32_e32 v57, 31, v56
	v_or_b32_e32 v6, 8, v56
	v_lshl_add_u64 v[20:21], s[42:43], 2, v[16:17]
	v_lshlrev_b64 v[2:3], 13, v[56:57]
	v_ashrrev_i32_e32 v7, 31, v6
	v_or_b32_e32 v10, 16, v56
	v_lshl_add_u64 v[2:3], v[20:21], 0, v[2:3]
	v_lshlrev_b64 v[6:7], 13, v[6:7]
	v_ashrrev_i32_e32 v11, 31, v10
	v_or_b32_e32 v22, 24, v56
	global_load_dwordx4 v[2:5], v[2:3], off
	v_lshl_add_u64 v[6:7], v[20:21], 0, v[6:7]
	v_lshlrev_b64 v[10:11], 13, v[10:11]
	v_ashrrev_i32_e32 v23, 31, v22
	v_or_b32_e32 v26, 32, v56
	global_load_dwordx4 v[6:9], v[6:7], off
	v_lshl_add_u64 v[10:11], v[20:21], 0, v[10:11]
	v_lshlrev_b64 v[22:23], 13, v[22:23]
	v_ashrrev_i32_e32 v27, 31, v26
	global_load_dwordx4 v[10:13], v[10:11], off
	v_lshl_add_u64 v[22:23], v[20:21], 0, v[22:23]
	v_lshlrev_b64 v[26:27], 13, v[26:27]
	v_or_b32_e32 v34, 40, v56
	global_load_dwordx4 v[22:25], v[22:23], off
	v_lshl_add_u64 v[26:27], v[20:21], 0, v[26:27]
	v_ashrrev_i32_e32 v35, 31, v34
	global_load_dwordx4 v[26:29], v[26:27], off
	v_lshlrev_b64 v[34:35], 13, v[34:35]
	v_or_b32_e32 v52, 48, v56
	v_lshl_add_u64 v[34:35], v[20:21], 0, v[34:35]
	v_ashrrev_i32_e32 v53, 31, v52
	global_load_dwordx4 v[34:37], v[34:35], off
	v_lshlrev_b64 v[52:53], 13, v[52:53]
	v_or_b32_e32 v56, 56, v56
	v_lshl_add_u64 v[52:53], v[20:21], 0, v[52:53]
	v_ashrrev_i32_e32 v57, 31, v56
	global_load_dwordx4 v[52:55], v[52:53], off
	v_lshlrev_b64 v[56:57], 13, v[56:57]
	v_lshl_add_u64 v[20:21], v[20:21], 0, v[56:57]
	global_load_dwordx4 v[56:59], v[20:21], off
	v_add_u32_e32 v20, v47, v39
	s_ashr_i32 s45, s44, 31
	s_add_i32 s5, s5, s10
	s_add_i32 s3, s3, s2
	s_cmpk_lt_i32 s5, 0x400
	s_waitcnt vmcnt(7)
	ds_write2_b32 v20, v2, v3 offset1:1
	ds_write2_b32 v20, v4, v5 offset0:2 offset1:3
	v_add_u32_e32 v2, v47, v41
	s_waitcnt vmcnt(6)
	ds_write2_b32 v2, v6, v7 offset1:1
	ds_write2_b32 v2, v8, v9 offset0:2 offset1:3
	v_add_u32_e32 v2, v47, v43
	s_waitcnt vmcnt(5)
	ds_write2_b32 v2, v10, v11 offset1:1
	ds_write2_b32 v2, v12, v13 offset0:2 offset1:3
	v_add_u32_e32 v2, v47, v45
	s_waitcnt vmcnt(4)
	ds_write2_b32 v2, v22, v23 offset1:1
	ds_write2_b32 v2, v24, v25 offset0:2 offset1:3
	v_add_u32_e32 v2, 0x1080, v20
	v_lshl_add_u64 v[6:7], s[44:45], 1, v[18:19]
	s_waitcnt vmcnt(3)
	ds_write2_b32 v2, v26, v27 offset1:1
	v_add_u32_e32 v2, 0x1088, v20
	ds_write2_b32 v2, v28, v29 offset1:1
	v_add_u32_e32 v2, 0x14a0, v20
	s_waitcnt vmcnt(2)
	ds_write2_b32 v2, v34, v35 offset1:1
	v_add_u32_e32 v2, 0x14a8, v20
	ds_write2_b32 v2, v36, v37 offset1:1
	v_add_u32_e32 v2, 0x18c0, v20
	s_waitcnt vmcnt(1)
	ds_write2_b32 v2, v52, v53 offset1:1
	v_add_u32_e32 v2, 0x18c8, v20
	ds_write2_b32 v2, v54, v55 offset1:1
	v_add_u32_e32 v2, 0x1ce0, v20
	s_waitcnt vmcnt(0)
	ds_write2_b32 v2, v56, v57 offset1:1
	v_add_u32_e32 v2, 0x1ce8, v20
	ds_write2_b32 v2, v58, v59 offset1:1
	s_waitcnt lgkmcnt(0)
	ds_read2_b32 v[2:3], v48 offset1:33
	ds_read2_b32 v[4:5], v48 offset0:66 offset1:99
	ds_read2_b32 v[8:9], v48 offset0:198 offset1:231
	s_waitcnt lgkmcnt(2)
	v_cvt_pk_bf16_f32 v2, v2, v3
	s_waitcnt lgkmcnt(1)
	v_cvt_pk_bf16_f32 v3, v4, v5
	ds_read2_b32 v[4:5], v48 offset0:132 offset1:165
	s_waitcnt lgkmcnt(0)
	v_cvt_pk_bf16_f32 v4, v4, v5
	v_cvt_pk_bf16_f32 v5, v8, v9
	v_add_u32_e32 v8, s42, v46
	v_ashrrev_i32_e32 v9, 31, v8
	v_lshlrev_b64 v[8:9], 11, v[8:9]
	v_lshl_add_u64 v[8:9], v[6:7], 0, v[8:9]
	global_store_dwordx4 v[8:9], v[2:5], off nt
	ds_read2_b32 v[2:3], v49 offset1:33
	ds_read2_b32 v[4:5], v49 offset0:66 offset1:99
	ds_read2_b32 v[8:9], v49 offset0:198 offset1:231
	s_waitcnt lgkmcnt(2)
	v_cvt_pk_bf16_f32 v2, v2, v3
	s_waitcnt lgkmcnt(1)
	v_cvt_pk_bf16_f32 v3, v4, v5
	ds_read2_b32 v[4:5], v49 offset0:132 offset1:165
	s_waitcnt lgkmcnt(0)
	v_cvt_pk_bf16_f32 v4, v4, v5
	v_cvt_pk_bf16_f32 v5, v8, v9
	v_add_u32_e32 v8, s42, v40
	v_ashrrev_i32_e32 v9, 31, v8
	v_lshlrev_b64 v[8:9], 11, v[8:9]
	v_lshl_add_u64 v[8:9], v[6:7], 0, v[8:9]
	global_store_dwordx4 v[8:9], v[2:5], off nt
	ds_read2_b32 v[2:3], v50 offset1:33
	ds_read2_b32 v[4:5], v50 offset0:66 offset1:99
	ds_read2_b32 v[8:9], v50 offset0:198 offset1:231
	s_waitcnt lgkmcnt(2)
	v_cvt_pk_bf16_f32 v2, v2, v3
	s_waitcnt lgkmcnt(1)
	v_cvt_pk_bf16_f32 v3, v4, v5
	ds_read2_b32 v[4:5], v50 offset0:132 offset1:165
	s_waitcnt lgkmcnt(0)
	v_cvt_pk_bf16_f32 v4, v4, v5
	v_cvt_pk_bf16_f32 v5, v8, v9
	v_add_u32_e32 v8, s42, v42
	v_ashrrev_i32_e32 v9, 31, v8
	v_lshlrev_b64 v[8:9], 11, v[8:9]
	v_lshl_add_u64 v[8:9], v[6:7], 0, v[8:9]
	global_store_dwordx4 v[8:9], v[2:5], off nt
	ds_read2_b32 v[2:3], v51 offset1:33
	ds_read2_b32 v[4:5], v51 offset0:66 offset1:99
	ds_read2_b32 v[8:9], v51 offset0:198 offset1:231
	s_waitcnt lgkmcnt(2)
	v_cvt_pk_bf16_f32 v2, v2, v3
	s_waitcnt lgkmcnt(1)
	v_cvt_pk_bf16_f32 v3, v4, v5
	ds_read2_b32 v[4:5], v51 offset0:132 offset1:165
	s_waitcnt lgkmcnt(0)
	v_cvt_pk_bf16_f32 v4, v4, v5
	v_cvt_pk_bf16_f32 v5, v8, v9
	v_add_u32_e32 v8, s42, v44
	v_ashrrev_i32_e32 v9, 31, v8
	v_lshlrev_b64 v[8:9], 11, v[8:9]
	v_lshl_add_u64 v[6:7], v[6:7], 0, v[8:9]
	global_store_dwordx4 v[6:7], v[2:5], off nt
	s_waitcnt lgkmcnt(0)
	s_cbranch_scc1 .LBB0_956
	s_branch .LBB0_953

; #define LAS __attribute__((address_space(3)))
; #define GAS __attribute__((address_space(1)))
; #define LDS_WAIT() asm volatile("s_waitcnt lgkmcnt(0)" ::: "memory")
; __device__ __forceinline__ void transpose_item(const float* W, int K, int N, bf16_t* WT, int k0, int n0, int drow0, LAS float* scr, int lane) {
;     f32x4 v[8];
; #pragma unroll
;     for (int j = 0; j < 8; ++j) v[j] = *(const f32x4*)(W + (size_t)(k0 + (lane >> 3) + 8 * j) * N + n0 + 4 * (lane & 7));
; #pragma unroll
;     for (int j = 0; j < 8; ++j) { LAS float* d = scr + ((lane >> 3) + 8 * j) * 33 + 4 * (lane & 7); d[0] = v[j].x; d[1] = v[j].y; d[2] = v[j].z; d[3] = v[j].w; }
;     LDS_WAIT(); asm volatile("" ::: "memory");
;     const int c = lane & 7;
; #pragma unroll
;     for (int j = 0; j < 4; ++j) { const int n = (lane >> 3) + 8 * j; const LAS float* s = scr + (8 * c) * 33 + n;
;         u32x4 o; o.x = pk2(s[0 * 33], s[1 * 33]); o.y = pk2(s[2 * 33], s[3 * 33]); o.z = pk2(s[4 * 33], s[5 * 33]); o.w = pk2(s[6 * 33], s[7 * 33]);
;         *(GAS u32x4*)(WT + (size_t)(drow0 + n) * K + k0 + 8 * c) = o; }
;     LDS_WAIT(); asm volatile("" ::: "memory");
; }
; __device__ __forceinline__ void transpose_matrix(const float* W, int K, int N, bf16_t* WT, int rowmode, LAS float* scr, int gw, int ngw, int lane) {
;     const int nblk = N / 32, nitems = (K / 64) * nblk;
;     for (int it = gw; it < nitems; it += ngw) {
;         const int kb = it / nblk, nb = it - kb * nblk, n0 = 32 * nb;
;         int drow0 = n0;
;         if (rowmode == 1) { const int up = n0 >= DFF, j0 = up ? n0 - DFF : n0; drow0 = 256 * (j0 >> 7) + 128 * up + (j0 & 127); }
;         if (rowmode == 2 && n0 >= 5120 && n0 < 6400) {
;             const int tb = 5120 + (((n0 - 5120) >> 8) << 8), hh = ((n0 - tb) >> 7) & 1, d0 = (n0 - tb) & 127; drow0 = tb + ((d0 & 32) ? 128 : 0) + hh * 64 + ((d0 >> 6) << 5); }
;         if (rowmode == 2 && n0 >= 3072 && n0 < 5120) { const int wh = n0 >= 4096, j0 = n0 - 3072 - wh * 1024; drow0 = 3072 + 256 * (j0 >> 7) + 128 * wh + (j0 & 127); }
;         transpose_item(W, K, N, WT, 64 * kb, n0, drow0, scr, lane);
.LBB0_959:
	s_ashr_i32 s7, s5, 31
	s_lshr_b32 s7, s7, 26
	s_add_i32 s7, s5, s7
	s_lshl_b32 s8, s7, 5
	s_and_b32 s8, s8, 0xfffff800
	s_and_b32 s42, s7, 0xffffffc0
	s_sub_i32 s30, s3, s8
	v_or_b32_e32 v28, s42, v46
	s_ashr_i32 s31, s30, 31
	v_ashrrev_i32_e32 v29, 31, v28
	v_or_b32_e32 v6, 8, v28
	v_lshl_add_u64 v[18:19], s[30:31], 2, v[14:15]
	v_lshlrev_b64 v[2:3], 13, v[28:29]
	v_ashrrev_i32_e32 v7, 31, v6
	v_or_b32_e32 v10, 16, v28
	v_lshl_add_u64 v[2:3], v[18:19], 0, v[2:3]
	v_lshlrev_b64 v[6:7], 13, v[6:7]
	v_ashrrev_i32_e32 v11, 31, v10
	v_or_b32_e32 v20, 24, v28
	global_load_dwordx4 v[2:5], v[2:3], off
	v_lshl_add_u64 v[6:7], v[18:19], 0, v[6:7]
	v_lshlrev_b64 v[10:11], 13, v[10:11]
	v_ashrrev_i32_e32 v21, 31, v20
	v_or_b32_e32 v24, 32, v28
	global_load_dwordx4 v[6:9], v[6:7], off
	v_lshl_add_u64 v[10:11], v[18:19], 0, v[10:11]
	v_lshlrev_b64 v[20:21], 13, v[20:21]
	v_ashrrev_i32_e32 v25, 31, v24
	global_load_dwordx4 v[10:13], v[10:11], off
	v_lshl_add_u64 v[20:21], v[18:19], 0, v[20:21]
	v_lshlrev_b64 v[24:25], 13, v[24:25]
	v_or_b32_e32 v34, 40, v28
	global_load_dwordx4 v[20:23], v[20:21], off
	v_lshl_add_u64 v[24:25], v[18:19], 0, v[24:25]
	v_ashrrev_i32_e32 v35, 31, v34
	global_load_dwordx4 v[24:27], v[24:25], off
	v_lshlrev_b64 v[34:35], 13, v[34:35]
	v_or_b32_e32 v52, 48, v28
	v_lshl_add_u64 v[34:35], v[18:19], 0, v[34:35]
	v_ashrrev_i32_e32 v53, 31, v52
	global_load_dwordx4 v[34:37], v[34:35], off
	v_lshlrev_b64 v[52:53], 13, v[52:53]
	v_or_b32_e32 v28, 56, v28
	v_lshl_add_u64 v[52:53], v[18:19], 0, v[52:53]
	v_ashrrev_i32_e32 v29, 31, v28
	global_load_dwordx4 v[52:55], v[52:53], off
	v_lshlrev_b64 v[28:29], 13, v[28:29]
	v_lshl_add_u64 v[18:19], v[18:19], 0, v[28:29]
	global_load_dwordx4 v[56:59], v[18:19], off
	v_add_u32_e32 v18, v47, v39
	s_ashr_i32 s43, s42, 31
	s_add_i32 s5, s5, s10
	s_add_i32 s3, s3, s2
	s_cmpk_lt_i32 s5, 0x800
	s_waitcnt vmcnt(7)
	ds_write2_b32 v18, v2, v3 offset1:1
	ds_write2_b32 v18, v4, v5 offset0:2 offset1:3
	v_add_u32_e32 v2, v47, v41
	s_waitcnt vmcnt(6)
	ds_write2_b32 v2, v6, v7 offset1:1
	ds_write2_b32 v2, v8, v9 offset0:2 offset1:3
	v_add_u32_e32 v2, v47, v43
	s_waitcnt vmcnt(5)
	ds_write2_b32 v2, v10, v11 offset1:1
	ds_write2_b32 v2, v12, v13 offset0:2 offset1:3
	v_add_u32_e32 v2, v47, v45
	s_waitcnt vmcnt(4)
	ds_write2_b32 v2, v20, v21 offset1:1
	ds_write2_b32 v2, v22, v23 offset0:2 offset1:3
	v_add_u32_e32 v2, 0x1080, v18
	v_lshl_add_u64 v[6:7], s[42:43], 1, v[16:17]
	s_waitcnt vmcnt(3)
	ds_write2_b32 v2, v24, v25 offset1:1
	v_add_u32_e32 v2, 0x1088, v18
	ds_write2_b32 v2, v26, v27 offset1:1
	v_add_u32_e32 v2, 0x14a0, v18
	s_waitcnt vmcnt(2)
	ds_write2_b32 v2, v34, v35 offset1:1
	v_add_u32_e32 v2, 0x14a8, v18
	ds_write2_b32 v2, v36, v37 offset1:1
	v_add_u32_e32 v2, 0x18c0, v18
	s_waitcnt vmcnt(1)
	ds_write2_b32 v2, v52, v53 offset1:1
	v_add_u32_e32 v2, 0x18c8, v18
	ds_write2_b32 v2, v54, v55 offset1:1
	v_add_u32_e32 v2, 0x1ce0, v18
	s_waitcnt vmcnt(0)
	ds_write2_b32 v2, v56, v57 offset1:1
	v_add_u32_e32 v2, 0x1ce8, v18
	ds_write2_b32 v2, v58, v59 offset1:1
	s_waitcnt lgkmcnt(0)
	ds_read2_b32 v[2:3], v48 offset1:33
	ds_read2_b32 v[4:5], v48 offset0:66 offset1:99
	ds_read2_b32 v[8:9], v48 offset0:198 offset1:231
	s_waitcnt lgkmcnt(2)
	v_cvt_pk_bf16_f32 v2, v2, v3
	s_waitcnt lgkmcnt(1)
	v_cvt_pk_bf16_f32 v3, v4, v5
	ds_read2_b32 v[4:5], v48 offset0:132 offset1:165
	s_waitcnt lgkmcnt(0)
	v_cvt_pk_bf16_f32 v4, v4, v5
	v_cvt_pk_bf16_f32 v5, v8, v9
	v_add_u32_e32 v8, s30, v46
	v_ashrrev_i32_e32 v9, 31, v8
	v_lshlrev_b64 v[8:9], 12, v[8:9]
	v_lshl_add_u64 v[8:9], v[6:7], 0, v[8:9]
	global_store_dwordx4 v[8:9], v[2:5], off nt
	ds_read2_b32 v[2:3], v49 offset1:33
	ds_read2_b32 v[4:5], v49 offset0:66 offset1:99
	ds_read2_b32 v[8:9], v49 offset0:198 offset1:231
	s_waitcnt lgkmcnt(2)
	v_cvt_pk_bf16_f32 v2, v2, v3
	s_waitcnt lgkmcnt(1)
	v_cvt_pk_bf16_f32 v3, v4, v5
	ds_read2_b32 v[4:5], v49 offset0:132 offset1:165
	s_waitcnt lgkmcnt(0)
	v_cvt_pk_bf16_f32 v4, v4, v5
	v_cvt_pk_bf16_f32 v5, v8, v9
	v_add_u32_e32 v8, s30, v40
	v_ashrrev_i32_e32 v9, 31, v8
	v_lshlrev_b64 v[8:9], 12, v[8:9]
	v_lshl_add_u64 v[8:9], v[6:7], 0, v[8:9]
	global_store_dwordx4 v[8:9], v[2:5], off nt
	ds_read2_b32 v[2:3], v50 offset1:33
	ds_read2_b32 v[4:5], v50 offset0:66 offset1:99
	ds_read2_b32 v[8:9], v50 offset0:198 offset1:231
	s_waitcnt lgkmcnt(2)
	v_cvt_pk_bf16_f32 v2, v2, v3
	s_waitcnt lgkmcnt(1)
	v_cvt_pk_bf16_f32 v3, v4, v5
	ds_read2_b32 v[4:5], v50 offset0:132 offset1:165
	s_waitcnt lgkmcnt(0)
	v_cvt_pk_bf16_f32 v4, v4, v5
	v_cvt_pk_bf16_f32 v5, v8, v9
	v_add_u32_e32 v8, s30, v42
	v_ashrrev_i32_e32 v9, 31, v8
	v_lshlrev_b64 v[8:9], 12, v[8:9]
	v_lshl_add_u64 v[8:9], v[6:7], 0, v[8:9]
	global_store_dwordx4 v[8:9], v[2:5], off nt
	ds_read2_b32 v[2:3], v51 offset1:33
	ds_read2_b32 v[4:5], v51 offset0:66 offset1:99
	ds_read2_b32 v[8:9], v51 offset0:198 offset1:231
	s_waitcnt lgkmcnt(2)
	v_cvt_pk_bf16_f32 v2, v2, v3
	s_waitcnt lgkmcnt(1)
	v_cvt_pk_bf16_f32 v3, v4, v5
	ds_read2_b32 v[4:5], v51 offset0:132 offset1:165
	s_waitcnt lgkmcnt(0)
	v_cvt_pk_bf16_f32 v4, v4, v5
	v_cvt_pk_bf16_f32 v5, v8, v9
	v_add_u32_e32 v8, s30, v44
	v_ashrrev_i32_e32 v9, 31, v8
	v_lshlrev_b64 v[8:9], 12, v[8:9]
	v_lshl_add_u64 v[6:7], v[6:7], 0, v[8:9]
	global_store_dwordx4 v[6:7], v[2:5], off nt
	s_waitcnt lgkmcnt(0)
	s_cbranch_scc1 .LBB0_959

; #define LAS __attribute__((address_space(3)))
; #define GAS __attribute__((address_space(1)))
; #define LDS_WAIT() asm volatile("s_waitcnt lgkmcnt(0)" ::: "memory")
; __device__ __forceinline__ void transpose_item(const float* W, int K, int N, bf16_t* WT, int k0, int n0, int drow0, LAS float* scr, int lane) {
;     f32x4 v[8];
; #pragma unroll
;     for (int j = 0; j < 8; ++j) v[j] = *(const f32x4*)(W + (size_t)(k0 + (lane >> 3) + 8 * j) * N + n0 + 4 * (lane & 7));
; #pragma unroll
;     for (int j = 0; j < 8; ++j) { LAS float* d = scr + ((lane >> 3) + 8 * j) * 33 + 4 * (lane & 7); d[0] = v[j].x; d[1] = v[j].y; d[2] = v[j].z; d[3] = v[j].w; }
;     LDS_WAIT(); asm volatile("" ::: "memory");
;     const int c = lane & 7;
; #pragma unroll
;     for (int j = 0; j < 4; ++j) { const int n = (lane >> 3) + 8 * j; const LAS float* s = scr + (8 * c) * 33 + n;
;         u32x4 o; o.x = pk2(s[0 * 33], s[1 * 33]); o.y = pk2(s[2 * 33], s[3 * 33]); o.z = pk2(s[4 * 33], s[5 * 33]); o.w = pk2(s[6 * 33], s[7 * 33]);
;         *(GAS u32x4*)(WT + (size_t)(drow0 + n) * K + k0 + 8 * c) = o; }
;     LDS_WAIT(); asm volatile("" ::: "memory");
; }
; __device__ __forceinline__ void transpose_matrix(const float* W, int K, int N, bf16_t* WT, int rowmode, LAS float* scr, int gw, int ngw, int lane) {
;     const int nblk = N / 32, nitems = (K / 64) * nblk;
;     for (int it = gw; it < nitems; it += ngw) {
;         const int kb = it / nblk, nb = it - kb * nblk, n0 = 32 * nb;
;         int drow0 = n0;
;         if (rowmode == 1) { const int up = n0 >= DFF, j0 = up ? n0 - DFF : n0; drow0 = 256 * (j0 >> 7) + 128 * up + (j0 & 127); }
;         if (rowmode == 2 && n0 >= 5120 && n0 < 6400) {
;             const int tb = 5120 + (((n0 - 5120) >> 8) << 8), hh = ((n0 - tb) >> 7) & 1, d0 = (n0 - tb) & 127; drow0 = tb + ((d0 & 32) ? 128 : 0) + hh * 64 + ((d0 >> 6) << 5); }
;         if (rowmode == 2 && n0 >= 3072 && n0 < 5120) { const int wh = n0 >= 4096, j0 = n0 - 3072 - wh * 1024; drow0 = 3072 + 256 * (j0 >> 7) + 128 * wh + (j0 & 127); }
;         transpose_item(W, K, N, WT, 64 * kb, n0, drow0, scr, lane);
.LBB0_962:
	s_mul_hi_i32 s7, s5, 0x2fa0be83
	s_lshr_b32 s8, s7, 31
	s_ashr_i32 s7, s7, 6
	s_add_i32 s9, s7, s8
	s_mul_i32 s8, s9, 0xffffd500
	s_mul_i32 s7, s9, 0xfffffea8
	s_add_i32 s8, s3, s8
	s_add_i32 s7, s5, s7
	s_add_i32 s11, s8, 0xffffea80
	s_cmpk_gt_i32 s7, 0xab
	s_cselect_b32 s7, s11, s8
	s_cselect_b32 s11, 0x80, 0
	s_lshl_b32 s30, s9, 6
	s_ashr_i32 s9, s8, 31
	v_or_b32_e32 v56, s30, v46
	v_lshl_add_u64 v[2:3], s[8:9], 2, v[34:35]
	v_mad_i64_i32 v[4:5], s[8:9], v56, s27, v[2:3]
	global_load_dwordx4 v[52:55], v[4:5], off
	v_or_b32_e32 v4, 8, v56
	v_mad_i64_i32 v[4:5], s[8:9], v4, s27, v[2:3]
	global_load_dwordx4 v[26:29], v[4:5], off
	v_or_b32_e32 v4, 16, v56
	v_mad_i64_i32 v[4:5], s[8:9], v4, s27, v[2:3]
	global_load_dwordx4 v[22:25], v[4:5], off
	v_or_b32_e32 v4, 24, v56
	v_mad_i64_i32 v[4:5], s[8:9], v4, s27, v[2:3]
	global_load_dwordx4 v[18:21], v[4:5], off
	v_or_b32_e32 v4, 32, v56
	v_mad_i64_i32 v[4:5], s[8:9], v4, s27, v[2:3]
	global_load_dwordx4 v[14:17], v[4:5], off
	v_or_b32_e32 v4, 40, v56
	v_mad_i64_i32 v[4:5], s[8:9], v4, s27, v[2:3]
	global_load_dwordx4 v[10:13], v[4:5], off
	v_or_b32_e32 v4, 48, v56
	v_mad_i64_i32 v[4:5], s[8:9], v4, s27, v[2:3]
	global_load_dwordx4 v[6:9], v[4:5], off
	v_or_b32_e32 v4, 56, v56
	v_mad_i64_i32 v[2:3], s[8:9], v4, s27, v[2:3]
	global_load_dwordx4 v[2:5], v[2:3], off
	v_add_u32_e32 v56, v47, v39
	s_lshl_b32 s12, s7, 1
	s_and_b32 s7, s7, 0x60
	s_and_b32 s12, s12, 0xffffff00
	s_or_b32 s7, s7, s11
	s_or_b32 s7, s7, s12
	s_ashr_i32 s31, s30, 31
	s_add_i32 s5, s5, s10
	s_add_i32 s3, s3, s2
	s_cmpk_lt_i32 s5, 0x2b00
	s_waitcnt vmcnt(7)
	ds_write2_b32 v56, v52, v53 offset1:1
	ds_write2_b32 v56, v54, v55 offset0:2 offset1:3
	v_add_u32_e32 v52, v47, v41
	s_waitcnt vmcnt(6)
	ds_write2_b32 v52, v26, v27 offset1:1
	ds_write2_b32 v52, v28, v29 offset0:2 offset1:3
	v_add_u32_e32 v26, v47, v43
	s_waitcnt vmcnt(5)
	ds_write2_b32 v26, v22, v23 offset1:1
	ds_write2_b32 v26, v24, v25 offset0:2 offset1:3
	v_add_u32_e32 v22, v47, v45
	s_waitcnt vmcnt(4)
	ds_write2_b32 v22, v18, v19 offset1:1
	ds_write2_b32 v22, v20, v21 offset0:2 offset1:3
	v_add_u32_e32 v18, 0x1080, v56
	s_waitcnt vmcnt(3)
	ds_write2_b32 v18, v14, v15 offset1:1
	v_add_u32_e32 v14, 0x1088, v56
	ds_write2_b32 v14, v16, v17 offset1:1
	v_add_u32_e32 v14, 0x14a0, v56
	s_waitcnt vmcnt(2)
	ds_write2_b32 v14, v10, v11 offset1:1
	v_add_u32_e32 v10, 0x14a8, v56
	ds_write2_b32 v10, v12, v13 offset1:1
	v_add_u32_e32 v10, 0x18c0, v56
	s_waitcnt vmcnt(1)
	ds_write2_b32 v10, v6, v7 offset1:1
	v_add_u32_e32 v6, 0x18c8, v56
	ds_write2_b32 v6, v8, v9 offset1:1
	v_add_u32_e32 v6, 0x1ce0, v56
	s_waitcnt vmcnt(0)
	ds_write2_b32 v6, v2, v3 offset1:1
	v_add_u32_e32 v2, 0x1ce8, v56
	ds_write2_b32 v2, v4, v5 offset1:1
	s_waitcnt lgkmcnt(0)
	ds_read2_b32 v[2:3], v48 offset1:33
	ds_read2_b32 v[4:5], v48 offset0:66 offset1:99
	ds_read2_b32 v[8:9], v48 offset0:198 offset1:231
	v_lshl_add_u64 v[6:7], s[30:31], 1, v[36:37]
	s_waitcnt lgkmcnt(2)
	v_cvt_pk_bf16_f32 v2, v2, v3
	s_waitcnt lgkmcnt(1)
	v_cvt_pk_bf16_f32 v3, v4, v5
	ds_read2_b32 v[4:5], v48 offset0:132 offset1:165
	s_waitcnt lgkmcnt(0)
	v_cvt_pk_bf16_f32 v4, v4, v5
	v_cvt_pk_bf16_f32 v5, v8, v9
	v_or_b32_e32 v8, s7, v46
	v_ashrrev_i32_e32 v9, 31, v8
	v_lshlrev_b64 v[8:9], 12, v[8:9]
	v_lshl_add_u64 v[8:9], v[6:7], 0, v[8:9]
	global_store_dwordx4 v[8:9], v[2:5], off nt
	ds_read2_b32 v[2:3], v49 offset1:33
	ds_read2_b32 v[4:5], v49 offset0:66 offset1:99
	ds_read2_b32 v[8:9], v49 offset0:198 offset1:231
	s_waitcnt lgkmcnt(2)
	v_cvt_pk_bf16_f32 v2, v2, v3
	s_waitcnt lgkmcnt(1)
	v_cvt_pk_bf16_f32 v3, v4, v5
	ds_read2_b32 v[4:5], v49 offset0:132 offset1:165
	s_waitcnt lgkmcnt(0)
	v_cvt_pk_bf16_f32 v4, v4, v5
	v_cvt_pk_bf16_f32 v5, v8, v9
	v_or_b32_e32 v8, s7, v40
	v_ashrrev_i32_e32 v9, 31, v8
	v_lshlrev_b64 v[8:9], 12, v[8:9]
	v_lshl_add_u64 v[8:9], v[6:7], 0, v[8:9]
	global_store_dwordx4 v[8:9], v[2:5], off nt
	ds_read2_b32 v[2:3], v50 offset1:33
	ds_read2_b32 v[4:5], v50 offset0:66 offset1:99
	ds_read2_b32 v[8:9], v50 offset0:198 offset1:231
	s_waitcnt lgkmcnt(2)
	v_cvt_pk_bf16_f32 v2, v2, v3
	s_waitcnt lgkmcnt(1)
	v_cvt_pk_bf16_f32 v3, v4, v5
	ds_read2_b32 v[4:5], v50 offset0:132 offset1:165
	s_waitcnt lgkmcnt(0)
	v_cvt_pk_bf16_f32 v4, v4, v5
	v_cvt_pk_bf16_f32 v5, v8, v9
	v_or_b32_e32 v8, s7, v42
	v_ashrrev_i32_e32 v9, 31, v8
	v_lshlrev_b64 v[8:9], 12, v[8:9]
	v_lshl_add_u64 v[8:9], v[6:7], 0, v[8:9]
	global_store_dwordx4 v[8:9], v[2:5], off nt
	ds_read2_b32 v[2:3], v51 offset1:33
	ds_read2_b32 v[4:5], v51 offset0:66 offset1:99
	ds_read2_b32 v[8:9], v51 offset0:198 offset1:231
	s_waitcnt lgkmcnt(2)
	v_cvt_pk_bf16_f32 v2, v2, v3
	s_waitcnt lgkmcnt(1)
	v_cvt_pk_bf16_f32 v3, v4, v5
	ds_read2_b32 v[4:5], v51 offset0:132 offset1:165
	s_waitcnt lgkmcnt(0)
	v_cvt_pk_bf16_f32 v4, v4, v5
	v_cvt_pk_bf16_f32 v5, v8, v9
	v_or_b32_e32 v8, s7, v44
	v_ashrrev_i32_e32 v9, 31, v8
	v_lshlrev_b64 v[8:9], 12, v[8:9]
	v_lshl_add_u64 v[6:7], v[6:7], 0, v[8:9]
	global_store_dwordx4 v[6:7], v[2:5], off nt
	s_waitcnt lgkmcnt(0)
	s_cbranch_scc1 .LBB0_962
	v_readlane_b32 s11, v254, 50

; #define LAS __attribute__((address_space(3)))
; #define GAS __attribute__((address_space(1)))
; #define LDS_WAIT() asm volatile("s_waitcnt lgkmcnt(0)" ::: "memory")
; __device__ __forceinline__ void transpose_item(const float* W, int K, int N, bf16_t* WT, int k0, int n0, int drow0, LAS float* scr, int lane) {
;     f32x4 v[8];
; #pragma unroll
;     for (int j = 0; j < 8; ++j) v[j] = *(const f32x4*)(W + (size_t)(k0 + (lane >> 3) + 8 * j) * N + n0 + 4 * (lane & 7));
; #pragma unroll
;     for (int j = 0; j < 8; ++j) { LAS float* d = scr + ((lane >> 3) + 8 * j) * 33 + 4 * (lane & 7); d[0] = v[j].x; d[1] = v[j].y; d[2] = v[j].z; d[3] = v[j].w; }
;     LDS_WAIT(); asm volatile("" ::: "memory");
;     const int c = lane & 7;
; #pragma unroll
;     for (int j = 0; j < 4; ++j) { const int n = (lane >> 3) + 8 * j; const LAS float* s = scr + (8 * c) * 33 + n;
;         u32x4 o; o.x = pk2(s[0 * 33], s[1 * 33]); o.y = pk2(s[2 * 33], s[3 * 33]); o.z = pk2(s[4 * 33], s[5 * 33]); o.w = pk2(s[6 * 33], s[7 * 33]);
;         *(GAS u32x4*)(WT + (size_t)(drow0 + n) * K + k0 + 8 * c) = o; }
;     LDS_WAIT(); asm volatile("" ::: "memory");
; }
; __device__ __forceinline__ void transpose_matrix(const float* W, int K, int N, bf16_t* WT, int rowmode, LAS float* scr, int gw, int ngw, int lane) {
;     const int nblk = N / 32, nitems = (K / 64) * nblk;
;     for (int it = gw; it < nitems; it += ngw) {
;         const int kb = it / nblk, nb = it - kb * nblk, n0 = 32 * nb;
;         int drow0 = n0;
;         if (rowmode == 1) { const int up = n0 >= DFF, j0 = up ? n0 - DFF : n0; drow0 = 256 * (j0 >> 7) + 128 * up + (j0 & 127); }
;         if (rowmode == 2 && n0 >= 5120 && n0 < 6400) {
;             const int tb = 5120 + (((n0 - 5120) >> 8) << 8), hh = ((n0 - tb) >> 7) & 1, d0 = (n0 - tb) & 127; drow0 = tb + ((d0 & 32) ? 128 : 0) + hh * 64 + ((d0 >> 6) << 5); }
;         if (rowmode == 2 && n0 >= 3072 && n0 < 5120) { const int wh = n0 >= 4096, j0 = n0 - 3072 - wh * 1024; drow0 = 3072 + 256 * (j0 >> 7) + 128 * wh + (j0 & 127); }
;         transpose_item(W, K, N, WT, 64 * kb, n0, drow0, scr, lane);
.LBB0_966:
	s_ashr_i32 s5, s3, 31
	s_lshr_b32 s5, s5, 26
	s_add_i32 s5, s3, s5
	s_lshl_b32 s7, s5, 5
	s_and_b32 s7, s7, 0xfffff800
	s_and_b32 s38, s5, 0xffffffc0
	s_sub_i32 s30, s1, s7
	v_or_b32_e32 v36, s38, v46
	s_ashr_i32 s31, s30, 31
	v_ashrrev_i32_e32 v37, 31, v36
	v_or_b32_e32 v6, 8, v36
	v_lshl_add_u64 v[18:19], s[30:31], 2, v[14:15]
	v_lshlrev_b64 v[2:3], 13, v[36:37]
	v_ashrrev_i32_e32 v7, 31, v6
	v_or_b32_e32 v10, 16, v36
	v_lshl_add_u64 v[2:3], v[18:19], 0, v[2:3]
	v_lshlrev_b64 v[6:7], 13, v[6:7]
	v_ashrrev_i32_e32 v11, 31, v10
	v_or_b32_e32 v20, 24, v36
	global_load_dwordx4 v[2:5], v[2:3], off
	v_lshl_add_u64 v[6:7], v[18:19], 0, v[6:7]
	v_lshlrev_b64 v[10:11], 13, v[10:11]
	v_ashrrev_i32_e32 v21, 31, v20
	v_or_b32_e32 v24, 32, v36
	global_load_dwordx4 v[6:9], v[6:7], off
	v_lshl_add_u64 v[10:11], v[18:19], 0, v[10:11]
	v_lshlrev_b64 v[20:21], 13, v[20:21]
	v_ashrrev_i32_e32 v25, 31, v24
	global_load_dwordx4 v[10:13], v[10:11], off
	v_lshl_add_u64 v[20:21], v[18:19], 0, v[20:21]
	v_lshlrev_b64 v[24:25], 13, v[24:25]
	v_or_b32_e32 v28, 40, v36
	global_load_dwordx4 v[20:23], v[20:21], off
	v_lshl_add_u64 v[24:25], v[18:19], 0, v[24:25]
	v_ashrrev_i32_e32 v29, 31, v28
	global_load_dwordx4 v[24:27], v[24:25], off
	v_lshlrev_b64 v[28:29], 13, v[28:29]
	v_or_b32_e32 v32, 48, v36
	v_lshl_add_u64 v[28:29], v[18:19], 0, v[28:29]
	v_ashrrev_i32_e32 v33, 31, v32
	global_load_dwordx4 v[28:31], v[28:29], off
	v_lshlrev_b64 v[32:33], 13, v[32:33]
	v_or_b32_e32 v36, 56, v36
	v_lshl_add_u64 v[32:33], v[18:19], 0, v[32:33]
	v_ashrrev_i32_e32 v37, 31, v36
	global_load_dwordx4 v[32:35], v[32:33], off
	v_lshlrev_b64 v[36:37], 13, v[36:37]
	v_lshl_add_u64 v[18:19], v[18:19], 0, v[36:37]
	global_load_dwordx4 v[52:55], v[18:19], off
	v_add_u32_e32 v18, v47, v39
	s_ashr_i32 s39, s38, 31
	s_add_i32 s3, s3, s10
	s_add_i32 s1, s1, s2
	s_cmpk_lt_i32 s3, 0x1580
	s_waitcnt vmcnt(7)
	ds_write2_b32 v18, v2, v3 offset1:1
	ds_write2_b32 v18, v4, v5 offset0:2 offset1:3
	v_add_u32_e32 v2, v47, v41
	s_waitcnt vmcnt(6)
	ds_write2_b32 v2, v6, v7 offset1:1
	ds_write2_b32 v2, v8, v9 offset0:2 offset1:3
	v_add_u32_e32 v2, v47, v43
	s_waitcnt vmcnt(5)
	ds_write2_b32 v2, v10, v11 offset1:1
	ds_write2_b32 v2, v12, v13 offset0:2 offset1:3
	v_add_u32_e32 v2, v47, v45
	s_waitcnt vmcnt(4)
	ds_write2_b32 v2, v20, v21 offset1:1
	ds_write2_b32 v2, v22, v23 offset0:2 offset1:3
	v_add_u32_e32 v2, 0x1080, v18
	v_lshl_add_u64 v[6:7], s[38:39], 1, v[16:17]
	s_waitcnt vmcnt(3)
	ds_write2_b32 v2, v24, v25 offset1:1
	v_add_u32_e32 v2, 0x1088, v18
	ds_write2_b32 v2, v26, v27 offset1:1
	v_add_u32_e32 v2, 0x14a0, v18
	s_waitcnt vmcnt(2)
	ds_write2_b32 v2, v28, v29 offset1:1
	v_add_u32_e32 v2, 0x14a8, v18
	ds_write2_b32 v2, v30, v31 offset1:1
	v_add_u32_e32 v2, 0x18c0, v18
	s_waitcnt vmcnt(1)
	ds_write2_b32 v2, v32, v33 offset1:1
	v_add_u32_e32 v2, 0x18c8, v18
	ds_write2_b32 v2, v34, v35 offset1:1
	v_add_u32_e32 v2, 0x1ce0, v18
	s_waitcnt vmcnt(0)
	ds_write2_b32 v2, v52, v53 offset1:1
	v_add_u32_e32 v2, 0x1ce8, v18
	ds_write2_b32 v2, v54, v55 offset1:1
	s_waitcnt lgkmcnt(0)
	ds_read2_b32 v[2:3], v48 offset1:33
	ds_read2_b32 v[4:5], v48 offset0:66 offset1:99
	ds_read2_b32 v[8:9], v48 offset0:198 offset1:231
	s_waitcnt lgkmcnt(2)
	v_cvt_pk_bf16_f32 v2, v2, v3
	s_waitcnt lgkmcnt(1)
	v_cvt_pk_bf16_f32 v3, v4, v5
	ds_read2_b32 v[4:5], v48 offset0:132 offset1:165
	s_waitcnt lgkmcnt(0)
	v_cvt_pk_bf16_f32 v4, v4, v5
	v_cvt_pk_bf16_f32 v5, v8, v9
	v_add_u32_e32 v8, s30, v46
	v_mad_i64_i32 v[8:9], s[8:9], v8, s57, v[6:7]
	global_store_dwordx4 v[8:9], v[2:5], off nt
	ds_read2_b32 v[2:3], v49 offset1:33
	ds_read2_b32 v[4:5], v49 offset0:66 offset1:99
	ds_read2_b32 v[8:9], v49 offset0:198 offset1:231
	s_waitcnt lgkmcnt(2)
	v_cvt_pk_bf16_f32 v2, v2, v3
	s_waitcnt lgkmcnt(1)
	v_cvt_pk_bf16_f32 v3, v4, v5
	ds_read2_b32 v[4:5], v49 offset0:132 offset1:165
	s_waitcnt lgkmcnt(0)
	v_cvt_pk_bf16_f32 v4, v4, v5
	v_cvt_pk_bf16_f32 v5, v8, v9
	v_add_u32_e32 v8, s30, v40
	v_mad_i64_i32 v[8:9], s[8:9], v8, s57, v[6:7]
	global_store_dwordx4 v[8:9], v[2:5], off nt
	ds_read2_b32 v[2:3], v50 offset1:33
	ds_read2_b32 v[4:5], v50 offset0:66 offset1:99
	ds_read2_b32 v[8:9], v50 offset0:198 offset1:231
	s_waitcnt lgkmcnt(2)
	v_cvt_pk_bf16_f32 v2, v2, v3
	s_waitcnt lgkmcnt(1)
	v_cvt_pk_bf16_f32 v3, v4, v5
	ds_read2_b32 v[4:5], v50 offset0:132 offset1:165
	s_waitcnt lgkmcnt(0)
	v_cvt_pk_bf16_f32 v4, v4, v5
	v_cvt_pk_bf16_f32 v5, v8, v9
	v_add_u32_e32 v8, s30, v42
	v_mad_i64_i32 v[8:9], s[8:9], v8, s57, v[6:7]
	global_store_dwordx4 v[8:9], v[2:5], off nt
	ds_read2_b32 v[2:3], v51 offset1:33
	ds_read2_b32 v[4:5], v51 offset0:66 offset1:99
	ds_read2_b32 v[8:9], v51 offset0:198 offset1:231
	s_waitcnt lgkmcnt(2)
	v_cvt_pk_bf16_f32 v2, v2, v3
	s_waitcnt lgkmcnt(1)
	v_cvt_pk_bf16_f32 v3, v4, v5
	ds_read2_b32 v[4:5], v51 offset0:132 offset1:165
	s_waitcnt lgkmcnt(0)
	v_cvt_pk_bf16_f32 v4, v4, v5
	v_cvt_pk_bf16_f32 v5, v8, v9
	v_add_u32_e32 v8, s30, v44
	v_mad_i64_i32 v[6:7], s[8:9], v8, s57, v[6:7]
	global_store_dwordx4 v[6:7], v[2:5], off nt
	s_waitcnt lgkmcnt(0)
	s_cbranch_scc1 .LBB0_966

;     __host__ __device__ bool tile(int i, int& pm, int& pn) const { return tile(i, pm, pn, nwg); }
; __device__ __forceinline__ void convert_weights(const Args& a, int layer, LAS unsigned char* lds, int gw, int ngw, int wave, int lane) {
;     ...
;     for (int it = gw * 64 + lane; it < 4096 * 16; it += ngw * 64) {
;         const int row = it >> 4, din0 = (it & 15) * 8;
;         const int tile = row >> 8, gate = (row >> 7) & 1, e = row & 127, d = tile >> 3, q = tile & 7;
;         const float* src = (gate ? a.lru_w_x : a.lru_w_a) + ((((size_t)layer * 2 + d) * 8 + q) * 128 + din0) * 128 + e;
;         u32x4 o; o.x = pk2(src[0 * 128], src[1 * 128]); o.y = pk2(src[2 * 128], src[3 * 128]); o.z = pk2(src[4 * 128], src[5 * 128]); o.w = pk2(src[6 * 128], src[7 * 128]);
;         *(u32x4*)(wg + (size_t)row * 128 + din0) = o;
;     }
.LBB0_969:
	v_and_b32_e32 v5, 0x800, v2
	v_cmp_eq_u32_e32 vcc, 0, v5
	v_mov_b32_e32 v5, s17
	v_mov_b32_e32 v6, s13
	v_ashrrev_i32_e32 v4, 15, v2
	v_cndmask_b32_e32 v7, v5, v6, vcc
	v_mov_b32_e32 v5, s16
	v_mov_b32_e32 v6, s12
	v_cndmask_b32_e32 v6, v5, v6, vcc
	v_ashrrev_i32_e32 v5, 31, v4
	v_lshlrev_b64 v[4:5], 19, v[4:5]
	v_lshlrev_b32_e32 v9, 4, v2
	v_ashrrev_i32_e32 v8, 4, v2
	v_and_b32_e32 v12, 0x78, v3
	v_and_or_b32 v4, v9, s28, v4
	v_lshl_add_u64 v[4:5], v[6:7], 0, v[4:5]
	v_lshlrev_b32_e32 v174, 9, v12
	v_lshlrev_b32_e32 v6, 2, v8
	v_lshl_add_u64 v[4:5], v[4:5], 0, v[174:175]
	v_and_b32_e32 v174, 0x1fc, v6
	v_lshl_add_u64 v[4:5], v[4:5], 0, v[174:175]
	v_lshl_add_u64 v[10:11], v[4:5], 0, s[8:9]
	v_add_co_u32_e32 v4, vcc, s56, v4
	v_add_u32_e32 v2, s1, v2
	s_nop 0
	v_addc_co_u32_e32 v5, vcc, 0, v5, vcc
	global_load_dword v4, v[4:5], off
	s_nop 0
	global_load_dword v5, v[10:11], off offset:512
	v_lshlrev_b32_e32 v174, 1, v12
	v_cmp_lt_i32_e32 vcc, s26, v2
	v_add_u32_e32 v3, s2, v3
	s_or_b64 s[38:39], vcc, s[38:39]
	s_waitcnt vmcnt(0)
	v_cvt_pk_bf16_f32 v4, v4, v5
	global_load_dword v5, v[10:11], off offset:1024
	global_load_dword v6, v[10:11], off offset:1536
	s_waitcnt vmcnt(0)
	v_cvt_pk_bf16_f32 v5, v5, v6
	global_load_dword v6, v[10:11], off offset:2048
	global_load_dword v7, v[10:11], off offset:2560
	s_waitcnt vmcnt(0)
	v_cvt_pk_bf16_f32 v6, v6, v7
	global_load_dword v7, v[10:11], off offset:3072
	global_load_dword v9, v[10:11], off offset:3584
	s_waitcnt vmcnt(0)
	v_cvt_pk_bf16_f32 v7, v7, v9
	v_ashrrev_i32_e32 v9, 31, v8
	v_lshlrev_b64 v[8:9], 8, v[8:9]
	v_lshl_add_u64 v[8:9], s[34:35], 0, v[8:9]
	v_lshl_add_u64 v[8:9], v[8:9], 0, v[174:175]
	global_store_dwordx4 v[8:9], v[4:7], off nt
	s_andn2_b64 exec, exec, s[38:39]
	s_cbranch_execnz .LBB0_969

; __device__ __forceinline__ void row_rstd(const unsigned long long* ssq, int row0, float (&rs)[2][4]) {
;     unsigned long long q[2][4];
; #pragma unroll
;     for (int ai = 0; ai < 2; ++ai)
; #pragma unroll
;         for (int m = 0; m < 4; ++m) q[ai][m] = ssq[row0 + ai * HALF + m * 16];
;     asm volatile("" : "+v"(q[0][0]), "+v"(q[0][1]), "+v"(q[0][2]), "+v"(q[0][3]), "+v"(q[1][0]), "+v"(q[1][1]), "+v"(q[1][2]), "+v"(q[1][3]));
; #pragma unroll
;     for (int ai = 0; ai < 2; ++ai)
; #pragma unroll
;         for (int m = 0; m < 4; ++m) {
;             const float qf = __builtin_fmaf((float)(unsigned)(q[ai][m] >> 32), 4294967296.0f, (float)(unsigned)q[ai][m]);
;             rs[ai][m] = __builtin_amdgcn_rsqf(__builtin_fmaf(qf, 1.0f / (SSQ_SCALE * DM), EPS)); }
; }
;     template <int QVV> __device__ __forceinline__ void run(f32x4 (&acc)[2][2][4][2], const Unit& u, int wr, int wc, int fr, int fq) const {
;         constexpr int nai = (QVV == 2) ? 1 : 2; const int r0 = u.pm * BM + (QVV == 2 ? (u.seg - 1) * HALF : 0);
;         char* tb = (char*)(O + (size_t)r0 * NGC + u.pn * BM);
;         const int v = u.pm < 4 ? 4 : ((u.pm - 4) >> 5);
;         const char* swb = (const char*)(sw + (size_t)v * SWLD + u.pn * BM); const char* bmb = (const char*)(bm + u.pn * BM);
;         unsigned lo = (unsigned)((wr * 64 + fr) * NGC + wc * 32 + 8 * fq);
;         unsigned co = (unsigned)(wc * 32 + 8 * fq) * 4u;
;         asm volatile("" : "+v"(lo), "+v"(co));
;         float rs[2][4]; row_rstd(ssq, r0 + wr * 64 + fr, rs);
; #pragma unroll
;         for (int bj = 0; bj < 2; ++bj) {
;             const f32x4 s0 = (*(const f32x4*)(swb + co + bj * HALF * 4) + *(const f32x4*)(bmb + co + bj * HALF * 4)) * (-LOG2E) - 7.994353436858858f,
;                         s1 = (*(const f32x4*)(swb + co + bj * HALF * 4 + 16) + *(const f32x4*)(bmb + co + bj * HALF * 4 + 16)) * (-LOG2E) - 7.994353436858858f;
.LBB0_1279:
	s_mul_i32 s98, s53, 24
	s_add_i32 s98, s98, s52
	s_lshl_b32 s98, s98, 16
	s_add_u32 s98, s1, s98
	s_addc_u32 s99, s2, 0
	s_lshl_b32 s67, s53, 8
	v_add_u32_e32 v130, s67, v154
	v_ashrrev_i32_e32 v131, 31, v130
	v_and_b32_e32 v146, 0x1c0, v0
	v_lshlrev_b32_e32 v146, 7, v146
	v_and_b32_e32 v148, 48, v0
	v_lshl_or_b32 v146, v148, 4, v146
	v_and_b32_e32 v148, 15, v0
	v_lshl_or_b32 v146, v148, 3, v146
	v_mov_b32_e32 v159, v156
	v_lshl_add_u64 v[130:131], v[130:131], 3, s[44:45]
	global_load_dwordx2 v[132:133], v[130:131], off
	global_load_dwordx2 v[134:135], v[130:131], off offset:128
	global_load_dwordx2 v[136:137], v[130:131], off offset:256
	global_load_dwordx2 v[138:139], v[130:131], off offset:384
	global_load_dwordx2 v[140:141], v[130:131], off offset:1024
	global_load_dwordx2 v[142:143], v[130:131], off offset:1152
	global_load_dwordx2 v[144:145], v[130:131], off offset:1280
	s_nop 0
	global_load_dwordx2 v[130:131], v[130:131], off offset:1408
	s_mul_i32 s42, s53, 0x180000
	s_mul_hi_i32 s43, s67, 0x1800
	s_add_u32 s42, s1, s42
	s_addc_u32 s43, s2, s43
	s_lshl_b32 s52, s52, 8
	s_ashr_i32 s53, s52, 31
	s_add_u32 s42, s42, s52
	s_addc_u32 s43, s43, s53
	s_lshl_b64 s[30:31], s[30:31], 2
	s_add_u32 s62, s7, s30
	s_addc_u32 s63, s9, s31
	s_lshl_b64 s[30:31], s[52:53], 2
	s_add_u32 s62, s62, s30
	s_addc_u32 s63, s63, s31
	s_add_u32 s52, s3, s30
	s_flbit_i32_b32 s30, 0
	s_addc_u32 s53, s5, s31
	s_min_u32 s30, s30, 32
	s_sub_i32 s31, 32, s30
	v_mov_b32_e32 v147, v175
	s_waitcnt vmcnt(0)
	s_nop 0
	v_mov_b32_e32 v174, v133
	v_lshlrev_b64 v[148:149], s30, v[174:175]
	v_min_u32_e32 v133, 1, v148
	v_or_b32_e32 v133, v149, v133
	v_cvt_f32_u32_e32 v133, v133
	v_cvt_f32_u32_e32 v132, v132
	v_mov_b32_e32 v174, v135
	v_cvt_f32_u32_e32 v130, v130
	v_ldexp_f32 v133, v133, s31
	v_fmac_f32_e32 v132, 0x4f800000, v133
	v_fmamk_f32 v132, v132, 0x30000000, v231
	v_rsq_f32_e32 v168, v132
	v_lshlrev_b64 v[132:133], s30, v[174:175]
	v_min_u32_e32 v132, 1, v132
	v_or_b32_e32 v132, v133, v132
	v_cvt_f32_u32_e32 v132, v132
	v_cvt_f32_u32_e32 v133, v134
	v_mov_b32_e32 v174, v137
	v_lshl_add_u64 v[148:149], s[98:99], 0, v[146:147]
	v_ldexp_f32 v132, v132, s31
	v_fmac_f32_e32 v133, 0x4f800000, v132
	v_fmamk_f32 v132, v133, 0x30000000, v231
	v_rsq_f32_e32 v167, v132
	v_lshlrev_b64 v[132:133], s30, v[174:175]
	v_min_u32_e32 v132, 1, v132
	v_or_b32_e32 v132, v133, v132
	v_cvt_f32_u32_e32 v132, v132
	v_cvt_f32_u32_e32 v133, v136
	v_mov_b32_e32 v174, v139
	v_mul_f32_e32 v147, 0xbfb8aa3b, v168
	v_ldexp_f32 v132, v132, s31
	v_fmac_f32_e32 v133, 0x4f800000, v132
	v_fmamk_f32 v132, v133, 0x30000000, v231
	v_rsq_f32_e32 v166, v132
	v_lshlrev_b64 v[132:133], s30, v[174:175]
	v_min_u32_e32 v132, 1, v132
	v_or_b32_e32 v132, v133, v132
	v_cvt_f32_u32_e32 v132, v132
	v_cvt_f32_u32_e32 v133, v138
	v_mov_b32_e32 v174, v141
	v_ldexp_f32 v132, v132, s31
	v_fmac_f32_e32 v133, 0x4f800000, v132
	v_fmamk_f32 v132, v133, 0x30000000, v231
	v_rsq_f32_e32 v165, v132
	v_lshlrev_b64 v[132:133], s30, v[174:175]
	v_min_u32_e32 v132, 1, v132
	v_or_b32_e32 v132, v133, v132
	v_cvt_f32_u32_e32 v132, v132
	v_cvt_f32_u32_e32 v133, v140
	v_mov_b32_e32 v174, v143
	v_ldexp_f32 v132, v132, s31
	v_fmac_f32_e32 v133, 0x4f800000, v132
	v_fmamk_f32 v132, v133, 0x30000000, v231
	v_rsq_f32_e32 v164, v132
	v_lshlrev_b64 v[132:133], s30, v[174:175]
	v_min_u32_e32 v132, 1, v132
	v_or_b32_e32 v132, v133, v132
	v_cvt_f32_u32_e32 v132, v132
	v_cvt_f32_u32_e32 v133, v142
	v_mov_b32_e32 v174, v145
	v_ldexp_f32 v132, v132, s31
	v_fmac_f32_e32 v133, 0x4f800000, v132
	v_fmamk_f32 v132, v133, 0x30000000, v231
	v_rsq_f32_e32 v163, v132
	v_lshlrev_b64 v[132:133], s30, v[174:175]
	v_min_u32_e32 v132, 1, v132
	v_or_b32_e32 v132, v133, v132
	v_cvt_f32_u32_e32 v132, v132
	v_cvt_f32_u32_e32 v133, v144
	v_mov_b32_e32 v174, v131
	v_ldexp_f32 v132, v132, s31
	v_fmac_f32_e32 v133, 0x4f800000, v132
	v_fmamk_f32 v132, v133, 0x30000000, v231
	v_rsq_f32_e32 v161, v132
	v_lshlrev_b64 v[132:133], s30, v[174:175]
	v_min_u32_e32 v131, 1, v132
	v_or_b32_e32 v131, v133, v131
	v_cvt_f32_u32_e32 v131, v131
	s_mov_b32 s30, 0x400
	v_ldexp_f32 v131, v131, s31
	v_fmac_f32_e32 v130, 0x4f800000, v131
	v_fmamk_f32 v130, v130, 0x30000000, v231
	v_rsq_f32_e32 v160, v130
	global_load_dwordx4 v[130:133], v159, s[62:63] offset:16
	global_load_dwordx4 v[138:141], v159, s[62:63]
	global_load_dwordx4 v[134:137], v159, s[52:53] offset:16
	global_load_dwordx4 v[142:145], v159, s[52:53]
	s_waitcnt vmcnt(0)
;     template <int QVV> __device__ __forceinline__ void run(f32x4 (&acc)[2][2][4][2], const Unit& u, int wr, int wc, int fr, int fq) const {
;     ...
;         for (int bj = 0; bj < 2; ++bj) {
;             const f32x4 s0 = (*(const f32x4*)(swb + co + bj * HALF * 4) + *(const f32x4*)(bmb + co + bj * HALF * 4)) * (-LOG2E) - 7.994353436858858f,
;                         s1 = (*(const f32x4*)(swb + co + bj * HALF * 4 + 16) + *(const f32x4*)(bmb + co + bj * HALF * 4 + 16)) * (-LOG2E) - 7.994353436858858f;
; #pragma unroll
;             for (int ai = 0; ai < 2; ++ai)
; #pragma unroll
;                 for (int m = 0; m < 4; ++m) { if (ai >= nai) continue;
;                     const float rn = rs[ai][m] * (-LOG2E);
;                     const f32x4 x0 = acc[ai][bj][m][0] * rn + s0, x1 = acc[ai][bj][m][1] * rn + s1;
;                     f32x4 d0, d1;
; #pragma unroll
;                     for (int i = 0; i < 4; ++i) { d0[i] = __builtin_amdgcn_exp2f(x0[i]); d1[i] = __builtin_amdgcn_exp2f(x1[i]); }
;                     d0 = d0 + (1.0f / 255.0f); d1 = d1 + (1.0f / 255.0f);
;                     u32x2 w = {0u, 0u};
; #pragma unroll
;                     for (int i = 0; i < 4; ++i) { const float g0 = fmaxf(__builtin_amdgcn_rcpf(d0[i]), 1.0f), g1 = fmaxf(__builtin_amdgcn_rcpf(d1[i]), 1.0f);
;                         w.x = __builtin_amdgcn_cvt_pk_u8_f32(g0, i, w.x); w.y = __builtin_amdgcn_cvt_pk_u8_f32(g1, i, w.y); }
;                     *(u32x2*)(tb + lo + (unsigned)((ai * HALF + m * 16) * NGC + bj * HALF)) = w; }
	v_add_f32_e32 v138, v138, v142
	v_fmamk_f32 v138, v138, 0xbfb8aa3b, v236
	v_fma_f32 v126, v126, v147, v138
	v_exp_f32_e32 v142, v126
	v_add_f32_e32 v126, v130, v134
	v_fmamk_f32 v126, v126, 0xbfb8aa3b, v236
	v_fma_f32 v122, v122, v147, v126
	v_exp_f32_e32 v134, v122
	v_add_f32_e32 v122, v139, v143
	v_fmamk_f32 v130, v122, 0xbfb8aa3b, v236
	v_fma_f32 v122, v127, v147, v130
	v_exp_f32_e32 v143, v122
	v_add_f32_e32 v122, v131, v135
	v_fmamk_f32 v127, v122, 0xbfb8aa3b, v236
	v_fma_f32 v122, v123, v147, v127
	v_exp_f32_e32 v135, v122
	v_add_f32_e32 v122, v140, v144
	v_fmamk_f32 v123, v122, 0xbfb8aa3b, v236
	v_fma_f32 v122, v128, v147, v123
	v_exp_f32_e32 v140, v122
	v_add_f32_e32 v122, v132, v136
	v_fmamk_f32 v128, v122, 0xbfb8aa3b, v236
	v_fma_f32 v122, v124, v147, v128
	v_exp_f32_e32 v132, v122
	v_add_f32_e32 v122, v141, v145
	v_fmamk_f32 v124, v122, 0xbfb8aa3b, v236
	v_fma_f32 v122, v129, v147, v124
	v_exp_f32_e32 v141, v122
	v_add_f32_e32 v122, v133, v137
	v_fmamk_f32 v129, v122, 0xbfb8aa3b, v236
	v_fma_f32 v122, v125, v147, v129
	v_pk_add_f32 v[136:137], v[140:141], s[0:1] op_sel_hi:[1,0]
	v_pk_add_f32 v[140:141], v[142:143], s[0:1] op_sel_hi:[1,0]
	v_exp_f32_e32 v133, v122
	v_rcp_f32_e32 v122, v140
	v_rcp_f32_e32 v131, v141
	v_pk_add_f32 v[134:135], v[134:135], s[0:1] op_sel_hi:[1,0]
	v_pk_add_f32 v[132:133], v[132:133], s[0:1] op_sel_hi:[1,0]
	v_max_f32_e32 v122, 1.0, v122
	v_rcp_f32_e32 v125, v134
	v_cvt_pk_u8_f32 v122, v122, 0, 0
	v_max_f32_e32 v131, 1.0, v131
	v_rcp_f32_e32 v134, v135
	v_cvt_pk_u8_f32 v122, v131, 1, v122
	v_rcp_f32_e32 v131, v136
	v_rcp_f32_e32 v132, v132
	v_max_f32_e32 v125, 1.0, v125
	v_cvt_pk_u8_f32 v125, v125, 0, 0
	v_max_f32_e32 v134, 1.0, v134
	v_max_f32_e32 v131, 1.0, v131
	v_cvt_pk_u8_f32 v125, v134, 1, v125
	v_max_f32_e32 v132, 1.0, v132
	v_cvt_pk_u8_f32 v122, v131, 2, v122
	v_rcp_f32_e32 v131, v137
	v_cvt_pk_u8_f32 v125, v132, 2, v125
	v_rcp_f32_e32 v132, v133
	v_max_f32_e32 v131, 1.0, v131
	v_max_f32_e32 v133, 1.0, v132
	v_cvt_pk_u8_f32 v132, v131, 3, v122
	v_mul_f32_e32 v122, 0xbfb8aa3b, v167
	v_fma_f32 v114, v114, v122, v126
	v_fma_f32 v115, v115, v122, v127
	v_exp_f32_e32 v114, v114
	v_exp_f32_e32 v115, v115
	v_fma_f32 v116, v116, v122, v128
	v_fma_f32 v117, v117, v122, v129
	v_exp_f32_e32 v116, v116
	v_exp_f32_e32 v117, v117
	v_fma_f32 v118, v118, v122, v138
	v_fma_f32 v119, v119, v122, v130
	v_exp_f32_e32 v118, v118
	v_exp_f32_e32 v119, v119
	v_pk_add_f32 v[114:115], v[114:115], s[0:1] op_sel_hi:[1,0]
	v_fma_f32 v120, v120, v122, v123
	v_fma_f32 v121, v121, v122, v124
	v_rcp_f32_e32 v114, v114
	v_exp_f32_e32 v120, v120
	v_exp_f32_e32 v121, v121
	v_pk_add_f32 v[116:117], v[116:117], s[0:1] op_sel_hi:[1,0]
	v_rcp_f32_e32 v115, v115
	v_rcp_f32_e32 v116, v116
	v_pk_add_f32 v[118:119], v[118:119], s[0:1] op_sel_hi:[1,0]
	v_max_f32_e32 v114, 1.0, v114
	v_rcp_f32_e32 v118, v118
	v_pk_add_f32 v[120:121], v[120:121], s[0:1] op_sel_hi:[1,0]
	v_cvt_pk_u8_f32 v114, v114, 0, 0
	v_rcp_f32_e32 v119, v119
	v_max_f32_e32 v115, 1.0, v115
	v_cvt_pk_u8_f32 v114, v115, 1, v114
	v_rcp_f32_e32 v115, v120
	v_max_f32_e32 v116, 1.0, v116
	v_rcp_f32_e32 v117, v117
	v_cvt_pk_u8_f32 v114, v116, 2, v114
	v_rcp_f32_e32 v116, v121
	v_max_f32_e32 v118, 1.0, v118
	v_cvt_pk_u8_f32 v118, v118, 0, 0
	v_max_f32_e32 v119, 1.0, v119
	v_cvt_pk_u8_f32 v118, v119, 1, v118
	v_max_f32_e32 v115, 1.0, v115
	v_max_f32_e32 v117, 1.0, v117
	v_cvt_pk_u8_f32 v115, v115, 2, v118
	v_max_f32_e32 v116, 1.0, v116
	v_cvt_pk_u8_f32 v117, v117, 3, v114
	v_add_co_u32_e32 v114, vcc, s30, v148
	v_cvt_pk_u8_f32 v116, v116, 3, v115
	s_nop 0
	v_addc_co_u32_e32 v115, vcc, 0, v149, vcc
	global_store_dwordx2 v[114:115], v[116:117], off nt
	v_mul_f32_e32 v116, 0xbfb8aa3b, v166
	v_fma_f32 v106, v106, v116, v126
	v_fma_f32 v107, v107, v116, v127
	v_exp_f32_e32 v106, v106
	v_exp_f32_e32 v107, v107
	v_fma_f32 v108, v108, v116, v128
	v_fma_f32 v109, v109, v116, v129
	v_exp_f32_e32 v108, v108
	v_exp_f32_e32 v109, v109
	v_fma_f32 v110, v110, v116, v138
	v_fma_f32 v111, v111, v116, v130
	v_exp_f32_e32 v110, v110
	v_exp_f32_e32 v111, v111
	v_pk_add_f32 v[106:107], v[106:107], s[0:1] op_sel_hi:[1,0]
	v_fma_f32 v112, v112, v116, v123
	v_fma_f32 v113, v113, v116, v124
	v_rcp_f32_e32 v106, v106
	v_exp_f32_e32 v112, v112
	v_exp_f32_e32 v113, v113
	v_pk_add_f32 v[108:109], v[108:109], s[0:1] op_sel_hi:[1,0]
	v_rcp_f32_e32 v107, v107
	v_rcp_f32_e32 v108, v108
	v_pk_add_f32 v[110:111], v[110:111], s[0:1] op_sel_hi:[1,0]
	v_max_f32_e32 v106, 1.0, v106
	v_rcp_f32_e32 v110, v110
	v_pk_add_f32 v[112:113], v[112:113], s[0:1] op_sel_hi:[1,0]
	v_cvt_pk_u8_f32 v106, v106, 0, 0
	v_rcp_f32_e32 v111, v111
	v_max_f32_e32 v107, 1.0, v107
	v_cvt_pk_u8_f32 v106, v107, 1, v106
	v_rcp_f32_e32 v107, v112
	v_max_f32_e32 v108, 1.0, v108
	v_rcp_f32_e32 v109, v109
	v_cvt_pk_u8_f32 v106, v108, 2, v106
	v_rcp_f32_e32 v108, v113
	v_max_f32_e32 v110, 1.0, v110
	v_cvt_pk_u8_f32 v110, v110, 0, 0
	v_max_f32_e32 v111, 1.0, v111
	v_cvt_pk_u8_f32 v110, v111, 1, v110
	v_max_f32_e32 v107, 1.0, v107
	v_max_f32_e32 v109, 1.0, v109
	s_mov_b32 s30, 0x800
	v_cvt_pk_u8_f32 v107, v107, 2, v110
	v_max_f32_e32 v108, 1.0, v108
	v_cvt_pk_u8_f32 v109, v109, 3, v106
	v_add_co_u32_e32 v106, vcc, s30, v148
	v_cvt_pk_u8_f32 v108, v108, 3, v107
	s_nop 0
	v_addc_co_u32_e32 v107, vcc, 0, v149, vcc
	global_store_dwordx2 v[106:107], v[108:109], off nt
	v_mul_f32_e32 v108, 0xbfb8aa3b, v165
	v_fma_f32 v98, v98, v108, v126
	v_fma_f32 v99, v99, v108, v127
	v_exp_f32_e32 v98, v98
	v_exp_f32_e32 v99, v99
	v_fma_f32 v100, v100, v108, v128
	v_fma_f32 v101, v101, v108, v129
	v_exp_f32_e32 v100, v100
	v_exp_f32_e32 v101, v101
	v_fma_f32 v102, v102, v108, v138
;     template <int QVV> __device__ __forceinline__ void run(f32x4 (&acc)[2][2][4][2], const Unit& u, int wr, int wc, int fr, int fq) const {
;     ...
;             for (int ai = 0; ai < 2; ++ai)
; #pragma unroll
;                 for (int m = 0; m < 4; ++m) { if (ai >= nai) continue;
;                     const float rn = rs[ai][m] * (-LOG2E);
;                     const f32x4 x0 = acc[ai][bj][m][0] * rn + s0, x1 = acc[ai][bj][m][1] * rn + s1;
;                     f32x4 d0, d1;
; #pragma unroll
;                     for (int i = 0; i < 4; ++i) { d0[i] = __builtin_amdgcn_exp2f(x0[i]); d1[i] = __builtin_amdgcn_exp2f(x1[i]); }
;                     d0 = d0 + (1.0f / 255.0f); d1 = d1 + (1.0f / 255.0f);
;                     u32x2 w = {0u, 0u};
; #pragma unroll
;                     for (int i = 0; i < 4; ++i) { const float g0 = fmaxf(__builtin_amdgcn_rcpf(d0[i]), 1.0f), g1 = fmaxf(__builtin_amdgcn_rcpf(d1[i]), 1.0f);
;                         w.x = __builtin_amdgcn_cvt_pk_u8_f32(g0, i, w.x); w.y = __builtin_amdgcn_cvt_pk_u8_f32(g1, i, w.y); }
;                     *(u32x2*)(tb + lo + (unsigned)((ai * HALF + m * 16) * NGC + bj * HALF)) = w; }
	v_fma_f32 v103, v103, v108, v130
	v_exp_f32_e32 v102, v102
	v_exp_f32_e32 v103, v103
	v_pk_add_f32 v[98:99], v[98:99], s[0:1] op_sel_hi:[1,0]
	v_fma_f32 v104, v104, v108, v123
	v_fma_f32 v105, v105, v108, v124
	v_rcp_f32_e32 v98, v98
	v_exp_f32_e32 v104, v104
	v_exp_f32_e32 v105, v105
	v_pk_add_f32 v[100:101], v[100:101], s[0:1] op_sel_hi:[1,0]
	v_rcp_f32_e32 v99, v99
	v_rcp_f32_e32 v100, v100
	v_pk_add_f32 v[102:103], v[102:103], s[0:1] op_sel_hi:[1,0]
	v_max_f32_e32 v98, 1.0, v98
	v_rcp_f32_e32 v102, v102
	v_pk_add_f32 v[104:105], v[104:105], s[0:1] op_sel_hi:[1,0]
	v_cvt_pk_u8_f32 v98, v98, 0, 0
	v_rcp_f32_e32 v103, v103
	v_max_f32_e32 v99, 1.0, v99
	v_cvt_pk_u8_f32 v98, v99, 1, v98
	v_rcp_f32_e32 v99, v104
	v_max_f32_e32 v100, 1.0, v100
	v_rcp_f32_e32 v101, v101
	v_cvt_pk_u8_f32 v98, v100, 2, v98
	v_rcp_f32_e32 v100, v105
	v_max_f32_e32 v102, 1.0, v102
	v_cvt_pk_u8_f32 v102, v102, 0, 0
	v_max_f32_e32 v103, 1.0, v103
	v_cvt_pk_u8_f32 v102, v103, 1, v102
	v_max_f32_e32 v99, 1.0, v99
	v_max_f32_e32 v101, 1.0, v101
	s_mov_b32 s30, 0xc00
	v_cvt_pk_u8_f32 v99, v99, 2, v102
	v_max_f32_e32 v100, 1.0, v100
	v_cvt_pk_u8_f32 v101, v101, 3, v98
	v_add_co_u32_e32 v98, vcc, s30, v148
	v_cvt_pk_u8_f32 v100, v100, 3, v99
	s_nop 0
	v_addc_co_u32_e32 v99, vcc, 0, v149, vcc
	global_store_dwordx2 v[98:99], v[100:101], off nt
	v_mul_f32_e32 v100, 0xbfb8aa3b, v164
	v_fma_f32 v90, v90, v100, v126
	v_fma_f32 v91, v91, v100, v127
	v_exp_f32_e32 v90, v90
	v_exp_f32_e32 v91, v91
	v_fma_f32 v92, v92, v100, v128
	v_fma_f32 v93, v93, v100, v129
	v_exp_f32_e32 v92, v92
	v_exp_f32_e32 v93, v93
	v_fma_f32 v94, v94, v100, v138
	v_fma_f32 v95, v95, v100, v130
	v_exp_f32_e32 v94, v94
	v_exp_f32_e32 v95, v95
	v_pk_add_f32 v[90:91], v[90:91], s[0:1] op_sel_hi:[1,0]
	v_fma_f32 v96, v96, v100, v123
	v_fma_f32 v97, v97, v100, v124
	v_rcp_f32_e32 v90, v90
	v_exp_f32_e32 v96, v96
	v_exp_f32_e32 v97, v97
	v_pk_add_f32 v[92:93], v[92:93], s[0:1] op_sel_hi:[1,0]
	v_rcp_f32_e32 v91, v91
	v_rcp_f32_e32 v92, v92
	v_pk_add_f32 v[94:95], v[94:95], s[0:1] op_sel_hi:[1,0]
	v_max_f32_e32 v90, 1.0, v90
	v_rcp_f32_e32 v94, v94
	v_pk_add_f32 v[96:97], v[96:97], s[0:1] op_sel_hi:[1,0]
	v_cvt_pk_u8_f32 v90, v90, 0, 0
	v_rcp_f32_e32 v95, v95
	v_max_f32_e32 v91, 1.0, v91
	v_cvt_pk_u8_f32 v90, v91, 1, v90
	v_rcp_f32_e32 v91, v96
	v_max_f32_e32 v92, 1.0, v92
	v_rcp_f32_e32 v93, v93
	v_cvt_pk_u8_f32 v90, v92, 2, v90
	v_rcp_f32_e32 v92, v97
	v_max_f32_e32 v94, 1.0, v94
	v_cvt_pk_u8_f32 v94, v94, 0, 0
	v_max_f32_e32 v95, 1.0, v95
	v_cvt_pk_u8_f32 v94, v95, 1, v94
	v_max_f32_e32 v91, 1.0, v91
	v_max_f32_e32 v93, 1.0, v93
	s_mov_b32 s30, 0x1000
	v_cvt_pk_u8_f32 v91, v91, 2, v94
	v_max_f32_e32 v92, 1.0, v92
	v_cvt_pk_u8_f32 v93, v93, 3, v90
	v_add_co_u32_e32 v90, vcc, s30, v148
	v_cvt_pk_u8_f32 v92, v92, 3, v91
	s_nop 0
	v_addc_co_u32_e32 v91, vcc, 0, v149, vcc
	global_store_dwordx2 v[90:91], v[92:93], off nt
	v_mul_f32_e32 v92, 0xbfb8aa3b, v163
	v_fma_f32 v82, v82, v92, v126
	v_fma_f32 v83, v83, v92, v127
	v_exp_f32_e32 v82, v82
	v_exp_f32_e32 v83, v83
	v_fma_f32 v84, v84, v92, v128
	v_fma_f32 v85, v85, v92, v129
	v_exp_f32_e32 v84, v84
	v_exp_f32_e32 v85, v85
	v_fma_f32 v86, v86, v92, v138
	v_fma_f32 v87, v87, v92, v130
	v_exp_f32_e32 v86, v86
	v_exp_f32_e32 v87, v87
	v_pk_add_f32 v[82:83], v[82:83], s[0:1] op_sel_hi:[1,0]
	v_fma_f32 v88, v88, v92, v123
	v_fma_f32 v89, v89, v92, v124
	v_rcp_f32_e32 v82, v82
	v_exp_f32_e32 v88, v88
	v_exp_f32_e32 v89, v89
	v_pk_add_f32 v[84:85], v[84:85], s[0:1] op_sel_hi:[1,0]
	v_rcp_f32_e32 v83, v83
	v_rcp_f32_e32 v84, v84
	v_pk_add_f32 v[86:87], v[86:87], s[0:1] op_sel_hi:[1,0]
	v_max_f32_e32 v82, 1.0, v82
	v_rcp_f32_e32 v86, v86
	v_pk_add_f32 v[88:89], v[88:89], s[0:1] op_sel_hi:[1,0]
	v_cvt_pk_u8_f32 v82, v82, 0, 0
	v_rcp_f32_e32 v87, v87
	v_max_f32_e32 v83, 1.0, v83
	v_cvt_pk_u8_f32 v82, v83, 1, v82
	v_rcp_f32_e32 v83, v88
	v_max_f32_e32 v84, 1.0, v84
	v_rcp_f32_e32 v85, v85
	v_cvt_pk_u8_f32 v82, v84, 2, v82
	v_rcp_f32_e32 v84, v89
	v_max_f32_e32 v86, 1.0, v86
	v_cvt_pk_u8_f32 v86, v86, 0, 0
	v_max_f32_e32 v87, 1.0, v87
	v_cvt_pk_u8_f32 v86, v87, 1, v86
	v_max_f32_e32 v83, 1.0, v83
	v_max_f32_e32 v85, 1.0, v85
	s_mov_b32 s30, 0x1400
	v_cvt_pk_u8_f32 v83, v83, 2, v86
	v_max_f32_e32 v84, 1.0, v84
	v_cvt_pk_u8_f32 v85, v85, 3, v82
	v_add_co_u32_e32 v82, vcc, s30, v148
	v_cvt_pk_u8_f32 v84, v84, 3, v83
	s_nop 0
	v_addc_co_u32_e32 v83, vcc, 0, v149, vcc
	global_store_dwordx2 v[82:83], v[84:85], off nt
	v_mul_f32_e32 v84, 0xbfb8aa3b, v161
	v_fma_f32 v74, v74, v84, v126
	v_fma_f32 v75, v75, v84, v127
	v_exp_f32_e32 v74, v74
	v_exp_f32_e32 v75, v75
	v_fma_f32 v76, v76, v84, v128
	v_fma_f32 v77, v77, v84, v129
	v_exp_f32_e32 v76, v76
	v_exp_f32_e32 v77, v77
	v_fma_f32 v78, v78, v84, v138
	v_fma_f32 v79, v79, v84, v130
	v_exp_f32_e32 v78, v78
	v_exp_f32_e32 v79, v79
	v_pk_add_f32 v[74:75], v[74:75], s[0:1] op_sel_hi:[1,0]
	v_fma_f32 v80, v80, v84, v123
	v_fma_f32 v81, v81, v84, v124
	v_rcp_f32_e32 v74, v74
	v_exp_f32_e32 v80, v80
	v_exp_f32_e32 v81, v81
	v_pk_add_f32 v[76:77], v[76:77], s[0:1] op_sel_hi:[1,0]
	v_rcp_f32_e32 v75, v75
	v_rcp_f32_e32 v76, v76
	v_pk_add_f32 v[78:79], v[78:79], s[0:1] op_sel_hi:[1,0]
	v_max_f32_e32 v74, 1.0, v74
	v_rcp_f32_e32 v78, v78
	v_pk_add_f32 v[80:81], v[80:81], s[0:1] op_sel_hi:[1,0]
	v_cvt_pk_u8_f32 v74, v74, 0, 0
	v_rcp_f32_e32 v79, v79
	v_max_f32_e32 v75, 1.0, v75
	v_cvt_pk_u8_f32 v74, v75, 1, v74
	v_rcp_f32_e32 v75, v80
	v_max_f32_e32 v76, 1.0, v76
	v_rcp_f32_e32 v77, v77
	v_cvt_pk_u8_f32 v74, v76, 2, v74
	v_rcp_f32_e32 v76, v81
	v_max_f32_e32 v78, 1.0, v78
	v_cvt_pk_u8_f32 v78, v78, 0, 0
	v_max_f32_e32 v79, 1.0, v79
;     template <int QVV> __device__ __forceinline__ void run(f32x4 (&acc)[2][2][4][2], const Unit& u, int wr, int wc, int fr, int fq) const {
;     ...
;         for (int bj = 0; bj < 2; ++bj) {
;             const f32x4 s0 = (*(const f32x4*)(swb + co + bj * HALF * 4) + *(const f32x4*)(bmb + co + bj * HALF * 4)) * (-LOG2E) - 7.994353436858858f,
;                         s1 = (*(const f32x4*)(swb + co + bj * HALF * 4 + 16) + *(const f32x4*)(bmb + co + bj * HALF * 4 + 16)) * (-LOG2E) - 7.994353436858858f;
; #pragma unroll
;             for (int ai = 0; ai < 2; ++ai)
; #pragma unroll
;                 for (int m = 0; m < 4; ++m) { if (ai >= nai) continue;
;                     const float rn = rs[ai][m] * (-LOG2E);
;                     const f32x4 x0 = acc[ai][bj][m][0] * rn + s0, x1 = acc[ai][bj][m][1] * rn + s1;
;                     f32x4 d0, d1;
; #pragma unroll
;                     for (int i = 0; i < 4; ++i) { d0[i] = __builtin_amdgcn_exp2f(x0[i]); d1[i] = __builtin_amdgcn_exp2f(x1[i]); }
;                     d0 = d0 + (1.0f / 255.0f); d1 = d1 + (1.0f / 255.0f);
;                     u32x2 w = {0u, 0u};
; #pragma unroll
;                     for (int i = 0; i < 4; ++i) { const float g0 = fmaxf(__builtin_amdgcn_rcpf(d0[i]), 1.0f), g1 = fmaxf(__builtin_amdgcn_rcpf(d1[i]), 1.0f);
;                         w.x = __builtin_amdgcn_cvt_pk_u8_f32(g0, i, w.x); w.y = __builtin_amdgcn_cvt_pk_u8_f32(g1, i, w.y); }
;                     *(u32x2*)(tb + lo + (unsigned)((ai * HALF + m * 16) * NGC + bj * HALF)) = w; }
	v_cvt_pk_u8_f32 v78, v79, 1, v78
	v_max_f32_e32 v75, 1.0, v75
	v_max_f32_e32 v77, 1.0, v77
	s_mov_b32 s30, 0x1800
	v_cvt_pk_u8_f32 v75, v75, 2, v78
	v_max_f32_e32 v76, 1.0, v76
	v_cvt_pk_u8_f32 v77, v77, 3, v74
	v_add_co_u32_e32 v74, vcc, s30, v148
	v_cvt_pk_u8_f32 v76, v76, 3, v75
	s_nop 0
	v_addc_co_u32_e32 v75, vcc, 0, v149, vcc
	global_store_dwordx2 v[74:75], v[76:77], off nt
	v_mul_f32_e32 v76, 0xbfb8aa3b, v160
	v_fmac_f32_e32 v126, v66, v76
	v_fmac_f32_e32 v127, v67, v76
	v_exp_f32_e32 v66, v126
	v_exp_f32_e32 v67, v127
	v_fmac_f32_e32 v128, v68, v76
	v_fmac_f32_e32 v129, v69, v76
	v_exp_f32_e32 v68, v128
	v_exp_f32_e32 v69, v129
	v_fmac_f32_e32 v138, v70, v76
	v_fmac_f32_e32 v130, v71, v76
	v_exp_f32_e32 v70, v138
	v_exp_f32_e32 v71, v130
	v_pk_add_f32 v[66:67], v[66:67], s[0:1] op_sel_hi:[1,0]
	v_fmac_f32_e32 v123, v72, v76
	v_fmac_f32_e32 v124, v73, v76
	v_rcp_f32_e32 v66, v66
	v_exp_f32_e32 v72, v123
	v_exp_f32_e32 v73, v124
	v_pk_add_f32 v[68:69], v[68:69], s[0:1] op_sel_hi:[1,0]
	v_rcp_f32_e32 v67, v67
	v_rcp_f32_e32 v68, v68
	v_pk_add_f32 v[70:71], v[70:71], s[0:1] op_sel_hi:[1,0]
	v_max_f32_e32 v66, 1.0, v66
	v_rcp_f32_e32 v70, v70
	v_pk_add_f32 v[72:73], v[72:73], s[0:1] op_sel_hi:[1,0]
	v_cvt_pk_u8_f32 v66, v66, 0, 0
	v_rcp_f32_e32 v71, v71
	v_max_f32_e32 v67, 1.0, v67
	v_cvt_pk_u8_f32 v66, v67, 1, v66
	v_rcp_f32_e32 v67, v72
	v_max_f32_e32 v68, 1.0, v68
	v_rcp_f32_e32 v69, v69
	v_cvt_pk_u8_f32 v66, v68, 2, v66
	v_rcp_f32_e32 v68, v73
	v_max_f32_e32 v70, 1.0, v70
	v_cvt_pk_u8_f32 v70, v70, 0, 0
	v_max_f32_e32 v71, 1.0, v71
	v_cvt_pk_u8_f32 v70, v71, 1, v70
	v_max_f32_e32 v67, 1.0, v67
	v_max_f32_e32 v69, 1.0, v69
	s_mov_b32 s30, 0x1c00
	v_cvt_pk_u8_f32 v67, v67, 2, v70
	v_max_f32_e32 v68, 1.0, v68
	v_cvt_pk_u8_f32 v69, v69, 3, v66
	v_add_co_u32_e32 v66, vcc, s30, v148
	v_cvt_pk_u8_f32 v133, v133, 3, v125
	v_cvt_pk_u8_f32 v68, v68, 3, v67
	v_addc_co_u32_e32 v67, vcc, 0, v149, vcc
	global_store_dwordx2 v146, v[132:133], s[98:99] nt
	global_store_dwordx2 v[66:67], v[68:69], off nt
	global_load_dwordx4 v[70:73], v159, s[62:63] offset:528
	global_load_dwordx4 v[78:81], v159, s[62:63] offset:512
	global_load_dwordx4 v[86:89], v159, s[52:53] offset:528
	global_load_dwordx4 v[94:97], v159, s[52:53] offset:512
	s_mov_b64 s[30:31], -1
	s_andn2_b64 vcc, exec, s[38:39]
	s_waitcnt vmcnt(0)
	v_add_f32_e32 v68, v78, v94
	v_fmamk_f32 v68, v68, 0xbfb8aa3b, v236
	v_fma_f32 v62, v62, v147, v68
	v_exp_f32_e32 v78, v62
	v_add_f32_e32 v62, v70, v86
	v_fmamk_f32 v62, v62, 0xbfb8aa3b, v236
	v_fma_f32 v58, v58, v147, v62
	v_exp_f32_e32 v70, v58
	v_add_f32_e32 v58, v79, v95
	v_fmamk_f32 v58, v58, 0xbfb8aa3b, v236
	v_fma_f32 v63, v63, v147, v58
	v_exp_f32_e32 v79, v63
	v_add_f32_e32 v63, v71, v87
	v_fmamk_f32 v63, v63, 0xbfb8aa3b, v236
	v_fma_f32 v59, v59, v147, v63
	v_exp_f32_e32 v71, v59
	v_add_f32_e32 v59, v80, v96
	v_fmamk_f32 v59, v59, 0xbfb8aa3b, v236
	v_fma_f32 v64, v64, v147, v59
	v_exp_f32_e32 v80, v64
	v_add_f32_e32 v64, v72, v88
	v_fmamk_f32 v64, v64, 0xbfb8aa3b, v236
	v_fma_f32 v60, v60, v147, v64
	v_exp_f32_e32 v72, v60
	v_add_f32_e32 v60, v81, v97
	v_fmamk_f32 v60, v60, 0xbfb8aa3b, v236
	v_fma_f32 v65, v65, v147, v60
	v_exp_f32_e32 v81, v65
	v_add_f32_e32 v65, v73, v89
	v_fmamk_f32 v65, v65, 0xbfb8aa3b, v236
	v_fma_f32 v50, v50, v122, v62
	v_fma_f32 v51, v51, v122, v63
	v_fma_f32 v42, v42, v116, v62
	v_fma_f32 v43, v43, v116, v63
	v_fma_f32 v34, v34, v108, v62
	v_fma_f32 v35, v35, v108, v63
	v_fma_f32 v26, v26, v100, v62
	v_fma_f32 v27, v27, v100, v63
	v_fma_f32 v18, v18, v92, v62
	v_fma_f32 v19, v19, v92, v63
	v_fma_f32 v10, v10, v84, v62
	v_fma_f32 v11, v11, v84, v63
	v_fmac_f32_e32 v62, v2, v76
	v_fmac_f32_e32 v63, v3, v76
	v_fma_f32 v61, v61, v147, v65
	v_pk_add_f32 v[78:79], v[78:79], s[0:1] op_sel_hi:[1,0]
	v_pk_add_f32 v[70:71], v[70:71], s[0:1] op_sel_hi:[1,0]
	v_exp_f32_e32 v50, v50
	v_exp_f32_e32 v51, v51
	v_exp_f32_e32 v42, v42
	v_exp_f32_e32 v43, v43
	v_exp_f32_e32 v34, v34
	v_exp_f32_e32 v35, v35
	v_exp_f32_e32 v26, v26
	v_exp_f32_e32 v27, v27
	v_exp_f32_e32 v18, v18
	v_exp_f32_e32 v19, v19
	v_exp_f32_e32 v10, v10
	v_exp_f32_e32 v11, v11
	v_exp_f32_e32 v2, v62
	v_exp_f32_e32 v3, v63
	v_exp_f32_e32 v73, v61
	v_rcp_f32_e32 v61, v78
	v_rcp_f32_e32 v69, v70
	v_fma_f32 v52, v52, v122, v64
	v_fma_f32 v53, v53, v122, v65
	v_fma_f32 v44, v44, v116, v64
	v_fma_f32 v45, v45, v116, v65
	v_fma_f32 v36, v36, v108, v64
	v_fma_f32 v37, v37, v108, v65
	v_fma_f32 v28, v28, v100, v64
	v_fma_f32 v29, v29, v100, v65
	v_fma_f32 v20, v20, v92, v64
	v_fma_f32 v21, v21, v92, v65
	v_fma_f32 v12, v12, v84, v64
	v_fma_f32 v13, v13, v84, v65
	v_fmac_f32_e32 v64, v4, v76
	v_fmac_f32_e32 v65, v5, v76
	v_rcp_f32_e32 v70, v79
	v_rcp_f32_e32 v71, v71
	v_exp_f32_e32 v52, v52
	v_exp_f32_e32 v53, v53
	v_exp_f32_e32 v44, v44
	v_exp_f32_e32 v45, v45
	v_exp_f32_e32 v36, v36
	v_exp_f32_e32 v37, v37
	v_exp_f32_e32 v28, v28
	v_exp_f32_e32 v29, v29
	v_exp_f32_e32 v20, v20
	v_exp_f32_e32 v21, v21
	v_exp_f32_e32 v12, v12
	v_exp_f32_e32 v13, v13
	v_exp_f32_e32 v4, v64
	v_exp_f32_e32 v5, v65
	v_fma_f32 v54, v54, v122, v68
	v_fma_f32 v55, v55, v122, v58
	v_fma_f32 v46, v46, v116, v68
	v_fma_f32 v47, v47, v116, v58
	v_fma_f32 v38, v38, v108, v68
	v_fma_f32 v39, v39, v108, v58
	v_fma_f32 v30, v30, v100, v68
	v_fma_f32 v31, v31, v100, v58
	v_fma_f32 v22, v22, v92, v68
	v_fma_f32 v23, v23, v92, v58
	v_fma_f32 v14, v14, v84, v68
	v_fma_f32 v15, v15, v84, v58
	v_fmac_f32_e32 v68, v6, v76
	v_fmac_f32_e32 v58, v7, v76
	v_exp_f32_e32 v54, v54
	v_exp_f32_e32 v55, v55
	v_pk_add_f32 v[50:51], v[50:51], s[0:1] op_sel_hi:[1,0]
	v_exp_f32_e32 v46, v46
	v_exp_f32_e32 v47, v47
;     template <int QVV> __device__ __forceinline__ void run(f32x4 (&acc)[2][2][4][2], const Unit& u, int wr, int wc, int fr, int fq) const {
;     ...
;                 for (int m = 0; m < 4; ++m) { if (ai >= nai) continue;
;                     const float rn = rs[ai][m] * (-LOG2E);
;                     const f32x4 x0 = acc[ai][bj][m][0] * rn + s0, x1 = acc[ai][bj][m][1] * rn + s1;
;                     f32x4 d0, d1;
; #pragma unroll
;                     for (int i = 0; i < 4; ++i) { d0[i] = __builtin_amdgcn_exp2f(x0[i]); d1[i] = __builtin_amdgcn_exp2f(x1[i]); }
;                     d0 = d0 + (1.0f / 255.0f); d1 = d1 + (1.0f / 255.0f);
;                     u32x2 w = {0u, 0u};
; #pragma unroll
;                     for (int i = 0; i < 4; ++i) { const float g0 = fmaxf(__builtin_amdgcn_rcpf(d0[i]), 1.0f), g1 = fmaxf(__builtin_amdgcn_rcpf(d1[i]), 1.0f);
;                         w.x = __builtin_amdgcn_cvt_pk_u8_f32(g0, i, w.x); w.y = __builtin_amdgcn_cvt_pk_u8_f32(g1, i, w.y); }
	v_pk_add_f32 v[42:43], v[42:43], s[0:1] op_sel_hi:[1,0]
	v_exp_f32_e32 v38, v38
	v_exp_f32_e32 v39, v39
	v_pk_add_f32 v[34:35], v[34:35], s[0:1] op_sel_hi:[1,0]
	v_exp_f32_e32 v30, v30
	v_exp_f32_e32 v31, v31
	v_pk_add_f32 v[26:27], v[26:27], s[0:1] op_sel_hi:[1,0]
	v_exp_f32_e32 v22, v22
	v_exp_f32_e32 v23, v23
	v_pk_add_f32 v[18:19], v[18:19], s[0:1] op_sel_hi:[1,0]
	v_exp_f32_e32 v14, v14
	v_exp_f32_e32 v15, v15
	v_pk_add_f32 v[10:11], v[10:11], s[0:1] op_sel_hi:[1,0]
	v_exp_f32_e32 v6, v68
	v_exp_f32_e32 v7, v58
	v_pk_add_f32 v[2:3], v[2:3], s[0:1] op_sel_hi:[1,0]
	v_max_f32_e32 v61, 1.0, v61
	v_max_f32_e32 v69, 1.0, v69
	v_fma_f32 v56, v56, v122, v59
	v_fma_f32 v57, v57, v122, v60
	v_rcp_f32_e32 v50, v50
	v_fma_f32 v48, v48, v116, v59
	v_fma_f32 v49, v49, v116, v60
	v_rcp_f32_e32 v42, v42
	v_fma_f32 v40, v40, v108, v59
	v_fma_f32 v41, v41, v108, v60
	v_rcp_f32_e32 v34, v34
	v_fma_f32 v32, v32, v100, v59
	v_fma_f32 v33, v33, v100, v60
	v_rcp_f32_e32 v26, v26
	v_fma_f32 v24, v24, v92, v59
	v_fma_f32 v25, v25, v92, v60
	v_rcp_f32_e32 v18, v18
	v_fma_f32 v16, v16, v84, v59
	v_fma_f32 v17, v17, v84, v60
	v_rcp_f32_e32 v10, v10
	v_fmac_f32_e32 v59, v8, v76
	v_fmac_f32_e32 v60, v9, v76
	v_rcp_f32_e32 v2, v2
	v_pk_add_f32 v[80:81], v[80:81], s[0:1] op_sel_hi:[1,0]
	v_pk_add_f32 v[72:73], v[72:73], s[0:1] op_sel_hi:[1,0]
	v_cvt_pk_u8_f32 v61, v61, 0, 0
	v_cvt_pk_u8_f32 v69, v69, 0, 0
	v_max_f32_e32 v70, 1.0, v70
	v_max_f32_e32 v71, 1.0, v71
	v_exp_f32_e32 v56, v56
	v_exp_f32_e32 v57, v57
	v_pk_add_f32 v[52:53], v[52:53], s[0:1] op_sel_hi:[1,0]
	v_rcp_f32_e32 v51, v51
	v_exp_f32_e32 v48, v48
	v_exp_f32_e32 v49, v49
	v_pk_add_f32 v[44:45], v[44:45], s[0:1] op_sel_hi:[1,0]
	v_rcp_f32_e32 v43, v43
	v_exp_f32_e32 v40, v40
	v_exp_f32_e32 v41, v41
	v_pk_add_f32 v[36:37], v[36:37], s[0:1] op_sel_hi:[1,0]
	v_rcp_f32_e32 v35, v35
	v_exp_f32_e32 v32, v32
	v_exp_f32_e32 v33, v33
	v_pk_add_f32 v[28:29], v[28:29], s[0:1] op_sel_hi:[1,0]
	v_rcp_f32_e32 v27, v27
	v_exp_f32_e32 v24, v24
	v_exp_f32_e32 v25, v25
	v_pk_add_f32 v[20:21], v[20:21], s[0:1] op_sel_hi:[1,0]
	v_rcp_f32_e32 v19, v19
	v_exp_f32_e32 v16, v16
	v_exp_f32_e32 v17, v17
	v_pk_add_f32 v[12:13], v[12:13], s[0:1] op_sel_hi:[1,0]
	v_rcp_f32_e32 v11, v11
	v_exp_f32_e32 v8, v59
	v_exp_f32_e32 v9, v60
	v_pk_add_f32 v[4:5], v[4:5], s[0:1] op_sel_hi:[1,0]
	v_rcp_f32_e32 v3, v3
	v_cvt_pk_u8_f32 v61, v70, 1, v61
	v_cvt_pk_u8_f32 v69, v71, 1, v69
	v_rcp_f32_e32 v70, v80
	v_rcp_f32_e32 v71, v72
	v_rcp_f32_e32 v52, v52
	v_rcp_f32_e32 v44, v44
	v_rcp_f32_e32 v36, v36
	v_rcp_f32_e32 v28, v28
	v_rcp_f32_e32 v20, v20
	v_rcp_f32_e32 v12, v12
	v_rcp_f32_e32 v4, v4
	v_pk_add_f32 v[54:55], v[54:55], s[0:1] op_sel_hi:[1,0]
	v_pk_add_f32 v[46:47], v[46:47], s[0:1] op_sel_hi:[1,0]
	v_pk_add_f32 v[38:39], v[38:39], s[0:1] op_sel_hi:[1,0]
	v_pk_add_f32 v[30:31], v[30:31], s[0:1] op_sel_hi:[1,0]
	v_pk_add_f32 v[22:23], v[22:23], s[0:1] op_sel_hi:[1,0]
	v_pk_add_f32 v[14:15], v[14:15], s[0:1] op_sel_hi:[1,0]
	v_pk_add_f32 v[6:7], v[6:7], s[0:1] op_sel_hi:[1,0]
	v_rcp_f32_e32 v54, v54
	v_max_f32_e32 v50, 1.0, v50
	v_rcp_f32_e32 v46, v46
	v_max_f32_e32 v42, 1.0, v42
	v_rcp_f32_e32 v38, v38
	v_max_f32_e32 v34, 1.0, v34
	v_rcp_f32_e32 v30, v30
	v_max_f32_e32 v26, 1.0, v26
	v_rcp_f32_e32 v22, v22
	v_max_f32_e32 v18, 1.0, v18
	v_rcp_f32_e32 v14, v14
	v_max_f32_e32 v10, 1.0, v10
	v_rcp_f32_e32 v6, v6
	v_max_f32_e32 v2, 1.0, v2
	v_pk_add_f32 v[56:57], v[56:57], s[0:1] op_sel_hi:[1,0]
	v_cvt_pk_u8_f32 v50, v50, 0, 0
	v_rcp_f32_e32 v55, v55
	v_max_f32_e32 v51, 1.0, v51
	v_pk_add_f32 v[48:49], v[48:49], s[0:1] op_sel_hi:[1,0]
	v_cvt_pk_u8_f32 v42, v42, 0, 0
	v_rcp_f32_e32 v47, v47
	v_max_f32_e32 v43, 1.0, v43
	v_pk_add_f32 v[40:41], v[40:41], s[0:1] op_sel_hi:[1,0]
	v_cvt_pk_u8_f32 v34, v34, 0, 0
	v_rcp_f32_e32 v39, v39
	v_max_f32_e32 v35, 1.0, v35
	v_pk_add_f32 v[32:33], v[32:33], s[0:1] op_sel_hi:[1,0]
	v_cvt_pk_u8_f32 v26, v26, 0, 0
	v_rcp_f32_e32 v31, v31
	v_max_f32_e32 v27, 1.0, v27
	v_pk_add_f32 v[24:25], v[24:25], s[0:1] op_sel_hi:[1,0]
	v_cvt_pk_u8_f32 v18, v18, 0, 0
	v_rcp_f32_e32 v23, v23
	v_max_f32_e32 v19, 1.0, v19
	v_pk_add_f32 v[16:17], v[16:17], s[0:1] op_sel_hi:[1,0]
	v_cvt_pk_u8_f32 v10, v10, 0, 0
	v_rcp_f32_e32 v15, v15
	v_max_f32_e32 v11, 1.0, v11
	v_pk_add_f32 v[8:9], v[8:9], s[0:1] op_sel_hi:[1,0]
	v_cvt_pk_u8_f32 v2, v2, 0, 0
; #define PG8_BAR __builtin_amdgcn_s_barrier()
;     ...
;         if (wr == 0) PG8_BAR;
;         E.template run<QV>(acc, cur, wr, wc, fr, fq);
;         if (!has_next) break;
;         if (!cur.keep) {
; #pragma unroll
;             for (int a = 0; a < 2; ++a)
; #pragma unroll
;                 for (int b = 0; b < 2; ++b)
; #pragma unroll
;                     for (int m = 0; m < 4; ++m)
; #pragma unroll
;                         for (int n = 0; n < 2; ++n) { f32x2 z0, z1; asm("v_mov_b64 %0, 0\n\tv_mov_b64 %1, 0" : "=v"(z0), "=v"(z1));
;                     acc[a][b][m][n] = __builtin_shufflevector(z0, z1, 0, 1, 2, 3); }
;         }
;         cur = nxt; cA = nA; cB = nB; ++ui;
;         if (wr == 1) PG8_BAR;
;     template <int QVV> __device__ __forceinline__ void run(f32x4 (&acc)[2][2][4][2], const Unit& u, int wr, int wc, int fr, int fq) const {
;     ...
;                     for (int i = 0; i < 4; ++i) { d0[i] = __builtin_amdgcn_exp2f(x0[i]); d1[i] = __builtin_amdgcn_exp2f(x1[i]); }
;                     d0 = d0 + (1.0f / 255.0f); d1 = d1 + (1.0f / 255.0f);
;                     u32x2 w = {0u, 0u};
; #pragma unroll
;                     for (int i = 0; i < 4; ++i) { const float g0 = fmaxf(__builtin_amdgcn_rcpf(d0[i]), 1.0f), g1 = fmaxf(__builtin_amdgcn_rcpf(d1[i]), 1.0f);
;                         w.x = __builtin_amdgcn_cvt_pk_u8_f32(g0, i, w.x); w.y = __builtin_amdgcn_cvt_pk_u8_f32(g1, i, w.y); }
;                     *(u32x2*)(tb + lo + (unsigned)((ai * HALF + m * 16) * NGC + bj * HALF)) = w; }
	v_rcp_f32_e32 v7, v7
	v_max_f32_e32 v3, 1.0, v3
	v_max_f32_e32 v70, 1.0, v70
	v_max_f32_e32 v71, 1.0, v71
	v_cvt_pk_u8_f32 v50, v51, 1, v50
	v_rcp_f32_e32 v51, v56
	v_max_f32_e32 v52, 1.0, v52
	v_cvt_pk_u8_f32 v42, v43, 1, v42
	v_rcp_f32_e32 v43, v48
	v_max_f32_e32 v44, 1.0, v44
	v_cvt_pk_u8_f32 v34, v35, 1, v34
	v_rcp_f32_e32 v35, v40
	v_max_f32_e32 v36, 1.0, v36
	v_cvt_pk_u8_f32 v26, v27, 1, v26
	v_rcp_f32_e32 v27, v32
	v_max_f32_e32 v28, 1.0, v28
	v_cvt_pk_u8_f32 v18, v19, 1, v18
	v_rcp_f32_e32 v19, v24
	v_max_f32_e32 v20, 1.0, v20
	v_cvt_pk_u8_f32 v10, v11, 1, v10
	v_rcp_f32_e32 v11, v16
	v_max_f32_e32 v12, 1.0, v12
	v_cvt_pk_u8_f32 v2, v3, 1, v2
	v_rcp_f32_e32 v3, v8
	v_max_f32_e32 v4, 1.0, v4
	v_cvt_pk_u8_f32 v61, v70, 2, v61
	v_cvt_pk_u8_f32 v69, v71, 2, v69
	v_rcp_f32_e32 v70, v81
	v_rcp_f32_e32 v71, v73
	v_cvt_pk_u8_f32 v52, v52, 2, v50
	v_rcp_f32_e32 v50, v57
	v_rcp_f32_e32 v53, v53
	v_cvt_pk_u8_f32 v44, v44, 2, v42
	v_rcp_f32_e32 v42, v49
	v_rcp_f32_e32 v45, v45
	v_cvt_pk_u8_f32 v36, v36, 2, v34
	v_rcp_f32_e32 v34, v41
	v_rcp_f32_e32 v37, v37
	v_cvt_pk_u8_f32 v28, v28, 2, v26
	v_rcp_f32_e32 v26, v33
	v_rcp_f32_e32 v29, v29
	v_cvt_pk_u8_f32 v20, v20, 2, v18
	v_rcp_f32_e32 v18, v25
	v_rcp_f32_e32 v21, v21
	v_cvt_pk_u8_f32 v12, v12, 2, v10
	v_rcp_f32_e32 v10, v17
	v_rcp_f32_e32 v13, v13
	v_cvt_pk_u8_f32 v4, v4, 2, v2
	v_rcp_f32_e32 v2, v9
	v_rcp_f32_e32 v5, v5
	v_max_f32_e32 v54, 1.0, v54
	v_max_f32_e32 v46, 1.0, v46
	v_max_f32_e32 v38, 1.0, v38
	v_max_f32_e32 v30, 1.0, v30
	v_max_f32_e32 v22, 1.0, v22
	v_max_f32_e32 v14, 1.0, v14
	v_max_f32_e32 v6, 1.0, v6
	v_cvt_pk_u8_f32 v54, v54, 0, 0
	v_max_f32_e32 v55, 1.0, v55
	v_cvt_pk_u8_f32 v46, v46, 0, 0
	v_max_f32_e32 v47, 1.0, v47
	v_cvt_pk_u8_f32 v38, v38, 0, 0
	v_max_f32_e32 v39, 1.0, v39
	v_cvt_pk_u8_f32 v30, v30, 0, 0
	v_max_f32_e32 v31, 1.0, v31
	v_cvt_pk_u8_f32 v22, v22, 0, 0
	v_max_f32_e32 v23, 1.0, v23
	v_cvt_pk_u8_f32 v14, v14, 0, 0
	v_max_f32_e32 v15, 1.0, v15
	v_cvt_pk_u8_f32 v6, v6, 0, 0
	v_max_f32_e32 v7, 1.0, v7
	v_cvt_pk_u8_f32 v54, v55, 1, v54
	v_max_f32_e32 v51, 1.0, v51
	v_cvt_pk_u8_f32 v46, v47, 1, v46
	v_max_f32_e32 v43, 1.0, v43
	v_cvt_pk_u8_f32 v38, v39, 1, v38
	v_max_f32_e32 v35, 1.0, v35
	v_cvt_pk_u8_f32 v30, v31, 1, v30
	v_max_f32_e32 v27, 1.0, v27
	v_cvt_pk_u8_f32 v22, v23, 1, v22
	v_max_f32_e32 v19, 1.0, v19
	v_cvt_pk_u8_f32 v14, v15, 1, v14
	v_max_f32_e32 v11, 1.0, v11
	v_cvt_pk_u8_f32 v6, v7, 1, v6
	v_max_f32_e32 v3, 1.0, v3
	v_max_f32_e32 v70, 1.0, v70
	v_max_f32_e32 v71, 1.0, v71
	v_cvt_pk_u8_f32 v51, v51, 2, v54
	v_max_f32_e32 v50, 1.0, v50
	v_max_f32_e32 v53, 1.0, v53
	v_cvt_pk_u8_f32 v43, v43, 2, v46
	v_max_f32_e32 v42, 1.0, v42
	v_max_f32_e32 v45, 1.0, v45
	v_cvt_pk_u8_f32 v35, v35, 2, v38
	v_max_f32_e32 v34, 1.0, v34
	v_max_f32_e32 v37, 1.0, v37
	v_cvt_pk_u8_f32 v27, v27, 2, v30
	v_max_f32_e32 v26, 1.0, v26
	v_max_f32_e32 v29, 1.0, v29
	v_cvt_pk_u8_f32 v19, v19, 2, v22
	v_max_f32_e32 v18, 1.0, v18
	v_max_f32_e32 v21, 1.0, v21
	v_cvt_pk_u8_f32 v11, v11, 2, v14
	v_max_f32_e32 v10, 1.0, v10
	v_max_f32_e32 v13, 1.0, v13
	v_cvt_pk_u8_f32 v3, v3, 2, v6
	v_max_f32_e32 v2, 1.0, v2
	v_max_f32_e32 v5, 1.0, v5
	v_cvt_pk_u8_f32 v70, v70, 3, v61
	v_cvt_pk_u8_f32 v71, v71, 3, v69
	v_cvt_pk_u8_f32 v50, v50, 3, v51
	v_cvt_pk_u8_f32 v51, v53, 3, v52
	v_cvt_pk_u8_f32 v42, v42, 3, v43
	v_cvt_pk_u8_f32 v43, v45, 3, v44
	v_cvt_pk_u8_f32 v34, v34, 3, v35
	v_cvt_pk_u8_f32 v35, v37, 3, v36
	v_cvt_pk_u8_f32 v26, v26, 3, v27
	v_cvt_pk_u8_f32 v27, v29, 3, v28
	v_cvt_pk_u8_f32 v18, v18, 3, v19
	v_cvt_pk_u8_f32 v19, v21, 3, v20
	v_cvt_pk_u8_f32 v10, v10, 3, v11
	v_cvt_pk_u8_f32 v11, v13, 3, v12
	v_cvt_pk_u8_f32 v2, v2, 3, v3
	v_cvt_pk_u8_f32 v3, v5, 3, v4
	global_store_dwordx2 v146, v[70:71], s[98:99] offset:128 nt
	global_store_dwordx2 v[114:115], v[50:51], off offset:128 nt
	global_store_dwordx2 v[106:107], v[42:43], off offset:128 nt
	global_store_dwordx2 v[98:99], v[34:35], off offset:128 nt
	global_store_dwordx2 v[90:91], v[26:27], off offset:128 nt
	global_store_dwordx2 v[82:83], v[18:19], off offset:128 nt
	global_store_dwordx2 v[74:75], v[10:11], off offset:128 nt
	global_store_dwordx2 v[66:67], v[2:3], off offset:128 nt
	s_cbranch_vccnz .LBB0_1270
	s_andn2_b64 vcc, exec, s[48:49]
	v_mov_b64 v[2:3], 0
	v_mov_b64 v[4:5], 0
	s_cbranch_vccnz .LBB0_1269
	s_barrier
	s_branch .LBB0_1269

; __device__ __forceinline__ void row_rstd(const unsigned long long* ssq, int row0, float (&rs)[2][4]) {
;     unsigned long long q[2][4];
; #pragma unroll
;     for (int ai = 0; ai < 2; ++ai)
; #pragma unroll
;         for (int m = 0; m < 4; ++m) q[ai][m] = ssq[row0 + ai * HALF + m * 16];
;     asm volatile("" : "+v"(q[0][0]), "+v"(q[0][1]), "+v"(q[0][2]), "+v"(q[0][3]), "+v"(q[1][0]), "+v"(q[1][1]), "+v"(q[1][2]), "+v"(q[1][3]));
; #pragma unroll
;     for (int ai = 0; ai < 2; ++ai)
; #pragma unroll
;         for (int m = 0; m < 4; ++m) {
;             const float qf = __builtin_fmaf((float)(unsigned)(q[ai][m] >> 32), 4294967296.0f, (float)(unsigned)q[ai][m]);
;             rs[ai][m] = __builtin_amdgcn_rsqf(__builtin_fmaf(qf, 1.0f / (SSQ_SCALE * DM), EPS)); }
;     template <int QVV> __device__ __forceinline__ void run(f32x4 (&acc)[2][2][4][2], const Unit& u, int wr, int wc, int fr, int fq) const {
;         constexpr int nai = (QVV == 2) ? 1 : 2; const int r0 = u.pm * BM + (QVV == 2 ? (u.seg - 1) * HALF : 0);
;         char* tb = (char*)(O + (size_t)r0 * NGC + u.pn * BM);
;         const int v = u.pm < 4 ? 4 : ((u.pm - 4) >> 5);
;         const char* swb = (const char*)(sw + (size_t)v * SWLD + u.pn * BM); const char* bmb = (const char*)(bm + u.pn * BM);
;         unsigned lo = (unsigned)((wr * 64 + fr) * NGC + wc * 32 + 8 * fq);
;         unsigned co = (unsigned)(wc * 32 + 8 * fq) * 4u;
;         asm volatile("" : "+v"(lo), "+v"(co));
;         float rs[2][4]; row_rstd(ssq, r0 + wr * 64 + fr, rs);
; #pragma unroll
;         for (int bj = 0; bj < 2; ++bj) {
;             const f32x4 s0 = (*(const f32x4*)(swb + co + bj * HALF * 4) + *(const f32x4*)(bmb + co + bj * HALF * 4)) * (-LOG2E) - 7.994353436858858f,
;                         s1 = (*(const f32x4*)(swb + co + bj * HALF * 4 + 16) + *(const f32x4*)(bmb + co + bj * HALF * 4 + 16)) * (-LOG2E) - 7.994353436858858f;
; #pragma unroll
;             for (int ai = 0; ai < 2; ++ai)
; #pragma unroll
;                 for (int m = 0; m < 4; ++m) { if (ai >= nai) continue;
;                     const float rn = rs[ai][m] * (-LOG2E);
;                     const f32x4 x0 = acc[ai][bj][m][0] * rn + s0, x1 = acc[ai][bj][m][1] * rn + s1;
;                     f32x4 d0, d1;
; #pragma unroll
;                     for (int i = 0; i < 4; ++i) { d0[i] = __builtin_amdgcn_exp2f(x0[i]); d1[i] = __builtin_amdgcn_exp2f(x1[i]); }
.LBB0_1292:
	v_readlane_b32 s99, v253, 9
	s_mul_i32 s98, s10, 24
	s_add_i32 s98, s98, s11
	s_lshl_b32 s98, s98, 16
	s_lshl_b32 s99, s99, 5
	s_add_i32 s98, s98, s99
	s_add_u32 s98, s1, s98
	s_addc_u32 s99, s2, 0
	s_movk_i32 s12, 0x1800
	v_mul_lo_u32 v66, v70, s12
	s_lshl_b32 s10, s10, 8
	v_readlane_b32 s12, v253, 9
	s_or_b32 s10, s10, s12
	v_add_u32_e32 v68, s10, v70
	v_or_b32_e32 v67, s21, v71
	v_ashrrev_i32_e32 v69, 31, v68
	v_or3_b32 v66, v66, v71, s21
	v_lshlrev_b32_e32 v71, 2, v67
	v_lshl_add_u64 v[68:69], v[68:69], 3, s[44:45]
	global_load_dwordx2 v[88:89], v[68:69], off
	global_load_dwordx2 v[90:91], v[68:69], off offset:128
	global_load_dwordx2 v[92:93], v[68:69], off offset:256
	global_load_dwordx2 v[94:95], v[68:69], off offset:384
	global_load_dwordx2 v[72:73], v[68:69], off offset:1024
	global_load_dwordx2 v[74:75], v[68:69], off offset:1152
	global_load_dwordx2 v[76:77], v[68:69], off offset:1280
	s_nop 0
	global_load_dwordx2 v[68:69], v[68:69], off offset:1408
	s_mul_hi_i32 s12, s10, 0x1800
	s_mulk_i32 s10, 0x1800
	s_add_u32 s1, s1, s10
	s_addc_u32 s2, s2, s12
	s_lshl_b32 s10, s11, 8
	s_ashr_i32 s11, s10, 31
	s_add_u32 s30, s1, s10
	s_addc_u32 s31, s2, s11
	s_lshl_b64 s[12:13], s[38:39], 2
	s_add_u32 s1, s7, s12
	s_addc_u32 s2, s9, s13
	s_lshl_b64 s[10:11], s[10:11], 2
	s_add_u32 s38, s1, s10
	s_addc_u32 s39, s2, s11
	s_add_u32 s40, s3, s10
	s_addc_u32 s41, s5, s11
	s_flbit_i32_b32 s1, 0
	v_mov_b32_e32 v67, v175
	s_min_u32 s1, s1, 32
	s_sub_i32 s2, 32, s1
	s_waitcnt vmcnt(0)
	global_load_dwordx4 v[72:75], v71, s[38:39] offset:16
	global_load_dwordx4 v[76:79], v71, s[38:39]
	global_load_dwordx4 v[80:83], v71, s[40:41]
	global_load_dwordx4 v[84:87], v71, s[40:41] offset:16
	v_mov_b32_e32 v174, v89
	v_and_b32_e32 v66, 0x1c0, v0
	v_lshlrev_b32_e32 v66, 7, v66
	v_and_b32_e32 v69, 48, v0
	v_lshl_or_b32 v66, v69, 4, v66
	v_and_b32_e32 v69, 15, v0
	v_lshl_or_b32 v66, v69, 3, v66
	v_lshl_add_u64 v[68:69], s[98:99], 0, v[66:67]
	v_cvt_f32_u32_e32 v67, v88
	v_lshlrev_b64 v[88:89], s1, v[174:175]
	v_mov_b32_e32 v174, v91
	v_cvt_f32_u32_e32 v70, v90
	v_min_u32_e32 v88, 1, v88
	v_lshlrev_b64 v[90:91], s1, v[174:175]
	v_mov_b32_e32 v174, v93
	v_or_b32_e32 v93, v89, v88
	v_min_u32_e32 v90, 1, v90
	v_lshlrev_b64 v[88:89], s1, v[174:175]
	v_mov_b32_e32 v174, v95
	v_cvt_f32_u32_e32 v93, v93
	v_or_b32_e32 v95, v91, v90
	v_cvt_f32_u32_e32 v95, v95
	v_min_u32_e32 v88, 1, v88
	v_lshlrev_b64 v[90:91], s1, v[174:175]
	v_or_b32_e32 v88, v89, v88
	v_min_u32_e32 v89, 1, v90
	v_ldexp_f32 v90, v93, s2
	v_fmac_f32_e32 v67, 0x4f800000, v90
	v_ldexp_f32 v90, v95, s2
	v_fmac_f32_e32 v70, 0x4f800000, v90
	v_fmamk_f32 v67, v67, 0x30000000, v231
	v_fmamk_f32 v70, v70, 0x30000000, v231
	v_rsq_f32_e32 v67, v67
	v_rsq_f32_e32 v70, v70
	v_cvt_f32_u32_e32 v88, v88
	v_cvt_f32_u32_e32 v92, v92
	v_mul_f32_e32 v67, 0xbfb8aa3b, v67
	v_mul_f32_e32 v70, 0xbfb8aa3b, v70
	v_or_b32_e32 v89, v91, v89
	v_cvt_f32_u32_e32 v89, v89
	v_cvt_f32_u32_e32 v94, v94
	v_ldexp_f32 v88, v88, s2
	v_fmac_f32_e32 v92, 0x4f800000, v88
	v_ldexp_f32 v88, v89, s2
	v_fmamk_f32 v89, v92, 0x30000000, v231
	v_fmac_f32_e32 v94, 0x4f800000, v88
	v_rsq_f32_e32 v88, v89
	v_fmamk_f32 v89, v94, 0x30000000, v231
	v_rsq_f32_e32 v89, v89
	s_waitcnt vmcnt(1)
	v_add_f32_e32 v76, v76, v80
	s_waitcnt vmcnt(0)
	v_add_f32_e32 v72, v72, v84
	v_add_f32_e32 v77, v77, v81
	v_add_f32_e32 v73, v73, v85
	v_add_f32_e32 v74, v74, v86
	v_add_f32_e32 v75, v75, v87
	v_add_f32_e32 v78, v78, v82
	v_add_f32_e32 v79, v79, v83
	v_fmamk_f32 v76, v76, 0xbfb8aa3b, v236
	v_fmamk_f32 v72, v72, 0xbfb8aa3b, v236
	v_fmamk_f32 v77, v77, 0xbfb8aa3b, v236
	v_fmamk_f32 v73, v73, 0xbfb8aa3b, v236
	v_fmamk_f32 v74, v74, 0xbfb8aa3b, v236
	v_fmamk_f32 v75, v75, 0xbfb8aa3b, v236
	v_fmamk_f32 v78, v78, 0xbfb8aa3b, v236
	v_fmamk_f32 v79, v79, 0xbfb8aa3b, v236
	v_fma_f32 v62, v62, v67, v76
	v_fma_f32 v58, v58, v67, v72
	v_fma_f32 v63, v63, v67, v77
	v_fma_f32 v59, v59, v67, v73
	v_fma_f32 v60, v60, v67, v74
	v_fma_f32 v61, v61, v67, v75
	v_fma_f32 v81, v50, v70, v72
	v_fma_f32 v83, v51, v70, v73
	v_fma_f32 v84, v56, v70, v78
	v_fma_f32 v85, v52, v70, v74
	v_fma_f32 v86, v57, v70, v79
	v_fma_f32 v87, v53, v70, v75
	v_exp_f32_e32 v50, v62
	v_exp_f32_e32 v52, v58
	v_exp_f32_e32 v51, v63
	v_exp_f32_e32 v53, v59
	v_exp_f32_e32 v56, v60
	v_exp_f32_e32 v57, v61
	v_exp_f32_e32 v60, v81
	v_exp_f32_e32 v61, v83
	v_pk_add_f32 v[50:51], v[50:51], s[0:1] op_sel_hi:[1,0]
	v_pk_add_f32 v[52:53], v[52:53], s[0:1] op_sel_hi:[1,0]
	v_rcp_f32_e32 v50, v50
	v_pk_add_f32 v[60:61], v[60:61], s[0:1] op_sel_hi:[1,0]
	v_rcp_f32_e32 v52, v52
	v_rcp_f32_e32 v60, v60
	v_rcp_f32_e32 v51, v51
	v_rcp_f32_e32 v53, v53
	v_rcp_f32_e32 v61, v61
	v_max_f32_e32 v50, 1.0, v50
	v_max_f32_e32 v52, 1.0, v52
	v_max_f32_e32 v60, 1.0, v60
	v_max_f32_e32 v51, 1.0, v51
	v_max_f32_e32 v53, 1.0, v53
	v_max_f32_e32 v61, 1.0, v61
	v_cvt_pk_u8_f32 v50, v50, 0, 0
	v_cvt_pk_u8_f32 v52, v52, 0, 0
	v_cvt_pk_u8_f32 v60, v60, 0, 0
	v_fma_f32 v64, v64, v67, v78
	v_fma_f32 v65, v65, v67, v79
	v_fma_f32 v80, v54, v70, v76
	v_fma_f32 v82, v55, v70, v77
	v_cvt_pk_u8_f32 v50, v51, 1, v50
	v_cvt_pk_u8_f32 v51, v53, 1, v52
	v_cvt_pk_u8_f32 v53, v61, 1, v60
	v_mul_f32_e32 v60, 0xbfb8aa3b, v88
	v_exp_f32_e32 v54, v64
	v_exp_f32_e32 v55, v65
	v_exp_f32_e32 v58, v80
	v_exp_f32_e32 v59, v82
	v_exp_f32_e32 v62, v84
	v_exp_f32_e32 v64, v85
	v_exp_f32_e32 v63, v86
	v_exp_f32_e32 v65, v87
	v_fma_f32 v42, v42, v60, v72
	v_fma_f32 v43, v43, v60, v73
	v_exp_f32_e32 v42, v42
	v_exp_f32_e32 v43, v43
	v_fma_f32 v48, v48, v60, v78
	v_fma_f32 v49, v49, v60, v79
	v_exp_f32_e32 v48, v48
	v_exp_f32_e32 v49, v49
;     template <int QVV> __device__ __forceinline__ void run(f32x4 (&acc)[2][2][4][2], const Unit& u, int wr, int wc, int fr, int fq) const {
;     ...
;             for (int ai = 0; ai < 2; ++ai)
; #pragma unroll
;                 for (int m = 0; m < 4; ++m) { if (ai >= nai) continue;
;                     const float rn = rs[ai][m] * (-LOG2E);
;                     const f32x4 x0 = acc[ai][bj][m][0] * rn + s0, x1 = acc[ai][bj][m][1] * rn + s1;
;                     f32x4 d0, d1;
; #pragma unroll
;                     for (int i = 0; i < 4; ++i) { d0[i] = __builtin_amdgcn_exp2f(x0[i]); d1[i] = __builtin_amdgcn_exp2f(x1[i]); }
;                     d0 = d0 + (1.0f / 255.0f); d1 = d1 + (1.0f / 255.0f);
;                     u32x2 w = {0u, 0u};
; #pragma unroll
;                     for (int i = 0; i < 4; ++i) { const float g0 = fmaxf(__builtin_amdgcn_rcpf(d0[i]), 1.0f), g1 = fmaxf(__builtin_amdgcn_rcpf(d1[i]), 1.0f);
;                         w.x = __builtin_amdgcn_cvt_pk_u8_f32(g0, i, w.x); w.y = __builtin_amdgcn_cvt_pk_u8_f32(g1, i, w.y); }
;                     *(u32x2*)(tb + lo + (unsigned)((ai * HALF + m * 16) * NGC + bj * HALF)) = w; }
	v_pk_add_f32 v[54:55], v[54:55], s[0:1] op_sel_hi:[1,0]
	v_pk_add_f32 v[56:57], v[56:57], s[0:1] op_sel_hi:[1,0]
	v_pk_add_f32 v[62:63], v[62:63], s[0:1] op_sel_hi:[1,0]
	v_pk_add_f32 v[58:59], v[58:59], s[0:1] op_sel_hi:[1,0]
	v_pk_add_f32 v[64:65], v[64:65], s[0:1] op_sel_hi:[1,0]
	s_mov_b32 s1, 0x400
	v_rcp_f32_e32 v54, v54
	v_rcp_f32_e32 v56, v56
	v_pk_add_f32 v[42:43], v[42:43], s[0:1] op_sel_hi:[1,0]
	v_rcp_f32_e32 v55, v55
	v_rcp_f32_e32 v57, v57
	v_rcp_f32_e32 v42, v42
	v_pk_add_f32 v[48:49], v[48:49], s[0:1] op_sel_hi:[1,0]
	v_rcp_f32_e32 v43, v43
	v_rcp_f32_e32 v48, v48
	v_max_f32_e32 v54, 1.0, v54
	v_max_f32_e32 v56, 1.0, v56
	v_max_f32_e32 v55, 1.0, v55
	v_max_f32_e32 v57, 1.0, v57
	v_cvt_pk_u8_f32 v50, v54, 2, v50
	v_cvt_pk_u8_f32 v51, v56, 2, v51
	v_max_f32_e32 v42, 1.0, v42
	v_rcp_f32_e32 v64, v64
	v_cvt_pk_u8_f32 v50, v55, 3, v50
	v_cvt_pk_u8_f32 v51, v57, 3, v51
	v_fma_f32 v46, v46, v60, v76
	v_fma_f32 v47, v47, v60, v77
	v_cvt_pk_u8_f32 v42, v42, 0, 0
	v_max_f32_e32 v43, 1.0, v43
	global_store_dwordx2 v66, v[50:51], s[98:99] nt
	v_rcp_f32_e32 v50, v65
	v_exp_f32_e32 v46, v46
	v_exp_f32_e32 v47, v47
	v_fma_f32 v44, v44, v60, v74
	v_fma_f32 v45, v45, v60, v75
	v_cvt_pk_u8_f32 v42, v43, 1, v42
	v_max_f32_e32 v43, 1.0, v48
	v_mul_f32_e32 v48, 0xbfb8aa3b, v89
	v_exp_f32_e32 v44, v44
	v_exp_f32_e32 v45, v45
	v_fmac_f32_e32 v76, v38, v48
	v_fmac_f32_e32 v77, v39, v48
	v_exp_f32_e32 v38, v76
	v_exp_f32_e32 v39, v77
	v_max_f32_e32 v64, 1.0, v64
	v_fmac_f32_e32 v72, v34, v48
	v_fmac_f32_e32 v73, v35, v48
	v_cvt_pk_u8_f32 v53, v64, 2, v53
	v_max_f32_e32 v50, 1.0, v50
	v_pk_add_f32 v[46:47], v[46:47], s[0:1] op_sel_hi:[1,0]
	v_exp_f32_e32 v34, v72
	v_exp_f32_e32 v35, v73
	v_cvt_pk_u8_f32 v53, v50, 3, v53
	v_add_co_u32_e32 v50, vcc, s1, v68
	v_rcp_f32_e32 v46, v46
	v_pk_add_f32 v[44:45], v[44:45], s[0:1] op_sel_hi:[1,0]
	s_mov_b32 s1, 0x800
	v_fmac_f32_e32 v74, v36, v48
	v_fmac_f32_e32 v75, v37, v48
	v_rcp_f32_e32 v58, v58
	v_rcp_f32_e32 v47, v47
	v_fmac_f32_e32 v78, v40, v48
	v_exp_f32_e32 v36, v74
	v_fmac_f32_e32 v79, v41, v48
	v_exp_f32_e32 v37, v75
	v_pk_add_f32 v[38:39], v[38:39], s[0:1] op_sel_hi:[1,0]
	v_rcp_f32_e32 v59, v59
	v_exp_f32_e32 v40, v78
	v_exp_f32_e32 v41, v79
	v_rcp_f32_e32 v38, v38
	v_rcp_f32_e32 v62, v62
	v_pk_add_f32 v[34:35], v[34:35], s[0:1] op_sel_hi:[1,0]
	v_rcp_f32_e32 v39, v39
	v_rcp_f32_e32 v63, v63
	v_max_f32_e32 v46, 1.0, v46
	v_rcp_f32_e32 v44, v44
	v_rcp_f32_e32 v34, v34
	v_max_f32_e32 v58, 1.0, v58
	v_cvt_pk_u8_f32 v46, v46, 0, 0
	v_max_f32_e32 v47, 1.0, v47
	v_rcp_f32_e32 v45, v45
	v_pk_add_f32 v[36:37], v[36:37], s[0:1] op_sel_hi:[1,0]
	v_rcp_f32_e32 v35, v35
	v_max_f32_e32 v59, 1.0, v59
	v_cvt_pk_u8_f32 v58, v58, 0, 0
	v_cvt_pk_u8_f32 v46, v47, 1, v46
	v_rcp_f32_e32 v47, v49
	v_pk_add_f32 v[40:41], v[40:41], s[0:1] op_sel_hi:[1,0]
	v_max_f32_e32 v38, 1.0, v38
	v_rcp_f32_e32 v36, v36
	v_max_f32_e32 v62, 1.0, v62
	v_cvt_pk_u8_f32 v52, v59, 1, v58
	v_cvt_pk_u8_f32 v38, v38, 0, 0
	v_max_f32_e32 v39, 1.0, v39
	v_rcp_f32_e32 v40, v40
	v_rcp_f32_e32 v37, v37
	v_cvt_pk_u8_f32 v51, v62, 2, v52
	v_max_f32_e32 v52, 1.0, v63
	v_max_f32_e32 v44, 1.0, v44
	v_max_f32_e32 v34, 1.0, v34
	v_cvt_pk_u8_f32 v38, v39, 1, v38
	v_rcp_f32_e32 v39, v41
	v_cvt_pk_u8_f32 v52, v52, 3, v51
	v_addc_co_u32_e32 v51, vcc, 0, v69, vcc
	v_cvt_pk_u8_f32 v42, v44, 2, v42
	v_max_f32_e32 v45, 1.0, v45
	v_cvt_pk_u8_f32 v34, v34, 0, 0
	v_max_f32_e32 v35, 1.0, v35
	v_cvt_pk_u8_f32 v43, v43, 2, v46
	v_max_f32_e32 v44, 1.0, v47
	v_cvt_pk_u8_f32 v45, v45, 3, v42
	v_add_co_u32_e32 v42, vcc, s1, v68
	v_cvt_pk_u8_f32 v34, v35, 1, v34
	v_max_f32_e32 v36, 1.0, v36
	v_cvt_pk_u8_f32 v44, v44, 3, v43
	v_addc_co_u32_e32 v43, vcc, 0, v69, vcc
	v_max_f32_e32 v35, 1.0, v40
	v_cvt_pk_u8_f32 v34, v36, 2, v34
	v_max_f32_e32 v37, 1.0, v37
	s_mov_b32 s1, 0xc00
	v_cvt_pk_u8_f32 v35, v35, 2, v38
	v_max_f32_e32 v36, 1.0, v39
	v_cvt_pk_u8_f32 v37, v37, 3, v34
	v_add_co_u32_e32 v34, vcc, s1, v68
	v_cvt_pk_u8_f32 v36, v36, 3, v35
	s_nop 0
	v_addc_co_u32_e32 v35, vcc, 0, v69, vcc
	global_store_dwordx2 v[50:51], v[52:53], off nt
	global_store_dwordx2 v[42:43], v[44:45], off nt
	global_store_dwordx2 v[34:35], v[36:37], off nt
	global_load_dwordx4 v[36:39], v71, s[40:41] offset:512
	s_nop 0
	global_load_dwordx4 v[44:47], v71, s[38:39] offset:512
	global_load_dwordx4 v[52:55], v71, s[38:39] offset:528
	global_load_dwordx4 v[56:59], v71, s[40:41] offset:528
	s_waitcnt vmcnt(2)
	v_add_f32_e32 v36, v44, v36
	v_add_f32_e32 v37, v45, v37
	v_fmamk_f32 v36, v36, 0xbfb8aa3b, v236
	v_fmamk_f32 v37, v37, 0xbfb8aa3b, v236
	v_fma_f32 v30, v30, v67, v36
	v_fma_f32 v31, v31, v67, v37
	v_fma_f32 v22, v22, v70, v36
	v_fma_f32 v23, v23, v70, v37
	v_fma_f32 v14, v14, v60, v36
	v_fma_f32 v15, v15, v60, v37
	v_fmac_f32_e32 v36, v6, v48
	v_fmac_f32_e32 v37, v7, v48
	v_exp_f32_e32 v30, v30
	s_waitcnt vmcnt(0)
; #define PG8_WAIT_V(n) asm volatile("s_waitcnt vmcnt(" #n ")" ::: "memory")
; #define PG8_BAR __builtin_amdgcn_s_barrier()
;     ...
;     PG8_WAIT_V(0);
;     PG8_BAR;
;     template <int QVV> __device__ __forceinline__ void run(f32x4 (&acc)[2][2][4][2], const Unit& u, int wr, int wc, int fr, int fq) const {
;     ...
;         for (int bj = 0; bj < 2; ++bj) {
;             const f32x4 s0 = (*(const f32x4*)(swb + co + bj * HALF * 4) + *(const f32x4*)(bmb + co + bj * HALF * 4)) * (-LOG2E) - 7.994353436858858f,
;                         s1 = (*(const f32x4*)(swb + co + bj * HALF * 4 + 16) + *(const f32x4*)(bmb + co + bj * HALF * 4 + 16)) * (-LOG2E) - 7.994353436858858f;
; #pragma unroll
;             for (int ai = 0; ai < 2; ++ai)
; #pragma unroll
;                 for (int m = 0; m < 4; ++m) { if (ai >= nai) continue;
;                     const float rn = rs[ai][m] * (-LOG2E);
;                     const f32x4 x0 = acc[ai][bj][m][0] * rn + s0, x1 = acc[ai][bj][m][1] * rn + s1;
;                     f32x4 d0, d1;
; #pragma unroll
;                     for (int i = 0; i < 4; ++i) { d0[i] = __builtin_amdgcn_exp2f(x0[i]); d1[i] = __builtin_amdgcn_exp2f(x1[i]); }
;                     d0 = d0 + (1.0f / 255.0f); d1 = d1 + (1.0f / 255.0f);
;                     u32x2 w = {0u, 0u};
; #pragma unroll
;                     for (int i = 0; i < 4; ++i) { const float g0 = fmaxf(__builtin_amdgcn_rcpf(d0[i]), 1.0f), g1 = fmaxf(__builtin_amdgcn_rcpf(d1[i]), 1.0f);
;                         w.x = __builtin_amdgcn_cvt_pk_u8_f32(g0, i, w.x); w.y = __builtin_amdgcn_cvt_pk_u8_f32(g1, i, w.y); }
;                     *(u32x2*)(tb + lo + (unsigned)((ai * HALF + m * 16) * NGC + bj * HALF)) = w; }
	v_add_f32_e32 v40, v52, v56
	v_exp_f32_e32 v31, v31
	v_add_f32_e32 v41, v53, v57
	v_exp_f32_e32 v22, v22
	v_exp_f32_e32 v23, v23
	v_exp_f32_e32 v14, v14
	v_exp_f32_e32 v15, v15
	v_exp_f32_e32 v6, v36
	v_exp_f32_e32 v7, v37
	v_fmamk_f32 v40, v40, 0xbfb8aa3b, v236
	v_fmamk_f32 v41, v41, 0xbfb8aa3b, v236
	v_fma_f32 v26, v26, v67, v40
	v_fma_f32 v27, v27, v67, v41
	v_add_f32_e32 v38, v46, v38
	v_add_f32_e32 v44, v54, v58
	v_add_f32_e32 v39, v47, v39
	v_add_f32_e32 v45, v55, v59
	v_fma_f32 v18, v18, v70, v40
	v_fma_f32 v19, v19, v70, v41
	v_fma_f32 v10, v10, v60, v40
	v_fma_f32 v11, v11, v60, v41
	v_fmac_f32_e32 v40, v2, v48
	v_fmac_f32_e32 v41, v3, v48
	v_exp_f32_e32 v26, v26
	v_exp_f32_e32 v27, v27
	v_fmamk_f32 v38, v38, 0xbfb8aa3b, v236
	v_fmamk_f32 v44, v44, 0xbfb8aa3b, v236
	v_fmamk_f32 v39, v39, 0xbfb8aa3b, v236
	v_fmamk_f32 v45, v45, 0xbfb8aa3b, v236
	v_exp_f32_e32 v18, v18
	v_exp_f32_e32 v19, v19
	v_exp_f32_e32 v10, v10
	v_exp_f32_e32 v11, v11
	v_exp_f32_e32 v2, v40
	v_exp_f32_e32 v3, v41
	v_fma_f32 v32, v32, v67, v38
	v_fma_f32 v28, v28, v67, v44
	v_fma_f32 v33, v33, v67, v39
	v_fma_f32 v29, v29, v67, v45
	v_pk_add_f32 v[30:31], v[30:31], s[0:1] op_sel_hi:[1,0]
	v_fma_f32 v24, v24, v70, v38
	v_fma_f32 v20, v20, v70, v44
	v_fma_f32 v25, v25, v70, v39
	v_fma_f32 v21, v21, v70, v45
	v_pk_add_f32 v[22:23], v[22:23], s[0:1] op_sel_hi:[1,0]
	v_fma_f32 v16, v16, v60, v38
	v_fma_f32 v12, v12, v60, v44
	v_fma_f32 v17, v17, v60, v39
	v_fma_f32 v13, v13, v60, v45
	v_pk_add_f32 v[14:15], v[14:15], s[0:1] op_sel_hi:[1,0]
	v_fmac_f32_e32 v38, v8, v48
	v_fmac_f32_e32 v44, v4, v48
	v_fmac_f32_e32 v39, v9, v48
	v_fmac_f32_e32 v45, v5, v48
	v_pk_add_f32 v[6:7], v[6:7], s[0:1] op_sel_hi:[1,0]
	v_exp_f32_e32 v32, v32
	v_exp_f32_e32 v28, v28
	v_exp_f32_e32 v33, v33
	v_exp_f32_e32 v29, v29
	v_rcp_f32_e32 v30, v30
	v_exp_f32_e32 v24, v24
	v_exp_f32_e32 v20, v20
	v_exp_f32_e32 v25, v25
	v_exp_f32_e32 v21, v21
	v_rcp_f32_e32 v22, v22
	v_exp_f32_e32 v16, v16
	v_exp_f32_e32 v12, v12
	v_exp_f32_e32 v17, v17
	v_exp_f32_e32 v13, v13
	v_rcp_f32_e32 v14, v14
	v_exp_f32_e32 v8, v38
	v_exp_f32_e32 v4, v44
	v_exp_f32_e32 v9, v39
	v_exp_f32_e32 v5, v45
	v_rcp_f32_e32 v6, v6
	v_rcp_f32_e32 v31, v31
	v_rcp_f32_e32 v23, v23
	v_rcp_f32_e32 v15, v15
	v_rcp_f32_e32 v7, v7
	v_pk_add_f32 v[26:27], v[26:27], s[0:1] op_sel_hi:[1,0]
	v_pk_add_f32 v[18:19], v[18:19], s[0:1] op_sel_hi:[1,0]
	v_pk_add_f32 v[10:11], v[10:11], s[0:1] op_sel_hi:[1,0]
	v_pk_add_f32 v[2:3], v[2:3], s[0:1] op_sel_hi:[1,0]
	v_rcp_f32_e32 v26, v26
	v_rcp_f32_e32 v18, v18
	v_rcp_f32_e32 v10, v10
	v_rcp_f32_e32 v2, v2
	v_pk_add_f32 v[32:33], v[32:33], s[0:1] op_sel_hi:[1,0]
	v_pk_add_f32 v[28:29], v[28:29], s[0:1] op_sel_hi:[1,0]
	v_max_f32_e32 v30, 1.0, v30
	v_rcp_f32_e32 v27, v27
	v_pk_add_f32 v[24:25], v[24:25], s[0:1] op_sel_hi:[1,0]
	v_pk_add_f32 v[20:21], v[20:21], s[0:1] op_sel_hi:[1,0]
	v_max_f32_e32 v22, 1.0, v22
	v_rcp_f32_e32 v19, v19
	v_pk_add_f32 v[16:17], v[16:17], s[0:1] op_sel_hi:[1,0]
	v_pk_add_f32 v[12:13], v[12:13], s[0:1] op_sel_hi:[1,0]
	v_max_f32_e32 v14, 1.0, v14
	v_rcp_f32_e32 v11, v11
	v_pk_add_f32 v[8:9], v[8:9], s[0:1] op_sel_hi:[1,0]
	v_pk_add_f32 v[4:5], v[4:5], s[0:1] op_sel_hi:[1,0]
	v_max_f32_e32 v6, 1.0, v6
	v_rcp_f32_e32 v3, v3
	v_cvt_pk_u8_f32 v30, v30, 0, 0
	v_max_f32_e32 v31, 1.0, v31
	v_rcp_f32_e32 v32, v32
	v_rcp_f32_e32 v28, v28
	v_cvt_pk_u8_f32 v22, v22, 0, 0
	v_max_f32_e32 v23, 1.0, v23
	v_rcp_f32_e32 v24, v24
	v_rcp_f32_e32 v20, v20
	v_cvt_pk_u8_f32 v14, v14, 0, 0
	v_max_f32_e32 v15, 1.0, v15
	v_rcp_f32_e32 v16, v16
	v_rcp_f32_e32 v12, v12
	v_cvt_pk_u8_f32 v6, v6, 0, 0
	v_max_f32_e32 v7, 1.0, v7
	v_rcp_f32_e32 v8, v8
	v_rcp_f32_e32 v4, v4
	v_cvt_pk_u8_f32 v30, v31, 1, v30
	v_rcp_f32_e32 v31, v33
	v_rcp_f32_e32 v29, v29
	v_cvt_pk_u8_f32 v22, v23, 1, v22
	v_rcp_f32_e32 v23, v25
	v_rcp_f32_e32 v21, v21
	v_cvt_pk_u8_f32 v14, v15, 1, v14
	v_rcp_f32_e32 v15, v17
	v_rcp_f32_e32 v13, v13
	v_cvt_pk_u8_f32 v6, v7, 1, v6
	v_rcp_f32_e32 v7, v9
	v_rcp_f32_e32 v5, v5
	v_max_f32_e32 v26, 1.0, v26
	v_max_f32_e32 v18, 1.0, v18
	v_max_f32_e32 v10, 1.0, v10
	v_max_f32_e32 v2, 1.0, v2
	v_cvt_pk_u8_f32 v26, v26, 0, 0
	v_max_f32_e32 v27, 1.0, v27
	v_cvt_pk_u8_f32 v18, v18, 0, 0
	v_max_f32_e32 v19, 1.0, v19
	v_cvt_pk_u8_f32 v10, v10, 0, 0
	v_max_f32_e32 v11, 1.0, v11
	v_cvt_pk_u8_f32 v2, v2, 0, 0
	v_max_f32_e32 v3, 1.0, v3
	v_cvt_pk_u8_f32 v26, v27, 1, v26
	v_max_f32_e32 v27, 1.0, v32
	v_max_f32_e32 v28, 1.0, v28
	v_cvt_pk_u8_f32 v18, v19, 1, v18
	v_max_f32_e32 v19, 1.0, v24
	v_max_f32_e32 v20, 1.0, v20
	v_cvt_pk_u8_f32 v10, v11, 1, v10
	v_max_f32_e32 v11, 1.0, v16
	v_max_f32_e32 v12, 1.0, v12
	v_cvt_pk_u8_f32 v2, v3, 1, v2
	v_max_f32_e32 v3, 1.0, v8
	v_max_f32_e32 v4, 1.0, v4
	v_cvt_pk_u8_f32 v27, v27, 2, v30
	v_cvt_pk_u8_f32 v28, v28, 2, v26
	v_max_f32_e32 v26, 1.0, v31
	v_max_f32_e32 v29, 1.0, v29
	v_cvt_pk_u8_f32 v19, v19, 2, v22
	v_cvt_pk_u8_f32 v20, v20, 2, v18
	v_max_f32_e32 v18, 1.0, v23
	v_max_f32_e32 v21, 1.0, v21
	v_cvt_pk_u8_f32 v11, v11, 2, v14
	v_cvt_pk_u8_f32 v12, v12, 2, v10
	v_max_f32_e32 v10, 1.0, v15
	v_max_f32_e32 v13, 1.0, v13
	v_cvt_pk_u8_f32 v3, v3, 2, v6
	v_cvt_pk_u8_f32 v4, v4, 2, v2
	v_max_f32_e32 v2, 1.0, v7
	v_max_f32_e32 v5, 1.0, v5
	v_cvt_pk_u8_f32 v26, v26, 3, v27
	v_cvt_pk_u8_f32 v27, v29, 3, v28
	v_cvt_pk_u8_f32 v18, v18, 3, v19
	v_cvt_pk_u8_f32 v19, v21, 3, v20
	v_cvt_pk_u8_f32 v10, v10, 3, v11
	v_cvt_pk_u8_f32 v11, v13, 3, v12
	v_cvt_pk_u8_f32 v2, v2, 3, v3
	v_cvt_pk_u8_f32 v3, v5, 3, v4
	global_store_dwordx2 v66, v[26:27], s[98:99] offset:128 nt
	global_store_dwordx2 v[50:51], v[18:19], off offset:128 nt
	global_store_dwordx2 v[42:43], v[10:11], off offset:128 nt
	global_store_dwordx2 v[34:35], v[2:3], off offset:128 nt
	s_waitcnt vmcnt(0)
	s_barrier

; __device__ __forceinline__ void row_rstd(const unsigned long long* ssq, int row0, float (&rs)[2][4]) {
;     unsigned long long q[2][4];
; #pragma unroll
;     for (int ai = 0; ai < 2; ++ai)
; #pragma unroll
;         for (int m = 0; m < 4; ++m) q[ai][m] = ssq[row0 + ai * HALF + m * 16];
;     asm volatile("" : "+v"(q[0][0]), "+v"(q[0][1]), "+v"(q[0][2]), "+v"(q[0][3]), "+v"(q[1][0]), "+v"(q[1][1]), "+v"(q[1][2]), "+v"(q[1][3]));
; #pragma unroll
;     for (int ai = 0; ai < 2; ++ai)
; #pragma unroll
;         for (int m = 0; m < 4; ++m) {
;             const float qf = __builtin_fmaf((float)(unsigned)(q[ai][m] >> 32), 4294967296.0f, (float)(unsigned)q[ai][m]);
;             rs[ai][m] = __builtin_amdgcn_rsqf(__builtin_fmaf(qf, 1.0f / (SSQ_SCALE * DM), EPS)); }
; }
;     template <int QVV> __device__ __forceinline__ void run(f32x4 (&acc)[2][2][4][2], const Unit& u, int wr, int wc, int fr, int fq) const {
;         constexpr int nai = (QVV == 2) ? 1 : 2; const int r0 = u.pm * BM + (QVV == 2 ? (u.seg - 1) * HALF : 0);
;         char* tb = (char*)(O + (size_t)r0 * DFF + u.pn * HALF);
;         const int v = u.pm < 4 ? 4 : ((u.pm - 4) >> 5);
;         const char* swb = (const char*)(sw + (size_t)v * SWLD + u.pn * BM);
;         unsigned lo = (unsigned)((wr * 64 + fr) * DFF + wc * 32 + 8 * fq) * 2u;
;         unsigned co = (unsigned)(wc * 32 + 8 * fq) * 4u;
;         asm volatile("" : "+v"(lo), "+v"(co));
;         float rs[2][4]; row_rstd(ssq, r0 + wr * 64 + fr, rs);
;         f32x4 sg[2], su[2], sgn[2];
; #pragma unroll
;         for (int n = 0; n < 2; ++n) { sg[n] = *(const f32x4*)(swb + co + n * 16); su[n] = *(const f32x4*)(swb + co + HALF * 4 + n * 16); sgn[n] = sg[n] * (-LOG2E); }
.LBB0_1656:
	s_lshl_b32 s30, s60, 8
	v_add_u32_e32 v82, s30, v169
	v_ashrrev_i32_e32 v83, 31, v82
	v_mov_b32_e32 v98, v171
	v_mov_b32_e32 v166, v170
	v_lshl_add_u64 v[82:83], v[82:83], 3, s[34:35]
	global_load_dwordx2 v[150:151], v[82:83], off
	global_load_dwordx2 v[152:153], v[82:83], off offset:128
	global_load_dwordx2 v[154:155], v[82:83], off offset:256
	global_load_dwordx2 v[156:157], v[82:83], off offset:384
	global_load_dwordx2 v[178:179], v[82:83], off offset:1024
	global_load_dwordx2 v[180:181], v[82:83], off offset:1152
	global_load_dwordx2 v[182:183], v[82:83], off offset:1280
	global_load_dwordx2 v[184:185], v[82:83], off offset:1408
	s_mul_i32 s31, s60, 0x2b0000
	s_mul_hi_i32 s30, s30, 0x2b00
	s_add_u32 s60, s2, s31
	s_addc_u32 s61, s3, s30
	s_lshl_b32 s30, s59, 7
	s_ashr_i32 s31, s30, 31
	s_lshl_b64 s[30:31], s[30:31], 1
	s_add_u32 s30, s60, s30
	s_addc_u32 s31, s61, s31
	s_lshl_b64 s[42:43], s[42:43], 2
	s_add_u32 s60, s5, s42
	s_addc_u32 s61, s7, s43
	s_lshl_b32 s42, s59, 8
	s_ashr_i32 s43, s42, 31
	s_lshl_b64 s[42:43], s[42:43], 2
	s_add_u32 s42, s60, s42
	s_addc_u32 s43, s61, s43
	s_flbit_i32_b32 s59, 0
	s_min_u32 s59, s59, 32
	s_sub_i32 s60, 32, s59
	v_mov_b32_e32 v167, v175
	v_lshl_add_u64 v[146:147], s[30:31], 0, v[166:167]
	s_waitcnt vmcnt(0)
	global_load_dwordx4 v[86:89], v98, s[42:43] offset:16
	global_load_dwordx4 v[102:105], v98, s[42:43]
	global_load_dwordx4 v[82:85], v98, s[42:43] offset:528
	s_nop 0
	global_load_dwordx4 v[98:101], v98, s[42:43] offset:512
	v_mov_b32_e32 v174, v151
	v_cvt_f32_u32_e32 v148, v150
	v_lshlrev_b64 v[150:151], s59, v[174:175]
	v_mov_b32_e32 v174, v153
	v_cvt_f32_u32_e32 v158, v152
	v_min_u32_e32 v150, 1, v150
	v_lshlrev_b64 v[152:153], s59, v[174:175]
	v_mov_b32_e32 v174, v155
	v_or_b32_e32 v155, v151, v150
	v_min_u32_e32 v152, 1, v152
	v_lshlrev_b64 v[150:151], s59, v[174:175]
	v_mov_b32_e32 v174, v157
	v_cvt_f32_u32_e32 v155, v155
	v_or_b32_e32 v157, v153, v152
	v_min_u32_e32 v150, 1, v150
	v_lshlrev_b64 v[152:153], s59, v[174:175]
	v_mov_b32_e32 v174, v179
	v_cvt_f32_u32_e32 v157, v157
	v_or_b32_e32 v162, v151, v150
	v_min_u32_e32 v152, 1, v152
	v_lshlrev_b64 v[150:151], s59, v[174:175]
	v_mov_b32_e32 v174, v181
	v_cvt_f32_u32_e32 v162, v162
	v_or_b32_e32 v164, v153, v152
	v_min_u32_e32 v150, 1, v150
	v_lshlrev_b64 v[152:153], s59, v[174:175]
	v_mov_b32_e32 v174, v183
	v_cvt_f32_u32_e32 v154, v154
	v_cvt_f32_u32_e32 v164, v164
	v_or_b32_e32 v168, v151, v150
	v_lshlrev_b64 v[150:151], s59, v[174:175]
	v_cvt_f32_u32_e32 v156, v156
	v_min_u32_e32 v152, 1, v152
	v_mov_b32_e32 v174, v185
	v_ldexp_f32 v155, v155, s60
	v_cvt_f32_u32_e32 v168, v168
	v_min_u32_e32 v150, 1, v150
	v_cvt_f32_u32_e32 v160, v178
	v_or_b32_e32 v178, v153, v152
	v_lshlrev_b64 v[152:153], s59, v[174:175]
	v_fmac_f32_e32 v148, 0x4f800000, v155
	v_ldexp_f32 v155, v157, s60
	v_or_b32_e32 v150, v151, v150
	v_cvt_f32_u32_e32 v157, v178
	v_min_u32_e32 v151, 1, v152
	v_fmamk_f32 v148, v148, 0x30000000, v231
	v_fmac_f32_e32 v158, 0x4f800000, v155
	v_ldexp_f32 v152, v162, s60
	v_cvt_f32_u32_e32 v150, v150
	v_cvt_f32_u32_e32 v167, v180
	v_cvt_f32_u32_e32 v177, v182
	v_or_b32_e32 v151, v153, v151
	v_rsq_f32_e32 v174, v148
	v_fmamk_f32 v148, v158, 0x30000000, v231
	v_fmac_f32_e32 v154, 0x4f800000, v152
	v_ldexp_f32 v152, v164, s60
	v_cvt_f32_u32_e32 v151, v151
	v_rsq_f32_e32 v178, v148
	v_fmamk_f32 v148, v154, 0x30000000, v231
	v_fmac_f32_e32 v156, 0x4f800000, v152
	v_ldexp_f32 v152, v168, s60
	v_cvt_f32_u32_e32 v188, v184
	v_rsq_f32_e32 v168, v148
	v_fmamk_f32 v148, v156, 0x30000000, v231
	v_fmac_f32_e32 v160, 0x4f800000, v152
	v_ldexp_f32 v152, v157, s60
	v_rsq_f32_e32 v164, v148
	v_fmamk_f32 v148, v160, 0x30000000, v231
	v_ldexp_f32 v150, v150, s60
	v_fmac_f32_e32 v167, 0x4f800000, v152
	v_rsq_f32_e32 v162, v148
	v_fmac_f32_e32 v177, 0x4f800000, v150
	v_mul_f32_e32 v148, 0xbfb8aa3b, v174
	s_mov_b32 s42, 0xbfb8aa3b
	v_fmamk_f32 v152, v167, 0x30000000, v231
	v_ldexp_f32 v150, v151, s60
	v_fmamk_f32 v151, v177, 0x30000000, v231
	v_pk_mul_f32 v[182:183], v[142:143], v[148:149] op_sel_hi:[1,0]
	s_waitcnt vmcnt(2)
	v_pk_mul_f32 v[156:157], v[102:103], s[42:43] op_sel_hi:[1,0]
	v_rsq_f32_e32 v160, v152
	v_fmac_f32_e32 v188, 0x4f800000, v150
	v_pk_mul_f32 v[180:181], v[144:145], v[148:149] op_sel_hi:[1,0]
	v_pk_mul_f32 v[184:185], v[136:137], v[148:149] op_sel_hi:[1,0]
	v_pk_mul_f32 v[186:187], v[134:135], v[148:149] op_sel_hi:[1,0]
	v_rsq_f32_e32 v158, v151
	v_pk_mul_f32 v[154:155], v[104:105], s[42:43] op_sel_hi:[1,0]
	v_pk_mul_f32 v[150:151], v[88:89], s[42:43] op_sel_hi:[1,0]
	v_pk_mul_f32 v[152:153], v[86:87], s[42:43] op_sel_hi:[1,0]
	v_pk_fma_f32 v[144:145], v[144:145], v[174:175], v[104:105] op_sel_hi:[1,0,1]
	v_pk_fma_f32 v[142:143], v[142:143], v[174:175], v[102:103] op_sel_hi:[1,0,1]
	s_waitcnt vmcnt(0)
;     template <int QVV> __device__ __forceinline__ void run(f32x4 (&acc)[2][2][4][2], const Unit& u, int wr, int wc, int fr, int fq) const {
;     ...
; #pragma unroll
;         for (int ai = 0; ai < 2; ++ai)
; #pragma unroll
;             for (int m = 0; m < 4; ++m) { if (ai >= nai) continue;
;                 const float r = rs[ai][m], rn = r * (-LOG2E);
;                 f32x4 o[2];
; #pragma unroll
;                 for (int n = 0; n < 2; ++n) {
;                     const f32x4 gt = acc[ai][0][m][n] * r + sg[n], up = acc[ai][1][m][n] * r + su[n], ex = acc[ai][0][m][n] * rn + sgn[n];
;                     f32x4 den, rc;
; #pragma unroll
;                     for (int i = 0; i < 4; ++i) den[i] = __builtin_amdgcn_exp2f(ex[i]);
;                     den = den + 1.0f;
; #pragma unroll
;                     for (int i = 0; i < 4; ++i) rc[i] = __builtin_amdgcn_rcpf(den[i]);
;                     o[n] = (gt * up) * rc; }
;                 u32x4 w; w.x = pk2(o[0][0], o[0][1]); w.y = pk2(o[0][2], o[0][3]); w.z = pk2(o[1][0], o[1][1]); w.w = pk2(o[1][2], o[1][3]);
;                 *(u32x4*)(tb + lo + (unsigned)(ai * HALF + m * 16) * (DFF * 2)) = w; }
	v_pk_fma_f32 v[140:141], v[140:141], v[174:175], v[100:101] op_sel_hi:[1,0,1]
	v_pk_fma_f32 v[138:139], v[138:139], v[174:175], v[98:99] op_sel_hi:[1,0,1]
	v_pk_fma_f32 v[136:137], v[136:137], v[174:175], v[88:89] op_sel_hi:[1,0,1]
	v_pk_fma_f32 v[134:135], v[134:135], v[174:175], v[86:87] op_sel_hi:[1,0,1]
	v_pk_fma_f32 v[132:133], v[132:133], v[174:175], v[84:85] op_sel_hi:[1,0,1]
	v_pk_fma_f32 v[130:131], v[130:131], v[174:175], v[82:83] op_sel_hi:[1,0,1]
	v_add_f32_e32 v167, v156, v182
	v_add_f32_e32 v174, v157, v183
	v_add_f32_e32 v177, v154, v180
	v_add_f32_e32 v179, v155, v181
	v_pk_mul_f32 v[138:139], v[142:143], v[138:139]
	v_pk_mul_f32 v[140:141], v[144:145], v[140:141]
	v_add_f32_e32 v142, v152, v186
	v_add_f32_e32 v143, v153, v187
	v_add_f32_e32 v144, v150, v184
	v_add_f32_e32 v145, v151, v185
	v_pk_mul_f32 v[130:131], v[134:135], v[130:131]
	v_exp_f32_e32 v134, v167
	v_exp_f32_e32 v135, v174
	v_pk_mul_f32 v[132:133], v[136:137], v[132:133]
	v_exp_f32_e32 v136, v177
	v_exp_f32_e32 v137, v179
	v_exp_f32_e32 v142, v142
	v_exp_f32_e32 v144, v144
	v_exp_f32_e32 v145, v145
	v_exp_f32_e32 v143, v143
	v_pk_add_f32 v[134:135], v[134:135], 1.0 op_sel_hi:[1,0]
	v_pk_add_f32 v[136:137], v[136:137], 1.0 op_sel_hi:[1,0]
	v_pk_add_f32 v[144:145], v[144:145], 1.0 op_sel_hi:[1,0]
	v_pk_add_f32 v[142:143], v[142:143], 1.0 op_sel_hi:[1,0]
	v_rcp_f32_e32 v134, v134
	v_rcp_f32_e32 v135, v135
	v_rcp_f32_e32 v136, v136
	v_rcp_f32_e32 v137, v137
	v_rcp_f32_e32 v142, v142
	v_rcp_f32_e32 v144, v144
	v_rcp_f32_e32 v145, v145
	v_rcp_f32_e32 v143, v143
	v_pk_mul_f32 v[134:135], v[138:139], v[134:135]
	v_pk_mul_f32 v[136:137], v[140:141], v[136:137]
	v_pk_mul_f32 v[138:139], v[132:133], v[144:145]
	v_pk_mul_f32 v[132:133], v[130:131], v[142:143]
	v_cvt_pk_bf16_f32 v130, v134, v135
	v_mul_f32_e32 v134, 0xbfb8aa3b, v178
	v_cvt_pk_bf16_f32 v131, v136, v137
	v_pk_mul_f32 v[136:137], v[128:129], v[134:135] op_sel_hi:[1,0]
	v_pk_mul_f32 v[140:141], v[126:127], v[134:135] op_sel_hi:[1,0]
	v_add_f32_e32 v135, v154, v136
	v_exp_f32_e32 v136, v135
	v_add_f32_e32 v135, v155, v137
	v_pk_fma_f32 v[128:129], v[128:129], v[178:179], v[104:105] op_sel_hi:[1,0,1]
	v_pk_fma_f32 v[126:127], v[126:127], v[178:179], v[102:103] op_sel_hi:[1,0,1]
	v_pk_fma_f32 v[124:125], v[124:125], v[178:179], v[100:101] op_sel_hi:[1,0,1]
	v_pk_fma_f32 v[122:123], v[122:123], v[178:179], v[98:99] op_sel_hi:[1,0,1]
	v_pk_mul_f32 v[124:125], v[128:129], v[124:125]
	v_pk_mul_f32 v[122:123], v[126:127], v[122:123]
	v_pk_mul_f32 v[126:127], v[120:121], v[134:135] op_sel_hi:[1,0]
	v_pk_mul_f32 v[128:129], v[118:119], v[134:135] op_sel_hi:[1,0]
	v_cvt_pk_bf16_f32 v132, v132, v133
	v_add_f32_e32 v133, v156, v140
	v_add_f32_e32 v128, v152, v128
	v_add_f32_e32 v129, v153, v129
	v_add_f32_e32 v126, v150, v126
	v_add_f32_e32 v127, v151, v127
	v_exp_f32_e32 v140, v133
	v_add_f32_e32 v133, v157, v141
	v_exp_f32_e32 v128, v128
	v_exp_f32_e32 v126, v126
	v_exp_f32_e32 v127, v127
	v_exp_f32_e32 v129, v129
	v_exp_f32_e32 v141, v133
	v_cvt_pk_bf16_f32 v133, v138, v139
	v_pk_add_f32 v[126:127], v[126:127], 1.0 op_sel_hi:[1,0]
	v_pk_add_f32 v[128:129], v[128:129], 1.0 op_sel_hi:[1,0]
	global_store_dwordx4 v166, v[130:133], s[30:31] nt
	v_rcp_f32_e32 v128, v128
	v_rcp_f32_e32 v129, v129
	v_pk_add_f32 v[132:133], v[140:141], 1.0 op_sel_hi:[1,0]
	v_rcp_f32_e32 v126, v126
	v_rcp_f32_e32 v127, v127
	v_rcp_f32_e32 v132, v132
	v_rcp_f32_e32 v133, v133
	v_pk_fma_f32 v[120:121], v[120:121], v[178:179], v[88:89] op_sel_hi:[1,0,1]
	v_pk_fma_f32 v[118:119], v[118:119], v[178:179], v[86:87] op_sel_hi:[1,0,1]
	v_pk_fma_f32 v[116:117], v[116:117], v[178:179], v[84:85] op_sel_hi:[1,0,1]
	v_pk_fma_f32 v[114:115], v[114:115], v[178:179], v[82:83] op_sel_hi:[1,0,1]
	v_pk_mul_f32 v[116:117], v[120:121], v[116:117]
	v_pk_mul_f32 v[114:115], v[118:119], v[114:115]
	v_pk_mul_f32 v[118:119], v[116:117], v[126:127]
	v_pk_mul_f32 v[116:117], v[114:115], v[128:129]
	v_pk_mul_f32 v[122:123], v[122:123], v[132:133]
	v_cvt_pk_bf16_f32 v116, v116, v117
	v_cvt_pk_bf16_f32 v117, v118, v119
	v_mul_f32_e32 v118, 0xbfb8aa3b, v168
	v_exp_f32_e32 v137, v135
	v_cvt_pk_bf16_f32 v114, v122, v123
	v_pk_mul_f32 v[122:123], v[110:111], v[118:119] op_sel_hi:[1,0]
	v_pk_mul_f32 v[120:121], v[112:113], v[118:119] op_sel_hi:[1,0]
	v_add_f32_e32 v119, v156, v122
	v_exp_f32_e32 v122, v119
	v_add_f32_e32 v119, v157, v123
	v_exp_f32_e32 v123, v119
	v_add_f32_e32 v119, v154, v120
	v_pk_add_f32 v[130:131], v[136:137], 1.0 op_sel_hi:[1,0]
	v_exp_f32_e32 v120, v119
	v_add_f32_e32 v119, v155, v121
	v_pk_fma_f32 v[112:113], v[112:113], v[168:169], v[104:105] op_sel_hi:[1,0,1]
	v_pk_fma_f32 v[110:111], v[110:111], v[168:169], v[102:103] op_sel_hi:[1,0,1]
	v_pk_fma_f32 v[108:109], v[108:109], v[168:169], v[100:101] op_sel_hi:[1,0,1]
	v_pk_fma_f32 v[106:107], v[106:107], v[168:169], v[98:99] op_sel_hi:[1,0,1]
	v_rcp_f32_e32 v130, v130
	v_rcp_f32_e32 v131, v131
	v_pk_mul_f32 v[106:107], v[110:111], v[106:107]
	v_pk_mul_f32 v[108:109], v[112:113], v[108:109]
	v_pk_mul_f32 v[110:111], v[96:97], v[118:119] op_sel_hi:[1,0]
	v_pk_mul_f32 v[112:113], v[94:95], v[118:119] op_sel_hi:[1,0]
	v_add_f32_e32 v110, v150, v110
	v_add_f32_e32 v112, v152, v112
	v_add_f32_e32 v113, v153, v113
	v_add_f32_e32 v111, v151, v111
	v_exp_f32_e32 v112, v112
	v_exp_f32_e32 v110, v110
	v_exp_f32_e32 v111, v111
	v_exp_f32_e32 v113, v113
	v_pk_mul_f32 v[124:125], v[124:125], v[130:131]
	s_mov_b32 s30, 0x2b000
	v_cvt_pk_bf16_f32 v115, v124, v125
	v_add_co_u32_e32 v124, vcc, s30, v146
	v_pk_add_f32 v[110:111], v[110:111], 1.0 op_sel_hi:[1,0]
	s_nop 0
	v_addc_co_u32_e32 v125, vcc, 0, v147, vcc
;     template <int QVV> __device__ __forceinline__ void run(f32x4 (&acc)[2][2][4][2], const Unit& u, int wr, int wc, int fr, int fq) const {
;     ...
; #pragma unroll
;         for (int ai = 0; ai < 2; ++ai)
; #pragma unroll
;             for (int m = 0; m < 4; ++m) { if (ai >= nai) continue;
;                 const float r = rs[ai][m], rn = r * (-LOG2E);
;                 f32x4 o[2];
; #pragma unroll
;                 for (int n = 0; n < 2; ++n) {
;                     const f32x4 gt = acc[ai][0][m][n] * r + sg[n], up = acc[ai][1][m][n] * r + su[n], ex = acc[ai][0][m][n] * rn + sgn[n];
;                     f32x4 den, rc;
; #pragma unroll
;                     for (int i = 0; i < 4; ++i) den[i] = __builtin_amdgcn_exp2f(ex[i]);
;                     den = den + 1.0f;
; #pragma unroll
;                     for (int i = 0; i < 4; ++i) rc[i] = __builtin_amdgcn_rcpf(den[i]);
;                     o[n] = (gt * up) * rc; }
;                 u32x4 w; w.x = pk2(o[0][0], o[0][1]); w.y = pk2(o[0][2], o[0][3]); w.z = pk2(o[1][0], o[1][1]); w.w = pk2(o[1][2], o[1][3]);
;                 *(u32x4*)(tb + lo + (unsigned)(ai * HALF + m * 16) * (DFF * 2)) = w; }
	v_pk_add_f32 v[112:113], v[112:113], 1.0 op_sel_hi:[1,0]
	global_store_dwordx4 v[124:125], v[114:117], off nt
	v_rcp_f32_e32 v112, v112
	v_rcp_f32_e32 v113, v113
	v_pk_add_f32 v[116:117], v[122:123], 1.0 op_sel_hi:[1,0]
	v_rcp_f32_e32 v110, v110
	v_rcp_f32_e32 v111, v111
	v_rcp_f32_e32 v116, v116
	v_rcp_f32_e32 v117, v117
	v_pk_fma_f32 v[96:97], v[96:97], v[168:169], v[88:89] op_sel_hi:[1,0,1]
	v_pk_fma_f32 v[94:95], v[94:95], v[168:169], v[86:87] op_sel_hi:[1,0,1]
	v_pk_fma_f32 v[92:93], v[92:93], v[168:169], v[84:85] op_sel_hi:[1,0,1]
	v_pk_fma_f32 v[90:91], v[90:91], v[168:169], v[82:83] op_sel_hi:[1,0,1]
	v_pk_mul_f32 v[92:93], v[96:97], v[92:93]
	v_pk_mul_f32 v[90:91], v[94:95], v[90:91]
	v_pk_mul_f32 v[94:95], v[92:93], v[110:111]
	v_pk_mul_f32 v[92:93], v[90:91], v[112:113]
	v_pk_mul_f32 v[106:107], v[106:107], v[116:117]
	v_cvt_pk_bf16_f32 v92, v92, v93
	v_cvt_pk_bf16_f32 v93, v94, v95
	v_mul_f32_e32 v94, 0xbfb8aa3b, v164
	v_exp_f32_e32 v121, v119
	v_cvt_pk_bf16_f32 v90, v106, v107
	v_pk_mul_f32 v[106:107], v[78:79], v[94:95] op_sel_hi:[1,0]
	v_pk_mul_f32 v[96:97], v[80:81], v[94:95] op_sel_hi:[1,0]
	v_add_f32_e32 v95, v156, v106
	v_exp_f32_e32 v106, v95
	v_add_f32_e32 v95, v157, v107
	v_exp_f32_e32 v107, v95
	v_add_f32_e32 v95, v154, v96
	v_pk_add_f32 v[114:115], v[120:121], 1.0 op_sel_hi:[1,0]
	v_exp_f32_e32 v96, v95
	v_add_f32_e32 v95, v155, v97
	v_pk_fma_f32 v[80:81], v[80:81], v[164:165], v[104:105] op_sel_hi:[1,0,1]
	v_pk_fma_f32 v[78:79], v[78:79], v[164:165], v[102:103] op_sel_hi:[1,0,1]
	v_pk_fma_f32 v[76:77], v[76:77], v[164:165], v[100:101] op_sel_hi:[1,0,1]
	v_pk_fma_f32 v[74:75], v[74:75], v[164:165], v[98:99] op_sel_hi:[1,0,1]
	v_rcp_f32_e32 v114, v114
	v_rcp_f32_e32 v115, v115
	v_pk_mul_f32 v[74:75], v[78:79], v[74:75]
	v_pk_mul_f32 v[76:77], v[80:81], v[76:77]
	v_pk_mul_f32 v[78:79], v[72:73], v[94:95] op_sel_hi:[1,0]
	v_pk_mul_f32 v[80:81], v[70:71], v[94:95] op_sel_hi:[1,0]
	v_add_f32_e32 v78, v150, v78
	v_add_f32_e32 v80, v152, v80
	v_add_f32_e32 v81, v153, v81
	v_add_f32_e32 v79, v151, v79
	v_exp_f32_e32 v80, v80
	v_exp_f32_e32 v78, v78
	v_exp_f32_e32 v79, v79
	v_exp_f32_e32 v81, v81
	v_pk_mul_f32 v[108:109], v[108:109], v[114:115]
	s_mov_b32 s30, 0x56000
	v_cvt_pk_bf16_f32 v91, v108, v109
	v_add_co_u32_e32 v108, vcc, s30, v146
	v_pk_add_f32 v[78:79], v[78:79], 1.0 op_sel_hi:[1,0]
	s_nop 0
	v_addc_co_u32_e32 v109, vcc, 0, v147, vcc
	v_pk_add_f32 v[80:81], v[80:81], 1.0 op_sel_hi:[1,0]
	global_store_dwordx4 v[108:109], v[90:93], off nt
	v_rcp_f32_e32 v80, v80
	v_rcp_f32_e32 v81, v81
	v_pk_add_f32 v[92:93], v[106:107], 1.0 op_sel_hi:[1,0]
	v_rcp_f32_e32 v78, v78
	v_rcp_f32_e32 v79, v79
	v_rcp_f32_e32 v92, v92
	v_rcp_f32_e32 v93, v93
	v_pk_fma_f32 v[72:73], v[72:73], v[164:165], v[88:89] op_sel_hi:[1,0,1]
	v_pk_fma_f32 v[70:71], v[70:71], v[164:165], v[86:87] op_sel_hi:[1,0,1]
	v_pk_fma_f32 v[68:69], v[68:69], v[164:165], v[84:85] op_sel_hi:[1,0,1]
	v_pk_fma_f32 v[66:67], v[66:67], v[164:165], v[82:83] op_sel_hi:[1,0,1]
	v_pk_mul_f32 v[68:69], v[72:73], v[68:69]
	v_pk_mul_f32 v[66:67], v[70:71], v[66:67]
	v_pk_mul_f32 v[70:71], v[68:69], v[78:79]
	v_pk_mul_f32 v[68:69], v[66:67], v[80:81]
	v_pk_mul_f32 v[74:75], v[74:75], v[92:93]
	v_cvt_pk_bf16_f32 v68, v68, v69
	v_cvt_pk_bf16_f32 v69, v70, v71
	v_mul_f32_e32 v70, 0xbfb8aa3b, v162
	v_exp_f32_e32 v97, v95
	v_cvt_pk_bf16_f32 v66, v74, v75
	v_pk_mul_f32 v[74:75], v[62:63], v[70:71] op_sel_hi:[1,0]
	v_pk_mul_f32 v[72:73], v[64:65], v[70:71] op_sel_hi:[1,0]
	v_add_f32_e32 v71, v156, v74
	v_exp_f32_e32 v74, v71
	v_add_f32_e32 v71, v157, v75
	v_exp_f32_e32 v75, v71
	v_add_f32_e32 v71, v154, v72
	v_pk_add_f32 v[90:91], v[96:97], 1.0 op_sel_hi:[1,0]
	v_exp_f32_e32 v72, v71
	v_add_f32_e32 v71, v155, v73
	v_pk_fma_f32 v[64:65], v[64:65], v[162:163], v[104:105] op_sel_hi:[1,0,1]
	v_pk_fma_f32 v[62:63], v[62:63], v[162:163], v[102:103] op_sel_hi:[1,0,1]
	v_pk_fma_f32 v[60:61], v[60:61], v[162:163], v[100:101] op_sel_hi:[1,0,1]
	v_pk_fma_f32 v[58:59], v[58:59], v[162:163], v[98:99] op_sel_hi:[1,0,1]
	v_rcp_f32_e32 v90, v90
	v_rcp_f32_e32 v91, v91
	v_pk_mul_f32 v[58:59], v[62:63], v[58:59]
	v_pk_mul_f32 v[60:61], v[64:65], v[60:61]
	v_pk_mul_f32 v[62:63], v[56:57], v[70:71] op_sel_hi:[1,0]
	v_pk_mul_f32 v[64:65], v[54:55], v[70:71] op_sel_hi:[1,0]
	v_add_f32_e32 v62, v150, v62
	v_add_f32_e32 v64, v152, v64
	v_add_f32_e32 v65, v153, v65
	v_add_f32_e32 v63, v151, v63
	v_exp_f32_e32 v64, v64
	v_exp_f32_e32 v62, v62
	v_exp_f32_e32 v63, v63
	v_exp_f32_e32 v65, v65
	v_pk_mul_f32 v[76:77], v[76:77], v[90:91]
	s_mov_b32 s30, 0x81000
	v_cvt_pk_bf16_f32 v67, v76, v77
	v_add_co_u32_e32 v76, vcc, s30, v146
	v_pk_add_f32 v[62:63], v[62:63], 1.0 op_sel_hi:[1,0]
	s_nop 0
	v_addc_co_u32_e32 v77, vcc, 0, v147, vcc
	v_pk_add_f32 v[64:65], v[64:65], 1.0 op_sel_hi:[1,0]
	global_store_dwordx4 v[76:77], v[66:69], off nt
	v_rcp_f32_e32 v64, v64
	v_rcp_f32_e32 v65, v65
	v_pk_add_f32 v[68:69], v[74:75], 1.0 op_sel_hi:[1,0]
	v_rcp_f32_e32 v62, v62
	v_rcp_f32_e32 v63, v63
	v_rcp_f32_e32 v68, v68
	v_rcp_f32_e32 v69, v69
	v_pk_fma_f32 v[56:57], v[56:57], v[162:163], v[88:89] op_sel_hi:[1,0,1]
	v_pk_fma_f32 v[54:55], v[54:55], v[162:163], v[86:87] op_sel_hi:[1,0,1]
	v_pk_fma_f32 v[52:53], v[52:53], v[162:163], v[84:85] op_sel_hi:[1,0,1]
	v_pk_fma_f32 v[50:51], v[50:51], v[162:163], v[82:83] op_sel_hi:[1,0,1]
	v_pk_mul_f32 v[52:53], v[56:57], v[52:53]
	v_pk_mul_f32 v[50:51], v[54:55], v[50:51]
	v_pk_mul_f32 v[54:55], v[52:53], v[62:63]
	v_pk_mul_f32 v[52:53], v[50:51], v[64:65]
	v_pk_mul_f32 v[58:59], v[58:59], v[68:69]
	v_cvt_pk_bf16_f32 v52, v52, v53
	v_cvt_pk_bf16_f32 v53, v54, v55
;     template <int QVV> __device__ __forceinline__ void run(f32x4 (&acc)[2][2][4][2], const Unit& u, int wr, int wc, int fr, int fq) const {
;     ...
; #pragma unroll
;         for (int ai = 0; ai < 2; ++ai)
; #pragma unroll
;             for (int m = 0; m < 4; ++m) { if (ai >= nai) continue;
;                 const float r = rs[ai][m], rn = r * (-LOG2E);
;                 f32x4 o[2];
; #pragma unroll
;                 for (int n = 0; n < 2; ++n) {
;                     const f32x4 gt = acc[ai][0][m][n] * r + sg[n], up = acc[ai][1][m][n] * r + su[n], ex = acc[ai][0][m][n] * rn + sgn[n];
;                     f32x4 den, rc;
; #pragma unroll
;                     for (int i = 0; i < 4; ++i) den[i] = __builtin_amdgcn_exp2f(ex[i]);
;                     den = den + 1.0f;
; #pragma unroll
;                     for (int i = 0; i < 4; ++i) rc[i] = __builtin_amdgcn_rcpf(den[i]);
;                     o[n] = (gt * up) * rc; }
;                 u32x4 w; w.x = pk2(o[0][0], o[0][1]); w.y = pk2(o[0][2], o[0][3]); w.z = pk2(o[1][0], o[1][1]); w.w = pk2(o[1][2], o[1][3]);
;                 *(u32x4*)(tb + lo + (unsigned)(ai * HALF + m * 16) * (DFF * 2)) = w; }
	v_mul_f32_e32 v54, 0xbfb8aa3b, v160
	v_exp_f32_e32 v73, v71
	v_cvt_pk_bf16_f32 v50, v58, v59
	v_pk_mul_f32 v[58:59], v[46:47], v[54:55] op_sel_hi:[1,0]
	v_pk_mul_f32 v[56:57], v[48:49], v[54:55] op_sel_hi:[1,0]
	v_add_f32_e32 v55, v156, v58
	v_exp_f32_e32 v58, v55
	v_add_f32_e32 v55, v157, v59
	v_exp_f32_e32 v59, v55
	v_add_f32_e32 v55, v154, v56
	v_pk_add_f32 v[66:67], v[72:73], 1.0 op_sel_hi:[1,0]
	v_exp_f32_e32 v56, v55
	v_add_f32_e32 v55, v155, v57
	v_pk_fma_f32 v[48:49], v[48:49], v[160:161], v[104:105] op_sel_hi:[1,0,1]
	v_pk_fma_f32 v[46:47], v[46:47], v[160:161], v[102:103] op_sel_hi:[1,0,1]
	v_pk_fma_f32 v[44:45], v[44:45], v[160:161], v[100:101] op_sel_hi:[1,0,1]
	v_pk_fma_f32 v[42:43], v[42:43], v[160:161], v[98:99] op_sel_hi:[1,0,1]
	v_rcp_f32_e32 v66, v66
	v_rcp_f32_e32 v67, v67
	v_pk_mul_f32 v[42:43], v[46:47], v[42:43]
	v_pk_mul_f32 v[44:45], v[48:49], v[44:45]
	v_pk_mul_f32 v[46:47], v[40:41], v[54:55] op_sel_hi:[1,0]
	v_pk_mul_f32 v[48:49], v[38:39], v[54:55] op_sel_hi:[1,0]
	v_add_f32_e32 v46, v150, v46
	v_add_f32_e32 v48, v152, v48
	v_add_f32_e32 v49, v153, v49
	v_add_f32_e32 v47, v151, v47
	v_exp_f32_e32 v48, v48
	v_exp_f32_e32 v46, v46
	v_exp_f32_e32 v47, v47
	v_exp_f32_e32 v49, v49
	v_pk_mul_f32 v[60:61], v[60:61], v[66:67]
	s_mov_b32 s30, 0x158000
	v_cvt_pk_bf16_f32 v51, v60, v61
	v_add_co_u32_e32 v60, vcc, s30, v146
	v_pk_add_f32 v[46:47], v[46:47], 1.0 op_sel_hi:[1,0]
	s_nop 0
	v_addc_co_u32_e32 v61, vcc, 0, v147, vcc
	v_pk_add_f32 v[48:49], v[48:49], 1.0 op_sel_hi:[1,0]
	global_store_dwordx4 v[60:61], v[50:53], off nt
	v_rcp_f32_e32 v48, v48
	v_rcp_f32_e32 v49, v49
	v_pk_add_f32 v[52:53], v[58:59], 1.0 op_sel_hi:[1,0]
	v_rcp_f32_e32 v46, v46
	v_rcp_f32_e32 v47, v47
	v_rcp_f32_e32 v52, v52
	v_rcp_f32_e32 v53, v53
	v_pk_fma_f32 v[40:41], v[40:41], v[160:161], v[88:89] op_sel_hi:[1,0,1]
	v_pk_fma_f32 v[38:39], v[38:39], v[160:161], v[86:87] op_sel_hi:[1,0,1]
	v_pk_fma_f32 v[36:37], v[36:37], v[160:161], v[84:85] op_sel_hi:[1,0,1]
	v_pk_fma_f32 v[34:35], v[34:35], v[160:161], v[82:83] op_sel_hi:[1,0,1]
	v_pk_mul_f32 v[36:37], v[40:41], v[36:37]
	v_pk_mul_f32 v[34:35], v[38:39], v[34:35]
	v_pk_mul_f32 v[38:39], v[36:37], v[46:47]
	v_pk_mul_f32 v[36:37], v[34:35], v[48:49]
	v_pk_mul_f32 v[42:43], v[42:43], v[52:53]
	v_cvt_pk_bf16_f32 v36, v36, v37
	v_cvt_pk_bf16_f32 v37, v38, v39
	v_mul_f32_e32 v38, 0xbfb8aa3b, v158
	v_exp_f32_e32 v57, v55
	v_cvt_pk_bf16_f32 v34, v42, v43
	v_pk_mul_f32 v[42:43], v[30:31], v[38:39] op_sel_hi:[1,0]
	v_pk_mul_f32 v[40:41], v[32:33], v[38:39] op_sel_hi:[1,0]
	v_add_f32_e32 v39, v156, v42
	v_exp_f32_e32 v42, v39
	v_add_f32_e32 v39, v157, v43
	v_exp_f32_e32 v43, v39
	v_add_f32_e32 v39, v154, v40
	v_pk_add_f32 v[50:51], v[56:57], 1.0 op_sel_hi:[1,0]
	v_exp_f32_e32 v40, v39
	v_add_f32_e32 v39, v155, v41
	v_pk_fma_f32 v[32:33], v[32:33], v[158:159], v[104:105] op_sel_hi:[1,0,1]
	v_pk_fma_f32 v[30:31], v[30:31], v[158:159], v[102:103] op_sel_hi:[1,0,1]
	v_pk_fma_f32 v[28:29], v[28:29], v[158:159], v[100:101] op_sel_hi:[1,0,1]
	v_pk_fma_f32 v[26:27], v[26:27], v[158:159], v[98:99] op_sel_hi:[1,0,1]
	v_rcp_f32_e32 v50, v50
	v_rcp_f32_e32 v51, v51
	v_pk_mul_f32 v[26:27], v[30:31], v[26:27]
	v_pk_mul_f32 v[28:29], v[32:33], v[28:29]
	v_pk_mul_f32 v[30:31], v[24:25], v[38:39] op_sel_hi:[1,0]
	v_pk_mul_f32 v[32:33], v[22:23], v[38:39] op_sel_hi:[1,0]
	v_add_f32_e32 v30, v150, v30
	v_add_f32_e32 v32, v152, v32
	v_add_f32_e32 v33, v153, v33
	v_add_f32_e32 v31, v151, v31
	v_exp_f32_e32 v32, v32
	v_exp_f32_e32 v30, v30
	v_exp_f32_e32 v31, v31
	v_exp_f32_e32 v33, v33
	v_pk_mul_f32 v[44:45], v[44:45], v[50:51]
	s_mov_b32 s30, 0x183000
	v_cvt_pk_bf16_f32 v35, v44, v45
	v_add_co_u32_e32 v44, vcc, s30, v146
	v_pk_add_f32 v[30:31], v[30:31], 1.0 op_sel_hi:[1,0]
	s_nop 0
	v_addc_co_u32_e32 v45, vcc, 0, v147, vcc
; #define PG8_BAR __builtin_amdgcn_s_barrier()
;     ...
;         if (wr == 0) PG8_BAR;
;         E.template run<QV>(acc, cur, wr, wc, fr, fq);
;         if (!has_next) break;
;         if (!cur.keep) {
; #pragma unroll
;             for (int a = 0; a < 2; ++a)
; #pragma unroll
;                 for (int b = 0; b < 2; ++b)
; #pragma unroll
;                     for (int m = 0; m < 4; ++m)
; #pragma unroll
;                         for (int n = 0; n < 2; ++n) { f32x2 z0, z1; asm("v_mov_b64 %0, 0\n\tv_mov_b64 %1, 0" : "=v"(z0), "=v"(z1));
;                     acc[a][b][m][n] = __builtin_shufflevector(z0, z1, 0, 1, 2, 3); }
;         }
;         cur = nxt; cA = nA; cB = nB; ++ui;
;         if (wr == 1) PG8_BAR;
;     template <int QVV> __device__ __forceinline__ void run(f32x4 (&acc)[2][2][4][2], const Unit& u, int wr, int wc, int fr, int fq) const {
;     ...
; #pragma unroll
;         for (int ai = 0; ai < 2; ++ai)
; #pragma unroll
;             for (int m = 0; m < 4; ++m) { if (ai >= nai) continue;
;                 const float r = rs[ai][m], rn = r * (-LOG2E);
;                 f32x4 o[2];
; #pragma unroll
;                 for (int n = 0; n < 2; ++n) {
;                     const f32x4 gt = acc[ai][0][m][n] * r + sg[n], up = acc[ai][1][m][n] * r + su[n], ex = acc[ai][0][m][n] * rn + sgn[n];
;                     f32x4 den, rc;
; #pragma unroll
;                     for (int i = 0; i < 4; ++i) den[i] = __builtin_amdgcn_exp2f(ex[i]);
;                     den = den + 1.0f;
; #pragma unroll
;                     for (int i = 0; i < 4; ++i) rc[i] = __builtin_amdgcn_rcpf(den[i]);
;                     o[n] = (gt * up) * rc; }
;                 u32x4 w; w.x = pk2(o[0][0], o[0][1]); w.y = pk2(o[0][2], o[0][3]); w.z = pk2(o[1][0], o[1][1]); w.w = pk2(o[1][2], o[1][3]);
;                 *(u32x4*)(tb + lo + (unsigned)(ai * HALF + m * 16) * (DFF * 2)) = w; }
	v_pk_add_f32 v[32:33], v[32:33], 1.0 op_sel_hi:[1,0]
	v_fmamk_f32 v148, v188, 0x30000000, v231
	global_store_dwordx4 v[44:45], v[34:37], off nt
	v_rcp_f32_e32 v32, v32
	v_rcp_f32_e32 v33, v33
	v_pk_add_f32 v[36:37], v[42:43], 1.0 op_sel_hi:[1,0]
	v_rcp_f32_e32 v30, v30
	v_rcp_f32_e32 v31, v31
	v_rsq_f32_e32 v148, v148
	v_rcp_f32_e32 v36, v36
	v_rcp_f32_e32 v37, v37
	v_pk_fma_f32 v[24:25], v[24:25], v[158:159], v[88:89] op_sel_hi:[1,0,1]
	v_pk_fma_f32 v[22:23], v[22:23], v[158:159], v[86:87] op_sel_hi:[1,0,1]
	v_pk_fma_f32 v[20:21], v[20:21], v[158:159], v[84:85] op_sel_hi:[1,0,1]
	v_pk_fma_f32 v[18:19], v[18:19], v[158:159], v[82:83] op_sel_hi:[1,0,1]
	v_pk_mul_f32 v[20:21], v[24:25], v[20:21]
	v_pk_mul_f32 v[18:19], v[22:23], v[18:19]
	v_pk_mul_f32 v[22:23], v[20:21], v[30:31]
	v_pk_mul_f32 v[20:21], v[18:19], v[32:33]
	v_pk_mul_f32 v[26:27], v[26:27], v[36:37]
	v_cvt_pk_bf16_f32 v20, v20, v21
	v_cvt_pk_bf16_f32 v21, v22, v23
	v_mul_f32_e32 v22, 0xbfb8aa3b, v148
	v_cvt_pk_bf16_f32 v18, v26, v27
	v_pk_mul_f32 v[26:27], v[14:15], v[22:23] op_sel_hi:[1,0]
	v_exp_f32_e32 v41, v39
	v_pk_mul_f32 v[24:25], v[16:17], v[22:23] op_sel_hi:[1,0]
	v_add_f32_e32 v23, v156, v26
	v_exp_f32_e32 v26, v23
	v_add_f32_e32 v23, v157, v27
	v_exp_f32_e32 v27, v23
	v_add_f32_e32 v23, v154, v24
	v_exp_f32_e32 v24, v23
	v_add_f32_e32 v23, v155, v25
	v_pk_fma_f32 v[16:17], v[16:17], v[148:149], v[104:105] op_sel_hi:[1,0,1]
	v_pk_fma_f32 v[14:15], v[14:15], v[148:149], v[102:103] op_sel_hi:[1,0,1]
	v_pk_fma_f32 v[12:13], v[12:13], v[148:149], v[100:101] op_sel_hi:[1,0,1]
	v_pk_fma_f32 v[10:11], v[10:11], v[148:149], v[98:99] op_sel_hi:[1,0,1]
	v_pk_add_f32 v[34:35], v[40:41], 1.0 op_sel_hi:[1,0]
	v_pk_mul_f32 v[10:11], v[14:15], v[10:11]
	v_pk_mul_f32 v[12:13], v[16:17], v[12:13]
	v_pk_mul_f32 v[14:15], v[8:9], v[22:23] op_sel_hi:[1,0]
	v_pk_mul_f32 v[16:17], v[6:7], v[22:23] op_sel_hi:[1,0]
	v_rcp_f32_e32 v34, v34
	v_rcp_f32_e32 v35, v35
	v_add_f32_e32 v16, v152, v16
	v_add_f32_e32 v17, v153, v17
	v_add_f32_e32 v14, v150, v14
	v_add_f32_e32 v15, v151, v15
	v_exp_f32_e32 v16, v16
	v_exp_f32_e32 v14, v14
	v_exp_f32_e32 v15, v15
	v_exp_f32_e32 v17, v17
	v_exp_f32_e32 v25, v23
	v_pk_mul_f32 v[28:29], v[28:29], v[34:35]
	s_mov_b32 s30, 0x1ae000
	v_cvt_pk_bf16_f32 v19, v28, v29
	v_add_co_u32_e32 v28, vcc, s30, v146
	v_pk_add_f32 v[14:15], v[14:15], 1.0 op_sel_hi:[1,0]
	v_pk_add_f32 v[16:17], v[16:17], 1.0 op_sel_hi:[1,0]
	v_addc_co_u32_e32 v29, vcc, 0, v147, vcc
	v_rcp_f32_e32 v16, v16
	v_rcp_f32_e32 v17, v17
	v_rcp_f32_e32 v14, v14
	v_rcp_f32_e32 v15, v15
	global_store_dwordx4 v[28:29], v[18:21], off nt
	v_pk_fma_f32 v[8:9], v[8:9], v[148:149], v[88:89] op_sel_hi:[1,0,1]
	v_pk_fma_f32 v[6:7], v[6:7], v[148:149], v[86:87] op_sel_hi:[1,0,1]
	v_pk_add_f32 v[18:19], v[24:25], 1.0 op_sel_hi:[1,0]
	v_pk_add_f32 v[20:21], v[26:27], 1.0 op_sel_hi:[1,0]
	v_rcp_f32_e32 v18, v18
	v_rcp_f32_e32 v20, v20
	v_rcp_f32_e32 v21, v21
	v_rcp_f32_e32 v19, v19
	v_pk_fma_f32 v[4:5], v[4:5], v[148:149], v[84:85] op_sel_hi:[1,0,1]
	v_pk_fma_f32 v[2:3], v[2:3], v[148:149], v[82:83] op_sel_hi:[1,0,1]
	v_pk_mul_f32 v[4:5], v[8:9], v[4:5]
	v_pk_mul_f32 v[2:3], v[6:7], v[2:3]
	v_pk_mul_f32 v[6:7], v[4:5], v[14:15]
	v_pk_mul_f32 v[4:5], v[2:3], v[16:17]
	v_pk_mul_f32 v[12:13], v[12:13], v[18:19]
	v_cvt_pk_bf16_f32 v4, v4, v5
	v_cvt_pk_bf16_f32 v5, v6, v7
	v_add_co_u32_e32 v6, vcc, 0x1d9000, v146
	v_pk_mul_f32 v[10:11], v[10:11], v[20:21]
	s_nop 0
	v_addc_co_u32_e32 v7, vcc, 0, v147, vcc
	v_cvt_pk_bf16_f32 v2, v10, v11
	v_cvt_pk_bf16_f32 v3, v12, v13
	s_andn2_b64 vcc, exec, s[38:39]
	s_mov_b64 s[30:31], -1
	global_store_dwordx4 v[6:7], v[2:5], off nt
	s_cbranch_vccnz .LBB0_1643
	s_andn2_b64 vcc, exec, s[46:47]
	v_mov_b64 v[2:3], 0
	v_mov_b64 v[4:5], 0
	s_cbranch_vccnz .LBB0_1642
	s_barrier
	s_branch .LBB0_1642

; __device__ __forceinline__ void row_rstd(const unsigned long long* ssq, int row0, float (&rs)[2][4]) {
;     unsigned long long q[2][4];
; #pragma unroll
;     for (int ai = 0; ai < 2; ++ai)
; #pragma unroll
;         for (int m = 0; m < 4; ++m) q[ai][m] = ssq[row0 + ai * HALF + m * 16];
;     asm volatile("" : "+v"(q[0][0]), "+v"(q[0][1]), "+v"(q[0][2]), "+v"(q[0][3]), "+v"(q[1][0]), "+v"(q[1][1]), "+v"(q[1][2]), "+v"(q[1][3]));
; #pragma unroll
;     for (int ai = 0; ai < 2; ++ai)
; #pragma unroll
;         for (int m = 0; m < 4; ++m) {
;             const float qf = __builtin_fmaf((float)(unsigned)(q[ai][m] >> 32), 4294967296.0f, (float)(unsigned)q[ai][m]);
;     template <int QVV> __device__ __forceinline__ void run(f32x4 (&acc)[2][2][4][2], const Unit& u, int wr, int wc, int fr, int fq) const {
;         constexpr int nai = (QVV == 2) ? 1 : 2; const int r0 = u.pm * BM + (QVV == 2 ? (u.seg - 1) * HALF : 0);
;         char* tb = (char*)(O + (size_t)r0 * DFF + u.pn * HALF);
;         const int v = u.pm < 4 ? 4 : ((u.pm - 4) >> 5);
;         const char* swb = (const char*)(sw + (size_t)v * SWLD + u.pn * BM);
;         unsigned lo = (unsigned)((wr * 64 + fr) * DFF + wc * 32 + 8 * fq) * 2u;
;         unsigned co = (unsigned)(wc * 32 + 8 * fq) * 4u;
;         asm volatile("" : "+v"(lo), "+v"(co));
;         float rs[2][4]; row_rstd(ssq, r0 + wr * 64 + fr, rs);
;         f32x4 sg[2], su[2], sgn[2];
; #pragma unroll
;         for (int n = 0; n < 2; ++n) { sg[n] = *(const f32x4*)(swb + co + n * 16); su[n] = *(const f32x4*)(swb + co + HALF * 4 + n * 16); sgn[n] = sg[n] * (-LOG2E); }
; #pragma unroll
;         for (int ai = 0; ai < 2; ++ai)
; #pragma unroll
;             for (int m = 0; m < 4; ++m) { if (ai >= nai) continue;
;                 const float r = rs[ai][m], rn = r * (-LOG2E);
;                 f32x4 o[2];
; #pragma unroll
;                 for (int n = 0; n < 2; ++n) {
;                     const f32x4 gt = acc[ai][0][m][n] * r + sg[n], up = acc[ai][1][m][n] * r + su[n], ex = acc[ai][0][m][n] * rn + sgn[n];
;                     f32x4 den, rc;
; #pragma unroll
;                     for (int i = 0; i < 4; ++i) den[i] = __builtin_amdgcn_exp2f(ex[i]);
;                     den = den + 1.0f;
; #pragma unroll
;                     for (int i = 0; i < 4; ++i) rc[i] = __builtin_amdgcn_rcpf(den[i]);
;                     o[n] = (gt * up) * rc; }
.LBB0_1673:
	s_movk_i32 s10, 0x1580
	v_mul_lo_u32 v66, v70, s10
	s_lshl_b32 s8, s8, 8
	v_readlane_b32 s10, v253, 9
	v_or3_b32 v66, v66, v71, s19
	s_or_b32 s8, s8, s10
	v_or_b32_e32 v67, s19, v71
	v_lshlrev_b32_e32 v86, 1, v66
	v_add_u32_e32 v66, s8, v70
	v_lshlrev_b32_e32 v82, 2, v67
	v_ashrrev_i32_e32 v67, 31, v66
	v_lshl_add_u64 v[66:67], v[66:67], 3, s[34:35]
	global_load_dwordx2 v[84:85], v[66:67], off
	global_load_dwordx2 v[88:89], v[66:67], off offset:128
	global_load_dwordx2 v[90:91], v[66:67], off offset:256
	global_load_dwordx2 v[92:93], v[66:67], off offset:384
	global_load_dwordx2 v[68:69], v[66:67], off offset:1024
	global_load_dwordx2 v[70:71], v[66:67], off offset:1152
	global_load_dwordx2 v[72:73], v[66:67], off offset:1280
	s_nop 0
	global_load_dwordx2 v[66:67], v[66:67], off offset:1408
	s_mul_hi_i32 s10, s8, 0x2b00
	s_mulk_i32 s8, 0x2b00
	s_add_u32 s8, s2, s8
	s_addc_u32 s10, s3, s10
	s_lshl_b32 s2, s9, 7
	s_ashr_i32 s3, s2, 31
	s_lshl_b64 s[2:3], s[2:3], 1
	s_add_u32 s30, s8, s2
	s_addc_u32 s31, s10, s3
	s_lshl_b64 s[2:3], s[38:39], 2
	s_add_u32 s5, s5, s2
	s_addc_u32 s7, s7, s3
	s_lshl_b32 s2, s9, 8
	s_ashr_i32 s3, s2, 31
	s_lshl_b64 s[2:3], s[2:3], 2
	s_add_u32 s2, s5, s2
	s_addc_u32 s3, s7, s3
	v_mov_b32_e32 v87, v175
	s_waitcnt vmcnt(0)
	global_load_dwordx4 v[78:81], v82, s[2:3]
	global_load_dwordx4 v[70:73], v82, s[2:3] offset:16
	global_load_dwordx4 v[74:77], v82, s[2:3] offset:512
	global_load_dwordx4 v[66:69], v82, s[2:3] offset:528
	s_flbit_i32_b32 s2, 0
	s_min_u32 s2, s2, 32
	v_mov_b32_e32 v174, v89
	v_lshl_add_u64 v[82:83], s[30:31], 0, v[86:87]
	v_cvt_f32_u32_e32 v87, v88
	v_lshlrev_b64 v[88:89], s2, v[174:175]
	v_mov_b32_e32 v174, v91
	v_cvt_f32_u32_e32 v95, v90
	v_cvt_f32_u32_e32 v96, v84
	v_min_u32_e32 v84, 1, v88
	v_lshlrev_b64 v[90:91], s2, v[174:175]
	v_mov_b32_e32 v174, v93
	v_or_b32_e32 v84, v89, v84
	v_min_u32_e32 v90, 1, v90
	v_lshlrev_b64 v[88:89], s2, v[174:175]
	v_mov_b32_e32 v174, v85
	v_cvt_f32_u32_e32 v93, v84
	v_or_b32_e32 v90, v91, v90
	v_min_u32_e32 v88, 1, v88
	v_lshlrev_b64 v[84:85], s2, v[174:175]
	v_cvt_f32_u32_e32 v90, v90
	v_or_b32_e32 v88, v89, v88
	v_min_u32_e32 v84, 1, v84
	v_cvt_f32_u32_e32 v88, v88
	v_or_b32_e32 v84, v85, v84
	s_sub_i32 s3, 32, s2
	v_cvt_f32_u32_e32 v92, v92
	v_cvt_f32_u32_e32 v84, v84
	v_ldexp_f32 v85, v93, s3
	v_fmac_f32_e32 v87, 0x4f800000, v85
	v_ldexp_f32 v85, v90, s3
	v_fmac_f32_e32 v95, 0x4f800000, v85
	v_ldexp_f32 v85, v88, s3
	v_fmac_f32_e32 v92, 0x4f800000, v85
	v_ldexp_f32 v84, v84, s3
	v_fmamk_f32 v87, v87, 0x30000000, v231
	v_fmamk_f32 v85, v92, 0x30000000, v231
	v_fmac_f32_e32 v96, 0x4f800000, v84
	v_rsq_f32_e32 v94, v87
	v_rsq_f32_e32 v84, v85
	v_fmamk_f32 v85, v96, 0x30000000, v231
	v_rsq_f32_e32 v96, v85
	v_mul_f32_e32 v90, 0xbfb8aa3b, v94
	v_pk_mul_f32 v[98:99], v[56:57], v[90:91] op_sel_hi:[1,0]
	v_pk_mul_f32 v[100:101], v[54:55], v[90:91] op_sel_hi:[1,0]
	v_pk_mul_f32 v[102:103], v[40:41], v[90:91] op_sel_hi:[1,0]
	v_pk_mul_f32 v[104:105], v[38:39], v[90:91] op_sel_hi:[1,0]
	v_mul_f32_e32 v90, 0xbfb8aa3b, v96
	s_mov_b32 s2, 0xbfb8aa3b
	v_fmamk_f32 v87, v95, 0x30000000, v231
	v_pk_mul_f32 v[106:107], v[64:65], v[90:91] op_sel_hi:[1,0]
	v_pk_mul_f32 v[108:109], v[62:63], v[90:91] op_sel_hi:[1,0]
	v_pk_mul_f32 v[110:111], v[60:61], v[90:91] op_sel_hi:[1,0]
	v_pk_mul_f32 v[112:113], v[58:59], v[90:91] op_sel_hi:[1,0]
	v_rsq_f32_e32 v88, v87
	s_waitcnt vmcnt(3)
	v_pk_mul_f32 v[114:115], v[80:81], s[2:3] op_sel_hi:[1,0]
	v_pk_mul_f32 v[116:117], v[78:79], s[2:3] op_sel_hi:[1,0]
	s_waitcnt vmcnt(2)
	v_pk_mul_f32 v[90:91], v[72:73], s[2:3] op_sel_hi:[1,0]
	v_pk_mul_f32 v[92:93], v[70:71], s[2:3] op_sel_hi:[1,0]
	v_pk_fma_f32 v[64:65], v[64:65], v[96:97], v[80:81] op_sel_hi:[1,0,1]
	v_pk_fma_f32 v[62:63], v[62:63], v[96:97], v[78:79] op_sel_hi:[1,0,1]
	s_waitcnt vmcnt(1)
	v_pk_fma_f32 v[52:53], v[52:53], v[96:97], v[76:77] op_sel_hi:[1,0,1]
	v_pk_fma_f32 v[50:51], v[50:51], v[96:97], v[74:75] op_sel_hi:[1,0,1]
	v_pk_fma_f32 v[60:61], v[60:61], v[96:97], v[72:73] op_sel_hi:[1,0,1]
	v_pk_fma_f32 v[58:59], v[58:59], v[96:97], v[70:71] op_sel_hi:[1,0,1]
	s_waitcnt vmcnt(0)
	v_pk_fma_f32 v[48:49], v[48:49], v[96:97], v[68:69] op_sel_hi:[1,0,1]
	v_pk_fma_f32 v[46:47], v[46:47], v[96:97], v[66:67] op_sel_hi:[1,0,1]
	v_pk_fma_f32 v[56:57], v[56:57], v[94:95], v[80:81] op_sel_hi:[1,0,1]
	v_pk_fma_f32 v[54:55], v[54:55], v[94:95], v[78:79] op_sel_hi:[1,0,1]
	v_pk_fma_f32 v[44:45], v[44:45], v[94:95], v[76:77] op_sel_hi:[1,0,1]
	v_pk_fma_f32 v[42:43], v[42:43], v[94:95], v[74:75] op_sel_hi:[1,0,1]
	v_add_f32_e32 v85, v116, v108
	v_add_f32_e32 v87, v117, v109
	v_add_f32_e32 v89, v114, v106
	v_add_f32_e32 v95, v115, v107
	v_pk_mul_f32 v[50:51], v[62:63], v[50:51]
	v_pk_mul_f32 v[52:53], v[64:65], v[52:53]
	v_add_f32_e32 v62, v92, v112
	v_add_f32_e32 v63, v93, v113
	v_add_f32_e32 v64, v90, v110
	v_add_f32_e32 v65, v91, v111
	v_pk_mul_f32 v[46:47], v[58:59], v[46:47]
	v_pk_mul_f32 v[48:49], v[60:61], v[48:49]
	v_add_f32_e32 v96, v116, v100
	v_add_f32_e32 v97, v117, v101
	v_add_f32_e32 v98, v114, v98
	v_add_f32_e32 v99, v115, v99
	v_pk_mul_f32 v[42:43], v[54:55], v[42:43]
	v_pk_mul_f32 v[44:45], v[56:57], v[44:45]
	v_exp_f32_e32 v54, v85
	v_exp_f32_e32 v55, v87
	v_exp_f32_e32 v56, v89
	v_exp_f32_e32 v57, v95
	v_exp_f32_e32 v58, v62
	v_exp_f32_e32 v59, v63
	v_exp_f32_e32 v60, v64
	v_exp_f32_e32 v61, v65
	v_exp_f32_e32 v62, v96
	v_exp_f32_e32 v63, v97
	v_exp_f32_e32 v64, v98
	v_exp_f32_e32 v65, v99
	v_pk_add_f32 v[56:57], v[56:57], 1.0 op_sel_hi:[1,0]
	v_pk_add_f32 v[54:55], v[54:55], 1.0 op_sel_hi:[1,0]
	v_pk_add_f32 v[60:61], v[60:61], 1.0 op_sel_hi:[1,0]
; #define PG8_WAIT_V(n) asm volatile("s_waitcnt vmcnt(" #n ")" ::: "memory")
; #define PG8_BAR __builtin_amdgcn_s_barrier()
;     ...
;     PG8_WAIT_V(0);
;     PG8_BAR;
;     template <int QVV> __device__ __forceinline__ void run(f32x4 (&acc)[2][2][4][2], const Unit& u, int wr, int wc, int fr, int fq) const {
;     ...
;             for (int m = 0; m < 4; ++m) { if (ai >= nai) continue;
;                 const float r = rs[ai][m], rn = r * (-LOG2E);
;                 f32x4 o[2];
; #pragma unroll
;                 for (int n = 0; n < 2; ++n) {
;                     const f32x4 gt = acc[ai][0][m][n] * r + sg[n], up = acc[ai][1][m][n] * r + su[n], ex = acc[ai][0][m][n] * rn + sgn[n];
;                     f32x4 den, rc;
; #pragma unroll
;                     for (int i = 0; i < 4; ++i) den[i] = __builtin_amdgcn_exp2f(ex[i]);
;                     den = den + 1.0f;
; #pragma unroll
;                     for (int i = 0; i < 4; ++i) rc[i] = __builtin_amdgcn_rcpf(den[i]);
;                     o[n] = (gt * up) * rc; }
;                 u32x4 w; w.x = pk2(o[0][0], o[0][1]); w.y = pk2(o[0][2], o[0][3]); w.z = pk2(o[1][0], o[1][1]); w.w = pk2(o[1][2], o[1][3]);
;                 *(u32x4*)(tb + lo + (unsigned)(ai * HALF + m * 16) * (DFF * 2)) = w; }
	v_pk_add_f32 v[58:59], v[58:59], 1.0 op_sel_hi:[1,0]
	v_pk_add_f32 v[64:65], v[64:65], 1.0 op_sel_hi:[1,0]
	v_pk_add_f32 v[62:63], v[62:63], 1.0 op_sel_hi:[1,0]
	v_rcp_f32_e32 v54, v54
	v_rcp_f32_e32 v55, v55
	v_rcp_f32_e32 v56, v56
	v_rcp_f32_e32 v57, v57
	v_rcp_f32_e32 v58, v58
	v_rcp_f32_e32 v59, v59
	v_rcp_f32_e32 v60, v60
	v_rcp_f32_e32 v61, v61
	v_add_f32_e32 v100, v92, v104
	v_add_f32_e32 v101, v93, v105
	v_add_f32_e32 v102, v90, v102
	v_add_f32_e32 v103, v91, v103
	v_rcp_f32_e32 v62, v62
	v_rcp_f32_e32 v63, v63
	v_rcp_f32_e32 v64, v64
	v_rcp_f32_e32 v65, v65
	v_exp_f32_e32 v96, v100
	v_exp_f32_e32 v97, v101
	v_exp_f32_e32 v98, v102
	v_exp_f32_e32 v99, v103
	v_pk_mul_f32 v[52:53], v[52:53], v[56:57]
	v_pk_mul_f32 v[50:51], v[50:51], v[54:55]
	v_pk_mul_f32 v[48:49], v[48:49], v[60:61]
	v_pk_mul_f32 v[46:47], v[46:47], v[58:59]
	v_pk_mul_f32 v[54:55], v[44:45], v[64:65]
	v_pk_mul_f32 v[56:57], v[42:43], v[62:63]
	v_cvt_pk_bf16_f32 v42, v50, v51
	v_cvt_pk_bf16_f32 v43, v52, v53
	v_cvt_pk_bf16_f32 v44, v46, v47
	v_cvt_pk_bf16_f32 v45, v48, v49
	v_pk_add_f32 v[98:99], v[98:99], 1.0 op_sel_hi:[1,0]
	global_store_dwordx4 v86, v[42:45], s[30:31] nt
	v_pk_fma_f32 v[40:41], v[40:41], v[94:95], v[72:73] op_sel_hi:[1,0,1]
	v_pk_fma_f32 v[38:39], v[38:39], v[94:95], v[70:71] op_sel_hi:[1,0,1]
	v_pk_add_f32 v[42:43], v[96:97], 1.0 op_sel_hi:[1,0]
	v_rcp_f32_e32 v44, v98
	v_rcp_f32_e32 v42, v42
	v_rcp_f32_e32 v43, v43
	v_rcp_f32_e32 v45, v99
	v_pk_fma_f32 v[36:37], v[36:37], v[94:95], v[68:69] op_sel_hi:[1,0,1]
	v_pk_fma_f32 v[34:35], v[34:35], v[94:95], v[66:67] op_sel_hi:[1,0,1]
	v_pk_mul_f32 v[36:37], v[40:41], v[36:37]
	v_pk_mul_f32 v[34:35], v[38:39], v[34:35]
	v_pk_mul_f32 v[38:39], v[36:37], v[44:45]
	v_pk_mul_f32 v[36:37], v[34:35], v[42:43]
	v_pk_fma_f32 v[28:29], v[28:29], v[88:89], v[76:77] op_sel_hi:[1,0,1]
	v_cvt_pk_bf16_f32 v36, v36, v37
	v_cvt_pk_bf16_f32 v37, v38, v39
	v_mul_f32_e32 v38, 0xbfb8aa3b, v88
	v_pk_mul_f32 v[42:43], v[30:31], v[38:39] op_sel_hi:[1,0]
	v_pk_mul_f32 v[40:41], v[32:33], v[38:39] op_sel_hi:[1,0]
	v_add_f32_e32 v39, v116, v42
	v_exp_f32_e32 v42, v39
	v_add_f32_e32 v39, v117, v43
	v_exp_f32_e32 v43, v39
	v_add_f32_e32 v39, v114, v40
	v_exp_f32_e32 v40, v39
	v_add_f32_e32 v39, v115, v41
	v_pk_fma_f32 v[32:33], v[32:33], v[88:89], v[80:81] op_sel_hi:[1,0,1]
	v_pk_fma_f32 v[30:31], v[30:31], v[88:89], v[78:79] op_sel_hi:[1,0,1]
	v_pk_fma_f32 v[26:27], v[26:27], v[88:89], v[74:75] op_sel_hi:[1,0,1]
	v_pk_mul_f32 v[28:29], v[32:33], v[28:29]
	v_pk_mul_f32 v[26:27], v[30:31], v[26:27]
	v_pk_mul_f32 v[30:31], v[24:25], v[38:39] op_sel_hi:[1,0]
	v_pk_mul_f32 v[32:33], v[22:23], v[38:39] op_sel_hi:[1,0]
	v_add_f32_e32 v30, v90, v30
	v_add_f32_e32 v32, v92, v32
	v_add_f32_e32 v33, v93, v33
	v_add_f32_e32 v31, v91, v31
	v_exp_f32_e32 v32, v32
	v_exp_f32_e32 v30, v30
	v_exp_f32_e32 v31, v31
	v_exp_f32_e32 v33, v33
	s_mov_b32 s2, 0x2b000
	v_add_co_u32_e32 v44, vcc, s2, v82
	v_cvt_pk_bf16_f32 v34, v56, v57
	v_cvt_pk_bf16_f32 v35, v54, v55
	v_addc_co_u32_e32 v45, vcc, 0, v83, vcc
	v_pk_add_f32 v[30:31], v[30:31], 1.0 op_sel_hi:[1,0]
	v_pk_add_f32 v[32:33], v[32:33], 1.0 op_sel_hi:[1,0]
	global_store_dwordx4 v[44:45], v[34:37], off nt
	v_rcp_f32_e32 v32, v32
	v_rcp_f32_e32 v33, v33
	v_pk_add_f32 v[36:37], v[42:43], 1.0 op_sel_hi:[1,0]
	v_rcp_f32_e32 v30, v30
	v_rcp_f32_e32 v31, v31
	v_rcp_f32_e32 v36, v36
	v_rcp_f32_e32 v37, v37
	v_pk_fma_f32 v[24:25], v[24:25], v[88:89], v[72:73] op_sel_hi:[1,0,1]
	v_pk_fma_f32 v[22:23], v[22:23], v[88:89], v[70:71] op_sel_hi:[1,0,1]
	v_pk_fma_f32 v[20:21], v[20:21], v[88:89], v[68:69] op_sel_hi:[1,0,1]
	v_pk_fma_f32 v[18:19], v[18:19], v[88:89], v[66:67] op_sel_hi:[1,0,1]
	v_pk_mul_f32 v[20:21], v[24:25], v[20:21]
	v_pk_mul_f32 v[18:19], v[22:23], v[18:19]
	v_pk_mul_f32 v[22:23], v[20:21], v[30:31]
	v_pk_mul_f32 v[20:21], v[18:19], v[32:33]
	v_pk_mul_f32 v[26:27], v[26:27], v[36:37]
	v_cvt_pk_bf16_f32 v20, v20, v21
	v_cvt_pk_bf16_f32 v21, v22, v23
	v_mul_f32_e32 v22, 0xbfb8aa3b, v84
	v_exp_f32_e32 v41, v39
	v_cvt_pk_bf16_f32 v18, v26, v27
	v_pk_mul_f32 v[26:27], v[14:15], v[22:23] op_sel_hi:[1,0]
	v_pk_mul_f32 v[24:25], v[16:17], v[22:23] op_sel_hi:[1,0]
	v_add_f32_e32 v23, v116, v26
	v_exp_f32_e32 v26, v23
	v_add_f32_e32 v23, v117, v27
	v_exp_f32_e32 v27, v23
	v_add_f32_e32 v23, v114, v24
	v_pk_add_f32 v[34:35], v[40:41], 1.0 op_sel_hi:[1,0]
	v_exp_f32_e32 v24, v23
	v_add_f32_e32 v23, v115, v25
	v_pk_fma_f32 v[16:17], v[16:17], v[84:85], v[80:81] op_sel_hi:[1,0,1]
	v_pk_fma_f32 v[14:15], v[14:15], v[84:85], v[78:79] op_sel_hi:[1,0,1]
	v_pk_fma_f32 v[12:13], v[12:13], v[84:85], v[76:77] op_sel_hi:[1,0,1]
	v_pk_fma_f32 v[10:11], v[10:11], v[84:85], v[74:75] op_sel_hi:[1,0,1]
	v_rcp_f32_e32 v34, v34
	v_rcp_f32_e32 v35, v35
	v_pk_mul_f32 v[10:11], v[14:15], v[10:11]
	v_pk_mul_f32 v[12:13], v[16:17], v[12:13]
	v_pk_mul_f32 v[14:15], v[8:9], v[22:23] op_sel_hi:[1,0]
	v_pk_mul_f32 v[16:17], v[6:7], v[22:23] op_sel_hi:[1,0]
	v_add_f32_e32 v14, v90, v14
	v_add_f32_e32 v16, v92, v16
	v_add_f32_e32 v17, v93, v17
	v_add_f32_e32 v15, v91, v15
	v_exp_f32_e32 v16, v16
	v_exp_f32_e32 v14, v14
	v_exp_f32_e32 v15, v15
	v_exp_f32_e32 v17, v17
	v_exp_f32_e32 v25, v23
	v_pk_mul_f32 v[28:29], v[28:29], v[34:35]
	s_mov_b32 s2, 0x56000
	v_cvt_pk_bf16_f32 v19, v28, v29
	v_add_co_u32_e32 v28, vcc, s2, v82
	v_pk_add_f32 v[14:15], v[14:15], 1.0 op_sel_hi:[1,0]
	s_nop 0
	v_addc_co_u32_e32 v29, vcc, 0, v83, vcc
	v_pk_add_f32 v[16:17], v[16:17], 1.0 op_sel_hi:[1,0]
	global_store_dwordx4 v[28:29], v[18:21], off nt
	v_rcp_f32_e32 v16, v16
	v_rcp_f32_e32 v17, v17
	v_pk_add_f32 v[18:19], v[24:25], 1.0 op_sel_hi:[1,0]
	v_pk_add_f32 v[20:21], v[26:27], 1.0 op_sel_hi:[1,0]
	v_rcp_f32_e32 v14, v14
	v_rcp_f32_e32 v15, v15
	v_rcp_f32_e32 v20, v20
	v_rcp_f32_e32 v21, v21
	v_rcp_f32_e32 v18, v18
	v_rcp_f32_e32 v19, v19
	v_pk_fma_f32 v[8:9], v[8:9], v[84:85], v[72:73] op_sel_hi:[1,0,1]
	v_pk_fma_f32 v[6:7], v[6:7], v[84:85], v[70:71] op_sel_hi:[1,0,1]
	v_pk_fma_f32 v[4:5], v[4:5], v[84:85], v[68:69] op_sel_hi:[1,0,1]
	v_pk_fma_f32 v[2:3], v[2:3], v[84:85], v[66:67] op_sel_hi:[1,0,1]
	v_pk_mul_f32 v[4:5], v[8:9], v[4:5]
	v_pk_mul_f32 v[2:3], v[6:7], v[2:3]
	v_pk_mul_f32 v[6:7], v[4:5], v[14:15]
	v_pk_mul_f32 v[4:5], v[2:3], v[16:17]
	v_pk_mul_f32 v[12:13], v[12:13], v[18:19]
	v_pk_mul_f32 v[10:11], v[10:11], v[20:21]
	v_cvt_pk_bf16_f32 v4, v4, v5
	v_cvt_pk_bf16_f32 v5, v6, v7
	v_add_co_u32_e32 v6, vcc, 0x81000, v82
	v_cvt_pk_bf16_f32 v2, v10, v11
	v_cvt_pk_bf16_f32 v3, v12, v13
	v_addc_co_u32_e32 v7, vcc, 0, v83, vcc
	global_store_dwordx4 v[6:7], v[2:5], off nt
	s_waitcnt vmcnt(0)
	s_barrier
